# on top of v26: the last per-DMA VALU address adds removed from the GEMM mainloops (only 2 left in the dilated O-proj loop)
# baseline (speedup 1.0000x reference)
; #define PG8_STAGE(bufoff, gbase) do { _Pragma("unroll") for (int _i = 0; _i < 2; ++_i) \
;         __builtin_amdgcn_global_load_lds((const unsigned*)((const char*)(gbase) + voff[_i]), (LAS unsigned*)(lds + (bufoff) + ldsw + _i * 8192), 16, 0, 0); } while (0)
; #define PG8_LDA(dst, b, h) do { _Pragma("unroll") for (int m = 0; m < 4; ++m) _Pragma("unroll") for (int k = 0; k < 2; ++k) dst[m][k] = *(const LAS bf16x8*)(lds + PG8_SA(b, h) + aoff + m * 2048 + k * 1024); } while (0)
; #define PG8_LDB(dst, b, h) do { _Pragma("unroll") for (int n = 0; n < 2; ++n) _Pragma("unroll") for (int k = 0; k < 2; ++k) dst[n][k] = *(const LAS bf16x8*)(lds + PG8_SB(b, h) + boff + n * 2048 + k * 1024); } while (0)
; template <class Epi>
; DI void gemm_phase(LAS unsigned char* lds, const Gemm g, const StaticOrder& S, const Epi& E) {
;     ...
;         for (int t = 0; t < nt; t += 2) {
;             const bool last = (t == nt - 2);
;             const char* a1 = cA + (size_t)(t + 1) * kstep;
;             const char* a2 = last ? nA : cA + (size_t)(t + 2) * kstep; const char* b2 = last ? nB : cB + (size_t)(t + 2) * kstep;
;             const char* a3 = a2 + kstep; const char* b3 = b2 + kstep;
;             PG8_LDB(B0, 0, 0); PG8_SCHED; PG8_LDA(At, 0, 0); PG8_STAGE(PG8_SA(1, 1), a1 + hstep);
;             PG8_WAIT_L(8); PG8_BAR; PG8_WAIT_L(0); PG8_MMA(0, 0, At, B0); PG8_BAR; PG8_SCHED;
;             PG8_LDB(B1, 0, 1); PG8_STAGE(PG8_SB(0, 0), b2);
;             PG8_BAR; PG8_WAIT_L(0); PG8_MMA(0, 1, At, B1); PG8_BAR;
;             PG8_LDA(At, 0, 1); PG8_STAGE(PG8_SA(0, 0), a2);
;             PG8_BAR; PG8_WAIT_L(0); PG8_MMA(1, 0, At, B0); PG8_BAR; PG8_SCHED;
;             PG8_STAGE(PG8_SB(0, 1), b2 + hstep);
;             PG8_WAIT_V(6); PG8_BAR; PG8_MMA(1, 1, At, B1); PG8_BAR;
;             PG8_LDB(B0, 1, 0); PG8_SCHED; PG8_LDA(At, 1, 0); PG8_STAGE(PG8_SA(0, 1), a2 + hstep);
;             PG8_WAIT_L(8); PG8_BAR; PG8_WAIT_L(0); PG8_MMA(0, 0, At, B0); PG8_BAR; PG8_SCHED;
;             PG8_LDB(B1, 1, 1); PG8_STAGE(PG8_SB(1, 0), b3);
;             PG8_BAR; PG8_WAIT_L(0); PG8_MMA(0, 1, At, B1); PG8_BAR;
;             PG8_LDA(At, 1, 1); PG8_STAGE(PG8_SA(1, 0), a3);
;             PG8_BAR; PG8_WAIT_L(0); PG8_MMA(1, 0, At, B0); PG8_BAR; PG8_SCHED;
;             PG8_STAGE(PG8_SB(1, 1), b3 + hstep);
;             PG8_WAIT_V(6); PG8_BAR; PG8_MMA(1, 1, At, B1); PG8_BAR;
.LBB0_37:
	s_add_u32 s20, s18, 0xfff80080
	s_addc_u32 s21, s19, -1
	s_add_i32 s39, 0, 0x10000
	ds_read_b128 v[138:141], v135
	ds_read_b128 v[142:145], v135 offset:1024
	ds_read_b128 v[146:149], v135 offset:2048
	ds_read_b128 v[150:153], v135 offset:3072
	s_cmp_eq_u32 s38, 28
	s_cselect_b32 s23, s4, s21
	s_cselect_b32 s22, s5, s20
	s_cselect_b32 s21, s9, s37
	s_cselect_b32 s20, s11, s33
	s_add_i32 m0, s28, 0xc000
	ds_read_b128 v[186:189], v137
	ds_read_b128 v[190:193], v137 offset:1024
	ds_read_b128 v[194:197], v137 offset:2048
	ds_read_b128 v[198:201], v137 offset:3072
	ds_read_b128 v[202:205], v137 offset:4096
	ds_read_b128 v[206:209], v137 offset:5120
	ds_read_b128 v[210:213], v137 offset:6144
	ds_read_b128 v[214:217], v137 offset:7168
	global_load_lds_dwordx4 v130, s[18:19]
	s_add_i32 m0, s28, 0xe000
	s_nop 0
	global_load_lds_dwordx4 v132, s[18:19]
	s_waitcnt lgkmcnt(8)
	s_setprio 1
	s_barrier
	s_waitcnt lgkmcnt(0)
	v_mfma_f32_16x16x32_bf16 v[124:127], v[138:141], v[186:189], v[124:127]
	v_mfma_f32_16x16x32_bf16 v[120:123], v[146:149], v[186:189], v[120:123]
	v_mfma_f32_16x16x32_bf16 v[108:111], v[138:141], v[194:197], v[108:111]
	v_mfma_f32_16x16x32_bf16 v[104:107], v[146:149], v[194:197], v[104:107]
	v_mfma_f32_16x16x32_bf16 v[92:95], v[138:141], v[202:205], v[92:95]
	v_mfma_f32_16x16x32_bf16 v[88:91], v[146:149], v[202:205], v[88:91]
	v_mfma_f32_16x16x32_bf16 v[76:79], v[138:141], v[210:213], v[76:79]
	v_mfma_f32_16x16x32_bf16 v[72:75], v[146:149], v[210:213], v[72:75]
	v_mfma_f32_16x16x32_bf16 v[124:127], v[142:145], v[190:193], v[124:127]
	v_mfma_f32_16x16x32_bf16 v[120:123], v[150:153], v[190:193], v[120:123]
	v_mfma_f32_16x16x32_bf16 v[108:111], v[142:145], v[198:201], v[108:111]
	v_mfma_f32_16x16x32_bf16 v[104:107], v[150:153], v[198:201], v[104:107]
	v_mfma_f32_16x16x32_bf16 v[92:95], v[142:145], v[206:209], v[92:95]
	v_mfma_f32_16x16x32_bf16 v[88:91], v[150:153], v[206:209], v[88:91]
	v_mfma_f32_16x16x32_bf16 v[76:79], v[142:145], v[214:217], v[76:79]
	s_setprio 0
	v_mfma_f32_16x16x32_bf16 v[72:75], v[150:153], v[214:217], v[72:75]
	s_barrier
	s_add_i32 s42, 0, 0x14000
	s_add_i32 s39, s39, s27
	ds_read_b128 v[226:229], v135 offset:16384
	ds_read_b128 v[230:233], v135 offset:17408
	ds_read_b128 v[234:237], v135 offset:18432
	ds_read_b128 v[238:241], v135 offset:19456
	s_mov_b32 m0, s39
	s_nop 0
	global_load_lds_dwordx4 v158, s[20:21]
	s_add_i32 m0, s39, 0x2000
	s_nop 0
	global_load_lds_dwordx4 v128, s[20:21]
	s_waitcnt lgkmcnt(0)
	s_setprio 1
	s_barrier
	v_mfma_f32_16x16x32_bf16 v[116:119], v[226:229], v[186:189], v[116:119]
	v_mfma_f32_16x16x32_bf16 v[112:115], v[234:237], v[186:189], v[112:115]
	v_mfma_f32_16x16x32_bf16 v[100:103], v[226:229], v[194:197], v[100:103]
	v_mfma_f32_16x16x32_bf16 v[96:99], v[234:237], v[194:197], v[96:99]
	v_mfma_f32_16x16x32_bf16 v[84:87], v[226:229], v[202:205], v[84:87]
	v_mfma_f32_16x16x32_bf16 v[80:83], v[234:237], v[202:205], v[80:83]
	v_mfma_f32_16x16x32_bf16 v[68:71], v[226:229], v[210:213], v[68:71]
	v_mfma_f32_16x16x32_bf16 v[64:67], v[234:237], v[210:213], v[64:67]
	v_mfma_f32_16x16x32_bf16 v[116:119], v[230:233], v[190:193], v[116:119]
	s_mov_b32 m0, s28
	v_mfma_f32_16x16x32_bf16 v[112:115], v[238:241], v[190:193], v[112:115]
	s_mov_b64 s[100:101], s[22:23]
	v_mfma_f32_16x16x32_bf16 v[100:103], v[230:233], v[198:201], v[100:103]
	v_mfma_f32_16x16x32_bf16 v[96:99], v[238:241], v[198:201], v[96:99]
	v_mfma_f32_16x16x32_bf16 v[84:87], v[230:233], v[206:209], v[84:87]
	v_mfma_f32_16x16x32_bf16 v[80:83], v[238:241], v[206:209], v[80:83]
	v_mfma_f32_16x16x32_bf16 v[68:71], v[230:233], v[214:217], v[68:71]
	s_setprio 0
	v_mfma_f32_16x16x32_bf16 v[64:67], v[238:241], v[214:217], v[64:67]
	s_barrier
	ds_read_b128 v[186:189], v137 offset:16384
	ds_read_b128 v[190:193], v137 offset:17408
	ds_read_b128 v[194:197], v137 offset:18432
	ds_read_b128 v[198:201], v137 offset:19456
	ds_read_b128 v[202:205], v137 offset:20480
	ds_read_b128 v[206:209], v137 offset:21504
	ds_read_b128 v[210:213], v137 offset:22528
	ds_read_b128 v[214:217], v137 offset:23552
	global_load_lds_dwordx4 v158, s[22:23]
	s_mov_b64 s[100:101], s[22:23]
	s_mov_b32 m0, s29
	s_nop 0
	global_load_lds_dwordx4 v128, s[22:23]
	s_waitcnt lgkmcnt(0)
	s_setprio 1
	s_barrier
	v_mfma_f32_16x16x32_bf16 v[60:63], v[138:141], v[186:189], v[60:63]
	v_mfma_f32_16x16x32_bf16 v[56:59], v[146:149], v[186:189], v[56:59]
	v_mfma_f32_16x16x32_bf16 v[44:47], v[138:141], v[194:197], v[44:47]
	v_mfma_f32_16x16x32_bf16 v[40:43], v[146:149], v[194:197], v[40:43]
	v_mfma_f32_16x16x32_bf16 v[28:31], v[138:141], v[202:205], v[28:31]
	v_mfma_f32_16x16x32_bf16 v[24:27], v[146:149], v[202:205], v[24:27]
	v_mfma_f32_16x16x32_bf16 v[12:15], v[138:141], v[210:213], v[12:15]
	v_mfma_f32_16x16x32_bf16 v[8:11], v[146:149], v[210:213], v[8:11]
	v_mfma_f32_16x16x32_bf16 v[60:63], v[142:145], v[190:193], v[60:63]
	v_mfma_f32_16x16x32_bf16 v[56:59], v[150:153], v[190:193], v[56:59]
	v_mfma_f32_16x16x32_bf16 v[44:47], v[142:145], v[198:201], v[44:47]
	v_mfma_f32_16x16x32_bf16 v[40:43], v[150:153], v[198:201], v[40:43]
	v_mfma_f32_16x16x32_bf16 v[28:31], v[142:145], v[206:209], v[28:31]
	v_mfma_f32_16x16x32_bf16 v[24:27], v[150:153], v[206:209], v[24:27]
	v_mfma_f32_16x16x32_bf16 v[12:15], v[142:145], v[214:217], v[12:15]
	s_setprio 0
	v_mfma_f32_16x16x32_bf16 v[8:11], v[150:153], v[214:217], v[8:11]
	s_barrier
	s_add_u32 s40, s20, 0x80000
	s_addc_u32 s41, s21, 0
	s_add_i32 s39, s42, s27
	s_mov_b32 m0, s39
	s_nop 0
	global_load_lds_dwordx4 v158, s[40:41]
	s_add_i32 m0, s39, 0x2000
	s_nop 0
	global_load_lds_dwordx4 v128, s[40:41]
	s_waitcnt vmcnt(6)
	s_setprio 1
	s_barrier
; #define PG8_STAGE(bufoff, gbase) do { _Pragma("unroll") for (int _i = 0; _i < 2; ++_i) \
;         __builtin_amdgcn_global_load_lds((const unsigned*)((const char*)(gbase) + voff[_i]), (LAS unsigned*)(lds + (bufoff) + ldsw + _i * 8192), 16, 0, 0); } while (0)
; #define PG8_LDA(dst, b, h) do { _Pragma("unroll") for (int m = 0; m < 4; ++m) _Pragma("unroll") for (int k = 0; k < 2; ++k) dst[m][k] = *(const LAS bf16x8*)(lds + PG8_SA(b, h) + aoff + m * 2048 + k * 1024); } while (0)
; #define PG8_LDB(dst, b, h) do { _Pragma("unroll") for (int n = 0; n < 2; ++n) _Pragma("unroll") for (int k = 0; k < 2; ++k) dst[n][k] = *(const LAS bf16x8*)(lds + PG8_SB(b, h) + boff + n * 2048 + k * 1024); } while (0)
; template <class Epi>
; DI void gemm_phase(LAS unsigned char* lds, const Gemm g, const StaticOrder& S, const Epi& E) {
;     ...
;         for (int t = 0; t < nt; t += 2) {
;             const bool last = (t == nt - 2);
;             const char* a1 = cA + (size_t)(t + 1) * kstep;
;             const char* a2 = last ? nA : cA + (size_t)(t + 2) * kstep; const char* b2 = last ? nB : cB + (size_t)(t + 2) * kstep;
;             const char* a3 = a2 + kstep; const char* b3 = b2 + kstep;
;             PG8_LDB(B0, 0, 0); PG8_SCHED; PG8_LDA(At, 0, 0); PG8_STAGE(PG8_SA(1, 1), a1 + hstep);
;             PG8_WAIT_L(8); PG8_BAR; PG8_WAIT_L(0); PG8_MMA(0, 0, At, B0); PG8_BAR; PG8_SCHED;
;             PG8_LDB(B1, 0, 1); PG8_STAGE(PG8_SB(0, 0), b2);
;             PG8_BAR; PG8_WAIT_L(0); PG8_MMA(0, 1, At, B1); PG8_BAR;
;             PG8_LDA(At, 0, 1); PG8_STAGE(PG8_SA(0, 0), a2);
;             PG8_BAR; PG8_WAIT_L(0); PG8_MMA(1, 0, At, B0); PG8_BAR; PG8_SCHED;
;             PG8_STAGE(PG8_SB(0, 1), b2 + hstep);
;             PG8_WAIT_V(6); PG8_BAR; PG8_MMA(1, 1, At, B1); PG8_BAR;
;             PG8_LDB(B0, 1, 0); PG8_SCHED; PG8_LDA(At, 1, 0); PG8_STAGE(PG8_SA(0, 1), a2 + hstep);
;             PG8_WAIT_L(8); PG8_BAR; PG8_WAIT_L(0); PG8_MMA(0, 0, At, B0); PG8_BAR; PG8_SCHED;
;             PG8_LDB(B1, 1, 1); PG8_STAGE(PG8_SB(1, 0), b3);
;             PG8_BAR; PG8_WAIT_L(0); PG8_MMA(0, 1, At, B1); PG8_BAR;
;             PG8_LDA(At, 1, 1); PG8_STAGE(PG8_SA(1, 0), a3);
;             PG8_BAR; PG8_WAIT_L(0); PG8_MMA(1, 0, At, B0); PG8_BAR; PG8_SCHED;
;             PG8_STAGE(PG8_SB(1, 1), b3 + hstep);
;             PG8_WAIT_V(6); PG8_BAR; PG8_MMA(1, 1, At, B1); PG8_BAR;
	v_mfma_f32_16x16x32_bf16 v[52:55], v[226:229], v[186:189], v[52:55]
	v_mfma_f32_16x16x32_bf16 v[48:51], v[234:237], v[186:189], v[48:51]
	v_mfma_f32_16x16x32_bf16 v[36:39], v[226:229], v[194:197], v[36:39]
	v_mfma_f32_16x16x32_bf16 v[32:35], v[234:237], v[194:197], v[32:35]
	v_mfma_f32_16x16x32_bf16 v[20:23], v[226:229], v[202:205], v[20:23]
	v_mfma_f32_16x16x32_bf16 v[16:19], v[234:237], v[202:205], v[16:19]
	v_mfma_f32_16x16x32_bf16 v[4:7], v[226:229], v[210:213], v[4:7]
	v_mfma_f32_16x16x32_bf16 v[0:3], v[234:237], v[210:213], v[0:3]
	v_mfma_f32_16x16x32_bf16 v[52:55], v[230:233], v[190:193], v[52:55]
	s_add_i32 s39, 0, 0x18000
	v_mfma_f32_16x16x32_bf16 v[48:51], v[238:241], v[190:193], v[48:51]
	v_mfma_f32_16x16x32_bf16 v[36:39], v[230:233], v[198:201], v[36:39]
	v_mfma_f32_16x16x32_bf16 v[32:35], v[238:241], v[198:201], v[32:35]
	v_mfma_f32_16x16x32_bf16 v[20:23], v[230:233], v[206:209], v[20:23]
	v_mfma_f32_16x16x32_bf16 v[16:19], v[238:241], v[206:209], v[16:19]
	v_mfma_f32_16x16x32_bf16 v[4:7], v[230:233], v[214:217], v[4:7]
	s_setprio 0
	v_mfma_f32_16x16x32_bf16 v[0:3], v[238:241], v[214:217], v[0:3]
	s_barrier
	ds_read_b128 v[138:141], v135 offset:32768
	ds_read_b128 v[142:145], v135 offset:33792
	ds_read_b128 v[146:149], v135 offset:34816
	ds_read_b128 v[150:153], v135 offset:35840
	s_add_u32 s22, s22, 0x80000
	s_addc_u32 s23, s23, 0
	s_mov_b32 m0, s30
	ds_read_b128 v[186:189], v137 offset:32768
	ds_read_b128 v[190:193], v137 offset:33792
	ds_read_b128 v[194:197], v137 offset:34816
	ds_read_b128 v[198:201], v137 offset:35840
	ds_read_b128 v[202:205], v137 offset:36864
	ds_read_b128 v[206:209], v137 offset:37888
	ds_read_b128 v[210:213], v137 offset:38912
	ds_read_b128 v[214:217], v137 offset:39936
	global_load_lds_dwordx4 v158, s[22:23]
	s_mov_b32 m0, s31
	s_nop 0
	global_load_lds_dwordx4 v128, s[22:23]
	s_waitcnt lgkmcnt(8)
	s_setprio 1
	s_barrier
	s_waitcnt lgkmcnt(0)
	v_mfma_f32_16x16x32_bf16 v[124:127], v[138:141], v[186:189], v[124:127]
	v_mfma_f32_16x16x32_bf16 v[120:123], v[146:149], v[186:189], v[120:123]
	v_mfma_f32_16x16x32_bf16 v[108:111], v[138:141], v[194:197], v[108:111]
	v_mfma_f32_16x16x32_bf16 v[104:107], v[146:149], v[194:197], v[104:107]
	v_mfma_f32_16x16x32_bf16 v[92:95], v[138:141], v[202:205], v[92:95]
	v_mfma_f32_16x16x32_bf16 v[88:91], v[146:149], v[202:205], v[88:91]
	v_mfma_f32_16x16x32_bf16 v[76:79], v[138:141], v[210:213], v[76:79]
	v_mfma_f32_16x16x32_bf16 v[72:75], v[146:149], v[210:213], v[72:75]
	v_mfma_f32_16x16x32_bf16 v[124:127], v[142:145], v[190:193], v[124:127]
	v_mfma_f32_16x16x32_bf16 v[120:123], v[150:153], v[190:193], v[120:123]
	v_mfma_f32_16x16x32_bf16 v[108:111], v[142:145], v[198:201], v[108:111]
	v_mfma_f32_16x16x32_bf16 v[104:107], v[150:153], v[198:201], v[104:107]
	v_mfma_f32_16x16x32_bf16 v[92:95], v[142:145], v[206:209], v[92:95]
	v_mfma_f32_16x16x32_bf16 v[88:91], v[150:153], v[206:209], v[88:91]
	v_mfma_f32_16x16x32_bf16 v[76:79], v[142:145], v[214:217], v[76:79]
	s_setprio 0
	v_mfma_f32_16x16x32_bf16 v[72:75], v[150:153], v[214:217], v[72:75]
	s_barrier
	s_add_i32 s22, 0, 0x1c000
	s_add_i32 s23, s39, s27
	s_add_i32 m0, s23, 0xffffff80
	ds_read_b128 v[226:229], v135 offset:49152
	ds_read_b128 v[230:233], v135 offset:50176
	ds_read_b128 v[234:237], v135 offset:51200
	ds_read_b128 v[238:241], v135 offset:52224
	global_load_lds_dwordx4 v158, s[20:21] offset:128
	s_add_i32 m0, s23, 0x1f80
	s_nop 0
	global_load_lds_dwordx4 v128, s[20:21] offset:128
	s_waitcnt lgkmcnt(0)
	s_setprio 1
	s_barrier
	v_mfma_f32_16x16x32_bf16 v[116:119], v[226:229], v[186:189], v[116:119]
	v_mfma_f32_16x16x32_bf16 v[112:115], v[234:237], v[186:189], v[112:115]
	v_mfma_f32_16x16x32_bf16 v[100:103], v[226:229], v[194:197], v[100:103]
	v_mfma_f32_16x16x32_bf16 v[96:99], v[234:237], v[194:197], v[96:99]
	v_mfma_f32_16x16x32_bf16 v[84:87], v[226:229], v[202:205], v[84:87]
	v_mfma_f32_16x16x32_bf16 v[80:83], v[234:237], v[202:205], v[80:83]
	v_mfma_f32_16x16x32_bf16 v[68:71], v[226:229], v[210:213], v[68:71]
	v_mfma_f32_16x16x32_bf16 v[64:67], v[234:237], v[210:213], v[64:67]
	v_mfma_f32_16x16x32_bf16 v[116:119], v[230:233], v[190:193], v[116:119]
	s_add_i32 m0, s34, 0xffffff80
	v_mfma_f32_16x16x32_bf16 v[112:115], v[238:241], v[190:193], v[112:115]
	v_mfma_f32_16x16x32_bf16 v[100:103], v[230:233], v[198:201], v[100:103]
	v_mfma_f32_16x16x32_bf16 v[96:99], v[238:241], v[198:201], v[96:99]
	v_mfma_f32_16x16x32_bf16 v[84:87], v[230:233], v[206:209], v[84:87]
	v_mfma_f32_16x16x32_bf16 v[80:83], v[238:241], v[206:209], v[80:83]
	v_mfma_f32_16x16x32_bf16 v[68:71], v[230:233], v[214:217], v[68:71]
	s_setprio 0
	v_mfma_f32_16x16x32_bf16 v[64:67], v[238:241], v[214:217], v[64:67]
	s_barrier
	ds_read_b128 v[186:189], v137 offset:49152
	ds_read_b128 v[190:193], v137 offset:50176
	ds_read_b128 v[194:197], v137 offset:51200
	ds_read_b128 v[198:201], v137 offset:52224
	ds_read_b128 v[202:205], v137 offset:53248
	ds_read_b128 v[206:209], v137 offset:54272
	ds_read_b128 v[210:213], v137 offset:55296
	ds_read_b128 v[214:217], v137 offset:56320
	global_load_lds_dwordx4 v158, s[100:101] offset:128
	s_add_i32 m0, s35, 0xffffff80
	s_nop 0
	global_load_lds_dwordx4 v128, s[100:101] offset:128
	s_waitcnt lgkmcnt(0)
	s_setprio 1
	s_barrier
; #define PG8_BAR __builtin_amdgcn_s_barrier()
; template <class Epi>
; DI void gemm_phase(LAS unsigned char* lds, const Gemm g, const StaticOrder& S, const Epi& E) {
;     ...
;         for (int t = 0; t < nt; t += 2) {
;             const bool last = (t == nt - 2);
;             const char* a1 = cA + (size_t)(t + 1) * kstep;
;             const char* a2 = last ? nA : cA + (size_t)(t + 2) * kstep; const char* b2 = last ? nB : cB + (size_t)(t + 2) * kstep;
;             const char* a3 = a2 + kstep; const char* b3 = b2 + kstep;
;             PG8_LDB(B0, 0, 0); PG8_SCHED; PG8_LDA(At, 0, 0); PG8_STAGE(PG8_SA(1, 1), a1 + hstep);
;             PG8_WAIT_L(8); PG8_BAR; PG8_WAIT_L(0); PG8_MMA(0, 0, At, B0); PG8_BAR; PG8_SCHED;
;             PG8_LDB(B1, 0, 1); PG8_STAGE(PG8_SB(0, 0), b2);
;             PG8_BAR; PG8_WAIT_L(0); PG8_MMA(0, 1, At, B1); PG8_BAR;
;             PG8_LDA(At, 0, 1); PG8_STAGE(PG8_SA(0, 0), a2);
;             PG8_BAR; PG8_WAIT_L(0); PG8_MMA(1, 0, At, B0); PG8_BAR; PG8_SCHED;
;             PG8_STAGE(PG8_SB(0, 1), b2 + hstep);
;             PG8_WAIT_V(6); PG8_BAR; PG8_MMA(1, 1, At, B1); PG8_BAR;
;             PG8_LDB(B0, 1, 0); PG8_SCHED; PG8_LDA(At, 1, 0); PG8_STAGE(PG8_SA(0, 1), a2 + hstep);
;             PG8_WAIT_L(8); PG8_BAR; PG8_WAIT_L(0); PG8_MMA(0, 0, At, B0); PG8_BAR; PG8_SCHED;
;             PG8_LDB(B1, 1, 1); PG8_STAGE(PG8_SB(1, 0), b3);
;             PG8_BAR; PG8_WAIT_L(0); PG8_MMA(0, 1, At, B1); PG8_BAR;
;             PG8_LDA(At, 1, 1); PG8_STAGE(PG8_SA(1, 0), a3);
;             PG8_BAR; PG8_WAIT_L(0); PG8_MMA(1, 0, At, B0); PG8_BAR; PG8_SCHED;
;             PG8_STAGE(PG8_SB(1, 1), b3 + hstep);
;             PG8_WAIT_V(6); PG8_BAR; PG8_MMA(1, 1, At, B1); PG8_BAR;
;     DI void operator()(const f32x4 (&acc)[2][2][4][2], const Unit& u, int wr, int wc, int fr, int fq) const {
;         const int row0 = u.pm * BM + wr * 64 + fr, col0 = u.pn * HALF + wc * 32 + 8 * fq;
; #pragma unroll
;         for (int ai = 0; ai < 2; ++ai)
; #pragma unroll
;             for (int m = 0; m < 4; ++m) { float hv[8];
; #pragma unroll
;                 for (int n = 0; n < 2; ++n)
; #pragma unroll
;                     for (int e = 0; e < 4; ++e) { const float gt = acc[ai][0][m][n][e], up = acc[ai][1][m][n][e];
;                         hv[n * 4 + e] = gt * __builtin_amdgcn_rcpf(1.f + __builtin_amdgcn_exp2f(-1.4426950408889634f * gt)) * up; }
	v_mfma_f32_16x16x32_bf16 v[60:63], v[138:141], v[186:189], v[60:63]
	v_mfma_f32_16x16x32_bf16 v[56:59], v[146:149], v[186:189], v[56:59]
	v_mfma_f32_16x16x32_bf16 v[44:47], v[138:141], v[194:197], v[44:47]
	v_mfma_f32_16x16x32_bf16 v[40:43], v[146:149], v[194:197], v[40:43]
	v_mfma_f32_16x16x32_bf16 v[28:31], v[138:141], v[202:205], v[28:31]
	v_mfma_f32_16x16x32_bf16 v[24:27], v[146:149], v[202:205], v[24:27]
	v_mfma_f32_16x16x32_bf16 v[12:15], v[138:141], v[210:213], v[12:15]
	v_mfma_f32_16x16x32_bf16 v[8:11], v[146:149], v[210:213], v[8:11]
	v_mfma_f32_16x16x32_bf16 v[60:63], v[142:145], v[190:193], v[60:63]
	v_mfma_f32_16x16x32_bf16 v[56:59], v[150:153], v[190:193], v[56:59]
	v_mfma_f32_16x16x32_bf16 v[44:47], v[142:145], v[198:201], v[44:47]
	v_mfma_f32_16x16x32_bf16 v[40:43], v[150:153], v[198:201], v[40:43]
	v_mfma_f32_16x16x32_bf16 v[28:31], v[142:145], v[206:209], v[28:31]
	v_mfma_f32_16x16x32_bf16 v[24:27], v[150:153], v[206:209], v[24:27]
	v_mfma_f32_16x16x32_bf16 v[12:15], v[142:145], v[214:217], v[12:15]
	s_setprio 0
	v_mfma_f32_16x16x32_bf16 v[8:11], v[150:153], v[214:217], v[8:11]
	s_barrier
	s_add_u32 s20, s20, 0x80080
	s_addc_u32 s21, s21, 0
	s_add_i32 s22, s22, s27
	s_mov_b32 m0, s22
	s_nop 0
	global_load_lds_dwordx4 v158, s[20:21]
	s_add_i32 m0, s22, 0x2000
	s_nop 0
	global_load_lds_dwordx4 v128, s[20:21]
	s_waitcnt vmcnt(6)
	s_setprio 1
	s_barrier
	v_mfma_f32_16x16x32_bf16 v[52:55], v[226:229], v[186:189], v[52:55]
	v_mfma_f32_16x16x32_bf16 v[48:51], v[234:237], v[186:189], v[48:51]
	v_mfma_f32_16x16x32_bf16 v[36:39], v[226:229], v[194:197], v[36:39]
	v_mfma_f32_16x16x32_bf16 v[32:35], v[234:237], v[194:197], v[32:35]
	v_mfma_f32_16x16x32_bf16 v[20:23], v[226:229], v[202:205], v[20:23]
	v_mfma_f32_16x16x32_bf16 v[16:19], v[234:237], v[202:205], v[16:19]
	v_mfma_f32_16x16x32_bf16 v[4:7], v[226:229], v[210:213], v[4:7]
	v_mfma_f32_16x16x32_bf16 v[0:3], v[234:237], v[210:213], v[0:3]
	v_mfma_f32_16x16x32_bf16 v[52:55], v[230:233], v[190:193], v[52:55]
	s_add_i32 s38, s38, 2
	v_mfma_f32_16x16x32_bf16 v[48:51], v[238:241], v[190:193], v[48:51]
	s_add_u32 s18, s18, 0x100
	v_mfma_f32_16x16x32_bf16 v[36:39], v[230:233], v[198:201], v[36:39]
	s_addc_u32 s19, s19, 0
	v_mfma_f32_16x16x32_bf16 v[32:35], v[238:241], v[198:201], v[32:35]
	s_add_u32 s33, s33, 0x100
	v_mfma_f32_16x16x32_bf16 v[20:23], v[230:233], v[206:209], v[20:23]
	s_addc_u32 s37, s37, 0
	v_mfma_f32_16x16x32_bf16 v[16:19], v[238:241], v[206:209], v[16:19]
	s_cmp_gt_u32 s38, 29
	v_mfma_f32_16x16x32_bf16 v[4:7], v[230:233], v[214:217], v[4:7]
	s_setprio 0
	v_mfma_f32_16x16x32_bf16 v[0:3], v[238:241], v[214:217], v[0:3]
	s_barrier
	s_cbranch_scc0 .LBB0_37
	v_mul_f32_e32 v139, 0xbfb8aa3b, v124
	v_exp_f32_e32 v139, v139
	v_lshl_or_b32 v140, s2, 7, v136
	v_lshl_add_u32 v138, s3, 8, v134
	v_ashrrev_i32_e32 v141, 31, v140
	v_add_f32_e32 v139, 1.0, v139
	v_rcp_f32_e32 v142, v139
	v_mul_f32_e32 v139, 0xbfb8aa3b, v125
	v_exp_f32_e32 v139, v139
	s_movk_i32 s4, 0x2c00
	s_and_b64 vcc, exec, s[6:7]
	s_mov_b64 s[20:21], s[16:17]
	v_add_f32_e32 v139, 1.0, v139
	v_rcp_f32_e32 v143, v139
	v_mul_f32_e32 v139, 0xbfb8aa3b, v126
	v_exp_f32_e32 v139, v139
	s_mov_b64 s[18:19], s[14:15]
	v_pk_mul_f32 v[124:125], v[124:125], v[142:143]
	v_add_f32_e32 v139, 1.0, v139
	v_rcp_f32_e32 v144, v139
	v_mul_f32_e32 v139, 0xbfb8aa3b, v127
	v_exp_f32_e32 v139, v139
	v_pk_mul_f32 v[116:117], v[124:125], v[116:117]
	v_add_f32_e32 v139, 1.0, v139
	v_rcp_f32_e32 v145, v139
	v_mul_f32_e32 v139, 0xbfb8aa3b, v120
	v_exp_f32_e32 v139, v139
	v_cvt_pk_bf16_f32 v116, v116, v117
	v_pk_mul_f32 v[124:125], v[126:127], v[144:145]
	v_add_f32_e32 v139, 1.0, v139
	v_rcp_f32_e32 v146, v139
	v_mul_f32_e32 v139, 0xbfb8aa3b, v121
	v_exp_f32_e32 v139, v139
	v_pk_mul_f32 v[118:119], v[124:125], v[118:119]
	v_add_f32_e32 v139, 1.0, v139
	v_rcp_f32_e32 v147, v139
	v_mul_f32_e32 v139, 0xbfb8aa3b, v122
	v_exp_f32_e32 v139, v139
	v_cvt_pk_bf16_f32 v117, v118, v119
	v_pk_mul_f32 v[118:119], v[120:121], v[146:147]
	v_add_f32_e32 v139, 1.0, v139
	v_rcp_f32_e32 v148, v139
	v_mul_f32_e32 v139, 0xbfb8aa3b, v123
	v_exp_f32_e32 v139, v139
	v_pk_mul_f32 v[112:113], v[118:119], v[112:113]
	v_add_f32_e32 v139, 1.0, v139
	v_rcp_f32_e32 v149, v139
	v_cvt_pk_bf16_f32 v118, v112, v113
	v_pk_mul_f32 v[112:113], v[122:123], v[148:149]
	s_nop 0
	v_pk_mul_f32 v[112:113], v[112:113], v[114:115]
	v_lshlrev_b64 v[114:115], 1, v[140:141]
	v_cvt_pk_bf16_f32 v119, v112, v113
	v_mov_b64_e32 v[112:113], s[54:55]
	v_mad_i64_i32 v[120:121], s[2:3], v138, s4, v[112:113]
	v_lshl_add_u64 v[120:121], v[120:121], 0, v[114:115]
	global_store_dwordx4 v[120:121], v[116:119], off
	v_mul_f32_e32 v120, 0xbfb8aa3b, v104
	v_mul_f32_e32 v121, 0xbfb8aa3b, v105
	v_mul_f32_e32 v116, 0xbfb8aa3b, v108
	v_mul_f32_e32 v117, 0xbfb8aa3b, v109
	v_exp_f32_e32 v116, v116
	v_exp_f32_e32 v117, v117
	v_mul_f32_e32 v118, 0xbfb8aa3b, v110
	v_mul_f32_e32 v119, 0xbfb8aa3b, v111
	v_exp_f32_e32 v118, v118
	v_exp_f32_e32 v119, v119
	v_exp_f32_e32 v120, v120
	v_exp_f32_e32 v121, v121
	v_add_f32_e32 v116, 1.0, v116
	v_add_f32_e32 v117, 1.0, v117
	v_mul_f32_e32 v122, 0xbfb8aa3b, v106
	v_mul_f32_e32 v123, 0xbfb8aa3b, v107
	v_rcp_f32_e32 v116, v116
	v_rcp_f32_e32 v117, v117
	v_add_f32_e32 v118, 1.0, v118
	v_add_f32_e32 v119, 1.0, v119
	v_exp_f32_e32 v122, v122
	v_exp_f32_e32 v123, v123
	v_rcp_f32_e32 v118, v118
	v_rcp_f32_e32 v119, v119
	v_add_f32_e32 v120, 1.0, v120
	v_add_f32_e32 v121, 1.0, v121
	v_rcp_f32_e32 v120, v120
	v_rcp_f32_e32 v121, v121
	v_add_f32_e32 v122, 1.0, v122
	v_add_f32_e32 v123, 1.0, v123
	v_pk_mul_f32 v[108:109], v[108:109], v[116:117]
	v_rcp_f32_e32 v122, v122
;     DI void operator()(const f32x4 (&acc)[2][2][4][2], const Unit& u, int wr, int wc, int fr, int fq) const {
;         const int row0 = u.pm * BM + wr * 64 + fr, col0 = u.pn * HALF + wc * 32 + 8 * fq;
; #pragma unroll
;         for (int ai = 0; ai < 2; ++ai)
; #pragma unroll
;             for (int m = 0; m < 4; ++m) { float hv[8];
; #pragma unroll
;                 for (int n = 0; n < 2; ++n)
; #pragma unroll
;                     for (int e = 0; e < 4; ++e) { const float gt = acc[ai][0][m][n][e], up = acc[ai][1][m][n][e];
;                         hv[n * 4 + e] = gt * __builtin_amdgcn_rcpf(1.f + __builtin_amdgcn_exp2f(-1.4426950408889634f * gt)) * up; }
;                 *(u32x4*)(H + (size_t)(row0 + ai * HALF + m * 16) * DFF + col0) = (u32x4){pk(hv[0], hv[1]), pk(hv[2], hv[3]), pk(hv[4], hv[5]), pk(hv[6], hv[7])}; }
	v_rcp_f32_e32 v123, v123
	v_pk_mul_f32 v[100:101], v[108:109], v[100:101]
	v_pk_mul_f32 v[108:109], v[110:111], v[118:119]
	v_cvt_pk_bf16_f32 v100, v100, v101
	v_pk_mul_f32 v[102:103], v[108:109], v[102:103]
	s_nop 0
	v_cvt_pk_bf16_f32 v101, v102, v103
	v_pk_mul_f32 v[102:103], v[104:105], v[120:121]
	s_nop 0
	v_pk_mul_f32 v[96:97], v[102:103], v[96:97]
	s_nop 0
	v_cvt_pk_bf16_f32 v102, v96, v97
	v_pk_mul_f32 v[96:97], v[106:107], v[122:123]
	s_nop 0
	v_pk_mul_f32 v[96:97], v[96:97], v[98:99]
	v_mul_f32_e32 v98, 0xbfb8aa3b, v94
	v_cvt_pk_bf16_f32 v103, v96, v97
	v_or_b32_e32 v96, 16, v138
	v_mad_i64_i32 v[96:97], s[2:3], v96, s4, v[112:113]
	v_lshl_add_u64 v[96:97], v[96:97], 0, v[114:115]
	global_store_dwordx4 v[96:97], v[100:103], off
	v_mul_f32_e32 v96, 0xbfb8aa3b, v92
	v_mul_f32_e32 v97, 0xbfb8aa3b, v93
	v_exp_f32_e32 v96, v96
	v_exp_f32_e32 v97, v97
	v_mul_f32_e32 v99, 0xbfb8aa3b, v95
	v_exp_f32_e32 v98, v98
	v_exp_f32_e32 v99, v99
	v_mul_f32_e32 v100, 0xbfb8aa3b, v88
	v_mul_f32_e32 v101, 0xbfb8aa3b, v89
	v_exp_f32_e32 v100, v100
	v_exp_f32_e32 v101, v101
	v_add_f32_e32 v96, 1.0, v96
	v_add_f32_e32 v97, 1.0, v97
	v_mul_f32_e32 v102, 0xbfb8aa3b, v90
	v_mul_f32_e32 v103, 0xbfb8aa3b, v91
	v_rcp_f32_e32 v96, v96
	v_rcp_f32_e32 v97, v97
	v_add_f32_e32 v98, 1.0, v98
	v_add_f32_e32 v99, 1.0, v99
	v_exp_f32_e32 v102, v102
	v_exp_f32_e32 v103, v103
	v_rcp_f32_e32 v98, v98
	v_rcp_f32_e32 v99, v99
	v_add_f32_e32 v100, 1.0, v100
	v_add_f32_e32 v101, 1.0, v101
	v_rcp_f32_e32 v100, v100
	v_rcp_f32_e32 v101, v101
	v_add_f32_e32 v102, 1.0, v102
	v_add_f32_e32 v103, 1.0, v103
	v_pk_mul_f32 v[92:93], v[92:93], v[96:97]
	v_rcp_f32_e32 v102, v102
	v_rcp_f32_e32 v103, v103
	v_pk_mul_f32 v[84:85], v[92:93], v[84:85]
	v_pk_mul_f32 v[92:93], v[94:95], v[98:99]
	v_cvt_pk_bf16_f32 v84, v84, v85
	v_pk_mul_f32 v[86:87], v[92:93], v[86:87]
	s_nop 0
	v_cvt_pk_bf16_f32 v85, v86, v87
	v_pk_mul_f32 v[86:87], v[88:89], v[100:101]
	s_nop 0
	v_pk_mul_f32 v[80:81], v[86:87], v[80:81]
	s_nop 0
	v_cvt_pk_bf16_f32 v86, v80, v81
	v_pk_mul_f32 v[80:81], v[90:91], v[102:103]
	s_nop 0
	v_pk_mul_f32 v[80:81], v[80:81], v[82:83]
	v_mul_f32_e32 v82, 0xbfb8aa3b, v78
	v_cvt_pk_bf16_f32 v87, v80, v81
	v_or_b32_e32 v80, 32, v138
	v_mad_i64_i32 v[80:81], s[2:3], v80, s4, v[112:113]
	v_lshl_add_u64 v[80:81], v[80:81], 0, v[114:115]
	global_store_dwordx4 v[80:81], v[84:87], off
	v_mul_f32_e32 v80, 0xbfb8aa3b, v76
	v_mul_f32_e32 v81, 0xbfb8aa3b, v77
	v_exp_f32_e32 v80, v80
	v_exp_f32_e32 v81, v81
	v_mul_f32_e32 v83, 0xbfb8aa3b, v79
	v_exp_f32_e32 v82, v82
	v_exp_f32_e32 v83, v83
	v_mul_f32_e32 v84, 0xbfb8aa3b, v72
	v_mul_f32_e32 v85, 0xbfb8aa3b, v73
	v_exp_f32_e32 v84, v84
	v_exp_f32_e32 v85, v85
	v_add_f32_e32 v80, 1.0, v80
	v_add_f32_e32 v81, 1.0, v81
	v_mul_f32_e32 v86, 0xbfb8aa3b, v74
	v_mul_f32_e32 v87, 0xbfb8aa3b, v75
	v_rcp_f32_e32 v80, v80
	v_rcp_f32_e32 v81, v81
	v_add_f32_e32 v82, 1.0, v82
	v_add_f32_e32 v83, 1.0, v83
	v_exp_f32_e32 v86, v86
	v_exp_f32_e32 v87, v87
	v_rcp_f32_e32 v82, v82
	v_rcp_f32_e32 v83, v83
	v_add_f32_e32 v84, 1.0, v84
	v_add_f32_e32 v85, 1.0, v85
	v_rcp_f32_e32 v84, v84
	v_rcp_f32_e32 v85, v85
	v_add_f32_e32 v86, 1.0, v86
	v_add_f32_e32 v87, 1.0, v87
	v_pk_mul_f32 v[76:77], v[76:77], v[80:81]
	v_rcp_f32_e32 v86, v86
	v_rcp_f32_e32 v87, v87
	v_pk_mul_f32 v[68:69], v[76:77], v[68:69]
	v_pk_mul_f32 v[76:77], v[78:79], v[82:83]
	v_cvt_pk_bf16_f32 v68, v68, v69
	v_pk_mul_f32 v[70:71], v[76:77], v[70:71]
	s_nop 0
	v_cvt_pk_bf16_f32 v69, v70, v71
	v_pk_mul_f32 v[70:71], v[72:73], v[84:85]
	v_add_u32_e32 v72, 0x80, v138
	v_pk_mul_f32 v[64:65], v[70:71], v[64:65]
	s_nop 0
	v_cvt_pk_bf16_f32 v70, v64, v65
	v_pk_mul_f32 v[64:65], v[74:75], v[86:87]
	s_nop 0
	v_pk_mul_f32 v[64:65], v[64:65], v[66:67]
	v_mul_f32_e32 v66, 0xbfb8aa3b, v62
	v_cvt_pk_bf16_f32 v71, v64, v65
	v_or_b32_e32 v64, 48, v138
	v_mad_i64_i32 v[64:65], s[2:3], v64, s4, v[112:113]
	v_lshl_add_u64 v[64:65], v[64:65], 0, v[114:115]
	global_store_dwordx4 v[64:65], v[68:71], off
	v_mul_f32_e32 v64, 0xbfb8aa3b, v60
	v_mul_f32_e32 v65, 0xbfb8aa3b, v61
	v_exp_f32_e32 v64, v64
	v_exp_f32_e32 v65, v65
	v_mul_f32_e32 v67, 0xbfb8aa3b, v63
	v_exp_f32_e32 v66, v66
	v_exp_f32_e32 v67, v67
	v_mul_f32_e32 v68, 0xbfb8aa3b, v56
	v_mul_f32_e32 v69, 0xbfb8aa3b, v57
	v_exp_f32_e32 v68, v68
	v_exp_f32_e32 v69, v69
	v_add_f32_e32 v64, 1.0, v64
	v_add_f32_e32 v65, 1.0, v65
	v_mul_f32_e32 v70, 0xbfb8aa3b, v58
	v_mul_f32_e32 v71, 0xbfb8aa3b, v59
	v_rcp_f32_e32 v64, v64
	v_rcp_f32_e32 v65, v65
	v_add_f32_e32 v66, 1.0, v66
	v_add_f32_e32 v67, 1.0, v67
	v_exp_f32_e32 v70, v70
	v_exp_f32_e32 v71, v71
	v_rcp_f32_e32 v66, v66
	v_rcp_f32_e32 v67, v67
	v_add_f32_e32 v68, 1.0, v68
	v_add_f32_e32 v69, 1.0, v69
	v_rcp_f32_e32 v68, v68
	v_rcp_f32_e32 v69, v69
	v_add_f32_e32 v70, 1.0, v70
	v_add_f32_e32 v71, 1.0, v71
	v_pk_mul_f32 v[60:61], v[60:61], v[64:65]
	v_rcp_f32_e32 v70, v70
	v_rcp_f32_e32 v71, v71
	v_pk_mul_f32 v[52:53], v[60:61], v[52:53]
	v_pk_mul_f32 v[60:61], v[62:63], v[66:67]
	v_cvt_pk_bf16_f32 v52, v52, v53
	v_pk_mul_f32 v[54:55], v[60:61], v[54:55]
	s_nop 0
	v_cvt_pk_bf16_f32 v53, v54, v55
	v_pk_mul_f32 v[54:55], v[56:57], v[68:69]
	s_nop 0
	v_pk_mul_f32 v[48:49], v[54:55], v[48:49]
; #define PG8_WAIT_V(n) asm volatile("s_waitcnt vmcnt(" #n ")" ::: "memory")
; #define PG8_BAR __builtin_amdgcn_s_barrier()
; template <class Epi>
; DI void gemm_phase(LAS unsigned char* lds, const Gemm g, const StaticOrder& S, const Epi& E) {
;     ...
;         E(acc, cur, wr, wc, fr, fq);
;         if (!has_next) break;
; #pragma unroll
;         for (int a = 0; a < 2; ++a)
; #pragma unroll
;             for (int b = 0; b < 2; ++b)
; #pragma unroll
;                 for (int m = 0; m < 4; ++m)
; #pragma unroll
;                     for (int n = 0; n < 2; ++n) acc[a][b][m][n] = (f32x4){0.f, 0.f, 0.f, 0.f};
;         cur = nxt; cA = nA; cB = nB; ++ui;
;     }
;     PG8_WAIT_V(0);
;     if (wr == 0) PG8_BAR;
;     PG8_BAR;
;     DI void operator()(const f32x4 (&acc)[2][2][4][2], const Unit& u, int wr, int wc, int fr, int fq) const {
;         const int row0 = u.pm * BM + wr * 64 + fr, col0 = u.pn * HALF + wc * 32 + 8 * fq;
; #pragma unroll
;         for (int ai = 0; ai < 2; ++ai)
; #pragma unroll
;             for (int m = 0; m < 4; ++m) { float hv[8];
; #pragma unroll
;                 for (int n = 0; n < 2; ++n)
; #pragma unroll
;                     for (int e = 0; e < 4; ++e) { const float gt = acc[ai][0][m][n][e], up = acc[ai][1][m][n][e];
;                         hv[n * 4 + e] = gt * __builtin_amdgcn_rcpf(1.f + __builtin_amdgcn_exp2f(-1.4426950408889634f * gt)) * up; }
;                 *(u32x4*)(H + (size_t)(row0 + ai * HALF + m * 16) * DFF + col0) = (u32x4){pk(hv[0], hv[1]), pk(hv[2], hv[3]), pk(hv[4], hv[5]), pk(hv[6], hv[7])}; }
	s_nop 0
	v_cvt_pk_bf16_f32 v54, v48, v49
	v_pk_mul_f32 v[48:49], v[58:59], v[70:71]
	s_nop 0
	v_pk_mul_f32 v[48:49], v[48:49], v[50:51]
	v_mul_f32_e32 v50, 0xbfb8aa3b, v46
	v_cvt_pk_bf16_f32 v55, v48, v49
	v_mad_i64_i32 v[48:49], s[2:3], v72, s4, v[112:113]
	v_lshl_add_u64 v[48:49], v[48:49], 0, v[114:115]
	global_store_dwordx4 v[48:49], v[52:55], off
	v_mul_f32_e32 v48, 0xbfb8aa3b, v44
	v_mul_f32_e32 v49, 0xbfb8aa3b, v45
	v_exp_f32_e32 v48, v48
	v_exp_f32_e32 v49, v49
	v_mul_f32_e32 v51, 0xbfb8aa3b, v47
	v_exp_f32_e32 v50, v50
	v_exp_f32_e32 v51, v51
	v_mul_f32_e32 v52, 0xbfb8aa3b, v40
	v_mul_f32_e32 v53, 0xbfb8aa3b, v41
	v_exp_f32_e32 v52, v52
	v_exp_f32_e32 v53, v53
	v_add_f32_e32 v48, 1.0, v48
	v_add_f32_e32 v49, 1.0, v49
	v_mul_f32_e32 v54, 0xbfb8aa3b, v42
	v_mul_f32_e32 v55, 0xbfb8aa3b, v43
	v_rcp_f32_e32 v48, v48
	v_rcp_f32_e32 v49, v49
	v_add_f32_e32 v50, 1.0, v50
	v_add_f32_e32 v51, 1.0, v51
	v_exp_f32_e32 v54, v54
	v_exp_f32_e32 v55, v55
	v_rcp_f32_e32 v50, v50
	v_rcp_f32_e32 v51, v51
	v_add_f32_e32 v52, 1.0, v52
	v_add_f32_e32 v53, 1.0, v53
	v_rcp_f32_e32 v52, v52
	v_rcp_f32_e32 v53, v53
	v_add_f32_e32 v54, 1.0, v54
	v_add_f32_e32 v55, 1.0, v55
	v_pk_mul_f32 v[44:45], v[44:45], v[48:49]
	v_rcp_f32_e32 v54, v54
	v_rcp_f32_e32 v55, v55
	v_pk_mul_f32 v[36:37], v[44:45], v[36:37]
	v_pk_mul_f32 v[44:45], v[46:47], v[50:51]
	v_cvt_pk_bf16_f32 v36, v36, v37
	v_pk_mul_f32 v[38:39], v[44:45], v[38:39]
	s_nop 0
	v_cvt_pk_bf16_f32 v37, v38, v39
	v_pk_mul_f32 v[38:39], v[40:41], v[52:53]
	s_nop 0
	v_pk_mul_f32 v[32:33], v[38:39], v[32:33]
	s_nop 0
	v_cvt_pk_bf16_f32 v38, v32, v33
	v_pk_mul_f32 v[32:33], v[42:43], v[54:55]
	s_nop 0
	v_pk_mul_f32 v[32:33], v[32:33], v[34:35]
	v_mul_f32_e32 v34, 0xbfb8aa3b, v30
	v_cvt_pk_bf16_f32 v39, v32, v33
	v_add_u32_e32 v32, 0x90, v138
	v_mad_i64_i32 v[32:33], s[2:3], v32, s4, v[112:113]
	v_lshl_add_u64 v[32:33], v[32:33], 0, v[114:115]
	global_store_dwordx4 v[32:33], v[36:39], off
	v_mul_f32_e32 v32, 0xbfb8aa3b, v28
	v_mul_f32_e32 v33, 0xbfb8aa3b, v29
	v_exp_f32_e32 v32, v32
	v_exp_f32_e32 v33, v33
	v_mul_f32_e32 v35, 0xbfb8aa3b, v31
	v_exp_f32_e32 v34, v34
	v_exp_f32_e32 v35, v35
	v_mul_f32_e32 v36, 0xbfb8aa3b, v24
	v_mul_f32_e32 v37, 0xbfb8aa3b, v25
	v_exp_f32_e32 v36, v36
	v_exp_f32_e32 v37, v37
	v_add_f32_e32 v32, 1.0, v32
	v_add_f32_e32 v33, 1.0, v33
	v_mul_f32_e32 v38, 0xbfb8aa3b, v26
	v_mul_f32_e32 v39, 0xbfb8aa3b, v27
	v_rcp_f32_e32 v32, v32
	v_rcp_f32_e32 v33, v33
	v_add_f32_e32 v34, 1.0, v34
	v_add_f32_e32 v35, 1.0, v35
	v_exp_f32_e32 v38, v38
	v_exp_f32_e32 v39, v39
	v_rcp_f32_e32 v34, v34
	v_rcp_f32_e32 v35, v35
	v_add_f32_e32 v36, 1.0, v36
	v_add_f32_e32 v37, 1.0, v37
	v_rcp_f32_e32 v36, v36
	v_rcp_f32_e32 v37, v37
	v_add_f32_e32 v38, 1.0, v38
	v_add_f32_e32 v39, 1.0, v39
	v_pk_mul_f32 v[28:29], v[28:29], v[32:33]
	v_rcp_f32_e32 v38, v38
	v_rcp_f32_e32 v39, v39
	v_pk_mul_f32 v[20:21], v[28:29], v[20:21]
	v_pk_mul_f32 v[28:29], v[30:31], v[34:35]
	v_cvt_pk_bf16_f32 v20, v20, v21
	v_pk_mul_f32 v[22:23], v[28:29], v[22:23]
	s_nop 0
	v_cvt_pk_bf16_f32 v21, v22, v23
	v_pk_mul_f32 v[22:23], v[24:25], v[36:37]
	s_nop 0
	v_pk_mul_f32 v[16:17], v[22:23], v[16:17]
	s_nop 0
	v_cvt_pk_bf16_f32 v22, v16, v17
	v_pk_mul_f32 v[16:17], v[26:27], v[38:39]
	s_nop 0
	v_pk_mul_f32 v[16:17], v[16:17], v[18:19]
	v_mul_f32_e32 v18, 0xbfb8aa3b, v14
	v_cvt_pk_bf16_f32 v23, v16, v17
	v_add_u32_e32 v16, 0xa0, v138
	v_mad_i64_i32 v[16:17], s[2:3], v16, s4, v[112:113]
	v_lshl_add_u64 v[16:17], v[16:17], 0, v[114:115]
	global_store_dwordx4 v[16:17], v[20:23], off
	v_mul_f32_e32 v16, 0xbfb8aa3b, v12
	v_mul_f32_e32 v17, 0xbfb8aa3b, v13
	v_exp_f32_e32 v16, v16
	v_exp_f32_e32 v17, v17
	v_mul_f32_e32 v19, 0xbfb8aa3b, v15
	v_exp_f32_e32 v18, v18
	v_exp_f32_e32 v19, v19
	v_mul_f32_e32 v20, 0xbfb8aa3b, v8
	v_mul_f32_e32 v21, 0xbfb8aa3b, v9
	v_exp_f32_e32 v20, v20
	v_exp_f32_e32 v21, v21
	v_add_f32_e32 v16, 1.0, v16
	v_add_f32_e32 v17, 1.0, v17
	v_mul_f32_e32 v22, 0xbfb8aa3b, v10
	v_mul_f32_e32 v23, 0xbfb8aa3b, v11
	v_rcp_f32_e32 v16, v16
	v_rcp_f32_e32 v17, v17
	v_add_f32_e32 v18, 1.0, v18
	v_add_f32_e32 v19, 1.0, v19
	v_exp_f32_e32 v22, v22
	v_exp_f32_e32 v23, v23
	v_rcp_f32_e32 v18, v18
	v_rcp_f32_e32 v19, v19
	v_add_f32_e32 v20, 1.0, v20
	v_add_f32_e32 v21, 1.0, v21
	v_rcp_f32_e32 v20, v20
	v_rcp_f32_e32 v21, v21
	v_add_f32_e32 v22, 1.0, v22
	v_add_f32_e32 v23, 1.0, v23
	v_pk_mul_f32 v[12:13], v[12:13], v[16:17]
	v_rcp_f32_e32 v22, v22
	v_rcp_f32_e32 v23, v23
	v_pk_mul_f32 v[4:5], v[12:13], v[4:5]
	v_pk_mul_f32 v[12:13], v[14:15], v[18:19]
	v_cvt_pk_bf16_f32 v4, v4, v5
	v_pk_mul_f32 v[6:7], v[12:13], v[6:7]
	s_nop 0
	v_cvt_pk_bf16_f32 v5, v6, v7
	v_pk_mul_f32 v[6:7], v[8:9], v[20:21]
	s_nop 0
	v_pk_mul_f32 v[0:1], v[6:7], v[0:1]
	s_nop 0
	v_cvt_pk_bf16_f32 v6, v0, v1
	v_pk_mul_f32 v[0:1], v[10:11], v[22:23]
	s_nop 0
	v_pk_mul_f32 v[0:1], v[0:1], v[2:3]
	s_nop 0
	v_cvt_pk_bf16_f32 v7, v0, v1
	v_add_u32_e32 v0, 0xb0, v138
	v_mad_i64_i32 v[0:1], s[2:3], v0, s4, v[112:113]
	v_lshl_add_u64 v[0:1], v[0:1], 0, v[114:115]
	s_mov_b32 s2, s8
	s_mov_b32 s3, s10
	global_store_dwordx4 v[0:1], v[4:7], off
	s_cbranch_vccz .LBB0_34
	s_waitcnt vmcnt(0)
	s_cmpk_gt_u32 s24, 0xff
	s_cbranch_scc1 .LBB0_41
	s_barrier

; #define PG8_STAGE(bufoff, gbase) do { _Pragma("unroll") for (int _i = 0; _i < 2; ++_i) \
;         __builtin_amdgcn_global_load_lds((const unsigned*)((const char*)(gbase) + voff[_i]), (LAS unsigned*)(lds + (bufoff) + ldsw + _i * 8192), 16, 0, 0); } while (0)
; #define PG8_LDA(dst, b, h) do { _Pragma("unroll") for (int m = 0; m < 4; ++m) _Pragma("unroll") for (int k = 0; k < 2; ++k) dst[m][k] = *(const LAS bf16x8*)(lds + PG8_SA(b, h) + aoff + m * 2048 + k * 1024); } while (0)
; #define PG8_LDB(dst, b, h) do { _Pragma("unroll") for (int n = 0; n < 2; ++n) _Pragma("unroll") for (int k = 0; k < 2; ++k) dst[n][k] = *(const LAS bf16x8*)(lds + PG8_SB(b, h) + boff + n * 2048 + k * 1024); } while (0)
; template <class Epi>
; DI void gemm_phase(LAS unsigned char* lds, const Gemm g, const StaticOrder& S, const Epi& E) {
;     ...
;         for (int t = 0; t < nt; t += 2) {
;             const bool last = (t == nt - 2);
;             const char* a1 = cA + (size_t)(t + 1) * kstep;
;             const char* a2 = last ? nA : cA + (size_t)(t + 2) * kstep; const char* b2 = last ? nB : cB + (size_t)(t + 2) * kstep;
;             const char* a3 = a2 + kstep; const char* b3 = b2 + kstep;
;             PG8_LDB(B0, 0, 0); PG8_SCHED; PG8_LDA(At, 0, 0); PG8_STAGE(PG8_SA(1, 1), a1 + hstep);
;             PG8_WAIT_L(8); PG8_BAR; PG8_WAIT_L(0); PG8_MMA(0, 0, At, B0); PG8_BAR; PG8_SCHED;
;             PG8_LDB(B1, 0, 1); PG8_STAGE(PG8_SB(0, 0), b2);
;             PG8_BAR; PG8_WAIT_L(0); PG8_MMA(0, 1, At, B1); PG8_BAR;
;             PG8_LDA(At, 0, 1); PG8_STAGE(PG8_SA(0, 0), a2);
;             PG8_BAR; PG8_WAIT_L(0); PG8_MMA(1, 0, At, B0); PG8_BAR; PG8_SCHED;
;             PG8_STAGE(PG8_SB(0, 1), b2 + hstep);
;             PG8_WAIT_V(6); PG8_BAR; PG8_MMA(1, 1, At, B1); PG8_BAR;
;             PG8_LDB(B0, 1, 0); PG8_SCHED; PG8_LDA(At, 1, 0); PG8_STAGE(PG8_SA(0, 1), a2 + hstep);
;             PG8_WAIT_L(8); PG8_BAR; PG8_WAIT_L(0); PG8_MMA(0, 0, At, B0); PG8_BAR; PG8_SCHED;
;             PG8_LDB(B1, 1, 1); PG8_STAGE(PG8_SB(1, 0), b3);
;             PG8_BAR; PG8_WAIT_L(0); PG8_MMA(0, 1, At, B1); PG8_BAR;
;             PG8_LDA(At, 1, 1); PG8_STAGE(PG8_SA(1, 0), a3);
;             PG8_BAR; PG8_WAIT_L(0); PG8_MMA(1, 0, At, B0); PG8_BAR; PG8_SCHED;
;             PG8_STAGE(PG8_SB(1, 1), b3 + hstep);
;             PG8_WAIT_V(6); PG8_BAR; PG8_MMA(1, 1, At, B1); PG8_BAR;
.LBB0_77:
	s_add_u32 s22, s20, 0x100
	s_addc_u32 s23, s21, 0
	s_add_i32 s43, 0, 0x10000
	ds_read_b128 v[128:131], v226
	ds_read_b128 v[132:135], v226 offset:1024
	ds_read_b128 v[136:139], v226 offset:2048
	ds_read_b128 v[140:143], v226 offset:3072
	s_cmp_eq_u32 s33, 32
	s_cselect_b32 s27, s9, s23
	s_cselect_b32 s26, s8, s22
	s_cselect_b32 s25, s11, s5
	s_cselect_b32 s24, s10, s4
	s_add_i32 m0, s34, 0xc000
	ds_read_b128 v[144:147], v228
	ds_read_b128 v[148:151], v228 offset:1024
	ds_read_b128 v[152:155], v228 offset:2048
	ds_read_b128 v[194:197], v228 offset:3072
	ds_read_b128 v[198:201], v228 offset:4096
	ds_read_b128 v[202:205], v228 offset:5120
	ds_read_b128 v[206:209], v228 offset:6144
	ds_read_b128 v[210:213], v228 offset:7168
	global_load_lds_dwordx4 v190, s[20:21]
	s_add_i32 m0, s34, 0xe000
	s_nop 0
	global_load_lds_dwordx4 v192, s[20:21]
	s_waitcnt lgkmcnt(8)
	s_setprio 1
	s_barrier
	s_waitcnt lgkmcnt(0)
	v_mfma_f32_16x16x32_bf16 v[124:127], v[128:131], v[144:147], v[124:127]
	v_mfma_f32_16x16x32_bf16 v[120:123], v[136:139], v[144:147], v[120:123]
	v_mfma_f32_16x16x32_bf16 v[116:119], v[128:131], v[152:155], v[116:119]
	v_mfma_f32_16x16x32_bf16 v[112:115], v[136:139], v[152:155], v[112:115]
	v_mfma_f32_16x16x32_bf16 v[108:111], v[128:131], v[198:201], v[108:111]
	v_mfma_f32_16x16x32_bf16 v[104:107], v[136:139], v[198:201], v[104:107]
	v_mfma_f32_16x16x32_bf16 v[100:103], v[128:131], v[206:209], v[100:103]
	v_mfma_f32_16x16x32_bf16 v[96:99], v[136:139], v[206:209], v[96:99]
	v_mfma_f32_16x16x32_bf16 v[124:127], v[132:135], v[148:151], v[124:127]
	v_mfma_f32_16x16x32_bf16 v[120:123], v[140:143], v[148:151], v[120:123]
	v_mfma_f32_16x16x32_bf16 v[116:119], v[132:135], v[194:197], v[116:119]
	v_mfma_f32_16x16x32_bf16 v[112:115], v[140:143], v[194:197], v[112:115]
	v_mfma_f32_16x16x32_bf16 v[108:111], v[132:135], v[202:205], v[108:111]
	v_mfma_f32_16x16x32_bf16 v[104:107], v[140:143], v[202:205], v[104:107]
	v_mfma_f32_16x16x32_bf16 v[100:103], v[132:135], v[210:213], v[100:103]
	s_setprio 0
	v_mfma_f32_16x16x32_bf16 v[96:99], v[140:143], v[210:213], v[96:99]
	s_barrier
	s_add_i32 s44, 0, 0x14000
	s_add_i32 s20, s43, s31
	s_mov_b32 m0, s20
	ds_read_b128 v[214:217], v226 offset:16384
	ds_read_b128 v[230:233], v226 offset:17408
	ds_read_b128 v[234:237], v226 offset:18432
	ds_read_b128 v[238:241], v226 offset:19456
	global_load_lds_dwordx4 v188, s[24:25]
	s_add_i32 m0, s20, 0x2000
	s_nop 0
	global_load_lds_dwordx4 v186, s[24:25]
	s_waitcnt lgkmcnt(0)
	s_setprio 1
	s_barrier
	v_mfma_f32_16x16x32_bf16 v[60:63], v[214:217], v[144:147], v[60:63]
	v_mfma_f32_16x16x32_bf16 v[56:59], v[234:237], v[144:147], v[56:59]
	v_mfma_f32_16x16x32_bf16 v[52:55], v[214:217], v[152:155], v[52:55]
	v_mfma_f32_16x16x32_bf16 v[48:51], v[234:237], v[152:155], v[48:51]
	v_mfma_f32_16x16x32_bf16 v[44:47], v[214:217], v[198:201], v[44:47]
	v_mfma_f32_16x16x32_bf16 v[40:43], v[234:237], v[198:201], v[40:43]
	v_mfma_f32_16x16x32_bf16 v[36:39], v[214:217], v[206:209], v[36:39]
	v_mfma_f32_16x16x32_bf16 v[32:35], v[234:237], v[206:209], v[32:35]
	v_mfma_f32_16x16x32_bf16 v[60:63], v[230:233], v[148:151], v[60:63]
	s_mov_b32 m0, s34
	v_mfma_f32_16x16x32_bf16 v[56:59], v[238:241], v[148:151], v[56:59]
	s_mov_b64 s[100:101], s[26:27]
	v_mfma_f32_16x16x32_bf16 v[52:55], v[230:233], v[194:197], v[52:55]
	v_mfma_f32_16x16x32_bf16 v[48:51], v[238:241], v[194:197], v[48:51]
	v_mfma_f32_16x16x32_bf16 v[44:47], v[230:233], v[202:205], v[44:47]
	v_mfma_f32_16x16x32_bf16 v[40:43], v[238:241], v[202:205], v[40:43]
	v_mfma_f32_16x16x32_bf16 v[36:39], v[230:233], v[210:213], v[36:39]
	s_setprio 0
	v_mfma_f32_16x16x32_bf16 v[32:35], v[238:241], v[210:213], v[32:35]
	s_barrier
	ds_read_b128 v[144:147], v228 offset:16384
	ds_read_b128 v[148:151], v228 offset:17408
	ds_read_b128 v[152:155], v228 offset:18432
	ds_read_b128 v[194:197], v228 offset:19456
	ds_read_b128 v[198:201], v228 offset:20480
	ds_read_b128 v[202:205], v228 offset:21504
	ds_read_b128 v[206:209], v228 offset:22528
	ds_read_b128 v[210:213], v228 offset:23552
	global_load_lds_dwordx4 v188, s[26:27]
	s_mov_b64 s[100:101], s[26:27]
	s_mov_b32 m0, s35
	s_nop 0
	global_load_lds_dwordx4 v186, s[26:27]
	s_waitcnt lgkmcnt(0)
	s_setprio 1
	s_barrier
	v_mfma_f32_16x16x32_bf16 v[92:95], v[128:131], v[144:147], v[92:95]
	v_mfma_f32_16x16x32_bf16 v[88:91], v[136:139], v[144:147], v[88:91]
	v_mfma_f32_16x16x32_bf16 v[84:87], v[128:131], v[152:155], v[84:87]
	v_mfma_f32_16x16x32_bf16 v[80:83], v[136:139], v[152:155], v[80:83]
	v_mfma_f32_16x16x32_bf16 v[76:79], v[128:131], v[198:201], v[76:79]
	v_mfma_f32_16x16x32_bf16 v[72:75], v[136:139], v[198:201], v[72:75]
	v_mfma_f32_16x16x32_bf16 v[68:71], v[128:131], v[206:209], v[68:71]
	v_mfma_f32_16x16x32_bf16 v[64:67], v[136:139], v[206:209], v[64:67]
	v_mfma_f32_16x16x32_bf16 v[92:95], v[132:135], v[148:151], v[92:95]
	v_mfma_f32_16x16x32_bf16 v[88:91], v[140:143], v[148:151], v[88:91]
	v_mfma_f32_16x16x32_bf16 v[84:87], v[132:135], v[194:197], v[84:87]
	v_mfma_f32_16x16x32_bf16 v[80:83], v[140:143], v[194:197], v[80:83]
	v_mfma_f32_16x16x32_bf16 v[76:79], v[132:135], v[202:205], v[76:79]
	v_mfma_f32_16x16x32_bf16 v[72:75], v[140:143], v[202:205], v[72:75]
	v_mfma_f32_16x16x32_bf16 v[68:71], v[132:135], v[210:213], v[68:71]
	s_setprio 0
	v_mfma_f32_16x16x32_bf16 v[64:67], v[140:143], v[210:213], v[64:67]
	s_barrier
	s_add_u32 s20, s24, 0x90000
	s_addc_u32 s21, s25, 0
	s_add_i32 s43, s44, s31
	s_mov_b32 m0, s43
	s_nop 0
	global_load_lds_dwordx4 v188, s[20:21]
	s_add_i32 m0, s43, 0x2000
	s_nop 0
	global_load_lds_dwordx4 v186, s[20:21]
	s_waitcnt vmcnt(6)
	s_setprio 1
	s_barrier
; #define PG8_STAGE(bufoff, gbase) do { _Pragma("unroll") for (int _i = 0; _i < 2; ++_i) \
;         __builtin_amdgcn_global_load_lds((const unsigned*)((const char*)(gbase) + voff[_i]), (LAS unsigned*)(lds + (bufoff) + ldsw + _i * 8192), 16, 0, 0); } while (0)
; #define PG8_LDA(dst, b, h) do { _Pragma("unroll") for (int m = 0; m < 4; ++m) _Pragma("unroll") for (int k = 0; k < 2; ++k) dst[m][k] = *(const LAS bf16x8*)(lds + PG8_SA(b, h) + aoff + m * 2048 + k * 1024); } while (0)
; #define PG8_LDB(dst, b, h) do { _Pragma("unroll") for (int n = 0; n < 2; ++n) _Pragma("unroll") for (int k = 0; k < 2; ++k) dst[n][k] = *(const LAS bf16x8*)(lds + PG8_SB(b, h) + boff + n * 2048 + k * 1024); } while (0)
; #define PG8_MMA(ai, bj, At, Bt) do { __builtin_amdgcn_s_setprio(1); _Pragma("unroll") for (int m = 0; m < 4; ++m) _Pragma("unroll") for (int n = 0; n < 2; ++n) _Pragma("unroll") for (int k = 0; k < 2; ++k) \
;         acc[ai][bj][m][n] = __builtin_amdgcn_mfma_f32_16x16x32_bf16(Bt[n][k], At[m][k], acc[ai][bj][m][n], 0, 0, 0); __builtin_amdgcn_s_setprio(0); } while (0)
; #define PG8_WAIT_V(n) asm volatile("s_waitcnt vmcnt(" #n ")" ::: "memory")
; #define PG8_WAIT_L(n) asm volatile("s_waitcnt lgkmcnt(" #n ")" ::: "memory")
; #define PG8_BAR __builtin_amdgcn_s_barrier()
; #define PG8_SCHED __builtin_amdgcn_sched_barrier(0)
; template <class Epi>
; DI void gemm_phase(LAS unsigned char* lds, const Gemm g, const StaticOrder& S, const Epi& E) {
;     ...
;             PG8_WAIT_V(6); PG8_BAR; PG8_MMA(1, 1, At, B1); PG8_BAR;
;             PG8_LDB(B0, 1, 0); PG8_SCHED; PG8_LDA(At, 1, 0); PG8_STAGE(PG8_SA(0, 1), a2 + hstep);
;             PG8_WAIT_L(8); PG8_BAR; PG8_WAIT_L(0); PG8_MMA(0, 0, At, B0); PG8_BAR; PG8_SCHED;
;             PG8_LDB(B1, 1, 1); PG8_STAGE(PG8_SB(1, 0), b3);
;             PG8_BAR; PG8_WAIT_L(0); PG8_MMA(0, 1, At, B1); PG8_BAR;
;             PG8_LDA(At, 1, 1); PG8_STAGE(PG8_SA(1, 0), a3);
	v_mfma_f32_16x16x32_bf16 v[28:31], v[214:217], v[144:147], v[28:31]
	v_mfma_f32_16x16x32_bf16 v[24:27], v[234:237], v[144:147], v[24:27]
	v_mfma_f32_16x16x32_bf16 v[20:23], v[214:217], v[152:155], v[20:23]
	v_mfma_f32_16x16x32_bf16 v[16:19], v[234:237], v[152:155], v[16:19]
	v_mfma_f32_16x16x32_bf16 v[12:15], v[214:217], v[198:201], v[12:15]
	v_mfma_f32_16x16x32_bf16 v[8:11], v[234:237], v[198:201], v[8:11]
	v_mfma_f32_16x16x32_bf16 v[4:7], v[214:217], v[206:209], v[4:7]
	v_mfma_f32_16x16x32_bf16 v[0:3], v[234:237], v[206:209], v[0:3]
	v_mfma_f32_16x16x32_bf16 v[28:31], v[230:233], v[148:151], v[28:31]
	s_add_i32 s43, 0, 0x18000
	v_mfma_f32_16x16x32_bf16 v[24:27], v[238:241], v[148:151], v[24:27]
	v_mfma_f32_16x16x32_bf16 v[20:23], v[230:233], v[194:197], v[20:23]
	v_mfma_f32_16x16x32_bf16 v[16:19], v[238:241], v[194:197], v[16:19]
	v_mfma_f32_16x16x32_bf16 v[12:15], v[230:233], v[202:205], v[12:15]
	v_mfma_f32_16x16x32_bf16 v[8:11], v[238:241], v[202:205], v[8:11]
	v_mfma_f32_16x16x32_bf16 v[4:7], v[230:233], v[210:213], v[4:7]
	s_setprio 0
	v_mfma_f32_16x16x32_bf16 v[0:3], v[238:241], v[210:213], v[0:3]
	s_barrier
	ds_read_b128 v[128:131], v226 offset:32768
	ds_read_b128 v[132:135], v226 offset:33792
	ds_read_b128 v[136:139], v226 offset:34816
	ds_read_b128 v[140:143], v226 offset:35840
	s_add_u32 s20, s26, 0x90000
	s_addc_u32 s21, s27, 0
	s_mov_b32 m0, s36
	ds_read_b128 v[144:147], v228 offset:32768
	ds_read_b128 v[148:151], v228 offset:33792
	ds_read_b128 v[152:155], v228 offset:34816
	ds_read_b128 v[194:197], v228 offset:35840
	ds_read_b128 v[198:201], v228 offset:36864
	ds_read_b128 v[202:205], v228 offset:37888
	ds_read_b128 v[206:209], v228 offset:38912
	ds_read_b128 v[210:213], v228 offset:39936
	global_load_lds_dwordx4 v188, s[20:21]
	s_mov_b32 m0, s37
	s_nop 0
	global_load_lds_dwordx4 v186, s[20:21]
	s_waitcnt lgkmcnt(8)
	s_setprio 1
	s_barrier
	s_waitcnt lgkmcnt(0)
	v_mfma_f32_16x16x32_bf16 v[124:127], v[128:131], v[144:147], v[124:127]
	v_mfma_f32_16x16x32_bf16 v[120:123], v[136:139], v[144:147], v[120:123]
	v_mfma_f32_16x16x32_bf16 v[116:119], v[128:131], v[152:155], v[116:119]
	v_mfma_f32_16x16x32_bf16 v[112:115], v[136:139], v[152:155], v[112:115]
	v_mfma_f32_16x16x32_bf16 v[108:111], v[128:131], v[198:201], v[108:111]
	v_mfma_f32_16x16x32_bf16 v[104:107], v[136:139], v[198:201], v[104:107]
	v_mfma_f32_16x16x32_bf16 v[100:103], v[128:131], v[206:209], v[100:103]
	v_mfma_f32_16x16x32_bf16 v[96:99], v[136:139], v[206:209], v[96:99]
	v_mfma_f32_16x16x32_bf16 v[124:127], v[132:135], v[148:151], v[124:127]
	v_mfma_f32_16x16x32_bf16 v[120:123], v[140:143], v[148:151], v[120:123]
	v_mfma_f32_16x16x32_bf16 v[116:119], v[132:135], v[194:197], v[116:119]
	v_mfma_f32_16x16x32_bf16 v[112:115], v[140:143], v[194:197], v[112:115]
	v_mfma_f32_16x16x32_bf16 v[108:111], v[132:135], v[202:205], v[108:111]
	v_mfma_f32_16x16x32_bf16 v[104:107], v[140:143], v[202:205], v[104:107]
	v_mfma_f32_16x16x32_bf16 v[100:103], v[132:135], v[210:213], v[100:103]
	s_setprio 0
	v_mfma_f32_16x16x32_bf16 v[96:99], v[140:143], v[210:213], v[96:99]
	s_barrier
	s_add_i32 s26, 0, 0x1c000
	s_add_i32 s20, s43, s31
	s_add_i32 m0, s20, 0xffffff80
	ds_read_b128 v[214:217], v226 offset:49152
	ds_read_b128 v[230:233], v226 offset:50176
	ds_read_b128 v[234:237], v226 offset:51200
	ds_read_b128 v[238:241], v226 offset:52224
	global_load_lds_dwordx4 v188, s[24:25] offset:128
	s_add_i32 m0, s20, 0x1f80
	s_nop 0
	global_load_lds_dwordx4 v186, s[24:25] offset:128
	s_waitcnt lgkmcnt(0)
	s_setprio 1
	s_barrier
	v_mfma_f32_16x16x32_bf16 v[60:63], v[214:217], v[144:147], v[60:63]
	v_mfma_f32_16x16x32_bf16 v[56:59], v[234:237], v[144:147], v[56:59]
	v_mfma_f32_16x16x32_bf16 v[52:55], v[214:217], v[152:155], v[52:55]
	v_mfma_f32_16x16x32_bf16 v[48:51], v[234:237], v[152:155], v[48:51]
	v_mfma_f32_16x16x32_bf16 v[44:47], v[214:217], v[198:201], v[44:47]
	v_mfma_f32_16x16x32_bf16 v[40:43], v[234:237], v[198:201], v[40:43]
	v_mfma_f32_16x16x32_bf16 v[36:39], v[214:217], v[206:209], v[36:39]
	v_mfma_f32_16x16x32_bf16 v[32:35], v[234:237], v[206:209], v[32:35]
	v_mfma_f32_16x16x32_bf16 v[60:63], v[230:233], v[148:151], v[60:63]
	s_add_i32 m0, s38, 0xffffff80
	v_mfma_f32_16x16x32_bf16 v[56:59], v[238:241], v[148:151], v[56:59]
	v_mfma_f32_16x16x32_bf16 v[52:55], v[230:233], v[194:197], v[52:55]
	v_mfma_f32_16x16x32_bf16 v[48:51], v[238:241], v[194:197], v[48:51]
	v_mfma_f32_16x16x32_bf16 v[44:47], v[230:233], v[202:205], v[44:47]
	v_mfma_f32_16x16x32_bf16 v[40:43], v[238:241], v[202:205], v[40:43]
	v_mfma_f32_16x16x32_bf16 v[36:39], v[230:233], v[210:213], v[36:39]
	s_setprio 0
	v_mfma_f32_16x16x32_bf16 v[32:35], v[238:241], v[210:213], v[32:35]
	s_barrier
	ds_read_b128 v[144:147], v228 offset:49152
	ds_read_b128 v[148:151], v228 offset:50176
	ds_read_b128 v[152:155], v228 offset:51200
	ds_read_b128 v[194:197], v228 offset:52224
	ds_read_b128 v[198:201], v228 offset:53248
	ds_read_b128 v[202:205], v228 offset:54272
	ds_read_b128 v[206:209], v228 offset:55296
	ds_read_b128 v[210:213], v228 offset:56320
	global_load_lds_dwordx4 v188, s[100:101] offset:128
	s_add_i32 m0, s39, 0xffffff80
	s_nop 0
	global_load_lds_dwordx4 v186, s[100:101] offset:128
	s_waitcnt lgkmcnt(0)
	s_setprio 1
	s_barrier
; #define PG8_BAR __builtin_amdgcn_s_barrier()
; template <class Epi>
; DI void gemm_phase(LAS unsigned char* lds, const Gemm g, const StaticOrder& S, const Epi& E) {
;     ...
;             PG8_BAR; PG8_WAIT_L(0); PG8_MMA(1, 0, At, B0); PG8_BAR; PG8_SCHED;
;             PG8_STAGE(PG8_SB(1, 1), b3 + hstep);
;             PG8_WAIT_V(6); PG8_BAR; PG8_MMA(1, 1, At, B1); PG8_BAR;
;     template <bool LN, int BJ, int LO, int HI> DI void batch(const f32x4 (&acc)[2][2][4][2], unsigned row0, unsigned col0, const f32x4 (&gv)[2], const f32x4 (&bv)[2]) const {
;         f32x4 r[HI - LO]; float mean[(HI - LO) / 2], rstd[(HI - LO) / 2];
; #pragma unroll
;         for (int i = LO; i < HI; ++i) { const int ai = i >> 3, m = (i >> 1) & 3, n = i & 1; const unsigned row = row0 + ai * HALF + m * 16;
;             if (n == 0) { mean[(i - LO) >> 1] = 0.f; rstd[(i - LO) >> 1] = 1.f;
;                 if (LN) { const float2 st = *(const float2*)(stats + row * 2u); mean[(i - LO) >> 1] = st.x; rstd[(i - LO) >> 1] = st.y; } }
;             r[i - LO] = *(const f32x4*)(src + (row * (unsigned)DM + col0 + BJ * HALF + n * 16)); }
; #pragma unroll
;         for (int i = LO; i < HI; ++i) { const int ai = i >> 3, m = (i >> 1) & 3, n = i & 1; const unsigned row = row0 + ai * HALF + m * 16;
;             *(f32x4*)(Y + (row * (unsigned)DM + col0 + BJ * HALF + n * 16)) = acc[ai][BJ][m][n] + ((r[i - LO] - mean[(i - LO) >> 1]) * rstd[(i - LO) >> 1]) * gv[n] + bv[n]; }
;         __builtin_amdgcn_sched_barrier(0);
;     }
;     template <bool LN, int BJ> DI void load_gb(unsigned col0, f32x4 (&gv)[2], f32x4 (&bv)[2]) const {
; #pragma unroll
;         for (int n = 0; n < 2; ++n) {
;             if (LN) { gv[n] = *(const f32x4*)(gam + col0 + BJ * HALF + n * 16) * ALPHA; bv[n] = *(const f32x4*)(bet + col0 + BJ * HALF + n * 16) * ALPHA; }
;             else { gv[n] = (f32x4){ALPHA, ALPHA, ALPHA, ALPHA}; bv[n] = (f32x4){0.f, 0.f, 0.f, 0.f}; }
;         }
;     }
;     template <bool LN> DI void run(const f32x4 (&acc)[2][2][4][2], const Unit& u, int wr, int wc, int fr, int fq) const {
;         const unsigned row0 = u.pm * BM + wr * 64 + fr, col0 = u.pn * BM + wc * 32 + 4 * fq;
;         f32x4 gv[2], bv[2];
;         load_gb<LN, 0>(col0, gv, bv);
;         batch<LN, 0, 0, 4>(acc, row0, col0, gv, bv);
;         batch<LN, 0, 4, 8>(acc, row0, col0, gv, bv);
;         batch<LN, 0, 8, 12>(acc, row0, col0, gv, bv);
	v_mfma_f32_16x16x32_bf16 v[92:95], v[128:131], v[144:147], v[92:95]
	v_mfma_f32_16x16x32_bf16 v[88:91], v[136:139], v[144:147], v[88:91]
	v_mfma_f32_16x16x32_bf16 v[84:87], v[128:131], v[152:155], v[84:87]
	v_mfma_f32_16x16x32_bf16 v[80:83], v[136:139], v[152:155], v[80:83]
	v_mfma_f32_16x16x32_bf16 v[76:79], v[128:131], v[198:201], v[76:79]
	v_mfma_f32_16x16x32_bf16 v[72:75], v[136:139], v[198:201], v[72:75]
	v_mfma_f32_16x16x32_bf16 v[68:71], v[128:131], v[206:209], v[68:71]
	v_mfma_f32_16x16x32_bf16 v[64:67], v[136:139], v[206:209], v[64:67]
	v_mfma_f32_16x16x32_bf16 v[92:95], v[132:135], v[148:151], v[92:95]
	v_mfma_f32_16x16x32_bf16 v[88:91], v[140:143], v[148:151], v[88:91]
	v_mfma_f32_16x16x32_bf16 v[84:87], v[132:135], v[194:197], v[84:87]
	v_mfma_f32_16x16x32_bf16 v[80:83], v[140:143], v[194:197], v[80:83]
	v_mfma_f32_16x16x32_bf16 v[76:79], v[132:135], v[202:205], v[76:79]
	v_mfma_f32_16x16x32_bf16 v[72:75], v[140:143], v[202:205], v[72:75]
	v_mfma_f32_16x16x32_bf16 v[68:71], v[132:135], v[210:213], v[68:71]
	s_setprio 0
	v_mfma_f32_16x16x32_bf16 v[64:67], v[140:143], v[210:213], v[64:67]
	s_barrier
	s_add_u32 s20, s24, 0x90080
	s_addc_u32 s21, s25, 0
	s_add_i32 s24, s26, s31
	s_mov_b32 m0, s24
	s_nop 0
	global_load_lds_dwordx4 v188, s[20:21]
	s_add_i32 m0, s24, 0x2000
	s_nop 0
	global_load_lds_dwordx4 v186, s[20:21]
	s_waitcnt vmcnt(6)
	s_setprio 1
	s_barrier
	v_mfma_f32_16x16x32_bf16 v[28:31], v[214:217], v[144:147], v[28:31]
	v_mfma_f32_16x16x32_bf16 v[24:27], v[234:237], v[144:147], v[24:27]
	v_mfma_f32_16x16x32_bf16 v[20:23], v[214:217], v[152:155], v[20:23]
	v_mfma_f32_16x16x32_bf16 v[16:19], v[234:237], v[152:155], v[16:19]
	v_mfma_f32_16x16x32_bf16 v[12:15], v[214:217], v[198:201], v[12:15]
	v_mfma_f32_16x16x32_bf16 v[8:11], v[234:237], v[198:201], v[8:11]
	v_mfma_f32_16x16x32_bf16 v[4:7], v[214:217], v[206:209], v[4:7]
	v_mfma_f32_16x16x32_bf16 v[0:3], v[234:237], v[206:209], v[0:3]
	v_mfma_f32_16x16x32_bf16 v[28:31], v[230:233], v[148:151], v[28:31]
	s_add_i32 s33, s33, 2
	v_mfma_f32_16x16x32_bf16 v[24:27], v[238:241], v[148:151], v[24:27]
	s_add_u32 s4, s4, 0x100
	v_mfma_f32_16x16x32_bf16 v[20:23], v[230:233], v[194:197], v[20:23]
	s_addc_u32 s5, s5, 0
	v_mfma_f32_16x16x32_bf16 v[16:19], v[238:241], v[194:197], v[16:19]
	s_cmp_gt_u32 s33, 33
	v_mfma_f32_16x16x32_bf16 v[12:15], v[230:233], v[202:205], v[12:15]
	s_mov_b64 s[20:21], s[22:23]
	v_mfma_f32_16x16x32_bf16 v[8:11], v[238:241], v[202:205], v[8:11]
	v_mfma_f32_16x16x32_bf16 v[4:7], v[230:233], v[210:213], v[4:7]
	s_setprio 0
	v_mfma_f32_16x16x32_bf16 v[0:3], v[238:241], v[210:213], v[0:3]
	s_barrier
	s_cbranch_scc0 .LBB0_77
	v_lshl_add_u32 v206, s3, 8, v225
	v_lshl_or_b32 v158, s2, 8, v227
	v_lshlrev_b32_e32 v232, 11, v206
	s_andn2_b64 vcc, exec, s[14:15]
	v_or_b32_e32 v231, 16, v158
	v_add_u32_e32 v194, v232, v158
	v_or_b32_e32 v230, 0x80, v158
	v_or_b32_e32 v229, 0x90, v158
	s_cbranch_vccnz .LBB0_80
	v_lshlrev_b64 v[132:133], 2, v[158:159]
	v_lshl_add_u64 v[140:141], s[16:17], 0, v[132:133]
	global_load_dwordx4 v[128:131], v[140:141], off
	v_lshl_add_u64 v[142:143], s[18:19], 0, v[132:133]
	v_readlane_b32 s2, v253, 8
	v_mov_b32_e32 v195, v159
	v_lshlrev_b32_e32 v136, 1, v206
	v_mov_b32_e32 v137, v159
	v_readlane_b32 s3, v253, 9
	v_lshlrev_b64 v[212:213], 2, v[194:195]
	v_add_u32_e32 v146, v232, v231
	v_lshl_add_u64 v[144:145], v[136:137], 2, s[2:3]
	v_lshl_add_u64 v[136:137], s[88:89], 0, v[212:213]
	v_mov_b32_e32 v147, v159
	v_lshl_add_u64 v[146:147], v[146:147], 2, s[88:89]
	v_or_b32_e32 v195, 16, v206
	v_mov_b32_e32 v201, v159
	v_mov_b32_e32 v209, v159
	v_lshl_add_u64 v[212:213], s[90:91], 0, v[212:213]
	s_waitcnt vmcnt(0)
	v_pk_mul_f32 v[152:153], v[130:131], s[78:79] op_sel_hi:[1,0]
	v_pk_mul_f32 v[154:155], v[128:129], s[78:79] op_sel_hi:[1,0]
	global_load_dwordx4 v[132:135], v[142:143], off
	global_load_dwordx4 v[128:131], v[140:141], off offset:64
	global_load_dwordx2 v[204:205], v[144:145], off
	global_load_dwordx4 v[196:199], v[146:147], off
	v_lshlrev_b32_e32 v146, 1, v195
	global_load_dwordx4 v[136:139], v[136:137], off
	v_lshlrev_b32_e32 v195, 11, v195
	v_mov_b32_e32 v147, v159
	v_add_u32_e32 v200, v195, v158
	v_lshl_add_u64 v[146:147], v[146:147], 2, s[2:3]
	v_lshl_add_u64 v[200:201], v[200:201], 2, s[88:89]
	global_load_dwordx2 v[214:215], v[146:147], off
	v_add_u32_e32 v208, v195, v231
	global_load_dwordx4 v[200:203], v[200:201], off
	v_lshl_add_u64 v[208:209], v[208:209], 2, s[88:89]
	global_load_dwordx4 v[208:211], v[208:209], off
	s_waitcnt vmcnt(0)
	v_pk_mul_f32 v[148:149], v[130:131], s[78:79] op_sel_hi:[1,0]
	v_pk_mul_f32 v[150:151], v[128:129], s[78:79] op_sel_hi:[1,0]
	global_load_dwordx4 v[128:131], v[142:143], off offset:64
	v_sub_f32_e32 v137, v137, v204
	v_sub_f32_e32 v136, v136, v204
	v_sub_f32_e32 v139, v139, v204
	v_sub_f32_e32 v138, v138, v204
	v_pk_mul_f32 v[138:139], v[204:205], v[138:139] op_sel:[1,0]
	v_pk_mul_f32 v[136:137], v[204:205], v[136:137] op_sel:[1,0]
	v_pk_fma_f32 v[138:139], v[152:153], v[138:139], v[126:127]
	v_pk_fma_f32 v[136:137], v[154:155], v[136:137], v[124:125]
	v_pk_fma_f32 v[138:139], v[134:135], s[78:79], v[138:139] op_sel_hi:[1,0,1]
	v_pk_fma_f32 v[136:137], v[132:133], s[78:79], v[136:137] op_sel_hi:[1,0,1]
	global_store_dwordx4 v[212:213], v[136:139], off
	s_nop 1
	v_sub_f32_e32 v137, v197, v204
	v_sub_f32_e32 v136, v196, v204
	v_sub_f32_e32 v139, v199, v204
	v_sub_f32_e32 v138, v198, v204
	v_pk_mul_f32 v[138:139], v[204:205], v[138:139] op_sel:[1,0]
	v_pk_mul_f32 v[136:137], v[204:205], v[136:137] op_sel:[1,0]
	v_pk_fma_f32 v[138:139], v[148:149], v[138:139], v[122:123]
	v_pk_fma_f32 v[136:137], v[150:151], v[136:137], v[120:121]
	v_or_b32_e32 v196, 16, v194
	v_mov_b32_e32 v197, v159
	v_lshl_add_u64 v[196:197], v[196:197], 2, s[90:91]
	s_waitcnt vmcnt(0)
;     template <bool LN, int BJ, int LO, int HI> DI void batch(const f32x4 (&acc)[2][2][4][2], unsigned row0, unsigned col0, const f32x4 (&gv)[2], const f32x4 (&bv)[2]) const {
;         f32x4 r[HI - LO]; float mean[(HI - LO) / 2], rstd[(HI - LO) / 2];
; #pragma unroll
;         for (int i = LO; i < HI; ++i) { const int ai = i >> 3, m = (i >> 1) & 3, n = i & 1; const unsigned row = row0 + ai * HALF + m * 16;
;             if (n == 0) { mean[(i - LO) >> 1] = 0.f; rstd[(i - LO) >> 1] = 1.f;
;                 if (LN) { const float2 st = *(const float2*)(stats + row * 2u); mean[(i - LO) >> 1] = st.x; rstd[(i - LO) >> 1] = st.y; } }
;             r[i - LO] = *(const f32x4*)(src + (row * (unsigned)DM + col0 + BJ * HALF + n * 16)); }
; #pragma unroll
;         for (int i = LO; i < HI; ++i) { const int ai = i >> 3, m = (i >> 1) & 3, n = i & 1; const unsigned row = row0 + ai * HALF + m * 16;
;             *(f32x4*)(Y + (row * (unsigned)DM + col0 + BJ * HALF + n * 16)) = acc[ai][BJ][m][n] + ((r[i - LO] - mean[(i - LO) >> 1]) * rstd[(i - LO) >> 1]) * gv[n] + bv[n]; }
;         __builtin_amdgcn_sched_barrier(0);
;     }
;     template <bool LN, int BJ> DI void load_gb(unsigned col0, f32x4 (&gv)[2], f32x4 (&bv)[2]) const {
; #pragma unroll
;         for (int n = 0; n < 2; ++n) {
;             if (LN) { gv[n] = *(const f32x4*)(gam + col0 + BJ * HALF + n * 16) * ALPHA; bv[n] = *(const f32x4*)(bet + col0 + BJ * HALF + n * 16) * ALPHA; }
;             else { gv[n] = (f32x4){ALPHA, ALPHA, ALPHA, ALPHA}; bv[n] = (f32x4){0.f, 0.f, 0.f, 0.f}; }
;         }
;     }
;     template <bool LN> DI void run(const f32x4 (&acc)[2][2][4][2], const Unit& u, int wr, int wc, int fr, int fq) const {
;         const unsigned row0 = u.pm * BM + wr * 64 + fr, col0 = u.pn * BM + wc * 32 + 4 * fq;
;         f32x4 gv[2], bv[2];
;         load_gb<LN, 0>(col0, gv, bv);
;         batch<LN, 0, 0, 4>(acc, row0, col0, gv, bv);
;         batch<LN, 0, 4, 8>(acc, row0, col0, gv, bv);
;         batch<LN, 0, 8, 12>(acc, row0, col0, gv, bv);
;         batch<LN, 0, 12, 16>(acc, row0, col0, gv, bv);
;         load_gb<LN, 1>(col0, gv, bv);
;         batch<LN, 1, 0, 8>(acc, row0, col0, gv, bv);
;         batch<LN, 1, 8, 16>(acc, row0, col0, gv, bv);
	v_pk_fma_f32 v[138:139], v[130:131], s[78:79], v[138:139] op_sel_hi:[1,0,1]
	v_pk_fma_f32 v[136:137], v[128:129], s[78:79], v[136:137] op_sel_hi:[1,0,1]
	global_store_dwordx4 v[196:197], v[136:139], off
	v_add_u32_e32 v196, 0x8000, v194
	v_mov_b32_e32 v197, v159
	v_sub_f32_e32 v137, v201, v214
	v_sub_f32_e32 v136, v200, v214
	v_sub_f32_e32 v139, v203, v214
	v_sub_f32_e32 v138, v202, v214
	v_pk_mul_f32 v[138:139], v[214:215], v[138:139] op_sel:[1,0]
	v_pk_mul_f32 v[136:137], v[214:215], v[136:137] op_sel:[1,0]
	v_pk_fma_f32 v[138:139], v[152:153], v[138:139], v[118:119]
	v_pk_fma_f32 v[136:137], v[154:155], v[136:137], v[116:117]
	v_pk_fma_f32 v[138:139], v[134:135], s[78:79], v[138:139] op_sel_hi:[1,0,1]
	v_pk_fma_f32 v[136:137], v[132:133], s[78:79], v[136:137] op_sel_hi:[1,0,1]
	v_lshl_add_u64 v[196:197], v[196:197], 2, s[90:91]
	global_store_dwordx4 v[196:197], v[136:139], off
	v_add_u32_e32 v196, 0x8010, v194
	v_mov_b32_e32 v197, v159
	v_sub_f32_e32 v137, v209, v214
	v_sub_f32_e32 v136, v208, v214
	v_sub_f32_e32 v139, v211, v214
	v_sub_f32_e32 v138, v210, v214
	v_pk_mul_f32 v[138:139], v[214:215], v[138:139] op_sel:[1,0]
	v_pk_mul_f32 v[136:137], v[214:215], v[136:137] op_sel:[1,0]
	v_pk_fma_f32 v[138:139], v[148:149], v[138:139], v[114:115]
	v_pk_fma_f32 v[136:137], v[150:151], v[136:137], v[112:113]
	v_pk_fma_f32 v[138:139], v[130:131], s[78:79], v[138:139] op_sel_hi:[1,0,1]
	v_pk_fma_f32 v[136:137], v[128:129], s[78:79], v[136:137] op_sel_hi:[1,0,1]
	v_lshl_add_u64 v[196:197], v[196:197], 2, s[90:91]
	global_store_dwordx4 v[196:197], v[136:139], off
	s_nop 1
	v_or_b32_e32 v138, 32, v206
	v_lshlrev_b32_e32 v136, 1, v138
	v_mov_b32_e32 v137, v159
	v_lshlrev_b32_e32 v236, 11, v138
	v_lshl_add_u64 v[200:201], v[136:137], 2, s[2:3]
	v_add_u32_e32 v136, v236, v158
	v_lshl_add_u64 v[136:137], v[136:137], 2, s[88:89]
	global_load_dwordx2 v[204:205], v[200:201], off
	v_add_u32_e32 v196, v236, v231
	global_load_dwordx4 v[136:139], v[136:137], off
	v_mov_b32_e32 v197, v159
	v_lshl_add_u64 v[196:197], v[196:197], 2, s[88:89]
	global_load_dwordx4 v[196:199], v[196:197], off
	v_or_b32_e32 v207, 48, v206
	v_lshlrev_b32_e32 v235, 11, v207
	v_lshlrev_b32_e32 v202, 1, v207
	v_mov_b32_e32 v203, v159
	v_add_u32_e32 v208, v235, v158
	v_mov_b32_e32 v209, v159
	v_lshl_add_u64 v[202:203], v[202:203], 2, s[2:3]
	v_lshl_add_u64 v[208:209], v[208:209], 2, s[88:89]
	global_load_dwordx2 v[216:217], v[202:203], off
	v_add_u32_e32 v212, v235, v231
	global_load_dwordx4 v[208:211], v[208:209], off
	v_mov_b32_e32 v213, v159
	v_lshl_add_u64 v[212:213], v[212:213], 2, s[88:89]
	global_load_dwordx4 v[212:215], v[212:213], off
	v_add_u32_e32 v218, 0x10000, v194
	v_mov_b32_e32 v219, v159
	v_lshl_add_u64 v[218:219], v[218:219], 2, s[90:91]
	s_waitcnt vmcnt(0)
	v_sub_f32_e32 v137, v137, v204
	v_sub_f32_e32 v136, v136, v204
	v_sub_f32_e32 v139, v139, v204
	v_sub_f32_e32 v138, v138, v204
	v_pk_mul_f32 v[138:139], v[204:205], v[138:139] op_sel:[1,0]
	v_pk_mul_f32 v[136:137], v[204:205], v[136:137] op_sel:[1,0]
	v_pk_fma_f32 v[138:139], v[152:153], v[138:139], v[110:111]
	v_pk_fma_f32 v[136:137], v[154:155], v[136:137], v[108:109]
	v_pk_fma_f32 v[138:139], v[134:135], s[78:79], v[138:139] op_sel_hi:[1,0,1]
	v_pk_fma_f32 v[136:137], v[132:133], s[78:79], v[136:137] op_sel_hi:[1,0,1]
	global_store_dwordx4 v[218:219], v[136:139], off
	s_nop 1
	v_sub_f32_e32 v137, v197, v204
	v_sub_f32_e32 v136, v196, v204
	v_sub_f32_e32 v139, v199, v204
	v_sub_f32_e32 v138, v198, v204
	v_pk_mul_f32 v[138:139], v[204:205], v[138:139] op_sel:[1,0]
	v_pk_mul_f32 v[136:137], v[204:205], v[136:137] op_sel:[1,0]
	v_pk_fma_f32 v[138:139], v[148:149], v[138:139], v[106:107]
	v_pk_fma_f32 v[136:137], v[150:151], v[136:137], v[104:105]
	v_add_u32_e32 v196, 0x10010, v194
	v_mov_b32_e32 v197, v159
	v_pk_fma_f32 v[138:139], v[130:131], s[78:79], v[138:139] op_sel_hi:[1,0,1]
	v_pk_fma_f32 v[136:137], v[128:129], s[78:79], v[136:137] op_sel_hi:[1,0,1]
	v_lshl_add_u64 v[196:197], v[196:197], 2, s[90:91]
	global_store_dwordx4 v[196:197], v[136:139], off
	v_add_u32_e32 v196, 0x18000, v194
	v_mov_b32_e32 v197, v159
	v_sub_f32_e32 v137, v209, v216
	v_sub_f32_e32 v136, v208, v216
	v_sub_f32_e32 v139, v211, v216
	v_sub_f32_e32 v138, v210, v216
	v_pk_mul_f32 v[138:139], v[216:217], v[138:139] op_sel:[1,0]
	v_pk_mul_f32 v[136:137], v[216:217], v[136:137] op_sel:[1,0]
	v_pk_fma_f32 v[138:139], v[152:153], v[138:139], v[102:103]
	v_pk_fma_f32 v[136:137], v[154:155], v[136:137], v[100:101]
	v_pk_fma_f32 v[138:139], v[134:135], s[78:79], v[138:139] op_sel_hi:[1,0,1]
	v_pk_fma_f32 v[136:137], v[132:133], s[78:79], v[136:137] op_sel_hi:[1,0,1]
	v_lshl_add_u64 v[196:197], v[196:197], 2, s[90:91]
	global_store_dwordx4 v[196:197], v[136:139], off
	v_add_u32_e32 v196, 0x18010, v194
	v_mov_b32_e32 v197, v159
	v_sub_f32_e32 v137, v213, v216
	v_sub_f32_e32 v136, v212, v216
	v_sub_f32_e32 v139, v215, v216
	v_sub_f32_e32 v138, v214, v216
	v_pk_mul_f32 v[138:139], v[216:217], v[138:139] op_sel:[1,0]
	v_pk_mul_f32 v[136:137], v[216:217], v[136:137] op_sel:[1,0]
	v_pk_fma_f32 v[138:139], v[148:149], v[138:139], v[98:99]
	v_pk_fma_f32 v[136:137], v[150:151], v[136:137], v[96:97]
	v_pk_fma_f32 v[138:139], v[130:131], s[78:79], v[138:139] op_sel_hi:[1,0,1]
	v_pk_fma_f32 v[136:137], v[128:129], s[78:79], v[136:137] op_sel_hi:[1,0,1]
	v_lshl_add_u64 v[196:197], v[196:197], 2, s[90:91]
	global_store_dwordx4 v[196:197], v[136:139], off
	s_nop 1
	v_add_u32_e32 v138, 0x80, v206
	v_lshlrev_b32_e32 v136, 1, v138
	v_mov_b32_e32 v137, v159
	v_lshlrev_b32_e32 v233, 11, v138
	v_lshl_add_u64 v[196:197], v[136:137], 2, s[2:3]
	v_add_u32_e32 v136, v233, v158
	v_lshl_add_u64 v[136:137], v[136:137], 2, s[88:89]
	global_load_dwordx2 v[204:205], v[196:197], off
	v_add_u32_e32 v198, v233, v231
	global_load_dwordx4 v[136:139], v[136:137], off
	v_mov_b32_e32 v199, v159
	v_add_u32_e32 v207, 0x90, v206
	v_lshl_add_u64 v[198:199], v[198:199], 2, s[88:89]
	v_lshlrev_b32_e32 v234, 11, v207
	global_load_dwordx4 v[208:211], v[198:199], off
	v_add_u32_e32 v212, v234, v158
	v_mov_b32_e32 v213, v159
	v_lshl_add_u64 v[212:213], v[212:213], 2, s[88:89]
	global_load_dwordx4 v[212:215], v[212:213], off
	v_lshlrev_b32_e32 v198, 1, v207
	v_mov_b32_e32 v199, v159
	v_lshl_add_u64 v[198:199], v[198:199], 2, s[2:3]
	global_load_dwordx2 v[220:221], v[198:199], off
	v_add_u32_e32 v216, v234, v231
	v_mov_b32_e32 v217, v159
	v_lshl_add_u64 v[216:217], v[216:217], 2, s[88:89]
	global_load_dwordx4 v[216:219], v[216:217], off
	v_add_u32_e32 v238, 0x40000, v194
	v_mov_b32_e32 v239, v159
	v_lshl_add_u64 v[238:239], v[238:239], 2, s[90:91]
	s_waitcnt vmcnt(0)
;     template <bool LN, int BJ, int LO, int HI> DI void batch(const f32x4 (&acc)[2][2][4][2], unsigned row0, unsigned col0, const f32x4 (&gv)[2], const f32x4 (&bv)[2]) const {
;         f32x4 r[HI - LO]; float mean[(HI - LO) / 2], rstd[(HI - LO) / 2];
; #pragma unroll
;         for (int i = LO; i < HI; ++i) { const int ai = i >> 3, m = (i >> 1) & 3, n = i & 1; const unsigned row = row0 + ai * HALF + m * 16;
;             if (n == 0) { mean[(i - LO) >> 1] = 0.f; rstd[(i - LO) >> 1] = 1.f;
;                 if (LN) { const float2 st = *(const float2*)(stats + row * 2u); mean[(i - LO) >> 1] = st.x; rstd[(i - LO) >> 1] = st.y; } }
;             r[i - LO] = *(const f32x4*)(src + (row * (unsigned)DM + col0 + BJ * HALF + n * 16)); }
; #pragma unroll
;         for (int i = LO; i < HI; ++i) { const int ai = i >> 3, m = (i >> 1) & 3, n = i & 1; const unsigned row = row0 + ai * HALF + m * 16;
;             *(f32x4*)(Y + (row * (unsigned)DM + col0 + BJ * HALF + n * 16)) = acc[ai][BJ][m][n] + ((r[i - LO] - mean[(i - LO) >> 1]) * rstd[(i - LO) >> 1]) * gv[n] + bv[n]; }
;         __builtin_amdgcn_sched_barrier(0);
;     }
;     template <bool LN, int BJ> DI void load_gb(unsigned col0, f32x4 (&gv)[2], f32x4 (&bv)[2]) const {
; #pragma unroll
;         for (int n = 0; n < 2; ++n) {
;             if (LN) { gv[n] = *(const f32x4*)(gam + col0 + BJ * HALF + n * 16) * ALPHA; bv[n] = *(const f32x4*)(bet + col0 + BJ * HALF + n * 16) * ALPHA; }
;             else { gv[n] = (f32x4){ALPHA, ALPHA, ALPHA, ALPHA}; bv[n] = (f32x4){0.f, 0.f, 0.f, 0.f}; }
;         }
;     }
;     template <bool LN> DI void run(const f32x4 (&acc)[2][2][4][2], const Unit& u, int wr, int wc, int fr, int fq) const {
;         const unsigned row0 = u.pm * BM + wr * 64 + fr, col0 = u.pn * BM + wc * 32 + 4 * fq;
;         f32x4 gv[2], bv[2];
;         load_gb<LN, 0>(col0, gv, bv);
;         batch<LN, 0, 0, 4>(acc, row0, col0, gv, bv);
;         batch<LN, 0, 4, 8>(acc, row0, col0, gv, bv);
;         batch<LN, 0, 8, 12>(acc, row0, col0, gv, bv);
;         batch<LN, 0, 12, 16>(acc, row0, col0, gv, bv);
;         load_gb<LN, 1>(col0, gv, bv);
;         batch<LN, 1, 0, 8>(acc, row0, col0, gv, bv);
;         batch<LN, 1, 8, 16>(acc, row0, col0, gv, bv);
	v_sub_f32_e32 v137, v137, v204
	v_sub_f32_e32 v136, v136, v204
	v_sub_f32_e32 v139, v139, v204
	v_sub_f32_e32 v138, v138, v204
	v_pk_mul_f32 v[138:139], v[204:205], v[138:139] op_sel:[1,0]
	v_pk_mul_f32 v[136:137], v[204:205], v[136:137] op_sel:[1,0]
	v_pk_fma_f32 v[138:139], v[152:153], v[138:139], v[94:95]
	v_pk_fma_f32 v[136:137], v[154:155], v[136:137], v[92:93]
	v_pk_fma_f32 v[138:139], v[134:135], s[78:79], v[138:139] op_sel_hi:[1,0,1]
	v_pk_fma_f32 v[136:137], v[132:133], s[78:79], v[136:137] op_sel_hi:[1,0,1]
	global_store_dwordx4 v[238:239], v[136:139], off
	s_nop 1
	v_sub_f32_e32 v137, v209, v204
	v_sub_f32_e32 v136, v208, v204
	v_sub_f32_e32 v139, v211, v204
	v_sub_f32_e32 v138, v210, v204
	v_pk_mul_f32 v[138:139], v[204:205], v[138:139] op_sel:[1,0]
	v_pk_mul_f32 v[136:137], v[204:205], v[136:137] op_sel:[1,0]
	v_pk_fma_f32 v[138:139], v[148:149], v[138:139], v[90:91]
	v_pk_fma_f32 v[136:137], v[150:151], v[136:137], v[88:89]
	v_add_u32_e32 v204, 0x40010, v194
	v_mov_b32_e32 v205, v159
	v_pk_fma_f32 v[138:139], v[130:131], s[78:79], v[138:139] op_sel_hi:[1,0,1]
	v_pk_fma_f32 v[136:137], v[128:129], s[78:79], v[136:137] op_sel_hi:[1,0,1]
	v_lshl_add_u64 v[204:205], v[204:205], 2, s[90:91]
	global_store_dwordx4 v[204:205], v[136:139], off
	v_add_u32_e32 v204, 0x48000, v194
	v_mov_b32_e32 v205, v159
	v_sub_f32_e32 v137, v213, v220
	v_sub_f32_e32 v136, v212, v220
	v_sub_f32_e32 v139, v215, v220
	v_sub_f32_e32 v138, v214, v220
	v_pk_mul_f32 v[138:139], v[220:221], v[138:139] op_sel:[1,0]
	v_pk_mul_f32 v[136:137], v[220:221], v[136:137] op_sel:[1,0]
	v_pk_fma_f32 v[138:139], v[152:153], v[138:139], v[86:87]
	v_pk_fma_f32 v[136:137], v[154:155], v[136:137], v[84:85]
	v_pk_fma_f32 v[138:139], v[134:135], s[78:79], v[138:139] op_sel_hi:[1,0,1]
	v_pk_fma_f32 v[136:137], v[132:133], s[78:79], v[136:137] op_sel_hi:[1,0,1]
	v_lshl_add_u64 v[204:205], v[204:205], 2, s[90:91]
	global_store_dwordx4 v[204:205], v[136:139], off
	v_add_u32_e32 v204, 0x48010, v194
	v_mov_b32_e32 v205, v159
	v_sub_f32_e32 v137, v217, v220
	v_sub_f32_e32 v136, v216, v220
	v_sub_f32_e32 v139, v219, v220
	v_sub_f32_e32 v138, v218, v220
	v_pk_mul_f32 v[138:139], v[220:221], v[138:139] op_sel:[1,0]
	v_pk_mul_f32 v[136:137], v[220:221], v[136:137] op_sel:[1,0]
	v_pk_fma_f32 v[138:139], v[148:149], v[138:139], v[82:83]
	v_pk_fma_f32 v[136:137], v[150:151], v[136:137], v[80:81]
	v_pk_fma_f32 v[138:139], v[130:131], s[78:79], v[138:139] op_sel_hi:[1,0,1]
	v_pk_fma_f32 v[136:137], v[128:129], s[78:79], v[136:137] op_sel_hi:[1,0,1]
	v_lshl_add_u64 v[204:205], v[204:205], 2, s[90:91]
	global_store_dwordx4 v[204:205], v[136:139], off
	s_nop 1
	v_add_u32_e32 v138, 0xa0, v206
	v_lshlrev_b32_e32 v136, 1, v138
	v_mov_b32_e32 v137, v159
	v_lshlrev_b32_e32 v237, 11, v138
	v_lshl_add_u64 v[204:205], v[136:137], 2, s[2:3]
	v_add_u32_e32 v136, v237, v158
	v_lshl_add_u64 v[136:137], v[136:137], 2, s[88:89]
	global_load_dwordx2 v[220:221], v[204:205], off
	v_add_u32_e32 v208, v237, v231
	global_load_dwordx4 v[136:139], v[136:137], off
	v_mov_b32_e32 v209, v159
	v_lshl_add_u64 v[208:209], v[208:209], 2, s[88:89]
	global_load_dwordx4 v[212:215], v[208:209], off
	v_add_u32_e32 v208, 0xb0, v206
	v_lshlrev_b32_e32 v206, 1, v208
	v_mov_b32_e32 v207, v159
	v_lshlrev_b32_e32 v238, 11, v208
	v_lshl_add_u64 v[210:211], v[206:207], 2, s[2:3]
	v_add_u32_e32 v206, v238, v158
	v_lshl_add_u64 v[206:207], v[206:207], 2, s[88:89]
	global_load_dwordx2 v[240:241], v[210:211], off
	v_add_u32_e32 v216, v238, v231
	global_load_dwordx4 v[206:209], v[206:207], off
	v_mov_b32_e32 v217, v159
	v_lshl_add_u64 v[216:217], v[216:217], 2, s[88:89]
	global_load_dwordx4 v[216:219], v[216:217], off
	v_add_u32_e32 v242, 0x50000, v194
	v_mov_b32_e32 v243, v159
	v_lshl_add_u64 v[242:243], v[242:243], 2, s[90:91]
	s_waitcnt vmcnt(0)
	v_sub_f32_e32 v137, v137, v220
	v_sub_f32_e32 v136, v136, v220
	v_sub_f32_e32 v139, v139, v220
	v_sub_f32_e32 v138, v138, v220
	v_pk_mul_f32 v[138:139], v[220:221], v[138:139] op_sel:[1,0]
	v_pk_mul_f32 v[136:137], v[220:221], v[136:137] op_sel:[1,0]
	v_pk_fma_f32 v[138:139], v[152:153], v[138:139], v[78:79]
	v_pk_fma_f32 v[136:137], v[154:155], v[136:137], v[76:77]
	v_pk_fma_f32 v[138:139], v[134:135], s[78:79], v[138:139] op_sel_hi:[1,0,1]
	v_pk_fma_f32 v[136:137], v[132:133], s[78:79], v[136:137] op_sel_hi:[1,0,1]
	global_store_dwordx4 v[242:243], v[136:139], off
	s_nop 1
	v_sub_f32_e32 v137, v213, v220
	v_sub_f32_e32 v136, v212, v220
	v_sub_f32_e32 v139, v215, v220
	v_sub_f32_e32 v138, v214, v220
	v_pk_mul_f32 v[138:139], v[220:221], v[138:139] op_sel:[1,0]
	v_pk_mul_f32 v[136:137], v[220:221], v[136:137] op_sel:[1,0]
	v_pk_fma_f32 v[138:139], v[148:149], v[138:139], v[74:75]
	v_pk_fma_f32 v[136:137], v[150:151], v[136:137], v[72:73]
	v_add_u32_e32 v212, 0x50010, v194
	v_mov_b32_e32 v213, v159
	v_pk_fma_f32 v[138:139], v[130:131], s[78:79], v[138:139] op_sel_hi:[1,0,1]
	v_pk_fma_f32 v[136:137], v[128:129], s[78:79], v[136:137] op_sel_hi:[1,0,1]
	v_lshl_add_u64 v[212:213], v[212:213], 2, s[90:91]
	global_store_dwordx4 v[212:213], v[136:139], off
	s_nop 1
	v_sub_f32_e32 v137, v207, v240
	v_sub_f32_e32 v136, v206, v240
	v_sub_f32_e32 v139, v209, v240
	v_sub_f32_e32 v138, v208, v240
	v_pk_mul_f32 v[136:137], v[240:241], v[136:137] op_sel:[1,0]
	v_pk_mul_f32 v[138:139], v[240:241], v[138:139] op_sel:[1,0]
	v_pk_fma_f32 v[136:137], v[154:155], v[136:137], v[68:69]
	v_pk_fma_f32 v[138:139], v[152:153], v[138:139], v[70:71]
	v_pk_fma_f32 v[132:133], v[132:133], s[78:79], v[136:137] op_sel_hi:[1,0,1]
	v_add_u32_e32 v136, 0x58000, v194
	v_mov_b32_e32 v137, v159
	v_pk_fma_f32 v[134:135], v[134:135], s[78:79], v[138:139] op_sel_hi:[1,0,1]
	v_lshl_add_u64 v[136:137], v[136:137], 2, s[90:91]
	global_store_dwordx4 v[136:137], v[132:135], off
	s_nop 1
	v_sub_f32_e32 v133, v217, v240
	v_sub_f32_e32 v132, v216, v240
	v_sub_f32_e32 v135, v219, v240
	v_sub_f32_e32 v134, v218, v240
	v_pk_mul_f32 v[132:133], v[240:241], v[132:133] op_sel:[1,0]
	v_pk_mul_f32 v[134:135], v[240:241], v[134:135] op_sel:[1,0]
	v_pk_fma_f32 v[132:133], v[150:151], v[132:133], v[64:65]
	v_pk_fma_f32 v[134:135], v[148:149], v[134:135], v[66:67]
	v_pk_fma_f32 v[128:129], v[128:129], s[78:79], v[132:133] op_sel_hi:[1,0,1]
	v_add_u32_e32 v132, 0x58010, v194
	v_mov_b32_e32 v133, v159
	v_pk_fma_f32 v[130:131], v[130:131], s[78:79], v[134:135] op_sel_hi:[1,0,1]
	v_lshl_add_u64 v[132:133], v[132:133], 2, s[90:91]
	global_store_dwordx4 v[132:133], v[128:131], off
	global_load_dwordx4 v[128:131], v[140:141], off offset:512
	v_add_u32_e32 v136, v232, v230
	v_mov_b32_e32 v137, v159
	v_lshl_add_u64 v[136:137], v[136:137], 2, s[88:89]
	s_waitcnt vmcnt(0)
;     template <bool LN, int BJ, int LO, int HI> DI void batch(const f32x4 (&acc)[2][2][4][2], unsigned row0, unsigned col0, const f32x4 (&gv)[2], const f32x4 (&bv)[2]) const {
;         f32x4 r[HI - LO]; float mean[(HI - LO) / 2], rstd[(HI - LO) / 2];
; #pragma unroll
;         for (int i = LO; i < HI; ++i) { const int ai = i >> 3, m = (i >> 1) & 3, n = i & 1; const unsigned row = row0 + ai * HALF + m * 16;
;             if (n == 0) { mean[(i - LO) >> 1] = 0.f; rstd[(i - LO) >> 1] = 1.f;
;                 if (LN) { const float2 st = *(const float2*)(stats + row * 2u); mean[(i - LO) >> 1] = st.x; rstd[(i - LO) >> 1] = st.y; } }
;             r[i - LO] = *(const f32x4*)(src + (row * (unsigned)DM + col0 + BJ * HALF + n * 16)); }
; #pragma unroll
;         for (int i = LO; i < HI; ++i) { const int ai = i >> 3, m = (i >> 1) & 3, n = i & 1; const unsigned row = row0 + ai * HALF + m * 16;
;             *(f32x4*)(Y + (row * (unsigned)DM + col0 + BJ * HALF + n * 16)) = acc[ai][BJ][m][n] + ((r[i - LO] - mean[(i - LO) >> 1]) * rstd[(i - LO) >> 1]) * gv[n] + bv[n]; }
;         __builtin_amdgcn_sched_barrier(0);
;     }
;     template <bool LN, int BJ> DI void load_gb(unsigned col0, f32x4 (&gv)[2], f32x4 (&bv)[2]) const {
; #pragma unroll
;         for (int n = 0; n < 2; ++n) {
;             if (LN) { gv[n] = *(const f32x4*)(gam + col0 + BJ * HALF + n * 16) * ALPHA; bv[n] = *(const f32x4*)(bet + col0 + BJ * HALF + n * 16) * ALPHA; }
;             else { gv[n] = (f32x4){ALPHA, ALPHA, ALPHA, ALPHA}; bv[n] = (f32x4){0.f, 0.f, 0.f, 0.f}; }
;         }
;     }
;     template <bool LN> DI void run(const f32x4 (&acc)[2][2][4][2], const Unit& u, int wr, int wc, int fr, int fq) const {
;         const unsigned row0 = u.pm * BM + wr * 64 + fr, col0 = u.pn * BM + wc * 32 + 4 * fq;
;         f32x4 gv[2], bv[2];
;         load_gb<LN, 0>(col0, gv, bv);
;         batch<LN, 0, 0, 4>(acc, row0, col0, gv, bv);
;         batch<LN, 0, 4, 8>(acc, row0, col0, gv, bv);
;         batch<LN, 0, 8, 12>(acc, row0, col0, gv, bv);
;         batch<LN, 0, 12, 16>(acc, row0, col0, gv, bv);
;         load_gb<LN, 1>(col0, gv, bv);
;         batch<LN, 1, 0, 8>(acc, row0, col0, gv, bv);
;         batch<LN, 1, 8, 16>(acc, row0, col0, gv, bv);
	v_pk_mul_f32 v[212:213], v[130:131], s[78:79] op_sel_hi:[1,0]
	v_pk_mul_f32 v[214:215], v[128:129], s[78:79] op_sel_hi:[1,0]
	global_load_dwordx4 v[132:135], v[142:143], off offset:512
	global_load_dwordx4 v[128:131], v[140:141], off offset:576
	s_waitcnt vmcnt(0)
	v_pk_mul_f32 v[206:207], v[130:131], s[78:79] op_sel_hi:[1,0]
	v_pk_mul_f32 v[208:209], v[128:129], s[78:79] op_sel_hi:[1,0]
	global_load_dwordx4 v[128:131], v[142:143], off offset:576
	global_load_dwordx2 v[220:221], v[144:145], off
	global_load_dwordx4 v[240:243], v[136:137], off
	v_add_u32_e32 v136, v232, v229
	v_mov_b32_e32 v137, v159
	v_lshl_add_u64 v[136:137], v[136:137], 2, s[88:89]
	global_load_dwordx4 v[244:247], v[136:137], off
	global_load_dwordx2 v[218:219], v[146:147], off
	v_add_u32_e32 v136, v195, v230
	v_mov_b32_e32 v137, v159
	v_lshl_add_u64 v[136:137], v[136:137], 2, s[88:89]
	global_load_dwordx4 v[248:251], v[136:137], off
	v_add_u32_e32 v136, v195, v229
	v_mov_b32_e32 v137, v159
	v_lshl_add_u64 v[136:137], v[136:137], 2, s[88:89]
	global_load_dwordx4 v[152:155], v[136:137], off
	global_load_dwordx2 v[216:217], v[200:201], off
	v_add_u32_e32 v136, v236, v230
	v_mov_b32_e32 v137, v159
	v_lshl_add_u64 v[136:137], v[136:137], 2, s[88:89]
	global_load_dwordx4 v[148:151], v[136:137], off
	v_add_u32_e32 v136, v236, v229
	v_mov_b32_e32 v137, v159
	v_lshl_add_u64 v[136:137], v[136:137], 2, s[88:89]
	global_load_dwordx4 v[144:147], v[136:137], off
	global_load_dwordx2 v[200:201], v[202:203], off
	v_add_u32_e32 v136, v235, v230
	v_mov_b32_e32 v137, v159
	v_lshl_add_u64 v[136:137], v[136:137], 2, s[88:89]
	global_load_dwordx4 v[140:143], v[136:137], off
	v_add_u32_e32 v136, v235, v229
	v_mov_b32_e32 v137, v159
	v_lshl_add_u64 v[136:137], v[136:137], 2, s[88:89]
	global_load_dwordx4 v[136:139], v[136:137], off
	v_add_u32_e32 v202, 0x80, v194
	v_mov_b32_e32 v203, v159
	v_lshl_add_u64 v[202:203], v[202:203], 2, s[90:91]
	s_waitcnt vmcnt(0)
	v_sub_f32_e32 v241, v241, v220
	v_sub_f32_e32 v240, v240, v220
	v_sub_f32_e32 v243, v243, v220
	v_sub_f32_e32 v242, v242, v220
	v_pk_mul_f32 v[242:243], v[220:221], v[242:243] op_sel:[1,0]
	v_pk_mul_f32 v[240:241], v[220:221], v[240:241] op_sel:[1,0]
	v_pk_fma_f32 v[242:243], v[212:213], v[242:243], v[62:63]
	v_pk_fma_f32 v[240:241], v[214:215], v[240:241], v[60:61]
	v_pk_fma_f32 v[242:243], v[134:135], s[78:79], v[242:243] op_sel_hi:[1,0,1]
	v_pk_fma_f32 v[240:241], v[132:133], s[78:79], v[240:241] op_sel_hi:[1,0,1]
	global_store_dwordx4 v[202:203], v[240:243], off
	v_sub_f32_e32 v203, v245, v220
	v_sub_f32_e32 v202, v244, v220
	v_sub_f32_e32 v241, v247, v220
	v_sub_f32_e32 v240, v246, v220
	v_pk_mul_f32 v[202:203], v[220:221], v[202:203] op_sel:[1,0]
	v_pk_mul_f32 v[240:241], v[220:221], v[240:241] op_sel:[1,0]
	v_pk_fma_f32 v[202:203], v[208:209], v[202:203], v[56:57]
	v_pk_fma_f32 v[220:221], v[206:207], v[240:241], v[58:59]
	v_pk_fma_f32 v[240:241], v[128:129], s[78:79], v[202:203] op_sel_hi:[1,0,1]
	v_add_u32_e32 v202, 0x90, v194
	v_mov_b32_e32 v203, v159
	v_pk_fma_f32 v[242:243], v[130:131], s[78:79], v[220:221] op_sel_hi:[1,0,1]
	v_lshl_add_u64 v[202:203], v[202:203], 2, s[90:91]
	global_store_dwordx4 v[202:203], v[240:243], off
	v_sub_f32_e32 v203, v249, v218
	v_sub_f32_e32 v202, v248, v218
	v_sub_f32_e32 v221, v251, v218
	v_sub_f32_e32 v220, v250, v218
	v_pk_mul_f32 v[202:203], v[218:219], v[202:203] op_sel:[1,0]
	v_pk_mul_f32 v[220:221], v[218:219], v[220:221] op_sel:[1,0]
	v_pk_fma_f32 v[202:203], v[214:215], v[202:203], v[52:53]
	v_pk_fma_f32 v[220:221], v[212:213], v[220:221], v[54:55]
	v_pk_fma_f32 v[240:241], v[132:133], s[78:79], v[202:203] op_sel_hi:[1,0,1]
	v_add_u32_e32 v202, 0x8080, v194
	v_mov_b32_e32 v203, v159
	v_sub_f32_e32 v153, v153, v218
	v_sub_f32_e32 v152, v152, v218
	v_sub_f32_e32 v155, v155, v218
	v_sub_f32_e32 v154, v154, v218
	v_pk_fma_f32 v[242:243], v[134:135], s[78:79], v[220:221] op_sel_hi:[1,0,1]
	v_lshl_add_u64 v[202:203], v[202:203], 2, s[90:91]
	v_pk_mul_f32 v[154:155], v[218:219], v[154:155] op_sel:[1,0]
	v_pk_mul_f32 v[152:153], v[218:219], v[152:153] op_sel:[1,0]
	global_store_dwordx4 v[202:203], v[240:243], off
	v_pk_fma_f32 v[152:153], v[208:209], v[152:153], v[48:49]
	v_pk_fma_f32 v[154:155], v[206:207], v[154:155], v[50:51]
	v_add_u32_e32 v202, 0x8090, v194
	v_mov_b32_e32 v203, v159
	v_sub_f32_e32 v149, v149, v216
	v_sub_f32_e32 v148, v148, v216
	v_sub_f32_e32 v151, v151, v216
	v_sub_f32_e32 v150, v150, v216
	v_pk_fma_f32 v[154:155], v[130:131], s[78:79], v[154:155] op_sel_hi:[1,0,1]
	v_pk_fma_f32 v[152:153], v[128:129], s[78:79], v[152:153] op_sel_hi:[1,0,1]
	v_lshl_add_u64 v[202:203], v[202:203], 2, s[90:91]
	v_pk_mul_f32 v[150:151], v[216:217], v[150:151] op_sel:[1,0]
	v_pk_mul_f32 v[148:149], v[216:217], v[148:149] op_sel:[1,0]
	global_store_dwordx4 v[202:203], v[152:155], off
	v_pk_fma_f32 v[148:149], v[214:215], v[148:149], v[44:45]
	v_pk_fma_f32 v[150:151], v[212:213], v[150:151], v[46:47]
	v_add_u32_e32 v152, 0x10080, v194
	v_mov_b32_e32 v153, v159
	v_sub_f32_e32 v145, v145, v216
	v_sub_f32_e32 v144, v144, v216
	v_sub_f32_e32 v147, v147, v216
	v_sub_f32_e32 v146, v146, v216
	v_pk_fma_f32 v[150:151], v[134:135], s[78:79], v[150:151] op_sel_hi:[1,0,1]
	v_pk_fma_f32 v[148:149], v[132:133], s[78:79], v[148:149] op_sel_hi:[1,0,1]
	v_lshl_add_u64 v[152:153], v[152:153], 2, s[90:91]
	v_pk_mul_f32 v[146:147], v[216:217], v[146:147] op_sel:[1,0]
	v_pk_mul_f32 v[144:145], v[216:217], v[144:145] op_sel:[1,0]
	global_store_dwordx4 v[152:153], v[148:151], off
	v_pk_fma_f32 v[144:145], v[208:209], v[144:145], v[40:41]
	v_pk_fma_f32 v[146:147], v[206:207], v[146:147], v[42:43]
;     template <bool LN, int BJ, int LO, int HI> DI void batch(const f32x4 (&acc)[2][2][4][2], unsigned row0, unsigned col0, const f32x4 (&gv)[2], const f32x4 (&bv)[2]) const {
;         f32x4 r[HI - LO]; float mean[(HI - LO) / 2], rstd[(HI - LO) / 2];
; #pragma unroll
;         for (int i = LO; i < HI; ++i) { const int ai = i >> 3, m = (i >> 1) & 3, n = i & 1; const unsigned row = row0 + ai * HALF + m * 16;
;             if (n == 0) { mean[(i - LO) >> 1] = 0.f; rstd[(i - LO) >> 1] = 1.f;
;                 if (LN) { const float2 st = *(const float2*)(stats + row * 2u); mean[(i - LO) >> 1] = st.x; rstd[(i - LO) >> 1] = st.y; } }
;             r[i - LO] = *(const f32x4*)(src + (row * (unsigned)DM + col0 + BJ * HALF + n * 16)); }
; #pragma unroll
;         for (int i = LO; i < HI; ++i) { const int ai = i >> 3, m = (i >> 1) & 3, n = i & 1; const unsigned row = row0 + ai * HALF + m * 16;
;             *(f32x4*)(Y + (row * (unsigned)DM + col0 + BJ * HALF + n * 16)) = acc[ai][BJ][m][n] + ((r[i - LO] - mean[(i - LO) >> 1]) * rstd[(i - LO) >> 1]) * gv[n] + bv[n]; }
;         __builtin_amdgcn_sched_barrier(0);
;     }
;     template <bool LN, int BJ> DI void load_gb(unsigned col0, f32x4 (&gv)[2], f32x4 (&bv)[2]) const {
; #pragma unroll
;         for (int n = 0; n < 2; ++n) {
;             if (LN) { gv[n] = *(const f32x4*)(gam + col0 + BJ * HALF + n * 16) * ALPHA; bv[n] = *(const f32x4*)(bet + col0 + BJ * HALF + n * 16) * ALPHA; }
;             else { gv[n] = (f32x4){ALPHA, ALPHA, ALPHA, ALPHA}; bv[n] = (f32x4){0.f, 0.f, 0.f, 0.f}; }
;         }
;     }
;     template <bool LN> DI void run(const f32x4 (&acc)[2][2][4][2], const Unit& u, int wr, int wc, int fr, int fq) const {
;         const unsigned row0 = u.pm * BM + wr * 64 + fr, col0 = u.pn * BM + wc * 32 + 4 * fq;
;         f32x4 gv[2], bv[2];
;         load_gb<LN, 0>(col0, gv, bv);
;         batch<LN, 0, 0, 4>(acc, row0, col0, gv, bv);
;         batch<LN, 0, 4, 8>(acc, row0, col0, gv, bv);
;         batch<LN, 0, 8, 12>(acc, row0, col0, gv, bv);
;         batch<LN, 0, 12, 16>(acc, row0, col0, gv, bv);
;         load_gb<LN, 1>(col0, gv, bv);
;         batch<LN, 1, 0, 8>(acc, row0, col0, gv, bv);
;         batch<LN, 1, 8, 16>(acc, row0, col0, gv, bv);
	v_add_u32_e32 v148, 0x10090, v194
	v_mov_b32_e32 v149, v159
	v_sub_f32_e32 v141, v141, v200
	v_sub_f32_e32 v140, v140, v200
	v_sub_f32_e32 v143, v143, v200
	v_sub_f32_e32 v142, v142, v200
	v_pk_fma_f32 v[146:147], v[130:131], s[78:79], v[146:147] op_sel_hi:[1,0,1]
	v_pk_fma_f32 v[144:145], v[128:129], s[78:79], v[144:145] op_sel_hi:[1,0,1]
	v_lshl_add_u64 v[148:149], v[148:149], 2, s[90:91]
	v_pk_mul_f32 v[142:143], v[200:201], v[142:143] op_sel:[1,0]
	v_pk_mul_f32 v[140:141], v[200:201], v[140:141] op_sel:[1,0]
	global_store_dwordx4 v[148:149], v[144:147], off
	v_pk_fma_f32 v[140:141], v[214:215], v[140:141], v[36:37]
	v_pk_fma_f32 v[142:143], v[212:213], v[142:143], v[38:39]
	v_add_u32_e32 v144, 0x18080, v194
	v_mov_b32_e32 v145, v159
	v_sub_f32_e32 v137, v137, v200
	v_sub_f32_e32 v136, v136, v200
	v_sub_f32_e32 v139, v139, v200
	v_sub_f32_e32 v138, v138, v200
	v_pk_fma_f32 v[142:143], v[134:135], s[78:79], v[142:143] op_sel_hi:[1,0,1]
	v_pk_fma_f32 v[140:141], v[132:133], s[78:79], v[140:141] op_sel_hi:[1,0,1]
	v_lshl_add_u64 v[144:145], v[144:145], 2, s[90:91]
	v_pk_mul_f32 v[138:139], v[200:201], v[138:139] op_sel:[1,0]
	v_pk_mul_f32 v[136:137], v[200:201], v[136:137] op_sel:[1,0]
	global_store_dwordx4 v[144:145], v[140:143], off
	v_pk_fma_f32 v[136:137], v[208:209], v[136:137], v[32:33]
	v_pk_fma_f32 v[138:139], v[206:207], v[138:139], v[34:35]
	v_add_u32_e32 v140, 0x18090, v194
	v_mov_b32_e32 v141, v159
	v_pk_fma_f32 v[138:139], v[130:131], s[78:79], v[138:139] op_sel_hi:[1,0,1]
	v_pk_fma_f32 v[136:137], v[128:129], s[78:79], v[136:137] op_sel_hi:[1,0,1]
	v_lshl_add_u64 v[140:141], v[140:141], 2, s[90:91]
	global_store_dwordx4 v[140:141], v[136:139], off
	s_nop 1
	v_add_u32_e32 v136, v233, v230
	v_mov_b32_e32 v137, v159
	v_lshl_add_u64 v[136:137], v[136:137], 2, s[88:89]
	global_load_dwordx2 v[220:221], v[196:197], off
	global_load_dwordx4 v[216:219], v[136:137], off
	v_add_u32_e32 v136, v233, v229
	v_mov_b32_e32 v137, v159
	v_lshl_add_u64 v[136:137], v[136:137], 2, s[88:89]
	global_load_dwordx4 v[240:243], v[136:137], off
	global_load_dwordx2 v[200:201], v[198:199], off
	v_add_u32_e32 v136, v234, v230
	v_mov_b32_e32 v137, v159
	v_lshl_add_u64 v[136:137], v[136:137], 2, s[88:89]
	global_load_dwordx4 v[244:247], v[136:137], off
	v_add_u32_e32 v136, v234, v229
	v_mov_b32_e32 v137, v159
	v_lshl_add_u64 v[136:137], v[136:137], 2, s[88:89]
	global_load_dwordx4 v[152:155], v[136:137], off
	global_load_dwordx2 v[198:199], v[204:205], off
	v_add_u32_e32 v136, v237, v230
	v_mov_b32_e32 v137, v159
	v_lshl_add_u64 v[136:137], v[136:137], 2, s[88:89]
	global_load_dwordx4 v[148:151], v[136:137], off
	v_add_u32_e32 v136, v237, v229
	v_mov_b32_e32 v137, v159
	v_lshl_add_u64 v[136:137], v[136:137], 2, s[88:89]
	global_load_dwordx4 v[144:147], v[136:137], off
	global_load_dwordx2 v[196:197], v[210:211], off
	v_add_u32_e32 v136, v238, v230
	v_mov_b32_e32 v137, v159
	v_lshl_add_u64 v[136:137], v[136:137], 2, s[88:89]
	global_load_dwordx4 v[140:143], v[136:137], off
	v_add_u32_e32 v136, v238, v229
	v_mov_b32_e32 v137, v159
	v_lshl_add_u64 v[136:137], v[136:137], 2, s[88:89]
	global_load_dwordx4 v[136:139], v[136:137], off
	v_add_u32_e32 v210, 0x40080, v194
	v_mov_b32_e32 v211, v159
	v_lshl_add_u64 v[210:211], v[210:211], 2, s[90:91]
	s_waitcnt vmcnt(0)
;     template <bool LN, int BJ, int LO, int HI> DI void batch(const f32x4 (&acc)[2][2][4][2], unsigned row0, unsigned col0, const f32x4 (&gv)[2], const f32x4 (&bv)[2]) const {
;         f32x4 r[HI - LO]; float mean[(HI - LO) / 2], rstd[(HI - LO) / 2];
; #pragma unroll
;         for (int i = LO; i < HI; ++i) { const int ai = i >> 3, m = (i >> 1) & 3, n = i & 1; const unsigned row = row0 + ai * HALF + m * 16;
;             if (n == 0) { mean[(i - LO) >> 1] = 0.f; rstd[(i - LO) >> 1] = 1.f;
;                 if (LN) { const float2 st = *(const float2*)(stats + row * 2u); mean[(i - LO) >> 1] = st.x; rstd[(i - LO) >> 1] = st.y; } }
;             r[i - LO] = *(const f32x4*)(src + (row * (unsigned)DM + col0 + BJ * HALF + n * 16)); }
; #pragma unroll
;         for (int i = LO; i < HI; ++i) { const int ai = i >> 3, m = (i >> 1) & 3, n = i & 1; const unsigned row = row0 + ai * HALF + m * 16;
;             *(f32x4*)(Y + (row * (unsigned)DM + col0 + BJ * HALF + n * 16)) = acc[ai][BJ][m][n] + ((r[i - LO] - mean[(i - LO) >> 1]) * rstd[(i - LO) >> 1]) * gv[n] + bv[n]; }
;         __builtin_amdgcn_sched_barrier(0);
;     }
;     template <bool LN, int BJ> DI void load_gb(unsigned col0, f32x4 (&gv)[2], f32x4 (&bv)[2]) const {
; #pragma unroll
;         for (int n = 0; n < 2; ++n) {
;             if (LN) { gv[n] = *(const f32x4*)(gam + col0 + BJ * HALF + n * 16) * ALPHA; bv[n] = *(const f32x4*)(bet + col0 + BJ * HALF + n * 16) * ALPHA; }
;             else { gv[n] = (f32x4){ALPHA, ALPHA, ALPHA, ALPHA}; bv[n] = (f32x4){0.f, 0.f, 0.f, 0.f}; }
;         }
;     }
;     template <bool LN> DI void run(const f32x4 (&acc)[2][2][4][2], const Unit& u, int wr, int wc, int fr, int fq) const {
;         const unsigned row0 = u.pm * BM + wr * 64 + fr, col0 = u.pn * BM + wc * 32 + 4 * fq;
;         f32x4 gv[2], bv[2];
;         load_gb<LN, 0>(col0, gv, bv);
;         batch<LN, 0, 0, 4>(acc, row0, col0, gv, bv);
;         batch<LN, 0, 4, 8>(acc, row0, col0, gv, bv);
;         batch<LN, 0, 8, 12>(acc, row0, col0, gv, bv);
;         batch<LN, 0, 12, 16>(acc, row0, col0, gv, bv);
;         load_gb<LN, 1>(col0, gv, bv);
;         batch<LN, 1, 0, 8>(acc, row0, col0, gv, bv);
;         batch<LN, 1, 8, 16>(acc, row0, col0, gv, bv);
	v_sub_f32_e32 v203, v217, v220
	v_sub_f32_e32 v202, v216, v220
	v_sub_f32_e32 v205, v219, v220
	v_sub_f32_e32 v204, v218, v220
	v_pk_mul_f32 v[204:205], v[220:221], v[204:205] op_sel:[1,0]
	v_pk_mul_f32 v[202:203], v[220:221], v[202:203] op_sel:[1,0]
	v_pk_fma_f32 v[204:205], v[212:213], v[204:205], v[30:31]
	v_pk_fma_f32 v[202:203], v[214:215], v[202:203], v[28:29]
	v_pk_fma_f32 v[204:205], v[134:135], s[78:79], v[204:205] op_sel_hi:[1,0,1]
	v_pk_fma_f32 v[202:203], v[132:133], s[78:79], v[202:203] op_sel_hi:[1,0,1]
	global_store_dwordx4 v[210:211], v[202:205], off
	v_add_u32_e32 v210, 0x40090, v194
	v_mov_b32_e32 v211, v159
	v_sub_f32_e32 v203, v241, v220
	v_sub_f32_e32 v202, v240, v220
	v_sub_f32_e32 v205, v243, v220
	v_sub_f32_e32 v204, v242, v220
	v_pk_mul_f32 v[204:205], v[220:221], v[204:205] op_sel:[1,0]
	v_pk_mul_f32 v[202:203], v[220:221], v[202:203] op_sel:[1,0]
	v_pk_fma_f32 v[204:205], v[206:207], v[204:205], v[26:27]
	v_pk_fma_f32 v[202:203], v[208:209], v[202:203], v[24:25]
	v_pk_fma_f32 v[204:205], v[130:131], s[78:79], v[204:205] op_sel_hi:[1,0,1]
	v_pk_fma_f32 v[202:203], v[128:129], s[78:79], v[202:203] op_sel_hi:[1,0,1]
	v_lshl_add_u64 v[210:211], v[210:211], 2, s[90:91]
	global_store_dwordx4 v[210:211], v[202:205], off
	v_sub_f32_e32 v149, v149, v198
	v_sub_f32_e32 v148, v148, v198
	v_sub_f32_e32 v203, v245, v200
	v_sub_f32_e32 v202, v244, v200
	v_sub_f32_e32 v141, v141, v196
	v_sub_f32_e32 v140, v140, v196
	v_sub_f32_e32 v205, v247, v200
	v_sub_f32_e32 v204, v246, v200
	v_pk_mul_f32 v[202:203], v[200:201], v[202:203] op_sel:[1,0]
	v_sub_f32_e32 v151, v151, v198
	v_sub_f32_e32 v150, v150, v198
	v_pk_mul_f32 v[148:149], v[198:199], v[148:149] op_sel:[1,0]
	v_sub_f32_e32 v143, v143, v196
	v_sub_f32_e32 v142, v142, v196
	v_pk_mul_f32 v[140:141], v[196:197], v[140:141] op_sel:[1,0]
	v_pk_mul_f32 v[204:205], v[200:201], v[204:205] op_sel:[1,0]
	v_pk_fma_f32 v[202:203], v[214:215], v[202:203], v[20:21]
	v_sub_f32_e32 v153, v153, v200
	v_sub_f32_e32 v152, v152, v200
	v_sub_f32_e32 v155, v155, v200
	v_sub_f32_e32 v154, v154, v200
	v_pk_mul_f32 v[150:151], v[198:199], v[150:151] op_sel:[1,0]
	v_pk_fma_f32 v[148:149], v[214:215], v[148:149], v[12:13]
	v_pk_mul_f32 v[142:143], v[196:197], v[142:143] op_sel:[1,0]
	v_pk_fma_f32 v[140:141], v[214:215], v[140:141], v[4:5]
	v_pk_fma_f32 v[204:205], v[212:213], v[204:205], v[22:23]
	v_pk_fma_f32 v[202:203], v[132:133], s[78:79], v[202:203] op_sel_hi:[1,0,1]
	v_pk_mul_f32 v[154:155], v[200:201], v[154:155] op_sel:[1,0]
	v_pk_mul_f32 v[152:153], v[200:201], v[152:153] op_sel:[1,0]
	v_pk_fma_f32 v[150:151], v[212:213], v[150:151], v[14:15]
	v_pk_fma_f32 v[148:149], v[132:133], s[78:79], v[148:149] op_sel_hi:[1,0,1]
	v_pk_fma_f32 v[142:143], v[212:213], v[142:143], v[6:7]
	v_pk_fma_f32 v[132:133], v[132:133], s[78:79], v[140:141] op_sel_hi:[1,0,1]
	v_add_u32_e32 v140, 0x58080, v194
	v_mov_b32_e32 v141, v159
	v_pk_fma_f32 v[204:205], v[134:135], s[78:79], v[204:205] op_sel_hi:[1,0,1]
	v_pk_fma_f32 v[152:153], v[208:209], v[152:153], v[16:17]
	v_pk_fma_f32 v[154:155], v[206:207], v[154:155], v[18:19]
	v_add_u32_e32 v200, 0x48090, v194
	v_mov_b32_e32 v201, v159
	v_pk_fma_f32 v[150:151], v[134:135], s[78:79], v[150:151] op_sel_hi:[1,0,1]
	v_pk_fma_f32 v[134:135], v[134:135], s[78:79], v[142:143] op_sel_hi:[1,0,1]
	v_lshl_add_u64 v[140:141], v[140:141], 2, s[90:91]
	v_pk_fma_f32 v[154:155], v[130:131], s[78:79], v[154:155] op_sel_hi:[1,0,1]
	v_pk_fma_f32 v[152:153], v[128:129], s[78:79], v[152:153] op_sel_hi:[1,0,1]
	v_lshl_add_u64 v[200:201], v[200:201], 2, s[90:91]
	v_sub_f32_e32 v145, v145, v198
	v_sub_f32_e32 v144, v144, v198
	global_store_dwordx4 v[140:141], v[132:135], off
	global_store_dwordx4 v[200:201], v[152:155], off
	v_sub_f32_e32 v147, v147, v198
	v_sub_f32_e32 v133, v137, v196
	v_sub_f32_e32 v132, v136, v196
	v_add_u32_e32 v152, 0x50080, v194
	v_mov_b32_e32 v153, v159
	v_sub_f32_e32 v146, v146, v198
	v_pk_mul_f32 v[144:145], v[198:199], v[144:145] op_sel:[1,0]
	v_sub_f32_e32 v135, v139, v196
	v_sub_f32_e32 v134, v138, v196
	v_pk_mul_f32 v[132:133], v[196:197], v[132:133] op_sel:[1,0]
	v_lshl_add_u64 v[152:153], v[152:153], 2, s[90:91]
	v_pk_mul_f32 v[146:147], v[198:199], v[146:147] op_sel:[1,0]
	v_pk_fma_f32 v[144:145], v[208:209], v[144:145], v[8:9]
	v_pk_mul_f32 v[134:135], v[196:197], v[134:135] op_sel:[1,0]
	v_pk_fma_f32 v[132:133], v[208:209], v[132:133], v[0:1]
	v_add_u32_e32 v210, 0x48080, v194
	v_mov_b32_e32 v211, v159
	global_store_dwordx4 v[152:153], v[148:151], off
	v_pk_fma_f32 v[146:147], v[206:207], v[146:147], v[10:11]
	v_pk_fma_f32 v[144:145], v[128:129], s[78:79], v[144:145] op_sel_hi:[1,0,1]
	v_add_u32_e32 v148, 0x50090, v194
	v_mov_b32_e32 v149, v159
	v_pk_fma_f32 v[134:135], v[206:207], v[134:135], v[2:3]
	v_pk_fma_f32 v[128:129], v[128:129], s[78:79], v[132:133] op_sel_hi:[1,0,1]
	v_add_u32_e32 v132, 0x58090, v194
	v_mov_b32_e32 v133, v159
	v_lshl_add_u64 v[210:211], v[210:211], 2, s[90:91]
	v_pk_fma_f32 v[146:147], v[130:131], s[78:79], v[146:147] op_sel_hi:[1,0,1]
	v_lshl_add_u64 v[148:149], v[148:149], 2, s[90:91]
	v_pk_fma_f32 v[130:131], v[130:131], s[78:79], v[134:135] op_sel_hi:[1,0,1]
	v_lshl_add_u64 v[132:133], v[132:133], 2, s[90:91]
	global_store_dwordx4 v[210:211], v[202:205], off
	global_store_dwordx4 v[148:149], v[144:147], off
	global_store_dwordx4 v[132:133], v[128:131], off
	s_mov_b64 s[20:21], 0
	s_branch .LBB0_81

; #define PG8_STAGE(bufoff, gbase) do { _Pragma("unroll") for (int _i = 0; _i < 2; ++_i) \
;         __builtin_amdgcn_global_load_lds((const unsigned*)((const char*)(gbase) + voff[_i]), (LAS unsigned*)(lds + (bufoff) + ldsw + _i * 8192), 16, 0, 0); } while (0)
; #define PG8_LDA(dst, b, h) do { _Pragma("unroll") for (int m = 0; m < 4; ++m) _Pragma("unroll") for (int k = 0; k < 2; ++k) dst[m][k] = *(const LAS bf16x8*)(lds + PG8_SA(b, h) + aoff + m * 2048 + k * 1024); } while (0)
; #define PG8_LDB(dst, b, h) do { _Pragma("unroll") for (int n = 0; n < 2; ++n) _Pragma("unroll") for (int k = 0; k < 2; ++k) dst[n][k] = *(const LAS bf16x8*)(lds + PG8_SB(b, h) + boff + n * 2048 + k * 1024); } while (0)
; #define PG8_MMA(ai, bj, At, Bt) do { __builtin_amdgcn_s_setprio(1); _Pragma("unroll") for (int m = 0; m < 4; ++m) _Pragma("unroll") for (int n = 0; n < 2; ++n) _Pragma("unroll") for (int k = 0; k < 2; ++k) \
;         acc[ai][bj][m][n] = __builtin_amdgcn_mfma_f32_16x16x32_bf16(Bt[n][k], At[m][k], acc[ai][bj][m][n], 0, 0, 0); __builtin_amdgcn_s_setprio(0); } while (0)
; #define PG8_WAIT_V(n) asm volatile("s_waitcnt vmcnt(" #n ")" ::: "memory")
; #define PG8_WAIT_L(n) asm volatile("s_waitcnt lgkmcnt(" #n ")" ::: "memory")
; #define PG8_BAR __builtin_amdgcn_s_barrier()
; #define PG8_SCHED __builtin_amdgcn_sched_barrier(0)
; template <class Epi>
; DI void gemm_phase(LAS unsigned char* lds, const Gemm g, const StaticOrder& S, const Epi& E) {
;     ...
;         for (int t = 0; t < nt; t += 2) {
;             const bool last = (t == nt - 2);
;             const char* a1 = cA + (size_t)(t + 1) * kstep;
;             const char* a2 = last ? nA : cA + (size_t)(t + 2) * kstep; const char* b2 = last ? nB : cB + (size_t)(t + 2) * kstep;
;             const char* a3 = a2 + kstep; const char* b3 = b2 + kstep;
;             PG8_LDB(B0, 0, 0); PG8_SCHED; PG8_LDA(At, 0, 0); PG8_STAGE(PG8_SA(1, 1), a1 + hstep);
;             PG8_WAIT_L(8); PG8_BAR; PG8_WAIT_L(0); PG8_MMA(0, 0, At, B0); PG8_BAR; PG8_SCHED;
;             PG8_LDB(B1, 0, 1); PG8_STAGE(PG8_SB(0, 0), b2);
;             PG8_BAR; PG8_WAIT_L(0); PG8_MMA(0, 1, At, B1); PG8_BAR;
;             PG8_LDA(At, 0, 1); PG8_STAGE(PG8_SA(0, 0), a2);
;             PG8_BAR; PG8_WAIT_L(0); PG8_MMA(1, 0, At, B0); PG8_BAR; PG8_SCHED;
;             PG8_STAGE(PG8_SB(0, 1), b2 + hstep);
;             PG8_WAIT_V(6); PG8_BAR; PG8_MMA(1, 1, At, B1); PG8_BAR;
.LBB0_134:
	s_add_u32 s18, s16, 0x100
	s_addc_u32 s19, s17, 0
	s_add_i32 s39, 0, 0x10000
	ds_read_b128 v[96:99], v199
	ds_read_b128 v[100:103], v199 offset:1024
	ds_read_b128 v[136:139], v199 offset:2048
	ds_read_b128 v[148:151], v199 offset:3072
	s_cmpk_eq_i32 s33, 0x54
	s_cselect_b32 s23, s9, s19
	s_cselect_b32 s22, s8, s18
	s_cselect_b32 s21, s11, s5
	s_cselect_b32 s20, s10, s4
	s_add_i32 m0, s28, 0xc000
	ds_read_b128 v[152:155], v201
	ds_read_b128 v[186:189], v201 offset:1024
	ds_read_b128 v[190:193], v201 offset:2048
	ds_read_b128 v[194:197], v201 offset:3072
	ds_read_b128 v[202:205], v201 offset:4096
	ds_read_b128 v[206:209], v201 offset:5120
	ds_read_b128 v[210:213], v201 offset:6144
	ds_read_b128 v[214:217], v201 offset:7168
	global_load_lds_dwordx4 v144, s[16:17]
	s_add_i32 m0, s28, 0xe000
	s_nop 0
	global_load_lds_dwordx4 v146, s[16:17]
	s_waitcnt lgkmcnt(8)
	s_setprio 1
	s_barrier
	s_waitcnt lgkmcnt(0)
	v_mfma_f32_16x16x32_bf16 v[132:135], v[96:99], v[152:155], v[132:135]
	v_mfma_f32_16x16x32_bf16 v[128:131], v[136:139], v[152:155], v[128:131]
	v_mfma_f32_16x16x32_bf16 v[124:127], v[96:99], v[190:193], v[124:127]
	v_mfma_f32_16x16x32_bf16 v[120:123], v[136:139], v[190:193], v[120:123]
	v_mfma_f32_16x16x32_bf16 v[116:119], v[96:99], v[202:205], v[116:119]
	v_mfma_f32_16x16x32_bf16 v[112:115], v[136:139], v[202:205], v[112:115]
	v_mfma_f32_16x16x32_bf16 v[108:111], v[96:99], v[210:213], v[108:111]
	v_mfma_f32_16x16x32_bf16 v[104:107], v[136:139], v[210:213], v[104:107]
	v_mfma_f32_16x16x32_bf16 v[132:135], v[100:103], v[186:189], v[132:135]
	v_mfma_f32_16x16x32_bf16 v[128:131], v[148:151], v[186:189], v[128:131]
	v_mfma_f32_16x16x32_bf16 v[124:127], v[100:103], v[194:197], v[124:127]
	v_mfma_f32_16x16x32_bf16 v[120:123], v[148:151], v[194:197], v[120:123]
	v_mfma_f32_16x16x32_bf16 v[116:119], v[100:103], v[206:209], v[116:119]
	v_mfma_f32_16x16x32_bf16 v[112:115], v[148:151], v[206:209], v[112:115]
	v_mfma_f32_16x16x32_bf16 v[108:111], v[100:103], v[214:217], v[108:111]
	s_setprio 0
	v_mfma_f32_16x16x32_bf16 v[104:107], v[148:151], v[214:217], v[104:107]
	s_barrier
	s_add_i32 s40, 0, 0x14000
	s_add_i32 s16, s39, s27
	s_mov_b32 m0, s16
	ds_read_b128 v[226:229], v199 offset:16384
	ds_read_b128 v[230:233], v199 offset:17408
	ds_read_b128 v[234:237], v199 offset:18432
	ds_read_b128 v[238:241], v199 offset:19456
	global_load_lds_dwordx4 v142, s[20:21]
	s_add_i32 m0, s16, 0x2000
	s_nop 0
	global_load_lds_dwordx4 v140, s[20:21]
	s_waitcnt lgkmcnt(0)
	s_setprio 1
	s_barrier
	v_mfma_f32_16x16x32_bf16 v[60:63], v[226:229], v[152:155], v[60:63]
	v_mfma_f32_16x16x32_bf16 v[56:59], v[234:237], v[152:155], v[56:59]
	v_mfma_f32_16x16x32_bf16 v[52:55], v[226:229], v[190:193], v[52:55]
	v_mfma_f32_16x16x32_bf16 v[48:51], v[234:237], v[190:193], v[48:51]
	v_mfma_f32_16x16x32_bf16 v[44:47], v[226:229], v[202:205], v[44:47]
	v_mfma_f32_16x16x32_bf16 v[40:43], v[234:237], v[202:205], v[40:43]
	v_mfma_f32_16x16x32_bf16 v[36:39], v[226:229], v[210:213], v[36:39]
	v_mfma_f32_16x16x32_bf16 v[32:35], v[234:237], v[210:213], v[32:35]
	v_mfma_f32_16x16x32_bf16 v[60:63], v[230:233], v[186:189], v[60:63]
	s_mov_b32 m0, s28
	v_mfma_f32_16x16x32_bf16 v[56:59], v[238:241], v[186:189], v[56:59]
	s_mov_b64 s[100:101], s[22:23]
	v_mfma_f32_16x16x32_bf16 v[52:55], v[230:233], v[194:197], v[52:55]
	v_mfma_f32_16x16x32_bf16 v[48:51], v[238:241], v[194:197], v[48:51]
	v_mfma_f32_16x16x32_bf16 v[44:47], v[230:233], v[206:209], v[44:47]
	v_mfma_f32_16x16x32_bf16 v[40:43], v[238:241], v[206:209], v[40:43]
	v_mfma_f32_16x16x32_bf16 v[36:39], v[230:233], v[214:217], v[36:39]
	s_setprio 0
	v_mfma_f32_16x16x32_bf16 v[32:35], v[238:241], v[214:217], v[32:35]
	s_barrier
	ds_read_b128 v[152:155], v201 offset:16384
	ds_read_b128 v[186:189], v201 offset:17408
	ds_read_b128 v[190:193], v201 offset:18432
	ds_read_b128 v[194:197], v201 offset:19456
	ds_read_b128 v[202:205], v201 offset:20480
	ds_read_b128 v[206:209], v201 offset:21504
	ds_read_b128 v[210:213], v201 offset:22528
	ds_read_b128 v[214:217], v201 offset:23552
	global_load_lds_dwordx4 v142, s[22:23]
	s_mov_b64 s[100:101], s[22:23]
	s_mov_b32 m0, s29
	s_nop 0
	global_load_lds_dwordx4 v140, s[22:23]
	s_waitcnt lgkmcnt(0)
	s_setprio 1
	s_barrier
	v_mfma_f32_16x16x32_bf16 v[92:95], v[96:99], v[152:155], v[92:95]
	v_mfma_f32_16x16x32_bf16 v[88:91], v[136:139], v[152:155], v[88:91]
	v_mfma_f32_16x16x32_bf16 v[84:87], v[96:99], v[190:193], v[84:87]
	v_mfma_f32_16x16x32_bf16 v[80:83], v[136:139], v[190:193], v[80:83]
	v_mfma_f32_16x16x32_bf16 v[76:79], v[96:99], v[202:205], v[76:79]
	v_mfma_f32_16x16x32_bf16 v[72:75], v[136:139], v[202:205], v[72:75]
	v_mfma_f32_16x16x32_bf16 v[68:71], v[96:99], v[210:213], v[68:71]
	v_mfma_f32_16x16x32_bf16 v[64:67], v[136:139], v[210:213], v[64:67]
	v_mfma_f32_16x16x32_bf16 v[92:95], v[100:103], v[186:189], v[92:95]
	v_mfma_f32_16x16x32_bf16 v[88:91], v[148:151], v[186:189], v[88:91]
	v_mfma_f32_16x16x32_bf16 v[84:87], v[100:103], v[194:197], v[84:87]
	v_mfma_f32_16x16x32_bf16 v[80:83], v[148:151], v[194:197], v[80:83]
	v_mfma_f32_16x16x32_bf16 v[76:79], v[100:103], v[206:209], v[76:79]
	v_mfma_f32_16x16x32_bf16 v[72:75], v[148:151], v[206:209], v[72:75]
	v_mfma_f32_16x16x32_bf16 v[68:71], v[100:103], v[214:217], v[68:71]
	s_setprio 0
	v_mfma_f32_16x16x32_bf16 v[64:67], v[148:151], v[214:217], v[64:67]
	s_barrier
	s_add_u32 s16, s20, 0x160000
	s_addc_u32 s17, s21, 0
	s_add_i32 s39, s40, s27
	s_mov_b32 m0, s39
	s_nop 0
	global_load_lds_dwordx4 v142, s[16:17]
	s_add_i32 m0, s39, 0x2000
	s_nop 0
	global_load_lds_dwordx4 v140, s[16:17]
	s_waitcnt vmcnt(6)
	s_setprio 1
	s_barrier
; #define PG8_STAGE(bufoff, gbase) do { _Pragma("unroll") for (int _i = 0; _i < 2; ++_i) \
;         __builtin_amdgcn_global_load_lds((const unsigned*)((const char*)(gbase) + voff[_i]), (LAS unsigned*)(lds + (bufoff) + ldsw + _i * 8192), 16, 0, 0); } while (0)
; #define PG8_LDA(dst, b, h) do { _Pragma("unroll") for (int m = 0; m < 4; ++m) _Pragma("unroll") for (int k = 0; k < 2; ++k) dst[m][k] = *(const LAS bf16x8*)(lds + PG8_SA(b, h) + aoff + m * 2048 + k * 1024); } while (0)
; #define PG8_LDB(dst, b, h) do { _Pragma("unroll") for (int n = 0; n < 2; ++n) _Pragma("unroll") for (int k = 0; k < 2; ++k) dst[n][k] = *(const LAS bf16x8*)(lds + PG8_SB(b, h) + boff + n * 2048 + k * 1024); } while (0)
; #define PG8_MMA(ai, bj, At, Bt) do { __builtin_amdgcn_s_setprio(1); _Pragma("unroll") for (int m = 0; m < 4; ++m) _Pragma("unroll") for (int n = 0; n < 2; ++n) _Pragma("unroll") for (int k = 0; k < 2; ++k) \
;         acc[ai][bj][m][n] = __builtin_amdgcn_mfma_f32_16x16x32_bf16(Bt[n][k], At[m][k], acc[ai][bj][m][n], 0, 0, 0); __builtin_amdgcn_s_setprio(0); } while (0)
; #define PG8_WAIT_V(n) asm volatile("s_waitcnt vmcnt(" #n ")" ::: "memory")
; #define PG8_WAIT_L(n) asm volatile("s_waitcnt lgkmcnt(" #n ")" ::: "memory")
; #define PG8_BAR __builtin_amdgcn_s_barrier()
; #define PG8_SCHED __builtin_amdgcn_sched_barrier(0)
; template <class Epi>
; DI void gemm_phase(LAS unsigned char* lds, const Gemm g, const StaticOrder& S, const Epi& E) {
;     ...
;             PG8_WAIT_V(6); PG8_BAR; PG8_MMA(1, 1, At, B1); PG8_BAR;
;             PG8_LDB(B0, 1, 0); PG8_SCHED; PG8_LDA(At, 1, 0); PG8_STAGE(PG8_SA(0, 1), a2 + hstep);
;             PG8_WAIT_L(8); PG8_BAR; PG8_WAIT_L(0); PG8_MMA(0, 0, At, B0); PG8_BAR; PG8_SCHED;
;             PG8_LDB(B1, 1, 1); PG8_STAGE(PG8_SB(1, 0), b3);
;             PG8_BAR; PG8_WAIT_L(0); PG8_MMA(0, 1, At, B1); PG8_BAR;
;             PG8_LDA(At, 1, 1); PG8_STAGE(PG8_SA(1, 0), a3);
	v_mfma_f32_16x16x32_bf16 v[28:31], v[226:229], v[152:155], v[28:31]
	v_mfma_f32_16x16x32_bf16 v[24:27], v[234:237], v[152:155], v[24:27]
	v_mfma_f32_16x16x32_bf16 v[20:23], v[226:229], v[190:193], v[20:23]
	v_mfma_f32_16x16x32_bf16 v[16:19], v[234:237], v[190:193], v[16:19]
	v_mfma_f32_16x16x32_bf16 v[12:15], v[226:229], v[202:205], v[12:15]
	v_mfma_f32_16x16x32_bf16 v[8:11], v[234:237], v[202:205], v[8:11]
	v_mfma_f32_16x16x32_bf16 v[4:7], v[226:229], v[210:213], v[4:7]
	v_mfma_f32_16x16x32_bf16 v[0:3], v[234:237], v[210:213], v[0:3]
	v_mfma_f32_16x16x32_bf16 v[28:31], v[230:233], v[186:189], v[28:31]
	s_add_i32 s39, 0, 0x18000
	v_mfma_f32_16x16x32_bf16 v[24:27], v[238:241], v[186:189], v[24:27]
	v_mfma_f32_16x16x32_bf16 v[20:23], v[230:233], v[194:197], v[20:23]
	v_mfma_f32_16x16x32_bf16 v[16:19], v[238:241], v[194:197], v[16:19]
	v_mfma_f32_16x16x32_bf16 v[12:15], v[230:233], v[206:209], v[12:15]
	v_mfma_f32_16x16x32_bf16 v[8:11], v[238:241], v[206:209], v[8:11]
	v_mfma_f32_16x16x32_bf16 v[4:7], v[230:233], v[214:217], v[4:7]
	s_setprio 0
	v_mfma_f32_16x16x32_bf16 v[0:3], v[238:241], v[214:217], v[0:3]
	s_barrier
	ds_read_b128 v[96:99], v199 offset:32768
	ds_read_b128 v[100:103], v199 offset:33792
	ds_read_b128 v[136:139], v199 offset:34816
	ds_read_b128 v[148:151], v199 offset:35840
	s_add_u32 s16, s22, 0x160000
	s_addc_u32 s17, s23, 0
	s_mov_b32 m0, s30
	ds_read_b128 v[152:155], v201 offset:32768
	ds_read_b128 v[186:189], v201 offset:33792
	ds_read_b128 v[190:193], v201 offset:34816
	ds_read_b128 v[194:197], v201 offset:35840
	ds_read_b128 v[202:205], v201 offset:36864
	ds_read_b128 v[206:209], v201 offset:37888
	ds_read_b128 v[210:213], v201 offset:38912
	ds_read_b128 v[214:217], v201 offset:39936
	global_load_lds_dwordx4 v142, s[16:17]
	s_mov_b32 m0, s31
	s_nop 0
	global_load_lds_dwordx4 v140, s[16:17]
	s_waitcnt lgkmcnt(8)
	s_setprio 1
	s_barrier
	s_waitcnt lgkmcnt(0)
	v_mfma_f32_16x16x32_bf16 v[132:135], v[96:99], v[152:155], v[132:135]
	v_mfma_f32_16x16x32_bf16 v[128:131], v[136:139], v[152:155], v[128:131]
	v_mfma_f32_16x16x32_bf16 v[124:127], v[96:99], v[190:193], v[124:127]
	v_mfma_f32_16x16x32_bf16 v[120:123], v[136:139], v[190:193], v[120:123]
	v_mfma_f32_16x16x32_bf16 v[116:119], v[96:99], v[202:205], v[116:119]
	v_mfma_f32_16x16x32_bf16 v[112:115], v[136:139], v[202:205], v[112:115]
	v_mfma_f32_16x16x32_bf16 v[108:111], v[96:99], v[210:213], v[108:111]
	v_mfma_f32_16x16x32_bf16 v[104:107], v[136:139], v[210:213], v[104:107]
	v_mfma_f32_16x16x32_bf16 v[132:135], v[100:103], v[186:189], v[132:135]
	v_mfma_f32_16x16x32_bf16 v[128:131], v[148:151], v[186:189], v[128:131]
	v_mfma_f32_16x16x32_bf16 v[124:127], v[100:103], v[194:197], v[124:127]
	v_mfma_f32_16x16x32_bf16 v[120:123], v[148:151], v[194:197], v[120:123]
	v_mfma_f32_16x16x32_bf16 v[116:119], v[100:103], v[206:209], v[116:119]
	v_mfma_f32_16x16x32_bf16 v[112:115], v[148:151], v[206:209], v[112:115]
	v_mfma_f32_16x16x32_bf16 v[108:111], v[100:103], v[214:217], v[108:111]
	s_setprio 0
	v_mfma_f32_16x16x32_bf16 v[104:107], v[148:151], v[214:217], v[104:107]
	s_barrier
	s_add_i32 s22, 0, 0x1c000
	s_add_i32 s16, s39, s27
	s_add_i32 m0, s16, 0xffffff80
	ds_read_b128 v[226:229], v199 offset:49152
	ds_read_b128 v[230:233], v199 offset:50176
	ds_read_b128 v[234:237], v199 offset:51200
	ds_read_b128 v[238:241], v199 offset:52224
	global_load_lds_dwordx4 v142, s[20:21] offset:128
	s_add_i32 m0, s16, 0x1f80
	s_nop 0
	global_load_lds_dwordx4 v140, s[20:21] offset:128
	s_waitcnt lgkmcnt(0)
	s_setprio 1
	s_barrier
	v_mfma_f32_16x16x32_bf16 v[60:63], v[226:229], v[152:155], v[60:63]
	v_mfma_f32_16x16x32_bf16 v[56:59], v[234:237], v[152:155], v[56:59]
	v_mfma_f32_16x16x32_bf16 v[52:55], v[226:229], v[190:193], v[52:55]
	v_mfma_f32_16x16x32_bf16 v[48:51], v[234:237], v[190:193], v[48:51]
	v_mfma_f32_16x16x32_bf16 v[44:47], v[226:229], v[202:205], v[44:47]
	v_mfma_f32_16x16x32_bf16 v[40:43], v[234:237], v[202:205], v[40:43]
	v_mfma_f32_16x16x32_bf16 v[36:39], v[226:229], v[210:213], v[36:39]
	v_mfma_f32_16x16x32_bf16 v[32:35], v[234:237], v[210:213], v[32:35]
	v_mfma_f32_16x16x32_bf16 v[60:63], v[230:233], v[186:189], v[60:63]
	s_add_i32 m0, s34, 0xffffff80
	v_mfma_f32_16x16x32_bf16 v[56:59], v[238:241], v[186:189], v[56:59]
	v_mfma_f32_16x16x32_bf16 v[52:55], v[230:233], v[194:197], v[52:55]
	v_mfma_f32_16x16x32_bf16 v[48:51], v[238:241], v[194:197], v[48:51]
	v_mfma_f32_16x16x32_bf16 v[44:47], v[230:233], v[206:209], v[44:47]
	v_mfma_f32_16x16x32_bf16 v[40:43], v[238:241], v[206:209], v[40:43]
	v_mfma_f32_16x16x32_bf16 v[36:39], v[230:233], v[214:217], v[36:39]
	s_setprio 0
	v_mfma_f32_16x16x32_bf16 v[32:35], v[238:241], v[214:217], v[32:35]
	s_barrier
	ds_read_b128 v[152:155], v201 offset:49152
	ds_read_b128 v[186:189], v201 offset:50176
	ds_read_b128 v[190:193], v201 offset:51200
	ds_read_b128 v[194:197], v201 offset:52224
	ds_read_b128 v[202:205], v201 offset:53248
	ds_read_b128 v[206:209], v201 offset:54272
	ds_read_b128 v[210:213], v201 offset:55296
	ds_read_b128 v[214:217], v201 offset:56320
	global_load_lds_dwordx4 v142, s[100:101] offset:128
	s_add_i32 m0, s35, 0xffffff80
	s_nop 0
	global_load_lds_dwordx4 v140, s[100:101] offset:128
	s_waitcnt lgkmcnt(0)
	s_setprio 1
	s_barrier
; #define PG8_BAR __builtin_amdgcn_s_barrier()
; template <class Epi>
; DI void gemm_phase(LAS unsigned char* lds, const Gemm g, const StaticOrder& S, const Epi& E) {
;     ...
;             PG8_BAR; PG8_WAIT_L(0); PG8_MMA(1, 0, At, B0); PG8_BAR; PG8_SCHED;
;             PG8_STAGE(PG8_SB(1, 1), b3 + hstep);
;             PG8_WAIT_V(6); PG8_BAR; PG8_MMA(1, 1, At, B1); PG8_BAR;
;     template <bool LN, int BJ, int LO, int HI> DI void batch(const f32x4 (&acc)[2][2][4][2], unsigned row0, unsigned col0, const f32x4 (&gv)[2], const f32x4 (&bv)[2]) const {
;         f32x4 r[HI - LO]; float mean[(HI - LO) / 2], rstd[(HI - LO) / 2];
; #pragma unroll
;         for (int i = LO; i < HI; ++i) { const int ai = i >> 3, m = (i >> 1) & 3, n = i & 1; const unsigned row = row0 + ai * HALF + m * 16;
;             if (n == 0) { mean[(i - LO) >> 1] = 0.f; rstd[(i - LO) >> 1] = 1.f;
;                 if (LN) { const float2 st = *(const float2*)(stats + row * 2u); mean[(i - LO) >> 1] = st.x; rstd[(i - LO) >> 1] = st.y; } }
;             r[i - LO] = *(const f32x4*)(src + (row * (unsigned)DM + col0 + BJ * HALF + n * 16)); }
; #pragma unroll
;         for (int i = LO; i < HI; ++i) { const int ai = i >> 3, m = (i >> 1) & 3, n = i & 1; const unsigned row = row0 + ai * HALF + m * 16;
;             *(f32x4*)(Y + (row * (unsigned)DM + col0 + BJ * HALF + n * 16)) = acc[ai][BJ][m][n] + ((r[i - LO] - mean[(i - LO) >> 1]) * rstd[(i - LO) >> 1]) * gv[n] + bv[n]; }
;         __builtin_amdgcn_sched_barrier(0);
;     }
;     template <bool LN, int BJ> DI void load_gb(unsigned col0, f32x4 (&gv)[2], f32x4 (&bv)[2]) const {
; #pragma unroll
;         for (int n = 0; n < 2; ++n) {
;             if (LN) { gv[n] = *(const f32x4*)(gam + col0 + BJ * HALF + n * 16) * ALPHA; bv[n] = *(const f32x4*)(bet + col0 + BJ * HALF + n * 16) * ALPHA; }
;             else { gv[n] = (f32x4){ALPHA, ALPHA, ALPHA, ALPHA}; bv[n] = (f32x4){0.f, 0.f, 0.f, 0.f}; }
;         }
;     }
;     template <bool LN> DI void run(const f32x4 (&acc)[2][2][4][2], const Unit& u, int wr, int wc, int fr, int fq) const {
;         const unsigned row0 = u.pm * BM + wr * 64 + fr, col0 = u.pn * BM + wc * 32 + 4 * fq;
;         f32x4 gv[2], bv[2];
;         load_gb<LN, 0>(col0, gv, bv);
;         batch<LN, 0, 0, 4>(acc, row0, col0, gv, bv);
;         batch<LN, 0, 4, 8>(acc, row0, col0, gv, bv);
;         batch<LN, 0, 8, 12>(acc, row0, col0, gv, bv);
	v_mfma_f32_16x16x32_bf16 v[92:95], v[96:99], v[152:155], v[92:95]
	v_mfma_f32_16x16x32_bf16 v[88:91], v[136:139], v[152:155], v[88:91]
	v_mfma_f32_16x16x32_bf16 v[84:87], v[96:99], v[190:193], v[84:87]
	v_mfma_f32_16x16x32_bf16 v[80:83], v[136:139], v[190:193], v[80:83]
	v_mfma_f32_16x16x32_bf16 v[76:79], v[96:99], v[202:205], v[76:79]
	v_mfma_f32_16x16x32_bf16 v[72:75], v[136:139], v[202:205], v[72:75]
	v_mfma_f32_16x16x32_bf16 v[68:71], v[96:99], v[210:213], v[68:71]
	v_mfma_f32_16x16x32_bf16 v[64:67], v[136:139], v[210:213], v[64:67]
	v_mfma_f32_16x16x32_bf16 v[92:95], v[100:103], v[186:189], v[92:95]
	v_mfma_f32_16x16x32_bf16 v[88:91], v[148:151], v[186:189], v[88:91]
	v_mfma_f32_16x16x32_bf16 v[84:87], v[100:103], v[194:197], v[84:87]
	v_mfma_f32_16x16x32_bf16 v[80:83], v[148:151], v[194:197], v[80:83]
	v_mfma_f32_16x16x32_bf16 v[76:79], v[100:103], v[206:209], v[76:79]
	v_mfma_f32_16x16x32_bf16 v[72:75], v[148:151], v[206:209], v[72:75]
	v_mfma_f32_16x16x32_bf16 v[68:71], v[100:103], v[214:217], v[68:71]
	s_setprio 0
	v_mfma_f32_16x16x32_bf16 v[64:67], v[148:151], v[214:217], v[64:67]
	s_barrier
	s_add_u32 s16, s20, 0x160080
	s_addc_u32 s17, s21, 0
	s_add_i32 s20, s22, s27
	s_mov_b32 m0, s20
	s_nop 0
	global_load_lds_dwordx4 v142, s[16:17]
	s_add_i32 m0, s20, 0x2000
	s_nop 0
	global_load_lds_dwordx4 v140, s[16:17]
	s_waitcnt vmcnt(6)
	s_setprio 1
	s_barrier
	v_mfma_f32_16x16x32_bf16 v[28:31], v[226:229], v[152:155], v[28:31]
	v_mfma_f32_16x16x32_bf16 v[24:27], v[234:237], v[152:155], v[24:27]
	v_mfma_f32_16x16x32_bf16 v[20:23], v[226:229], v[190:193], v[20:23]
	v_mfma_f32_16x16x32_bf16 v[16:19], v[234:237], v[190:193], v[16:19]
	v_mfma_f32_16x16x32_bf16 v[12:15], v[226:229], v[202:205], v[12:15]
	v_mfma_f32_16x16x32_bf16 v[8:11], v[234:237], v[202:205], v[8:11]
	v_mfma_f32_16x16x32_bf16 v[4:7], v[226:229], v[210:213], v[4:7]
	v_mfma_f32_16x16x32_bf16 v[0:3], v[234:237], v[210:213], v[0:3]
	v_mfma_f32_16x16x32_bf16 v[28:31], v[230:233], v[186:189], v[28:31]
	s_add_i32 s33, s33, 2
	v_mfma_f32_16x16x32_bf16 v[24:27], v[238:241], v[186:189], v[24:27]
	s_add_u32 s4, s4, 0x100
	v_mfma_f32_16x16x32_bf16 v[20:23], v[230:233], v[194:197], v[20:23]
	s_addc_u32 s5, s5, 0
	v_mfma_f32_16x16x32_bf16 v[16:19], v[238:241], v[194:197], v[16:19]
	s_cmpk_gt_u32 s33, 0x55
	v_mfma_f32_16x16x32_bf16 v[12:15], v[230:233], v[206:209], v[12:15]
	s_mov_b64 s[16:17], s[18:19]
	v_mfma_f32_16x16x32_bf16 v[8:11], v[238:241], v[206:209], v[8:11]
	v_mfma_f32_16x16x32_bf16 v[4:7], v[230:233], v[214:217], v[4:7]
	s_setprio 0
	v_mfma_f32_16x16x32_bf16 v[0:3], v[238:241], v[214:217], v[0:3]
	s_barrier
	s_cbranch_scc0 .LBB0_134
	v_lshl_or_b32 v158, s2, 8, v200
	v_lshlrev_b64 v[100:101], 2, v[158:159]
	v_lshl_add_u64 v[150:151], s[12:13], 0, v[100:101]
	global_load_dwordx4 v[96:99], v[150:151], off
	v_lshl_add_u64 v[152:153], s[14:15], 0, v[100:101]
	v_lshl_add_u32 v203, s3, 8, v198
	v_lshlrev_b32_e32 v202, 11, v203
	v_add_u32_e32 v148, v202, v158
	v_mov_b32_e32 v149, v159
	v_lshlrev_b32_e32 v136, 1, v203
	v_mov_b32_e32 v137, v159
	v_lshlrev_b64 v[220:221], 2, v[148:149]
	v_lshl_add_u64 v[154:155], v[136:137], 2, s[96:97]
	v_lshl_add_u64 v[136:137], s[90:91], 0, v[220:221]
	v_or_b32_e32 v204, 16, v158
	v_or_b32_e32 v138, 16, v203
	v_lshlrev_b32_e32 v149, 11, v138
	s_waitcnt vmcnt(0)
	v_pk_mul_f32 v[192:193], v[98:99], s[78:79] op_sel_hi:[1,0]
	v_pk_mul_f32 v[194:195], v[96:97], s[78:79] op_sel_hi:[1,0]
	global_load_dwordx4 v[100:103], v[152:153], off
	global_load_dwordx4 v[96:99], v[150:151], off offset:64
	global_load_dwordx2 v[218:219], v[154:155], off
	global_load_dwordx4 v[206:209], v[136:137], off
	v_add_u32_e32 v136, v202, v204
	v_mov_b32_e32 v137, v159
	v_lshl_add_u64 v[136:137], v[136:137], 2, s[90:91]
	global_load_dwordx4 v[210:213], v[136:137], off
	v_lshlrev_b32_e32 v136, 1, v138
	v_mov_b32_e32 v137, v159
	v_lshl_add_u64 v[186:187], v[136:137], 2, s[96:97]
	v_add_u32_e32 v136, v149, v158
	v_lshl_add_u64 v[136:137], v[136:137], 2, s[90:91]
	global_load_dwordx2 v[196:197], v[186:187], off
	global_load_dwordx4 v[214:217], v[136:137], off
	v_add_u32_e32 v136, v149, v204
	v_mov_b32_e32 v137, v159
	v_lshl_add_u64 v[136:137], v[136:137], 2, s[90:91]
	global_load_dwordx4 v[136:139], v[136:137], off
	s_waitcnt vmcnt(0)
	v_pk_mul_f32 v[188:189], v[98:99], s[78:79] op_sel_hi:[1,0]
	v_pk_mul_f32 v[190:191], v[96:97], s[78:79] op_sel_hi:[1,0]
	global_load_dwordx4 v[96:99], v[152:153], off offset:64
	v_sub_f32_e32 v207, v207, v218
	v_sub_f32_e32 v206, v206, v218
	v_sub_f32_e32 v209, v209, v218
	v_sub_f32_e32 v208, v208, v218
	v_pk_mul_f32 v[208:209], v[218:219], v[208:209] op_sel:[1,0]
	v_pk_mul_f32 v[206:207], v[218:219], v[206:207] op_sel:[1,0]
	v_pk_fma_f32 v[134:135], v[192:193], v[208:209], v[134:135]
	v_pk_fma_f32 v[132:133], v[194:195], v[206:207], v[132:133]
	v_pk_fma_f32 v[134:135], v[102:103], s[78:79], v[134:135] op_sel_hi:[1,0,1]
	v_pk_fma_f32 v[132:133], v[100:101], s[78:79], v[132:133] op_sel_hi:[1,0,1]
	v_lshl_add_u64 v[206:207], s[88:89], 0, v[220:221]
	global_store_dwordx4 v[206:207], v[132:135], off
	s_nop 1
	v_sub_f32_e32 v133, v211, v218
	v_sub_f32_e32 v132, v210, v218
	v_sub_f32_e32 v135, v213, v218
	v_sub_f32_e32 v134, v212, v218
	v_pk_mul_f32 v[134:135], v[218:219], v[134:135] op_sel:[1,0]
	v_pk_mul_f32 v[132:133], v[218:219], v[132:133] op_sel:[1,0]
	v_pk_fma_f32 v[130:131], v[188:189], v[134:135], v[130:131]
	v_pk_fma_f32 v[128:129], v[190:191], v[132:133], v[128:129]
	v_or_b32_e32 v132, 16, v148
	v_mov_b32_e32 v133, v159
	v_lshl_add_u64 v[132:133], v[132:133], 2, s[88:89]
	s_waitcnt vmcnt(0)
;     template <bool LN, int BJ, int LO, int HI> DI void batch(const f32x4 (&acc)[2][2][4][2], unsigned row0, unsigned col0, const f32x4 (&gv)[2], const f32x4 (&bv)[2]) const {
;         f32x4 r[HI - LO]; float mean[(HI - LO) / 2], rstd[(HI - LO) / 2];
; #pragma unroll
;         for (int i = LO; i < HI; ++i) { const int ai = i >> 3, m = (i >> 1) & 3, n = i & 1; const unsigned row = row0 + ai * HALF + m * 16;
;             if (n == 0) { mean[(i - LO) >> 1] = 0.f; rstd[(i - LO) >> 1] = 1.f;
;                 if (LN) { const float2 st = *(const float2*)(stats + row * 2u); mean[(i - LO) >> 1] = st.x; rstd[(i - LO) >> 1] = st.y; } }
;             r[i - LO] = *(const f32x4*)(src + (row * (unsigned)DM + col0 + BJ * HALF + n * 16)); }
; #pragma unroll
;         for (int i = LO; i < HI; ++i) { const int ai = i >> 3, m = (i >> 1) & 3, n = i & 1; const unsigned row = row0 + ai * HALF + m * 16;
;             *(f32x4*)(Y + (row * (unsigned)DM + col0 + BJ * HALF + n * 16)) = acc[ai][BJ][m][n] + ((r[i - LO] - mean[(i - LO) >> 1]) * rstd[(i - LO) >> 1]) * gv[n] + bv[n]; }
;         __builtin_amdgcn_sched_barrier(0);
;     }
;     template <bool LN, int BJ> DI void load_gb(unsigned col0, f32x4 (&gv)[2], f32x4 (&bv)[2]) const {
; #pragma unroll
;         for (int n = 0; n < 2; ++n) {
;             if (LN) { gv[n] = *(const f32x4*)(gam + col0 + BJ * HALF + n * 16) * ALPHA; bv[n] = *(const f32x4*)(bet + col0 + BJ * HALF + n * 16) * ALPHA; }
;             else { gv[n] = (f32x4){ALPHA, ALPHA, ALPHA, ALPHA}; bv[n] = (f32x4){0.f, 0.f, 0.f, 0.f}; }
;         }
;     }
;     template <bool LN> DI void run(const f32x4 (&acc)[2][2][4][2], const Unit& u, int wr, int wc, int fr, int fq) const {
;         const unsigned row0 = u.pm * BM + wr * 64 + fr, col0 = u.pn * BM + wc * 32 + 4 * fq;
;         f32x4 gv[2], bv[2];
;         load_gb<LN, 0>(col0, gv, bv);
;         batch<LN, 0, 0, 4>(acc, row0, col0, gv, bv);
;         batch<LN, 0, 4, 8>(acc, row0, col0, gv, bv);
;         batch<LN, 0, 8, 12>(acc, row0, col0, gv, bv);
;         batch<LN, 0, 12, 16>(acc, row0, col0, gv, bv);
;         load_gb<LN, 1>(col0, gv, bv);
;         batch<LN, 1, 0, 8>(acc, row0, col0, gv, bv);
;         batch<LN, 1, 8, 16>(acc, row0, col0, gv, bv);
	v_pk_fma_f32 v[130:131], v[98:99], s[78:79], v[130:131] op_sel_hi:[1,0,1]
	v_pk_fma_f32 v[128:129], v[96:97], s[78:79], v[128:129] op_sel_hi:[1,0,1]
	global_store_dwordx4 v[132:133], v[128:131], off
	s_nop 1
	v_sub_f32_e32 v129, v215, v196
	v_sub_f32_e32 v128, v214, v196
	v_sub_f32_e32 v131, v217, v196
	v_sub_f32_e32 v130, v216, v196
	v_pk_mul_f32 v[130:131], v[196:197], v[130:131] op_sel:[1,0]
	v_pk_mul_f32 v[128:129], v[196:197], v[128:129] op_sel:[1,0]
	v_pk_fma_f32 v[126:127], v[192:193], v[130:131], v[126:127]
	v_pk_fma_f32 v[124:125], v[194:195], v[128:129], v[124:125]
	v_add_u32_e32 v128, 0x8000, v148
	v_mov_b32_e32 v129, v159
	v_pk_fma_f32 v[126:127], v[102:103], s[78:79], v[126:127] op_sel_hi:[1,0,1]
	v_pk_fma_f32 v[124:125], v[100:101], s[78:79], v[124:125] op_sel_hi:[1,0,1]
	v_lshl_add_u64 v[128:129], v[128:129], 2, s[88:89]
	global_store_dwordx4 v[128:129], v[124:127], off
	s_nop 1
	v_sub_f32_e32 v125, v137, v196
	v_sub_f32_e32 v124, v136, v196
	v_sub_f32_e32 v127, v139, v196
	v_sub_f32_e32 v126, v138, v196
	v_pk_mul_f32 v[126:127], v[196:197], v[126:127] op_sel:[1,0]
	v_pk_mul_f32 v[124:125], v[196:197], v[124:125] op_sel:[1,0]
	v_pk_fma_f32 v[122:123], v[188:189], v[126:127], v[122:123]
	v_pk_fma_f32 v[120:121], v[190:191], v[124:125], v[120:121]
	v_add_u32_e32 v124, 0x8010, v148
	v_mov_b32_e32 v125, v159
	v_pk_fma_f32 v[122:123], v[98:99], s[78:79], v[122:123] op_sel_hi:[1,0,1]
	v_pk_fma_f32 v[120:121], v[96:97], s[78:79], v[120:121] op_sel_hi:[1,0,1]
	v_lshl_add_u64 v[124:125], v[124:125], 2, s[88:89]
	global_store_dwordx4 v[124:125], v[120:123], off
	s_nop 1
	v_or_b32_e32 v122, 32, v203
	v_lshlrev_b32_e32 v124, 11, v122
	v_lshlrev_b32_e32 v120, 1, v122
	v_mov_b32_e32 v121, v159
	v_add_u32_e32 v122, v124, v158
	v_mov_b32_e32 v123, v159
	v_lshl_add_u64 v[120:121], v[120:121], 2, s[96:97]
	v_lshl_add_u64 v[122:123], v[122:123], 2, s[90:91]
	global_load_dwordx2 v[138:139], v[120:121], off
	global_load_dwordx4 v[126:129], v[122:123], off
	v_add_u32_e32 v122, v124, v204
	v_mov_b32_e32 v123, v159
	v_lshl_add_u64 v[122:123], v[122:123], 2, s[90:91]
	global_load_dwordx4 v[130:133], v[122:123], off
	v_or_b32_e32 v125, 48, v203
	v_lshlrev_b32_e32 v122, 1, v125
	v_lshlrev_b32_e32 v125, 11, v125
	v_mov_b32_e32 v123, v159
	v_add_u32_e32 v134, v125, v158
	v_mov_b32_e32 v135, v159
	v_lshl_add_u64 v[122:123], v[122:123], 2, s[96:97]
	v_lshl_add_u64 v[134:135], v[134:135], 2, s[90:91]
	global_load_dwordx2 v[196:197], v[122:123], off
	v_add_u32_e32 v206, v125, v204
	global_load_dwordx4 v[134:137], v[134:135], off
	v_mov_b32_e32 v207, v159
	v_lshl_add_u64 v[206:207], v[206:207], 2, s[90:91]
	global_load_dwordx4 v[206:209], v[206:207], off
	s_waitcnt vmcnt(0)
	v_sub_f32_e32 v127, v127, v138
	v_sub_f32_e32 v126, v126, v138
	v_sub_f32_e32 v129, v129, v138
	v_sub_f32_e32 v128, v128, v138
	v_pk_mul_f32 v[128:129], v[138:139], v[128:129] op_sel:[1,0]
	v_pk_mul_f32 v[126:127], v[138:139], v[126:127] op_sel:[1,0]
	v_pk_fma_f32 v[118:119], v[192:193], v[128:129], v[118:119]
	v_pk_fma_f32 v[116:117], v[194:195], v[126:127], v[116:117]
	v_add_u32_e32 v126, 0x10000, v148
	v_mov_b32_e32 v127, v159
	v_pk_fma_f32 v[118:119], v[102:103], s[78:79], v[118:119] op_sel_hi:[1,0,1]
	v_pk_fma_f32 v[116:117], v[100:101], s[78:79], v[116:117] op_sel_hi:[1,0,1]
	v_lshl_add_u64 v[126:127], v[126:127], 2, s[88:89]
	global_store_dwordx4 v[126:127], v[116:119], off
	s_nop 1
	v_sub_f32_e32 v117, v131, v138
	v_sub_f32_e32 v116, v130, v138
	v_sub_f32_e32 v119, v133, v138
	v_sub_f32_e32 v118, v132, v138
	v_pk_mul_f32 v[118:119], v[138:139], v[118:119] op_sel:[1,0]
	v_pk_mul_f32 v[116:117], v[138:139], v[116:117] op_sel:[1,0]
	v_pk_fma_f32 v[114:115], v[188:189], v[118:119], v[114:115]
	v_pk_fma_f32 v[112:113], v[190:191], v[116:117], v[112:113]
	v_add_u32_e32 v116, 0x10010, v148
	v_mov_b32_e32 v117, v159
	v_pk_fma_f32 v[114:115], v[98:99], s[78:79], v[114:115] op_sel_hi:[1,0,1]
	v_pk_fma_f32 v[112:113], v[96:97], s[78:79], v[112:113] op_sel_hi:[1,0,1]
	v_lshl_add_u64 v[116:117], v[116:117], 2, s[88:89]
	global_store_dwordx4 v[116:117], v[112:115], off
	s_nop 1
	v_sub_f32_e32 v113, v135, v196
	v_sub_f32_e32 v112, v134, v196
	v_sub_f32_e32 v115, v137, v196
	v_sub_f32_e32 v114, v136, v196
	v_pk_mul_f32 v[114:115], v[196:197], v[114:115] op_sel:[1,0]
	v_pk_mul_f32 v[112:113], v[196:197], v[112:113] op_sel:[1,0]
	v_pk_fma_f32 v[110:111], v[192:193], v[114:115], v[110:111]
	v_pk_fma_f32 v[108:109], v[194:195], v[112:113], v[108:109]
	v_add_u32_e32 v112, 0x18000, v148
	v_mov_b32_e32 v113, v159
	v_pk_fma_f32 v[110:111], v[102:103], s[78:79], v[110:111] op_sel_hi:[1,0,1]
	v_pk_fma_f32 v[108:109], v[100:101], s[78:79], v[108:109] op_sel_hi:[1,0,1]
	v_lshl_add_u64 v[112:113], v[112:113], 2, s[88:89]
	global_store_dwordx4 v[112:113], v[108:111], off
	s_nop 1
	v_sub_f32_e32 v109, v207, v196
	v_sub_f32_e32 v108, v206, v196
	v_sub_f32_e32 v111, v209, v196
	v_sub_f32_e32 v110, v208, v196
	v_pk_mul_f32 v[110:111], v[196:197], v[110:111] op_sel:[1,0]
	v_pk_mul_f32 v[108:109], v[196:197], v[108:109] op_sel:[1,0]
	v_pk_fma_f32 v[106:107], v[188:189], v[110:111], v[106:107]
	v_pk_fma_f32 v[104:105], v[190:191], v[108:109], v[104:105]
	v_add_u32_e32 v108, 0x18010, v148
	v_mov_b32_e32 v109, v159
	v_pk_fma_f32 v[106:107], v[98:99], s[78:79], v[106:107] op_sel_hi:[1,0,1]
	v_pk_fma_f32 v[104:105], v[96:97], s[78:79], v[104:105] op_sel_hi:[1,0,1]
	v_lshl_add_u64 v[108:109], v[108:109], 2, s[88:89]
	global_store_dwordx4 v[108:109], v[104:107], off
	s_nop 1
	v_add_u32_e32 v106, 0x80, v203
	v_lshlrev_b32_e32 v114, 11, v106
	v_lshlrev_b32_e32 v104, 1, v106
	v_mov_b32_e32 v105, v159
	v_add_u32_e32 v106, v114, v158
	v_mov_b32_e32 v107, v159
	v_lshl_add_u64 v[104:105], v[104:105], 2, s[96:97]
	v_lshl_add_u64 v[106:107], v[106:107], 2, s[90:91]
	global_load_dwordx2 v[112:113], v[104:105], off
	global_load_dwordx4 v[108:111], v[106:107], off
	v_add_u32_e32 v106, v114, v204
	v_mov_b32_e32 v107, v159
	v_lshl_add_u64 v[106:107], v[106:107], 2, s[90:91]
	global_load_dwordx4 v[116:119], v[106:107], off
	v_add_u32_e32 v115, 0x90, v203
	v_lshlrev_b32_e32 v106, 1, v115
	v_lshlrev_b32_e32 v115, 11, v115
	v_mov_b32_e32 v107, v159
	v_add_u32_e32 v126, v115, v158
	v_mov_b32_e32 v127, v159
	v_lshl_add_u64 v[106:107], v[106:107], 2, s[96:97]
	v_lshl_add_u64 v[126:127], v[126:127], 2, s[90:91]
	global_load_dwordx2 v[134:135], v[106:107], off
	v_add_u32_e32 v130, v115, v204
	global_load_dwordx4 v[126:129], v[126:127], off
	v_mov_b32_e32 v131, v159
	v_lshl_add_u64 v[130:131], v[130:131], 2, s[90:91]
	global_load_dwordx4 v[130:133], v[130:131], off
	s_waitcnt vmcnt(0)
;     template <bool LN, int BJ, int LO, int HI> DI void batch(const f32x4 (&acc)[2][2][4][2], unsigned row0, unsigned col0, const f32x4 (&gv)[2], const f32x4 (&bv)[2]) const {
;         f32x4 r[HI - LO]; float mean[(HI - LO) / 2], rstd[(HI - LO) / 2];
; #pragma unroll
;         for (int i = LO; i < HI; ++i) { const int ai = i >> 3, m = (i >> 1) & 3, n = i & 1; const unsigned row = row0 + ai * HALF + m * 16;
;             if (n == 0) { mean[(i - LO) >> 1] = 0.f; rstd[(i - LO) >> 1] = 1.f;
;                 if (LN) { const float2 st = *(const float2*)(stats + row * 2u); mean[(i - LO) >> 1] = st.x; rstd[(i - LO) >> 1] = st.y; } }
;             r[i - LO] = *(const f32x4*)(src + (row * (unsigned)DM + col0 + BJ * HALF + n * 16)); }
; #pragma unroll
;         for (int i = LO; i < HI; ++i) { const int ai = i >> 3, m = (i >> 1) & 3, n = i & 1; const unsigned row = row0 + ai * HALF + m * 16;
;             *(f32x4*)(Y + (row * (unsigned)DM + col0 + BJ * HALF + n * 16)) = acc[ai][BJ][m][n] + ((r[i - LO] - mean[(i - LO) >> 1]) * rstd[(i - LO) >> 1]) * gv[n] + bv[n]; }
;         __builtin_amdgcn_sched_barrier(0);
;     }
;     template <bool LN, int BJ> DI void load_gb(unsigned col0, f32x4 (&gv)[2], f32x4 (&bv)[2]) const {
; #pragma unroll
;         for (int n = 0; n < 2; ++n) {
;             if (LN) { gv[n] = *(const f32x4*)(gam + col0 + BJ * HALF + n * 16) * ALPHA; bv[n] = *(const f32x4*)(bet + col0 + BJ * HALF + n * 16) * ALPHA; }
;             else { gv[n] = (f32x4){ALPHA, ALPHA, ALPHA, ALPHA}; bv[n] = (f32x4){0.f, 0.f, 0.f, 0.f}; }
;         }
;     }
;     template <bool LN> DI void run(const f32x4 (&acc)[2][2][4][2], const Unit& u, int wr, int wc, int fr, int fq) const {
;         const unsigned row0 = u.pm * BM + wr * 64 + fr, col0 = u.pn * BM + wc * 32 + 4 * fq;
;         f32x4 gv[2], bv[2];
;         load_gb<LN, 0>(col0, gv, bv);
;         batch<LN, 0, 0, 4>(acc, row0, col0, gv, bv);
;         batch<LN, 0, 4, 8>(acc, row0, col0, gv, bv);
;         batch<LN, 0, 8, 12>(acc, row0, col0, gv, bv);
;         batch<LN, 0, 12, 16>(acc, row0, col0, gv, bv);
;         load_gb<LN, 1>(col0, gv, bv);
;         batch<LN, 1, 0, 8>(acc, row0, col0, gv, bv);
;         batch<LN, 1, 8, 16>(acc, row0, col0, gv, bv);
	v_sub_f32_e32 v109, v109, v112
	v_sub_f32_e32 v108, v108, v112
	v_sub_f32_e32 v111, v111, v112
	v_sub_f32_e32 v110, v110, v112
	v_pk_mul_f32 v[110:111], v[112:113], v[110:111] op_sel:[1,0]
	v_pk_mul_f32 v[108:109], v[112:113], v[108:109] op_sel:[1,0]
	v_pk_fma_f32 v[94:95], v[192:193], v[110:111], v[94:95]
	v_pk_fma_f32 v[92:93], v[194:195], v[108:109], v[92:93]
	v_add_u32_e32 v108, 0x40000, v148
	v_mov_b32_e32 v109, v159
	v_pk_fma_f32 v[94:95], v[102:103], s[78:79], v[94:95] op_sel_hi:[1,0,1]
	v_pk_fma_f32 v[92:93], v[100:101], s[78:79], v[92:93] op_sel_hi:[1,0,1]
	v_lshl_add_u64 v[108:109], v[108:109], 2, s[88:89]
	global_store_dwordx4 v[108:109], v[92:95], off
	s_nop 1
	v_sub_f32_e32 v93, v117, v112
	v_sub_f32_e32 v92, v116, v112
	v_sub_f32_e32 v95, v119, v112
	v_sub_f32_e32 v94, v118, v112
	v_pk_mul_f32 v[94:95], v[112:113], v[94:95] op_sel:[1,0]
	v_pk_mul_f32 v[92:93], v[112:113], v[92:93] op_sel:[1,0]
	v_pk_fma_f32 v[90:91], v[188:189], v[94:95], v[90:91]
	v_pk_fma_f32 v[88:89], v[190:191], v[92:93], v[88:89]
	v_add_u32_e32 v92, 0x40010, v148
	v_mov_b32_e32 v93, v159
	v_pk_fma_f32 v[90:91], v[98:99], s[78:79], v[90:91] op_sel_hi:[1,0,1]
	v_pk_fma_f32 v[88:89], v[96:97], s[78:79], v[88:89] op_sel_hi:[1,0,1]
	v_lshl_add_u64 v[92:93], v[92:93], 2, s[88:89]
	global_store_dwordx4 v[92:93], v[88:91], off
	s_nop 1
	v_sub_f32_e32 v89, v127, v134
	v_sub_f32_e32 v88, v126, v134
	v_sub_f32_e32 v91, v129, v134
	v_sub_f32_e32 v90, v128, v134
	v_pk_mul_f32 v[90:91], v[134:135], v[90:91] op_sel:[1,0]
	v_pk_mul_f32 v[88:89], v[134:135], v[88:89] op_sel:[1,0]
	v_pk_fma_f32 v[86:87], v[192:193], v[90:91], v[86:87]
	v_pk_fma_f32 v[84:85], v[194:195], v[88:89], v[84:85]
	v_add_u32_e32 v88, 0x48000, v148
	v_mov_b32_e32 v89, v159
	v_pk_fma_f32 v[86:87], v[102:103], s[78:79], v[86:87] op_sel_hi:[1,0,1]
	v_pk_fma_f32 v[84:85], v[100:101], s[78:79], v[84:85] op_sel_hi:[1,0,1]
	v_lshl_add_u64 v[88:89], v[88:89], 2, s[88:89]
	global_store_dwordx4 v[88:89], v[84:87], off
	s_nop 1
	v_sub_f32_e32 v85, v131, v134
	v_sub_f32_e32 v84, v130, v134
	v_sub_f32_e32 v87, v133, v134
	v_sub_f32_e32 v86, v132, v134
	v_pk_mul_f32 v[86:87], v[134:135], v[86:87] op_sel:[1,0]
	v_pk_mul_f32 v[84:85], v[134:135], v[84:85] op_sel:[1,0]
	v_pk_fma_f32 v[82:83], v[188:189], v[86:87], v[82:83]
	v_pk_fma_f32 v[80:81], v[190:191], v[84:85], v[80:81]
	v_add_u32_e32 v84, 0x48010, v148
	v_mov_b32_e32 v85, v159
	v_pk_fma_f32 v[82:83], v[98:99], s[78:79], v[82:83] op_sel_hi:[1,0,1]
	v_pk_fma_f32 v[80:81], v[96:97], s[78:79], v[80:81] op_sel_hi:[1,0,1]
	v_lshl_add_u64 v[84:85], v[84:85], 2, s[88:89]
	global_store_dwordx4 v[84:85], v[80:83], off
	s_nop 1
	v_add_u32_e32 v82, 0xa0, v203
	v_lshlrev_b32_e32 v80, 1, v82
	v_mov_b32_e32 v81, v159
	v_lshlrev_b32_e32 v116, 11, v82
	v_lshl_add_u64 v[108:109], v[80:81], 2, s[96:97]
	v_add_u32_e32 v80, v116, v158
	v_lshl_add_u64 v[80:81], v[80:81], 2, s[90:91]
	global_load_dwordx2 v[112:113], v[108:109], off
	v_add_u32_e32 v84, v116, v204
	global_load_dwordx4 v[80:83], v[80:81], off
	v_mov_b32_e32 v85, v159
	v_lshl_add_u64 v[84:85], v[84:85], 2, s[90:91]
	global_load_dwordx4 v[84:87], v[84:85], off
	v_add_u32_e32 v90, 0xb0, v203
	v_lshlrev_b32_e32 v88, 1, v90
	v_mov_b32_e32 v89, v159
	v_lshlrev_b32_e32 v117, 11, v90
	v_lshl_add_u64 v[110:111], v[88:89], 2, s[96:97]
	v_add_u32_e32 v88, v117, v158
	v_lshl_add_u64 v[88:89], v[88:89], 2, s[90:91]
	global_load_dwordx2 v[118:119], v[110:111], off
	v_add_u32_e32 v92, v117, v204
	global_load_dwordx4 v[88:91], v[88:89], off
	v_mov_b32_e32 v93, v159
	v_lshl_add_u64 v[92:93], v[92:93], 2, s[90:91]
	global_load_dwordx4 v[92:95], v[92:93], off
	s_waitcnt vmcnt(0)
	v_sub_f32_e32 v81, v81, v112
	v_sub_f32_e32 v80, v80, v112
	v_sub_f32_e32 v83, v83, v112
	v_sub_f32_e32 v82, v82, v112
	v_pk_mul_f32 v[82:83], v[112:113], v[82:83] op_sel:[1,0]
	v_pk_mul_f32 v[80:81], v[112:113], v[80:81] op_sel:[1,0]
	v_pk_fma_f32 v[78:79], v[192:193], v[82:83], v[78:79]
	v_pk_fma_f32 v[76:77], v[194:195], v[80:81], v[76:77]
	v_add_u32_e32 v80, 0x50000, v148
	v_mov_b32_e32 v81, v159
	v_pk_fma_f32 v[78:79], v[102:103], s[78:79], v[78:79] op_sel_hi:[1,0,1]
	v_pk_fma_f32 v[76:77], v[100:101], s[78:79], v[76:77] op_sel_hi:[1,0,1]
	v_lshl_add_u64 v[80:81], v[80:81], 2, s[88:89]
	global_store_dwordx4 v[80:81], v[76:79], off
	s_nop 1
	v_sub_f32_e32 v77, v85, v112
	v_sub_f32_e32 v76, v84, v112
	v_sub_f32_e32 v79, v87, v112
	v_sub_f32_e32 v78, v86, v112
	v_pk_mul_f32 v[78:79], v[112:113], v[78:79] op_sel:[1,0]
	v_pk_mul_f32 v[76:77], v[112:113], v[76:77] op_sel:[1,0]
	v_pk_fma_f32 v[74:75], v[188:189], v[78:79], v[74:75]
	v_pk_fma_f32 v[72:73], v[190:191], v[76:77], v[72:73]
	v_add_u32_e32 v76, 0x50010, v148
	v_mov_b32_e32 v77, v159
	v_pk_fma_f32 v[74:75], v[98:99], s[78:79], v[74:75] op_sel_hi:[1,0,1]
	v_pk_fma_f32 v[72:73], v[96:97], s[78:79], v[72:73] op_sel_hi:[1,0,1]
	v_lshl_add_u64 v[76:77], v[76:77], 2, s[88:89]
	global_store_dwordx4 v[76:77], v[72:75], off
	s_nop 1
	v_sub_f32_e32 v73, v89, v118
	v_sub_f32_e32 v72, v88, v118
	v_sub_f32_e32 v75, v91, v118
	v_sub_f32_e32 v74, v90, v118
	v_pk_mul_f32 v[74:75], v[118:119], v[74:75] op_sel:[1,0]
	v_pk_mul_f32 v[72:73], v[118:119], v[72:73] op_sel:[1,0]
	v_pk_fma_f32 v[70:71], v[192:193], v[74:75], v[70:71]
	v_pk_fma_f32 v[68:69], v[194:195], v[72:73], v[68:69]
	v_add_u32_e32 v72, 0x58000, v148
	v_mov_b32_e32 v73, v159
	v_pk_fma_f32 v[70:71], v[102:103], s[78:79], v[70:71] op_sel_hi:[1,0,1]
	v_pk_fma_f32 v[68:69], v[100:101], s[78:79], v[68:69] op_sel_hi:[1,0,1]
	v_lshl_add_u64 v[72:73], v[72:73], 2, s[88:89]
	global_store_dwordx4 v[72:73], v[68:71], off
	s_nop 1
	v_sub_f32_e32 v69, v93, v118
	v_sub_f32_e32 v68, v92, v118
	v_sub_f32_e32 v71, v95, v118
	v_sub_f32_e32 v70, v94, v118
	v_pk_mul_f32 v[70:71], v[118:119], v[70:71] op_sel:[1,0]
	v_pk_mul_f32 v[68:69], v[118:119], v[68:69] op_sel:[1,0]
	v_pk_fma_f32 v[66:67], v[188:189], v[70:71], v[66:67]
	v_pk_fma_f32 v[64:65], v[190:191], v[68:69], v[64:65]
	v_add_u32_e32 v68, 0x58010, v148
	v_mov_b32_e32 v69, v159
	v_pk_fma_f32 v[66:67], v[98:99], s[78:79], v[66:67] op_sel_hi:[1,0,1]
	v_pk_fma_f32 v[64:65], v[96:97], s[78:79], v[64:65] op_sel_hi:[1,0,1]
	v_lshl_add_u64 v[68:69], v[68:69], 2, s[88:89]
	global_store_dwordx4 v[68:69], v[64:67], off
	global_load_dwordx4 v[64:67], v[150:151], off offset:512
	v_or_b32_e32 v119, 0x80, v158
	v_add_u32_e32 v72, v202, v119
	v_mov_b32_e32 v73, v159
	v_lshl_add_u64 v[72:73], v[72:73], 2, s[90:91]
	v_or_b32_e32 v118, 0x90, v158
	v_add_u32_e32 v158, v202, v118
	s_waitcnt vmcnt(0)
;     template <bool LN, int BJ, int LO, int HI> DI void batch(const f32x4 (&acc)[2][2][4][2], unsigned row0, unsigned col0, const f32x4 (&gv)[2], const f32x4 (&bv)[2]) const {
;         f32x4 r[HI - LO]; float mean[(HI - LO) / 2], rstd[(HI - LO) / 2];
; #pragma unroll
;         for (int i = LO; i < HI; ++i) { const int ai = i >> 3, m = (i >> 1) & 3, n = i & 1; const unsigned row = row0 + ai * HALF + m * 16;
;             if (n == 0) { mean[(i - LO) >> 1] = 0.f; rstd[(i - LO) >> 1] = 1.f;
;                 if (LN) { const float2 st = *(const float2*)(stats + row * 2u); mean[(i - LO) >> 1] = st.x; rstd[(i - LO) >> 1] = st.y; } }
;             r[i - LO] = *(const f32x4*)(src + (row * (unsigned)DM + col0 + BJ * HALF + n * 16)); }
; #pragma unroll
;         for (int i = LO; i < HI; ++i) { const int ai = i >> 3, m = (i >> 1) & 3, n = i & 1; const unsigned row = row0 + ai * HALF + m * 16;
;             *(f32x4*)(Y + (row * (unsigned)DM + col0 + BJ * HALF + n * 16)) = acc[ai][BJ][m][n] + ((r[i - LO] - mean[(i - LO) >> 1]) * rstd[(i - LO) >> 1]) * gv[n] + bv[n]; }
;         __builtin_amdgcn_sched_barrier(0);
;     }
;     template <bool LN, int BJ> DI void load_gb(unsigned col0, f32x4 (&gv)[2], f32x4 (&bv)[2]) const {
; #pragma unroll
;         for (int n = 0; n < 2; ++n) {
;             if (LN) { gv[n] = *(const f32x4*)(gam + col0 + BJ * HALF + n * 16) * ALPHA; bv[n] = *(const f32x4*)(bet + col0 + BJ * HALF + n * 16) * ALPHA; }
;             else { gv[n] = (f32x4){ALPHA, ALPHA, ALPHA, ALPHA}; bv[n] = (f32x4){0.f, 0.f, 0.f, 0.f}; }
;         }
;     }
;     template <bool LN> DI void run(const f32x4 (&acc)[2][2][4][2], const Unit& u, int wr, int wc, int fr, int fq) const {
;         const unsigned row0 = u.pm * BM + wr * 64 + fr, col0 = u.pn * BM + wc * 32 + 4 * fq;
;         f32x4 gv[2], bv[2];
;         load_gb<LN, 0>(col0, gv, bv);
;         batch<LN, 0, 0, 4>(acc, row0, col0, gv, bv);
;         batch<LN, 0, 4, 8>(acc, row0, col0, gv, bv);
;         batch<LN, 0, 8, 12>(acc, row0, col0, gv, bv);
;         batch<LN, 0, 12, 16>(acc, row0, col0, gv, bv);
;         load_gb<LN, 1>(col0, gv, bv);
;         batch<LN, 1, 0, 8>(acc, row0, col0, gv, bv);
;         batch<LN, 1, 8, 16>(acc, row0, col0, gv, bv);
	v_pk_mul_f32 v[96:97], v[66:67], s[78:79] op_sel_hi:[1,0]
	v_pk_mul_f32 v[98:99], v[64:65], s[78:79] op_sel_hi:[1,0]
	global_load_dwordx4 v[68:71], v[152:153], off offset:512
	global_load_dwordx4 v[64:67], v[150:151], off offset:576
	global_load_dwordx2 v[138:139], v[154:155], off
	global_load_dwordx4 v[126:129], v[72:73], off
	v_lshl_add_u64 v[72:73], v[158:159], 2, s[90:91]
	v_add_u32_e32 v158, v149, v119
	s_waitcnt vmcnt(0)
	v_pk_mul_f32 v[92:93], v[66:67], s[78:79] op_sel_hi:[1,0]
	v_pk_mul_f32 v[94:95], v[64:65], s[78:79] op_sel_hi:[1,0]
	global_load_dwordx4 v[64:67], v[152:153], off offset:576
	global_load_dwordx4 v[130:133], v[72:73], off
	global_load_dwordx2 v[112:113], v[186:187], off
	v_lshl_add_u64 v[72:73], v[158:159], 2, s[90:91]
	global_load_dwordx4 v[134:137], v[72:73], off
	v_add_u32_e32 v158, v149, v118
	v_lshl_add_u64 v[72:73], v[158:159], 2, s[90:91]
	global_load_dwordx4 v[88:91], v[72:73], off
	global_load_dwordx2 v[102:103], v[120:121], off
	v_add_u32_e32 v158, v124, v119
	v_lshl_add_u64 v[72:73], v[158:159], 2, s[90:91]
	global_load_dwordx4 v[84:87], v[72:73], off
	v_add_u32_e32 v158, v124, v118
	v_lshl_add_u64 v[72:73], v[158:159], 2, s[90:91]
	global_load_dwordx4 v[80:83], v[72:73], off
	global_load_dwordx2 v[100:101], v[122:123], off
	v_add_u32_e32 v158, v125, v119
	v_lshl_add_u64 v[72:73], v[158:159], 2, s[90:91]
	global_load_dwordx4 v[76:79], v[72:73], off
	v_add_u32_e32 v158, v125, v118
	v_lshl_add_u64 v[72:73], v[158:159], 2, s[90:91]
	global_load_dwordx4 v[72:75], v[72:73], off
	v_sub_f32_e32 v121, v127, v138
	v_sub_f32_e32 v120, v126, v138
	v_sub_f32_e32 v123, v129, v138
	v_sub_f32_e32 v122, v128, v138
	v_pk_mul_f32 v[122:123], v[138:139], v[122:123] op_sel:[1,0]
	v_pk_mul_f32 v[120:121], v[138:139], v[120:121] op_sel:[1,0]
	v_or_b32_e32 v158, 0x80, v148
	v_pk_fma_f32 v[60:61], v[98:99], v[120:121], v[60:61]
	v_pk_fma_f32 v[62:63], v[96:97], v[122:123], v[62:63]
	v_pk_fma_f32 v[60:61], v[68:69], s[78:79], v[60:61] op_sel_hi:[1,0,1]
	v_pk_fma_f32 v[62:63], v[70:71], s[78:79], v[62:63] op_sel_hi:[1,0,1]
	v_lshl_add_u64 v[120:121], v[158:159], 2, s[88:89]
	global_store_dwordx4 v[120:121], v[60:63], off
	v_or_b32_e32 v158, 0x90, v148
	s_waitcnt vmcnt(0)
	v_sub_f32_e32 v61, v131, v138
	v_sub_f32_e32 v60, v130, v138
	v_sub_f32_e32 v63, v133, v138
	v_sub_f32_e32 v62, v132, v138
	v_pk_mul_f32 v[62:63], v[138:139], v[62:63] op_sel:[1,0]
	v_pk_mul_f32 v[60:61], v[138:139], v[60:61] op_sel:[1,0]
	v_pk_fma_f32 v[58:59], v[92:93], v[62:63], v[58:59]
	v_pk_fma_f32 v[56:57], v[94:95], v[60:61], v[56:57]
	v_pk_fma_f32 v[58:59], v[66:67], s[78:79], v[58:59] op_sel_hi:[1,0,1]
	v_pk_fma_f32 v[56:57], v[64:65], s[78:79], v[56:57] op_sel_hi:[1,0,1]
	v_lshl_add_u64 v[60:61], v[158:159], 2, s[88:89]
	global_store_dwordx4 v[60:61], v[56:59], off
	v_add_u32_e32 v158, 0x8080, v148
	s_nop 0
	v_sub_f32_e32 v57, v135, v112
	v_sub_f32_e32 v56, v134, v112
	v_sub_f32_e32 v59, v137, v112
	v_sub_f32_e32 v58, v136, v112
	v_pk_mul_f32 v[58:59], v[112:113], v[58:59] op_sel:[1,0]
	v_pk_mul_f32 v[56:57], v[112:113], v[56:57] op_sel:[1,0]
	v_pk_fma_f32 v[54:55], v[96:97], v[58:59], v[54:55]
	v_pk_fma_f32 v[52:53], v[98:99], v[56:57], v[52:53]
	v_pk_fma_f32 v[54:55], v[70:71], s[78:79], v[54:55] op_sel_hi:[1,0,1]
	v_pk_fma_f32 v[52:53], v[68:69], s[78:79], v[52:53] op_sel_hi:[1,0,1]
	v_lshl_add_u64 v[56:57], v[158:159], 2, s[88:89]
	global_store_dwordx4 v[56:57], v[52:55], off
	v_add_u32_e32 v158, 0x8090, v148
	s_nop 0
	v_sub_f32_e32 v53, v89, v112
	v_sub_f32_e32 v52, v88, v112
	v_sub_f32_e32 v55, v91, v112
	v_sub_f32_e32 v54, v90, v112
	v_pk_mul_f32 v[54:55], v[112:113], v[54:55] op_sel:[1,0]
	v_pk_mul_f32 v[52:53], v[112:113], v[52:53] op_sel:[1,0]
	v_pk_fma_f32 v[50:51], v[92:93], v[54:55], v[50:51]
	v_pk_fma_f32 v[48:49], v[94:95], v[52:53], v[48:49]
	v_pk_fma_f32 v[50:51], v[66:67], s[78:79], v[50:51] op_sel_hi:[1,0,1]
	v_pk_fma_f32 v[48:49], v[64:65], s[78:79], v[48:49] op_sel_hi:[1,0,1]
	v_lshl_add_u64 v[52:53], v[158:159], 2, s[88:89]
	global_store_dwordx4 v[52:53], v[48:51], off
	v_add_u32_e32 v158, 0x10080, v148
	s_nop 0
	v_sub_f32_e32 v49, v85, v102
	v_sub_f32_e32 v48, v84, v102
	v_sub_f32_e32 v51, v87, v102
	v_sub_f32_e32 v50, v86, v102
	v_pk_mul_f32 v[50:51], v[102:103], v[50:51] op_sel:[1,0]
	v_pk_mul_f32 v[48:49], v[102:103], v[48:49] op_sel:[1,0]
	v_pk_fma_f32 v[46:47], v[96:97], v[50:51], v[46:47]
	v_pk_fma_f32 v[44:45], v[98:99], v[48:49], v[44:45]
	v_pk_fma_f32 v[46:47], v[70:71], s[78:79], v[46:47] op_sel_hi:[1,0,1]
	v_pk_fma_f32 v[44:45], v[68:69], s[78:79], v[44:45] op_sel_hi:[1,0,1]
	v_lshl_add_u64 v[48:49], v[158:159], 2, s[88:89]
	global_store_dwordx4 v[48:49], v[44:47], off
	v_add_u32_e32 v158, 0x10090, v148
	s_nop 0
	v_sub_f32_e32 v45, v81, v102
	v_sub_f32_e32 v44, v80, v102
	v_sub_f32_e32 v47, v83, v102
	v_sub_f32_e32 v46, v82, v102
	v_pk_mul_f32 v[46:47], v[102:103], v[46:47] op_sel:[1,0]
	v_pk_mul_f32 v[44:45], v[102:103], v[44:45] op_sel:[1,0]
	v_pk_fma_f32 v[42:43], v[92:93], v[46:47], v[42:43]
	v_pk_fma_f32 v[40:41], v[94:95], v[44:45], v[40:41]
	v_pk_fma_f32 v[42:43], v[66:67], s[78:79], v[42:43] op_sel_hi:[1,0,1]
	v_pk_fma_f32 v[40:41], v[64:65], s[78:79], v[40:41] op_sel_hi:[1,0,1]
	v_lshl_add_u64 v[44:45], v[158:159], 2, s[88:89]
	global_store_dwordx4 v[44:45], v[40:43], off
	v_add_u32_e32 v158, 0x18080, v148
	s_nop 0
	v_sub_f32_e32 v41, v77, v100
	v_sub_f32_e32 v40, v76, v100
	v_sub_f32_e32 v43, v79, v100
	v_sub_f32_e32 v42, v78, v100
	v_pk_mul_f32 v[42:43], v[100:101], v[42:43] op_sel:[1,0]
	v_pk_mul_f32 v[40:41], v[100:101], v[40:41] op_sel:[1,0]
	v_pk_fma_f32 v[38:39], v[96:97], v[42:43], v[38:39]
;     template <bool LN, int BJ, int LO, int HI> DI void batch(const f32x4 (&acc)[2][2][4][2], unsigned row0, unsigned col0, const f32x4 (&gv)[2], const f32x4 (&bv)[2]) const {
;         f32x4 r[HI - LO]; float mean[(HI - LO) / 2], rstd[(HI - LO) / 2];
; #pragma unroll
;         for (int i = LO; i < HI; ++i) { const int ai = i >> 3, m = (i >> 1) & 3, n = i & 1; const unsigned row = row0 + ai * HALF + m * 16;
;             if (n == 0) { mean[(i - LO) >> 1] = 0.f; rstd[(i - LO) >> 1] = 1.f;
;                 if (LN) { const float2 st = *(const float2*)(stats + row * 2u); mean[(i - LO) >> 1] = st.x; rstd[(i - LO) >> 1] = st.y; } }
;             r[i - LO] = *(const f32x4*)(src + (row * (unsigned)DM + col0 + BJ * HALF + n * 16)); }
; #pragma unroll
;         for (int i = LO; i < HI; ++i) { const int ai = i >> 3, m = (i >> 1) & 3, n = i & 1; const unsigned row = row0 + ai * HALF + m * 16;
;             *(f32x4*)(Y + (row * (unsigned)DM + col0 + BJ * HALF + n * 16)) = acc[ai][BJ][m][n] + ((r[i - LO] - mean[(i - LO) >> 1]) * rstd[(i - LO) >> 1]) * gv[n] + bv[n]; }
;         __builtin_amdgcn_sched_barrier(0);
;     }
;     template <bool LN, int BJ> DI void load_gb(unsigned col0, f32x4 (&gv)[2], f32x4 (&bv)[2]) const {
; #pragma unroll
;         for (int n = 0; n < 2; ++n) {
;             if (LN) { gv[n] = *(const f32x4*)(gam + col0 + BJ * HALF + n * 16) * ALPHA; bv[n] = *(const f32x4*)(bet + col0 + BJ * HALF + n * 16) * ALPHA; }
;             else { gv[n] = (f32x4){ALPHA, ALPHA, ALPHA, ALPHA}; bv[n] = (f32x4){0.f, 0.f, 0.f, 0.f}; }
;         }
;     }
;     template <bool LN> DI void run(const f32x4 (&acc)[2][2][4][2], const Unit& u, int wr, int wc, int fr, int fq) const {
;         const unsigned row0 = u.pm * BM + wr * 64 + fr, col0 = u.pn * BM + wc * 32 + 4 * fq;
;         f32x4 gv[2], bv[2];
;         load_gb<LN, 0>(col0, gv, bv);
;         batch<LN, 0, 0, 4>(acc, row0, col0, gv, bv);
;         batch<LN, 0, 4, 8>(acc, row0, col0, gv, bv);
;         batch<LN, 0, 8, 12>(acc, row0, col0, gv, bv);
;         batch<LN, 0, 12, 16>(acc, row0, col0, gv, bv);
;         load_gb<LN, 1>(col0, gv, bv);
;         batch<LN, 1, 0, 8>(acc, row0, col0, gv, bv);
;         batch<LN, 1, 8, 16>(acc, row0, col0, gv, bv);
	v_pk_fma_f32 v[36:37], v[98:99], v[40:41], v[36:37]
	v_pk_fma_f32 v[38:39], v[70:71], s[78:79], v[38:39] op_sel_hi:[1,0,1]
	v_pk_fma_f32 v[36:37], v[68:69], s[78:79], v[36:37] op_sel_hi:[1,0,1]
	v_lshl_add_u64 v[40:41], v[158:159], 2, s[88:89]
	global_store_dwordx4 v[40:41], v[36:39], off
	v_add_u32_e32 v158, 0x18090, v148
	s_nop 0
	v_sub_f32_e32 v37, v73, v100
	v_sub_f32_e32 v36, v72, v100
	v_sub_f32_e32 v39, v75, v100
	v_sub_f32_e32 v38, v74, v100
	v_pk_mul_f32 v[38:39], v[100:101], v[38:39] op_sel:[1,0]
	v_pk_mul_f32 v[36:37], v[100:101], v[36:37] op_sel:[1,0]
	v_pk_fma_f32 v[34:35], v[92:93], v[38:39], v[34:35]
	v_pk_fma_f32 v[32:33], v[94:95], v[36:37], v[32:33]
	v_pk_fma_f32 v[34:35], v[66:67], s[78:79], v[34:35] op_sel_hi:[1,0,1]
	v_pk_fma_f32 v[32:33], v[64:65], s[78:79], v[32:33] op_sel_hi:[1,0,1]
	v_lshl_add_u64 v[36:37], v[158:159], 2, s[88:89]
	global_store_dwordx4 v[36:37], v[32:35], off
	v_add_u32_e32 v158, v114, v119
	s_nop 0
	v_lshl_add_u64 v[32:33], v[158:159], 2, s[90:91]
	global_load_dwordx2 v[62:63], v[104:105], off
	global_load_dwordx4 v[54:57], v[32:33], off
	v_add_u32_e32 v158, v114, v118
	v_lshl_add_u64 v[32:33], v[158:159], 2, s[90:91]
	global_load_dwordx4 v[58:61], v[32:33], off
	global_load_dwordx2 v[52:53], v[106:107], off
	v_add_u32_e32 v158, v115, v119
	v_lshl_add_u64 v[32:33], v[158:159], 2, s[90:91]
	global_load_dwordx4 v[72:75], v[32:33], off
	v_add_u32_e32 v158, v115, v118
	v_lshl_add_u64 v[32:33], v[158:159], 2, s[90:91]
	global_load_dwordx4 v[76:79], v[32:33], off
	global_load_dwordx2 v[50:51], v[108:109], off
	v_add_u32_e32 v158, v116, v119
	v_lshl_add_u64 v[32:33], v[158:159], 2, s[90:91]
	global_load_dwordx4 v[44:47], v[32:33], off
	v_add_u32_e32 v158, v116, v118
	v_lshl_add_u64 v[32:33], v[158:159], 2, s[90:91]
	global_load_dwordx4 v[40:43], v[32:33], off
	global_load_dwordx2 v[48:49], v[110:111], off
	v_add_u32_e32 v158, v117, v119
	v_lshl_add_u64 v[32:33], v[158:159], 2, s[90:91]
	global_load_dwordx4 v[36:39], v[32:33], off
	v_add_u32_e32 v158, v117, v118
	v_lshl_add_u64 v[32:33], v[158:159], 2, s[90:91]
	global_load_dwordx4 v[32:35], v[32:33], off
	v_add_u32_e32 v158, 0x40080, v148
	s_waitcnt vmcnt(0)
; template <class Epi>
; DI void gemm_phase(LAS unsigned char* lds, const Gemm g, const StaticOrder& S, const Epi& E) {
;     ...
;         cur = nxt; cA = nA; cB = nB; ++ui;
;     template <bool LN, int BJ, int LO, int HI> DI void batch(const f32x4 (&acc)[2][2][4][2], unsigned row0, unsigned col0, const f32x4 (&gv)[2], const f32x4 (&bv)[2]) const {
;         f32x4 r[HI - LO]; float mean[(HI - LO) / 2], rstd[(HI - LO) / 2];
; #pragma unroll
;         for (int i = LO; i < HI; ++i) { const int ai = i >> 3, m = (i >> 1) & 3, n = i & 1; const unsigned row = row0 + ai * HALF + m * 16;
;             if (n == 0) { mean[(i - LO) >> 1] = 0.f; rstd[(i - LO) >> 1] = 1.f;
;                 if (LN) { const float2 st = *(const float2*)(stats + row * 2u); mean[(i - LO) >> 1] = st.x; rstd[(i - LO) >> 1] = st.y; } }
;             r[i - LO] = *(const f32x4*)(src + (row * (unsigned)DM + col0 + BJ * HALF + n * 16)); }
; #pragma unroll
;         for (int i = LO; i < HI; ++i) { const int ai = i >> 3, m = (i >> 1) & 3, n = i & 1; const unsigned row = row0 + ai * HALF + m * 16;
;             *(f32x4*)(Y + (row * (unsigned)DM + col0 + BJ * HALF + n * 16)) = acc[ai][BJ][m][n] + ((r[i - LO] - mean[(i - LO) >> 1]) * rstd[(i - LO) >> 1]) * gv[n] + bv[n]; }
;         __builtin_amdgcn_sched_barrier(0);
;     }
;     template <bool LN, int BJ> DI void load_gb(unsigned col0, f32x4 (&gv)[2], f32x4 (&bv)[2]) const {
; #pragma unroll
;         for (int n = 0; n < 2; ++n) {
;             if (LN) { gv[n] = *(const f32x4*)(gam + col0 + BJ * HALF + n * 16) * ALPHA; bv[n] = *(const f32x4*)(bet + col0 + BJ * HALF + n * 16) * ALPHA; }
;             else { gv[n] = (f32x4){ALPHA, ALPHA, ALPHA, ALPHA}; bv[n] = (f32x4){0.f, 0.f, 0.f, 0.f}; }
;         }
;     }
;     template <bool LN> DI void run(const f32x4 (&acc)[2][2][4][2], const Unit& u, int wr, int wc, int fr, int fq) const {
;         const unsigned row0 = u.pm * BM + wr * 64 + fr, col0 = u.pn * BM + wc * 32 + 4 * fq;
;         f32x4 gv[2], bv[2];
;         load_gb<LN, 0>(col0, gv, bv);
;         batch<LN, 0, 0, 4>(acc, row0, col0, gv, bv);
;         batch<LN, 0, 4, 8>(acc, row0, col0, gv, bv);
;         batch<LN, 0, 8, 12>(acc, row0, col0, gv, bv);
;         batch<LN, 0, 12, 16>(acc, row0, col0, gv, bv);
;         load_gb<LN, 1>(col0, gv, bv);
;         batch<LN, 1, 0, 8>(acc, row0, col0, gv, bv);
;         batch<LN, 1, 8, 16>(acc, row0, col0, gv, bv);
	v_sub_f32_e32 v55, v55, v62
	v_sub_f32_e32 v54, v54, v62
	v_sub_f32_e32 v57, v57, v62
	v_sub_f32_e32 v56, v56, v62
	v_pk_mul_f32 v[56:57], v[62:63], v[56:57] op_sel:[1,0]
	v_pk_mul_f32 v[54:55], v[62:63], v[54:55] op_sel:[1,0]
	v_pk_fma_f32 v[30:31], v[96:97], v[56:57], v[30:31]
	v_pk_fma_f32 v[28:29], v[98:99], v[54:55], v[28:29]
	v_pk_fma_f32 v[30:31], v[70:71], s[78:79], v[30:31] op_sel_hi:[1,0,1]
	v_pk_fma_f32 v[28:29], v[68:69], s[78:79], v[28:29] op_sel_hi:[1,0,1]
	v_lshl_add_u64 v[54:55], v[158:159], 2, s[88:89]
	global_store_dwordx4 v[54:55], v[28:31], off
	v_add_u32_e32 v158, 0x40090, v148
	s_nop 0
	v_sub_f32_e32 v29, v59, v62
	v_sub_f32_e32 v28, v58, v62
	v_sub_f32_e32 v31, v61, v62
	v_sub_f32_e32 v30, v60, v62
	v_pk_mul_f32 v[30:31], v[62:63], v[30:31] op_sel:[1,0]
	v_pk_mul_f32 v[28:29], v[62:63], v[28:29] op_sel:[1,0]
	v_pk_fma_f32 v[26:27], v[92:93], v[30:31], v[26:27]
	v_pk_fma_f32 v[24:25], v[94:95], v[28:29], v[24:25]
	v_pk_fma_f32 v[26:27], v[66:67], s[78:79], v[26:27] op_sel_hi:[1,0,1]
	v_pk_fma_f32 v[24:25], v[64:65], s[78:79], v[24:25] op_sel_hi:[1,0,1]
	v_lshl_add_u64 v[28:29], v[158:159], 2, s[88:89]
	global_store_dwordx4 v[28:29], v[24:27], off
	v_add_u32_e32 v158, 0x48080, v148
	s_nop 0
	v_sub_f32_e32 v25, v73, v52
	v_sub_f32_e32 v24, v72, v52
	v_sub_f32_e32 v27, v75, v52
	v_sub_f32_e32 v26, v74, v52
	v_pk_mul_f32 v[26:27], v[52:53], v[26:27] op_sel:[1,0]
	v_pk_mul_f32 v[24:25], v[52:53], v[24:25] op_sel:[1,0]
	v_pk_fma_f32 v[22:23], v[96:97], v[26:27], v[22:23]
	v_pk_fma_f32 v[20:21], v[98:99], v[24:25], v[20:21]
	v_pk_fma_f32 v[22:23], v[70:71], s[78:79], v[22:23] op_sel_hi:[1,0,1]
	v_pk_fma_f32 v[20:21], v[68:69], s[78:79], v[20:21] op_sel_hi:[1,0,1]
	v_lshl_add_u64 v[24:25], v[158:159], 2, s[88:89]
	global_store_dwordx4 v[24:25], v[20:23], off
	v_add_u32_e32 v158, 0x48090, v148
	s_nop 0
	v_sub_f32_e32 v21, v77, v52
	v_sub_f32_e32 v20, v76, v52
	v_sub_f32_e32 v23, v79, v52
	v_sub_f32_e32 v22, v78, v52
	v_pk_mul_f32 v[22:23], v[52:53], v[22:23] op_sel:[1,0]
	v_pk_mul_f32 v[20:21], v[52:53], v[20:21] op_sel:[1,0]
	v_pk_fma_f32 v[18:19], v[92:93], v[22:23], v[18:19]
	v_pk_fma_f32 v[16:17], v[94:95], v[20:21], v[16:17]
	v_pk_fma_f32 v[18:19], v[66:67], s[78:79], v[18:19] op_sel_hi:[1,0,1]
	v_pk_fma_f32 v[16:17], v[64:65], s[78:79], v[16:17] op_sel_hi:[1,0,1]
	v_lshl_add_u64 v[20:21], v[158:159], 2, s[88:89]
	global_store_dwordx4 v[20:21], v[16:19], off
	v_add_u32_e32 v158, 0x50080, v148
	s_nop 0
	v_sub_f32_e32 v17, v45, v50
	v_sub_f32_e32 v16, v44, v50
	v_sub_f32_e32 v19, v47, v50
	v_sub_f32_e32 v18, v46, v50
	v_pk_mul_f32 v[18:19], v[50:51], v[18:19] op_sel:[1,0]
	v_pk_mul_f32 v[16:17], v[50:51], v[16:17] op_sel:[1,0]
	v_pk_fma_f32 v[14:15], v[96:97], v[18:19], v[14:15]
	v_pk_fma_f32 v[12:13], v[98:99], v[16:17], v[12:13]
	v_pk_fma_f32 v[14:15], v[70:71], s[78:79], v[14:15] op_sel_hi:[1,0,1]
	v_pk_fma_f32 v[12:13], v[68:69], s[78:79], v[12:13] op_sel_hi:[1,0,1]
	v_lshl_add_u64 v[16:17], v[158:159], 2, s[88:89]
	global_store_dwordx4 v[16:17], v[12:15], off
	v_add_u32_e32 v158, 0x50090, v148
	s_nop 0
	v_sub_f32_e32 v13, v41, v50
	v_sub_f32_e32 v12, v40, v50
	v_sub_f32_e32 v15, v43, v50
	v_sub_f32_e32 v14, v42, v50
	v_pk_mul_f32 v[14:15], v[50:51], v[14:15] op_sel:[1,0]
	v_pk_mul_f32 v[12:13], v[50:51], v[12:13] op_sel:[1,0]
	v_pk_fma_f32 v[10:11], v[92:93], v[14:15], v[10:11]
	v_pk_fma_f32 v[8:9], v[94:95], v[12:13], v[8:9]
	v_pk_fma_f32 v[10:11], v[66:67], s[78:79], v[10:11] op_sel_hi:[1,0,1]
	v_pk_fma_f32 v[8:9], v[64:65], s[78:79], v[8:9] op_sel_hi:[1,0,1]
	v_lshl_add_u64 v[12:13], v[158:159], 2, s[88:89]
	global_store_dwordx4 v[12:13], v[8:11], off
	v_add_u32_e32 v158, 0x58080, v148
	s_nop 0
	v_sub_f32_e32 v9, v37, v48
	v_sub_f32_e32 v8, v36, v48
	v_sub_f32_e32 v11, v39, v48
	v_sub_f32_e32 v10, v38, v48
	v_pk_mul_f32 v[10:11], v[48:49], v[10:11] op_sel:[1,0]
	v_pk_mul_f32 v[8:9], v[48:49], v[8:9] op_sel:[1,0]
	v_pk_fma_f32 v[6:7], v[96:97], v[10:11], v[6:7]
	v_pk_fma_f32 v[4:5], v[98:99], v[8:9], v[4:5]
	v_pk_fma_f32 v[6:7], v[70:71], s[78:79], v[6:7] op_sel_hi:[1,0,1]
	v_pk_fma_f32 v[4:5], v[68:69], s[78:79], v[4:5] op_sel_hi:[1,0,1]
	v_lshl_add_u64 v[8:9], v[158:159], 2, s[88:89]
	global_store_dwordx4 v[8:9], v[4:7], off
	v_add_u32_e32 v158, 0x58090, v148
	s_nop 0
	v_sub_f32_e32 v5, v33, v48
	v_sub_f32_e32 v4, v32, v48
	v_sub_f32_e32 v7, v35, v48
	v_sub_f32_e32 v6, v34, v48
	v_pk_mul_f32 v[6:7], v[48:49], v[6:7] op_sel:[1,0]
	v_pk_mul_f32 v[4:5], v[48:49], v[4:5] op_sel:[1,0]
	v_pk_fma_f32 v[2:3], v[92:93], v[6:7], v[2:3]
	v_pk_fma_f32 v[0:1], v[94:95], v[4:5], v[0:1]
	v_pk_fma_f32 v[2:3], v[66:67], s[78:79], v[2:3] op_sel_hi:[1,0,1]
	v_pk_fma_f32 v[0:1], v[64:65], s[78:79], v[0:1] op_sel_hi:[1,0,1]
	v_lshl_add_u64 v[4:5], v[158:159], 2, s[88:89]
	global_store_dwordx4 v[4:5], v[0:3], off
	s_and_b64 vcc, exec, s[6:7]
	s_mov_b32 s2, s37
	s_mov_b32 s3, s38
	s_mov_b64 s[18:19], s[10:11]
	s_mov_b64 s[16:17], s[8:9]
	v_readlane_b32 s33, v255, 39
	s_cbranch_vccz .LBB0_123
	s_waitcnt vmcnt(0)
	s_cmpk_gt_u32 s24, 0xff
	s_cbranch_scc1 .LBB0_138
	s_barrier

; #define PG8_STAGE(bufoff, gbase) do { _Pragma("unroll") for (int _i = 0; _i < 2; ++_i) \
;         __builtin_amdgcn_global_load_lds((const unsigned*)((const char*)(gbase) + voff[_i]), (LAS unsigned*)(lds + (bufoff) + ldsw + _i * 8192), 16, 0, 0); } while (0)
; #define PG8_LDA(dst, b, h) do { _Pragma("unroll") for (int m = 0; m < 4; ++m) _Pragma("unroll") for (int k = 0; k < 2; ++k) dst[m][k] = *(const LAS bf16x8*)(lds + PG8_SA(b, h) + aoff + m * 2048 + k * 1024); } while (0)
; #define PG8_LDB(dst, b, h) do { _Pragma("unroll") for (int n = 0; n < 2; ++n) _Pragma("unroll") for (int k = 0; k < 2; ++k) dst[n][k] = *(const LAS bf16x8*)(lds + PG8_SB(b, h) + boff + n * 2048 + k * 1024); } while (0)
; #define PG8_MMA(ai, bj, At, Bt) do { __builtin_amdgcn_s_setprio(1); _Pragma("unroll") for (int m = 0; m < 4; ++m) _Pragma("unroll") for (int n = 0; n < 2; ++n) _Pragma("unroll") for (int k = 0; k < 2; ++k) \
;         acc[ai][bj][m][n] = __builtin_amdgcn_mfma_f32_16x16x32_bf16(Bt[n][k], At[m][k], acc[ai][bj][m][n], 0, 0, 0); __builtin_amdgcn_s_setprio(0); } while (0)
; #define PG8_WAIT_V(n) asm volatile("s_waitcnt vmcnt(" #n ")" ::: "memory")
; #define PG8_WAIT_L(n) asm volatile("s_waitcnt lgkmcnt(" #n ")" ::: "memory")
; #define PG8_BAR __builtin_amdgcn_s_barrier()
; #define PG8_SCHED __builtin_amdgcn_sched_barrier(0)
; template <class Epi>
; DI void gemm_phase(LAS unsigned char* lds, const Gemm g, const StaticOrder& S, const Epi& E) {
;     ...
;         for (int t = 0; t < nt; t += 2) {
;             const bool last = (t == nt - 2);
;             const char* a1 = cA + (size_t)(t + 1) * kstep;
;             const char* a2 = last ? nA : cA + (size_t)(t + 2) * kstep; const char* b2 = last ? nB : cB + (size_t)(t + 2) * kstep;
;             const char* a3 = a2 + kstep; const char* b3 = b2 + kstep;
;             PG8_LDB(B0, 0, 0); PG8_SCHED; PG8_LDA(At, 0, 0); PG8_STAGE(PG8_SA(1, 1), a1 + hstep);
;             PG8_WAIT_L(8); PG8_BAR; PG8_WAIT_L(0); PG8_MMA(0, 0, At, B0); PG8_BAR; PG8_SCHED;
;             PG8_LDB(B1, 0, 1); PG8_STAGE(PG8_SB(0, 0), b2);
;             PG8_BAR; PG8_WAIT_L(0); PG8_MMA(0, 1, At, B1); PG8_BAR;
;             PG8_LDA(At, 0, 1); PG8_STAGE(PG8_SA(0, 0), a2);
;             PG8_BAR; PG8_WAIT_L(0); PG8_MMA(1, 0, At, B0); PG8_BAR; PG8_SCHED;
;             PG8_STAGE(PG8_SB(0, 1), b2 + hstep);
;             PG8_WAIT_V(6); PG8_BAR; PG8_MMA(1, 1, At, B1); PG8_BAR;
.LBB0_202:
	s_add_u32 s18, s8, 0xfff80080
	s_addc_u32 s19, s9, -1
	s_add_i32 s37, 0, 0x10000
	s_waitcnt lgkmcnt(0)
	ds_read_b128 v[128:131], v187
	ds_read_b128 v[132:135], v187 offset:1024
	ds_read_b128 v[136:139], v187 offset:2048
	ds_read_b128 v[190:193], v187 offset:3072
	s_cmp_eq_u32 s36, 28
	s_cselect_b32 s21, s4, s19
	s_cselect_b32 s20, s5, s18
	s_cselect_b32 s19, s11, s35
	s_cselect_b32 s18, s13, s33
	s_add_i32 m0, s26, 0xc000
	ds_read_b128 v[194:197], v189
	ds_read_b128 v[198:201], v189 offset:1024
	ds_read_b128 v[202:205], v189 offset:2048
	ds_read_b128 v[206:209], v189 offset:3072
	ds_read_b128 v[210:213], v189 offset:4096
	ds_read_b128 v[214:217], v189 offset:5120
	ds_read_b128 v[226:229], v189 offset:6144
	ds_read_b128 v[230:233], v189 offset:7168
	global_load_lds_dwordx4 v150, s[8:9]
	s_add_i32 m0, s26, 0xe000
	s_nop 0
	global_load_lds_dwordx4 v152, s[8:9]
	s_waitcnt lgkmcnt(8)
	s_setprio 1
	s_barrier
	s_waitcnt lgkmcnt(0)
	v_mfma_f32_16x16x32_bf16 v[124:127], v[128:131], v[194:197], v[124:127]
	v_mfma_f32_16x16x32_bf16 v[120:123], v[136:139], v[194:197], v[120:123]
	v_mfma_f32_16x16x32_bf16 v[108:111], v[128:131], v[202:205], v[108:111]
	v_mfma_f32_16x16x32_bf16 v[104:107], v[136:139], v[202:205], v[104:107]
	v_mfma_f32_16x16x32_bf16 v[92:95], v[128:131], v[210:213], v[92:95]
	v_mfma_f32_16x16x32_bf16 v[88:91], v[136:139], v[210:213], v[88:91]
	v_mfma_f32_16x16x32_bf16 v[76:79], v[128:131], v[226:229], v[76:79]
	v_mfma_f32_16x16x32_bf16 v[72:75], v[136:139], v[226:229], v[72:75]
	v_mfma_f32_16x16x32_bf16 v[124:127], v[132:135], v[198:201], v[124:127]
	v_mfma_f32_16x16x32_bf16 v[120:123], v[190:193], v[198:201], v[120:123]
	v_mfma_f32_16x16x32_bf16 v[108:111], v[132:135], v[206:209], v[108:111]
	v_mfma_f32_16x16x32_bf16 v[104:107], v[190:193], v[206:209], v[104:107]
	v_mfma_f32_16x16x32_bf16 v[92:95], v[132:135], v[214:217], v[92:95]
	v_mfma_f32_16x16x32_bf16 v[88:91], v[190:193], v[214:217], v[88:91]
	v_mfma_f32_16x16x32_bf16 v[76:79], v[132:135], v[230:233], v[76:79]
	s_setprio 0
	v_mfma_f32_16x16x32_bf16 v[72:75], v[190:193], v[230:233], v[72:75]
	s_barrier
	s_add_i32 s40, 0, 0x14000
	s_add_i32 s37, s37, s25
	ds_read_b128 v[234:237], v187 offset:16384
	ds_read_b128 v[238:241], v187 offset:17408
	ds_read_b128 v[242:245], v187 offset:18432
	ds_read_b128 v[246:249], v187 offset:19456
	s_mov_b32 m0, s37
	s_nop 0
	global_load_lds_dwordx4 v144, s[18:19]
	s_add_i32 m0, s37, 0x2000
	s_nop 0
	global_load_lds_dwordx4 v142, s[18:19]
	s_waitcnt lgkmcnt(0)
	s_setprio 1
	s_barrier
	v_mfma_f32_16x16x32_bf16 v[116:119], v[234:237], v[194:197], v[116:119]
	v_mfma_f32_16x16x32_bf16 v[112:115], v[242:245], v[194:197], v[112:115]
	v_mfma_f32_16x16x32_bf16 v[100:103], v[234:237], v[202:205], v[100:103]
	v_mfma_f32_16x16x32_bf16 v[96:99], v[242:245], v[202:205], v[96:99]
	v_mfma_f32_16x16x32_bf16 v[84:87], v[234:237], v[210:213], v[84:87]
	v_mfma_f32_16x16x32_bf16 v[80:83], v[242:245], v[210:213], v[80:83]
	v_mfma_f32_16x16x32_bf16 v[68:71], v[234:237], v[226:229], v[68:71]
	v_mfma_f32_16x16x32_bf16 v[64:67], v[242:245], v[226:229], v[64:67]
	v_mfma_f32_16x16x32_bf16 v[116:119], v[238:241], v[198:201], v[116:119]
	s_mov_b32 m0, s26
	v_mfma_f32_16x16x32_bf16 v[112:115], v[246:249], v[198:201], v[112:115]
	s_mov_b64 s[100:101], s[20:21]
	v_mfma_f32_16x16x32_bf16 v[100:103], v[238:241], v[206:209], v[100:103]
	v_mfma_f32_16x16x32_bf16 v[96:99], v[246:249], v[206:209], v[96:99]
	v_mfma_f32_16x16x32_bf16 v[84:87], v[238:241], v[214:217], v[84:87]
	v_mfma_f32_16x16x32_bf16 v[80:83], v[246:249], v[214:217], v[80:83]
	v_mfma_f32_16x16x32_bf16 v[68:71], v[238:241], v[230:233], v[68:71]
	s_setprio 0
	v_mfma_f32_16x16x32_bf16 v[64:67], v[246:249], v[230:233], v[64:67]
	s_barrier
	ds_read_b128 v[194:197], v189 offset:16384
	ds_read_b128 v[198:201], v189 offset:17408
	ds_read_b128 v[202:205], v189 offset:18432
	ds_read_b128 v[206:209], v189 offset:19456
	ds_read_b128 v[210:213], v189 offset:20480
	ds_read_b128 v[214:217], v189 offset:21504
	ds_read_b128 v[226:229], v189 offset:22528
	ds_read_b128 v[230:233], v189 offset:23552
	global_load_lds_dwordx4 v144, s[20:21]
	s_mov_b64 s[100:101], s[20:21]
	s_mov_b32 m0, s27
	s_nop 0
	global_load_lds_dwordx4 v142, s[20:21]
	s_waitcnt lgkmcnt(0)
	s_setprio 1
	s_barrier
	v_mfma_f32_16x16x32_bf16 v[60:63], v[128:131], v[194:197], v[60:63]
	v_mfma_f32_16x16x32_bf16 v[56:59], v[136:139], v[194:197], v[56:59]
	v_mfma_f32_16x16x32_bf16 v[44:47], v[128:131], v[202:205], v[44:47]
	v_mfma_f32_16x16x32_bf16 v[40:43], v[136:139], v[202:205], v[40:43]
	v_mfma_f32_16x16x32_bf16 v[28:31], v[128:131], v[210:213], v[28:31]
	v_mfma_f32_16x16x32_bf16 v[24:27], v[136:139], v[210:213], v[24:27]
	v_mfma_f32_16x16x32_bf16 v[12:15], v[128:131], v[226:229], v[12:15]
	v_mfma_f32_16x16x32_bf16 v[8:11], v[136:139], v[226:229], v[8:11]
	v_mfma_f32_16x16x32_bf16 v[60:63], v[132:135], v[198:201], v[60:63]
	v_mfma_f32_16x16x32_bf16 v[56:59], v[190:193], v[198:201], v[56:59]
	v_mfma_f32_16x16x32_bf16 v[44:47], v[132:135], v[206:209], v[44:47]
	v_mfma_f32_16x16x32_bf16 v[40:43], v[190:193], v[206:209], v[40:43]
	v_mfma_f32_16x16x32_bf16 v[28:31], v[132:135], v[214:217], v[28:31]
	v_mfma_f32_16x16x32_bf16 v[24:27], v[190:193], v[214:217], v[24:27]
	v_mfma_f32_16x16x32_bf16 v[12:15], v[132:135], v[230:233], v[12:15]
	s_setprio 0
	v_mfma_f32_16x16x32_bf16 v[8:11], v[190:193], v[230:233], v[8:11]
	s_barrier
	s_add_u32 s38, s18, 0x80000
	s_addc_u32 s39, s19, 0
	s_add_i32 s37, s40, s25
	s_mov_b32 m0, s37
	s_nop 0
	global_load_lds_dwordx4 v144, s[38:39]
	s_add_i32 m0, s37, 0x2000
	s_nop 0
	global_load_lds_dwordx4 v142, s[38:39]
	s_waitcnt vmcnt(6)
	s_setprio 1
	s_barrier
; #define PG8_STAGE(bufoff, gbase) do { _Pragma("unroll") for (int _i = 0; _i < 2; ++_i) \
;         __builtin_amdgcn_global_load_lds((const unsigned*)((const char*)(gbase) + voff[_i]), (LAS unsigned*)(lds + (bufoff) + ldsw + _i * 8192), 16, 0, 0); } while (0)
; #define PG8_LDA(dst, b, h) do { _Pragma("unroll") for (int m = 0; m < 4; ++m) _Pragma("unroll") for (int k = 0; k < 2; ++k) dst[m][k] = *(const LAS bf16x8*)(lds + PG8_SA(b, h) + aoff + m * 2048 + k * 1024); } while (0)
; #define PG8_LDB(dst, b, h) do { _Pragma("unroll") for (int n = 0; n < 2; ++n) _Pragma("unroll") for (int k = 0; k < 2; ++k) dst[n][k] = *(const LAS bf16x8*)(lds + PG8_SB(b, h) + boff + n * 2048 + k * 1024); } while (0)
; #define PG8_MMA(ai, bj, At, Bt) do { __builtin_amdgcn_s_setprio(1); _Pragma("unroll") for (int m = 0; m < 4; ++m) _Pragma("unroll") for (int n = 0; n < 2; ++n) _Pragma("unroll") for (int k = 0; k < 2; ++k) \
;         acc[ai][bj][m][n] = __builtin_amdgcn_mfma_f32_16x16x32_bf16(Bt[n][k], At[m][k], acc[ai][bj][m][n], 0, 0, 0); __builtin_amdgcn_s_setprio(0); } while (0)
; #define PG8_WAIT_V(n) asm volatile("s_waitcnt vmcnt(" #n ")" ::: "memory")
; #define PG8_WAIT_L(n) asm volatile("s_waitcnt lgkmcnt(" #n ")" ::: "memory")
; #define PG8_BAR __builtin_amdgcn_s_barrier()
; #define PG8_SCHED __builtin_amdgcn_sched_barrier(0)
; template <class Epi>
; DI void gemm_phase(LAS unsigned char* lds, const Gemm g, const StaticOrder& S, const Epi& E) {
;     ...
;             PG8_WAIT_V(6); PG8_BAR; PG8_MMA(1, 1, At, B1); PG8_BAR;
;             PG8_LDB(B0, 1, 0); PG8_SCHED; PG8_LDA(At, 1, 0); PG8_STAGE(PG8_SA(0, 1), a2 + hstep);
;             PG8_WAIT_L(8); PG8_BAR; PG8_WAIT_L(0); PG8_MMA(0, 0, At, B0); PG8_BAR; PG8_SCHED;
;             PG8_LDB(B1, 1, 1); PG8_STAGE(PG8_SB(1, 0), b3);
;             PG8_BAR; PG8_WAIT_L(0); PG8_MMA(0, 1, At, B1); PG8_BAR;
;             PG8_LDA(At, 1, 1); PG8_STAGE(PG8_SA(1, 0), a3);
	v_mfma_f32_16x16x32_bf16 v[52:55], v[234:237], v[194:197], v[52:55]
	v_mfma_f32_16x16x32_bf16 v[48:51], v[242:245], v[194:197], v[48:51]
	v_mfma_f32_16x16x32_bf16 v[36:39], v[234:237], v[202:205], v[36:39]
	v_mfma_f32_16x16x32_bf16 v[32:35], v[242:245], v[202:205], v[32:35]
	v_mfma_f32_16x16x32_bf16 v[20:23], v[234:237], v[210:213], v[20:23]
	v_mfma_f32_16x16x32_bf16 v[16:19], v[242:245], v[210:213], v[16:19]
	v_mfma_f32_16x16x32_bf16 v[4:7], v[234:237], v[226:229], v[4:7]
	v_mfma_f32_16x16x32_bf16 v[0:3], v[242:245], v[226:229], v[0:3]
	v_mfma_f32_16x16x32_bf16 v[52:55], v[238:241], v[198:201], v[52:55]
	s_add_i32 s37, 0, 0x18000
	v_mfma_f32_16x16x32_bf16 v[48:51], v[246:249], v[198:201], v[48:51]
	v_mfma_f32_16x16x32_bf16 v[36:39], v[238:241], v[206:209], v[36:39]
	v_mfma_f32_16x16x32_bf16 v[32:35], v[246:249], v[206:209], v[32:35]
	v_mfma_f32_16x16x32_bf16 v[20:23], v[238:241], v[214:217], v[20:23]
	v_mfma_f32_16x16x32_bf16 v[16:19], v[246:249], v[214:217], v[16:19]
	v_mfma_f32_16x16x32_bf16 v[4:7], v[238:241], v[230:233], v[4:7]
	s_setprio 0
	v_mfma_f32_16x16x32_bf16 v[0:3], v[246:249], v[230:233], v[0:3]
	s_barrier
	ds_read_b128 v[128:131], v187 offset:32768
	ds_read_b128 v[132:135], v187 offset:33792
	ds_read_b128 v[136:139], v187 offset:34816
	ds_read_b128 v[190:193], v187 offset:35840
	s_add_u32 s20, s20, 0x80000
	s_addc_u32 s21, s21, 0
	s_mov_b32 m0, s28
	ds_read_b128 v[194:197], v189 offset:32768
	ds_read_b128 v[198:201], v189 offset:33792
	ds_read_b128 v[202:205], v189 offset:34816
	ds_read_b128 v[206:209], v189 offset:35840
	ds_read_b128 v[210:213], v189 offset:36864
	ds_read_b128 v[214:217], v189 offset:37888
	ds_read_b128 v[226:229], v189 offset:38912
	ds_read_b128 v[230:233], v189 offset:39936
	global_load_lds_dwordx4 v144, s[20:21]
	s_mov_b32 m0, s29
	s_nop 0
	global_load_lds_dwordx4 v142, s[20:21]
	s_waitcnt lgkmcnt(8)
	s_setprio 1
	s_barrier
	s_waitcnt lgkmcnt(0)
	v_mfma_f32_16x16x32_bf16 v[124:127], v[128:131], v[194:197], v[124:127]
	v_mfma_f32_16x16x32_bf16 v[120:123], v[136:139], v[194:197], v[120:123]
	v_mfma_f32_16x16x32_bf16 v[108:111], v[128:131], v[202:205], v[108:111]
	v_mfma_f32_16x16x32_bf16 v[104:107], v[136:139], v[202:205], v[104:107]
	v_mfma_f32_16x16x32_bf16 v[92:95], v[128:131], v[210:213], v[92:95]
	v_mfma_f32_16x16x32_bf16 v[88:91], v[136:139], v[210:213], v[88:91]
	v_mfma_f32_16x16x32_bf16 v[76:79], v[128:131], v[226:229], v[76:79]
	v_mfma_f32_16x16x32_bf16 v[72:75], v[136:139], v[226:229], v[72:75]
	v_mfma_f32_16x16x32_bf16 v[124:127], v[132:135], v[198:201], v[124:127]
	v_mfma_f32_16x16x32_bf16 v[120:123], v[190:193], v[198:201], v[120:123]
	v_mfma_f32_16x16x32_bf16 v[108:111], v[132:135], v[206:209], v[108:111]
	v_mfma_f32_16x16x32_bf16 v[104:107], v[190:193], v[206:209], v[104:107]
	v_mfma_f32_16x16x32_bf16 v[92:95], v[132:135], v[214:217], v[92:95]
	v_mfma_f32_16x16x32_bf16 v[88:91], v[190:193], v[214:217], v[88:91]
	v_mfma_f32_16x16x32_bf16 v[76:79], v[132:135], v[230:233], v[76:79]
	s_setprio 0
	v_mfma_f32_16x16x32_bf16 v[72:75], v[190:193], v[230:233], v[72:75]
	s_barrier
	s_add_i32 s20, 0, 0x1c000
	s_add_i32 s21, s37, s25
	s_add_i32 m0, s21, 0xffffff80
	ds_read_b128 v[234:237], v187 offset:49152
	ds_read_b128 v[238:241], v187 offset:50176
	ds_read_b128 v[242:245], v187 offset:51200
	ds_read_b128 v[246:249], v187 offset:52224
	global_load_lds_dwordx4 v144, s[18:19] offset:128
	s_add_i32 m0, s21, 0x1f80
	s_nop 0
	global_load_lds_dwordx4 v142, s[18:19] offset:128
	s_waitcnt lgkmcnt(0)
	s_setprio 1
	s_barrier
	v_mfma_f32_16x16x32_bf16 v[116:119], v[234:237], v[194:197], v[116:119]
	v_mfma_f32_16x16x32_bf16 v[112:115], v[242:245], v[194:197], v[112:115]
	v_mfma_f32_16x16x32_bf16 v[100:103], v[234:237], v[202:205], v[100:103]
	v_mfma_f32_16x16x32_bf16 v[96:99], v[242:245], v[202:205], v[96:99]
	v_mfma_f32_16x16x32_bf16 v[84:87], v[234:237], v[210:213], v[84:87]
	v_mfma_f32_16x16x32_bf16 v[80:83], v[242:245], v[210:213], v[80:83]
	v_mfma_f32_16x16x32_bf16 v[68:71], v[234:237], v[226:229], v[68:71]
	v_mfma_f32_16x16x32_bf16 v[64:67], v[242:245], v[226:229], v[64:67]
	v_mfma_f32_16x16x32_bf16 v[116:119], v[238:241], v[198:201], v[116:119]
	s_add_i32 m0, s30, 0xffffff80
	v_mfma_f32_16x16x32_bf16 v[112:115], v[246:249], v[198:201], v[112:115]
	v_mfma_f32_16x16x32_bf16 v[100:103], v[238:241], v[206:209], v[100:103]
	v_mfma_f32_16x16x32_bf16 v[96:99], v[246:249], v[206:209], v[96:99]
	v_mfma_f32_16x16x32_bf16 v[84:87], v[238:241], v[214:217], v[84:87]
	v_mfma_f32_16x16x32_bf16 v[80:83], v[246:249], v[214:217], v[80:83]
	v_mfma_f32_16x16x32_bf16 v[68:71], v[238:241], v[230:233], v[68:71]
	s_setprio 0
	v_mfma_f32_16x16x32_bf16 v[64:67], v[246:249], v[230:233], v[64:67]
	s_barrier
; #define PG8_STAGE(bufoff, gbase) do { _Pragma("unroll") for (int _i = 0; _i < 2; ++_i) \
;         __builtin_amdgcn_global_load_lds((const unsigned*)((const char*)(gbase) + voff[_i]), (LAS unsigned*)(lds + (bufoff) + ldsw + _i * 8192), 16, 0, 0); } while (0)
; #define PG8_LDA(dst, b, h) do { _Pragma("unroll") for (int m = 0; m < 4; ++m) _Pragma("unroll") for (int k = 0; k < 2; ++k) dst[m][k] = *(const LAS bf16x8*)(lds + PG8_SA(b, h) + aoff + m * 2048 + k * 1024); } while (0)
; #define PG8_MMA(ai, bj, At, Bt) do { __builtin_amdgcn_s_setprio(1); _Pragma("unroll") for (int m = 0; m < 4; ++m) _Pragma("unroll") for (int n = 0; n < 2; ++n) _Pragma("unroll") for (int k = 0; k < 2; ++k) \
;         acc[ai][bj][m][n] = __builtin_amdgcn_mfma_f32_16x16x32_bf16(Bt[n][k], At[m][k], acc[ai][bj][m][n], 0, 0, 0); __builtin_amdgcn_s_setprio(0); } while (0)
; #define PG8_WAIT_V(n) asm volatile("s_waitcnt vmcnt(" #n ")" ::: "memory")
; #define PG8_WAIT_L(n) asm volatile("s_waitcnt lgkmcnt(" #n ")" ::: "memory")
; #define PG8_BAR __builtin_amdgcn_s_barrier()
; #define PG8_SCHED __builtin_amdgcn_sched_barrier(0)
; template <class Epi>
; DI void gemm_phase(LAS unsigned char* lds, const Gemm g, const StaticOrder& S, const Epi& E) {
;     ...
;             PG8_LDA(At, 1, 1); PG8_STAGE(PG8_SA(1, 0), a3);
;             PG8_BAR; PG8_WAIT_L(0); PG8_MMA(1, 0, At, B0); PG8_BAR; PG8_SCHED;
;             PG8_STAGE(PG8_SB(1, 1), b3 + hstep);
;             PG8_WAIT_V(6); PG8_BAR; PG8_MMA(1, 1, At, B1); PG8_BAR;
;     DI void operator()(const f32x4 (&acc)[2][2][4][2], const Unit& u, int wr, int wc, int fr, int fq) const {
;         const int row0 = u.pm * BM + wr * 64 + fr, col0 = u.pn * BM + wc * 16 + 4 * fq;
;         const bool rot = u.pn < 18;
; #pragma unroll
;         for (int ai = 0; ai < 2; ++ai)
; #pragma unroll
;             for (int m = 0; m < 4; ++m) { const int row = row0 + ai * HALF + m * 16; u16* rowp = O + (size_t)row * NQKV_DIL + col0;
;                 f32x4 c4 = (f32x4){1.f, 1.f, 1.f, 1.f}, s4 = (f32x4){0.f, 0.f, 0.f, 0.f};
;                 if (rot) { const int pos = row & (SEQ - 1); c4 = *(const f32x4*)(cs + pos * 64 + wc * 16 + 4 * fq); s4 = *(const f32x4*)(sn + pos * 64 + wc * 16 + 4 * fq); }
	ds_read_b128 v[194:197], v189 offset:49152
	ds_read_b128 v[198:201], v189 offset:50176
	ds_read_b128 v[202:205], v189 offset:51200
	ds_read_b128 v[206:209], v189 offset:52224
	ds_read_b128 v[210:213], v189 offset:53248
	ds_read_b128 v[214:217], v189 offset:54272
	ds_read_b128 v[226:229], v189 offset:55296
	ds_read_b128 v[230:233], v189 offset:56320
	global_load_lds_dwordx4 v144, s[100:101] offset:128
	s_add_i32 m0, s31, 0xffffff80
	s_nop 0
	global_load_lds_dwordx4 v142, s[100:101] offset:128
	s_waitcnt lgkmcnt(0)
	s_setprio 1
	s_barrier
	v_mfma_f32_16x16x32_bf16 v[60:63], v[128:131], v[194:197], v[60:63]
	v_mfma_f32_16x16x32_bf16 v[56:59], v[136:139], v[194:197], v[56:59]
	v_mfma_f32_16x16x32_bf16 v[44:47], v[128:131], v[202:205], v[44:47]
	v_mfma_f32_16x16x32_bf16 v[40:43], v[136:139], v[202:205], v[40:43]
	v_mfma_f32_16x16x32_bf16 v[28:31], v[128:131], v[210:213], v[28:31]
	v_mfma_f32_16x16x32_bf16 v[24:27], v[136:139], v[210:213], v[24:27]
	v_mfma_f32_16x16x32_bf16 v[12:15], v[128:131], v[226:229], v[12:15]
	v_mfma_f32_16x16x32_bf16 v[8:11], v[136:139], v[226:229], v[8:11]
	v_mfma_f32_16x16x32_bf16 v[60:63], v[132:135], v[198:201], v[60:63]
	v_mfma_f32_16x16x32_bf16 v[56:59], v[190:193], v[198:201], v[56:59]
	v_mfma_f32_16x16x32_bf16 v[44:47], v[132:135], v[206:209], v[44:47]
	v_mfma_f32_16x16x32_bf16 v[40:43], v[190:193], v[206:209], v[40:43]
	v_mfma_f32_16x16x32_bf16 v[28:31], v[132:135], v[214:217], v[28:31]
	v_mfma_f32_16x16x32_bf16 v[24:27], v[190:193], v[214:217], v[24:27]
	v_mfma_f32_16x16x32_bf16 v[12:15], v[132:135], v[230:233], v[12:15]
	s_setprio 0
	v_mfma_f32_16x16x32_bf16 v[8:11], v[190:193], v[230:233], v[8:11]
	s_barrier
	s_add_u32 s18, s18, 0x80080
	s_addc_u32 s19, s19, 0
	s_add_i32 s20, s20, s25
	s_mov_b32 m0, s20
	s_nop 0
	global_load_lds_dwordx4 v144, s[18:19]
	s_add_i32 m0, s20, 0x2000
	s_nop 0
	global_load_lds_dwordx4 v142, s[18:19]
	s_waitcnt vmcnt(6)
	s_setprio 1
	s_barrier
	v_mfma_f32_16x16x32_bf16 v[52:55], v[234:237], v[194:197], v[52:55]
	v_mfma_f32_16x16x32_bf16 v[48:51], v[242:245], v[194:197], v[48:51]
	v_mfma_f32_16x16x32_bf16 v[36:39], v[234:237], v[202:205], v[36:39]
	v_mfma_f32_16x16x32_bf16 v[32:35], v[242:245], v[202:205], v[32:35]
	v_mfma_f32_16x16x32_bf16 v[20:23], v[234:237], v[210:213], v[20:23]
	v_mfma_f32_16x16x32_bf16 v[16:19], v[242:245], v[210:213], v[16:19]
	v_mfma_f32_16x16x32_bf16 v[4:7], v[234:237], v[226:229], v[4:7]
	v_mfma_f32_16x16x32_bf16 v[0:3], v[242:245], v[226:229], v[0:3]
	v_mfma_f32_16x16x32_bf16 v[52:55], v[238:241], v[198:201], v[52:55]
	s_add_i32 s36, s36, 2
	v_mfma_f32_16x16x32_bf16 v[48:51], v[246:249], v[198:201], v[48:51]
	s_add_u32 s8, s8, 0x100
	v_mfma_f32_16x16x32_bf16 v[36:39], v[238:241], v[206:209], v[36:39]
	s_addc_u32 s9, s9, 0
	v_mfma_f32_16x16x32_bf16 v[32:35], v[246:249], v[206:209], v[32:35]
	s_add_u32 s33, s33, 0x100
	v_mfma_f32_16x16x32_bf16 v[20:23], v[238:241], v[214:217], v[20:23]
	s_addc_u32 s35, s35, 0
	v_mfma_f32_16x16x32_bf16 v[16:19], v[246:249], v[214:217], v[16:19]
	s_cmp_gt_u32 s36, 29
	v_mfma_f32_16x16x32_bf16 v[4:7], v[238:241], v[230:233], v[4:7]
	s_setprio 0
	v_mfma_f32_16x16x32_bf16 v[0:3], v[246:249], v[230:233], v[0:3]
	s_barrier
	s_cbranch_scc0 .LBB0_202
	s_cmp_lt_i32 s2, 18
	v_lshl_add_u32 v190, s3, 8, v186
	v_mov_b32_e32 v128, 1.0
	v_mov_b32_e32 v132, 0
	s_cselect_b64 s[18:19], -1, 0
	s_cmp_gt_i32 s2, 17
	v_mov_b32_e32 v134, 0
	v_mov_b32_e32 v135, 0
	v_mov_b32_e32 v136, 0
	v_mov_b32_e32 v137, 0
	v_mov_b32_e32 v138, 1.0
	v_mov_b32_e32 v139, 1.0
	v_mov_b32_e32 v140, 1.0
	v_mov_b32_e32 v141, 1.0
	s_cbranch_scc1 .LBB0_205
	v_lshlrev_b32_e32 v129, 8, v190
	v_and_b32_e32 v158, 0xfcf00, v129
	v_lshl_add_u64 v[130:131], v[146:147], 0, v[158:159]
	v_lshl_add_u64 v[134:135], v[148:149], 0, v[158:159]
	global_load_dwordx4 v[138:141], v[130:131], off
	s_nop 0
	global_load_dwordx4 v[134:137], v[134:135], off

; #define PG8_STAGE(bufoff, gbase) do { _Pragma("unroll") for (int _i = 0; _i < 2; ++_i) \
;         __builtin_amdgcn_global_load_lds((const unsigned*)((const char*)(gbase) + voff[_i]), (LAS unsigned*)(lds + (bufoff) + ldsw + _i * 8192), 16, 0, 0); } while (0)
; #define PG8_LDA(dst, b, h) do { _Pragma("unroll") for (int m = 0; m < 4; ++m) _Pragma("unroll") for (int k = 0; k < 2; ++k) dst[m][k] = *(const LAS bf16x8*)(lds + PG8_SA(b, h) + aoff + m * 2048 + k * 1024); } while (0)
; #define PG8_LDB(dst, b, h) do { _Pragma("unroll") for (int n = 0; n < 2; ++n) _Pragma("unroll") for (int k = 0; k < 2; ++k) dst[n][k] = *(const LAS bf16x8*)(lds + PG8_SB(b, h) + boff + n * 2048 + k * 1024); } while (0)
; #define PG8_MMA(ai, bj, At, Bt) do { __builtin_amdgcn_s_setprio(1); _Pragma("unroll") for (int m = 0; m < 4; ++m) _Pragma("unroll") for (int n = 0; n < 2; ++n) _Pragma("unroll") for (int k = 0; k < 2; ++k) \
;         acc[ai][bj][m][n] = __builtin_amdgcn_mfma_f32_16x16x32_bf16(Bt[n][k], At[m][k], acc[ai][bj][m][n], 0, 0, 0); __builtin_amdgcn_s_setprio(0); } while (0)
; #define PG8_WAIT_V(n) asm volatile("s_waitcnt vmcnt(" #n ")" ::: "memory")
; #define PG8_WAIT_L(n) asm volatile("s_waitcnt lgkmcnt(" #n ")" ::: "memory")
; #define PG8_BAR __builtin_amdgcn_s_barrier()
; #define PG8_SCHED __builtin_amdgcn_sched_barrier(0)
; template <class Epi>
; DI void gemm_phase(LAS unsigned char* lds, const Gemm g, const StaticOrder& S, const Epi& E) {
;     ...
;         for (int t = 0; t < nt; t += 2) {
;             const bool last = (t == nt - 2);
;             const char* a1 = cA + (size_t)(t + 1) * kstep;
;             const char* a2 = last ? nA : cA + (size_t)(t + 2) * kstep; const char* b2 = last ? nB : cB + (size_t)(t + 2) * kstep;
;             const char* a3 = a2 + kstep; const char* b3 = b2 + kstep;
;             PG8_LDB(B0, 0, 0); PG8_SCHED; PG8_LDA(At, 0, 0); PG8_STAGE(PG8_SA(1, 1), a1 + hstep);
;             PG8_WAIT_L(8); PG8_BAR; PG8_WAIT_L(0); PG8_MMA(0, 0, At, B0); PG8_BAR; PG8_SCHED;
;             PG8_LDB(B1, 0, 1); PG8_STAGE(PG8_SB(0, 0), b2);
;             PG8_BAR; PG8_WAIT_L(0); PG8_MMA(0, 1, At, B1); PG8_BAR;
;             PG8_LDA(At, 0, 1); PG8_STAGE(PG8_SA(0, 0), a2);
;             PG8_BAR; PG8_WAIT_L(0); PG8_MMA(1, 0, At, B0); PG8_BAR; PG8_SCHED;
;             PG8_STAGE(PG8_SB(0, 1), b2 + hstep);
;             PG8_WAIT_V(6); PG8_BAR; PG8_MMA(1, 1, At, B1); PG8_BAR;
.LBB0_231:
	s_add_u32 s18, s16, 0xfff80080
	s_addc_u32 s19, s17, -1
	s_add_i32 s37, 0, 0x10000
	ds_read_b128 v[138:141], v135
	ds_read_b128 v[142:145], v135 offset:1024
	ds_read_b128 v[146:149], v135 offset:2048
	ds_read_b128 v[150:153], v135 offset:3072
	s_cmp_eq_u32 s36, 28
	s_cselect_b32 s21, s4, s19
	s_cselect_b32 s20, s5, s18
	s_cselect_b32 s19, s9, s35
	s_cselect_b32 s18, s11, s34
	s_add_i32 m0, s24, 0xc000
	ds_read_b128 v[186:189], v137
	ds_read_b128 v[190:193], v137 offset:1024
	ds_read_b128 v[194:197], v137 offset:2048
	ds_read_b128 v[198:201], v137 offset:3072
	ds_read_b128 v[202:205], v137 offset:4096
	ds_read_b128 v[206:209], v137 offset:5120
	ds_read_b128 v[210:213], v137 offset:6144
	ds_read_b128 v[214:217], v137 offset:7168
	global_load_lds_dwordx4 v130, s[16:17]
	s_add_i32 m0, s24, 0xe000
	s_nop 0
	global_load_lds_dwordx4 v132, s[16:17]
	s_waitcnt lgkmcnt(8)
	s_setprio 1
	s_barrier
	s_waitcnt lgkmcnt(0)
	v_mfma_f32_16x16x32_bf16 v[124:127], v[138:141], v[186:189], v[124:127]
	v_mfma_f32_16x16x32_bf16 v[120:123], v[146:149], v[186:189], v[120:123]
	v_mfma_f32_16x16x32_bf16 v[116:119], v[138:141], v[194:197], v[116:119]
	v_mfma_f32_16x16x32_bf16 v[112:115], v[146:149], v[194:197], v[112:115]
	v_mfma_f32_16x16x32_bf16 v[100:103], v[138:141], v[202:205], v[100:103]
	v_mfma_f32_16x16x32_bf16 v[96:99], v[146:149], v[202:205], v[96:99]
	v_mfma_f32_16x16x32_bf16 v[84:87], v[138:141], v[210:213], v[84:87]
	v_mfma_f32_16x16x32_bf16 v[80:83], v[146:149], v[210:213], v[80:83]
	v_mfma_f32_16x16x32_bf16 v[124:127], v[142:145], v[190:193], v[124:127]
	v_mfma_f32_16x16x32_bf16 v[120:123], v[150:153], v[190:193], v[120:123]
	v_mfma_f32_16x16x32_bf16 v[116:119], v[142:145], v[198:201], v[116:119]
	v_mfma_f32_16x16x32_bf16 v[112:115], v[150:153], v[198:201], v[112:115]
	v_mfma_f32_16x16x32_bf16 v[100:103], v[142:145], v[206:209], v[100:103]
	v_mfma_f32_16x16x32_bf16 v[96:99], v[150:153], v[206:209], v[96:99]
	v_mfma_f32_16x16x32_bf16 v[84:87], v[142:145], v[214:217], v[84:87]
	s_setprio 0
	v_mfma_f32_16x16x32_bf16 v[80:83], v[150:153], v[214:217], v[80:83]
	s_barrier
	s_add_i32 s40, 0, 0x14000
	s_add_i32 s37, s37, s23
	ds_read_b128 v[226:229], v135 offset:16384
	ds_read_b128 v[230:233], v135 offset:17408
	ds_read_b128 v[234:237], v135 offset:18432
	ds_read_b128 v[238:241], v135 offset:19456
	s_mov_b32 m0, s37
	s_nop 0
	global_load_lds_dwordx4 v158, s[18:19]
	s_add_i32 m0, s37, 0x2000
	s_nop 0
	global_load_lds_dwordx4 v128, s[18:19]
	s_waitcnt lgkmcnt(0)
	s_setprio 1
	s_barrier
	v_mfma_f32_16x16x32_bf16 v[108:111], v[226:229], v[186:189], v[108:111]
	v_mfma_f32_16x16x32_bf16 v[104:107], v[234:237], v[186:189], v[104:107]
	v_mfma_f32_16x16x32_bf16 v[92:95], v[226:229], v[194:197], v[92:95]
	v_mfma_f32_16x16x32_bf16 v[88:91], v[234:237], v[194:197], v[88:91]
	v_mfma_f32_16x16x32_bf16 v[76:79], v[226:229], v[202:205], v[76:79]
	v_mfma_f32_16x16x32_bf16 v[72:75], v[234:237], v[202:205], v[72:75]
	v_mfma_f32_16x16x32_bf16 v[68:71], v[226:229], v[210:213], v[68:71]
	v_mfma_f32_16x16x32_bf16 v[64:67], v[234:237], v[210:213], v[64:67]
	v_mfma_f32_16x16x32_bf16 v[108:111], v[230:233], v[190:193], v[108:111]
	s_mov_b32 m0, s24
	v_mfma_f32_16x16x32_bf16 v[104:107], v[238:241], v[190:193], v[104:107]
	s_mov_b64 s[100:101], s[20:21]
	v_mfma_f32_16x16x32_bf16 v[92:95], v[230:233], v[198:201], v[92:95]
	v_mfma_f32_16x16x32_bf16 v[88:91], v[238:241], v[198:201], v[88:91]
	v_mfma_f32_16x16x32_bf16 v[76:79], v[230:233], v[206:209], v[76:79]
	v_mfma_f32_16x16x32_bf16 v[72:75], v[238:241], v[206:209], v[72:75]
	v_mfma_f32_16x16x32_bf16 v[68:71], v[230:233], v[214:217], v[68:71]
	s_setprio 0
	v_mfma_f32_16x16x32_bf16 v[64:67], v[238:241], v[214:217], v[64:67]
	s_barrier
	ds_read_b128 v[186:189], v137 offset:16384
	ds_read_b128 v[190:193], v137 offset:17408
	ds_read_b128 v[194:197], v137 offset:18432
	ds_read_b128 v[198:201], v137 offset:19456
	ds_read_b128 v[202:205], v137 offset:20480
	ds_read_b128 v[206:209], v137 offset:21504
	ds_read_b128 v[210:213], v137 offset:22528
	ds_read_b128 v[214:217], v137 offset:23552
	global_load_lds_dwordx4 v158, s[20:21]
	s_mov_b64 s[100:101], s[20:21]
	s_mov_b32 m0, s25
	s_nop 0
	global_load_lds_dwordx4 v128, s[20:21]
	s_waitcnt lgkmcnt(0)
	s_setprio 1
	s_barrier
	v_mfma_f32_16x16x32_bf16 v[60:63], v[138:141], v[186:189], v[60:63]
	v_mfma_f32_16x16x32_bf16 v[56:59], v[146:149], v[186:189], v[56:59]
	v_mfma_f32_16x16x32_bf16 v[52:55], v[138:141], v[194:197], v[52:55]
	v_mfma_f32_16x16x32_bf16 v[48:51], v[146:149], v[194:197], v[48:51]
	v_mfma_f32_16x16x32_bf16 v[36:39], v[138:141], v[202:205], v[36:39]
	v_mfma_f32_16x16x32_bf16 v[32:35], v[146:149], v[202:205], v[32:35]
	v_mfma_f32_16x16x32_bf16 v[20:23], v[138:141], v[210:213], v[20:23]
	v_mfma_f32_16x16x32_bf16 v[16:19], v[146:149], v[210:213], v[16:19]
	v_mfma_f32_16x16x32_bf16 v[60:63], v[142:145], v[190:193], v[60:63]
	v_mfma_f32_16x16x32_bf16 v[56:59], v[150:153], v[190:193], v[56:59]
	v_mfma_f32_16x16x32_bf16 v[52:55], v[142:145], v[198:201], v[52:55]
	v_mfma_f32_16x16x32_bf16 v[48:51], v[150:153], v[198:201], v[48:51]
	v_mfma_f32_16x16x32_bf16 v[36:39], v[142:145], v[206:209], v[36:39]
	v_mfma_f32_16x16x32_bf16 v[32:35], v[150:153], v[206:209], v[32:35]
	v_mfma_f32_16x16x32_bf16 v[20:23], v[142:145], v[214:217], v[20:23]
	s_setprio 0
	v_mfma_f32_16x16x32_bf16 v[16:19], v[150:153], v[214:217], v[16:19]
	s_barrier
	s_add_u32 s38, s18, 0x80000
	s_addc_u32 s39, s19, 0
	s_add_i32 s37, s40, s23
	s_mov_b32 m0, s37
	s_nop 0
	global_load_lds_dwordx4 v158, s[38:39]
	s_add_i32 m0, s37, 0x2000
	s_nop 0
	global_load_lds_dwordx4 v128, s[38:39]
	s_waitcnt vmcnt(6)
	s_setprio 1
	s_barrier
; #define PG8_STAGE(bufoff, gbase) do { _Pragma("unroll") for (int _i = 0; _i < 2; ++_i) \
;         __builtin_amdgcn_global_load_lds((const unsigned*)((const char*)(gbase) + voff[_i]), (LAS unsigned*)(lds + (bufoff) + ldsw + _i * 8192), 16, 0, 0); } while (0)
; #define PG8_LDA(dst, b, h) do { _Pragma("unroll") for (int m = 0; m < 4; ++m) _Pragma("unroll") for (int k = 0; k < 2; ++k) dst[m][k] = *(const LAS bf16x8*)(lds + PG8_SA(b, h) + aoff + m * 2048 + k * 1024); } while (0)
; #define PG8_LDB(dst, b, h) do { _Pragma("unroll") for (int n = 0; n < 2; ++n) _Pragma("unroll") for (int k = 0; k < 2; ++k) dst[n][k] = *(const LAS bf16x8*)(lds + PG8_SB(b, h) + boff + n * 2048 + k * 1024); } while (0)
; #define PG8_MMA(ai, bj, At, Bt) do { __builtin_amdgcn_s_setprio(1); _Pragma("unroll") for (int m = 0; m < 4; ++m) _Pragma("unroll") for (int n = 0; n < 2; ++n) _Pragma("unroll") for (int k = 0; k < 2; ++k) \
;         acc[ai][bj][m][n] = __builtin_amdgcn_mfma_f32_16x16x32_bf16(Bt[n][k], At[m][k], acc[ai][bj][m][n], 0, 0, 0); __builtin_amdgcn_s_setprio(0); } while (0)
; #define PG8_WAIT_V(n) asm volatile("s_waitcnt vmcnt(" #n ")" ::: "memory")
; #define PG8_WAIT_L(n) asm volatile("s_waitcnt lgkmcnt(" #n ")" ::: "memory")
; #define PG8_BAR __builtin_amdgcn_s_barrier()
; #define PG8_SCHED __builtin_amdgcn_sched_barrier(0)
; template <class Epi>
; DI void gemm_phase(LAS unsigned char* lds, const Gemm g, const StaticOrder& S, const Epi& E) {
;     ...
;             PG8_WAIT_V(6); PG8_BAR; PG8_MMA(1, 1, At, B1); PG8_BAR;
;             PG8_LDB(B0, 1, 0); PG8_SCHED; PG8_LDA(At, 1, 0); PG8_STAGE(PG8_SA(0, 1), a2 + hstep);
;             PG8_WAIT_L(8); PG8_BAR; PG8_WAIT_L(0); PG8_MMA(0, 0, At, B0); PG8_BAR; PG8_SCHED;
;             PG8_LDB(B1, 1, 1); PG8_STAGE(PG8_SB(1, 0), b3);
;             PG8_BAR; PG8_WAIT_L(0); PG8_MMA(0, 1, At, B1); PG8_BAR;
;             PG8_LDA(At, 1, 1); PG8_STAGE(PG8_SA(1, 0), a3);
	v_mfma_f32_16x16x32_bf16 v[44:47], v[226:229], v[186:189], v[44:47]
	v_mfma_f32_16x16x32_bf16 v[40:43], v[234:237], v[186:189], v[40:43]
	v_mfma_f32_16x16x32_bf16 v[28:31], v[226:229], v[194:197], v[28:31]
	v_mfma_f32_16x16x32_bf16 v[24:27], v[234:237], v[194:197], v[24:27]
	v_mfma_f32_16x16x32_bf16 v[12:15], v[226:229], v[202:205], v[12:15]
	v_mfma_f32_16x16x32_bf16 v[8:11], v[234:237], v[202:205], v[8:11]
	v_mfma_f32_16x16x32_bf16 v[4:7], v[226:229], v[210:213], v[4:7]
	v_mfma_f32_16x16x32_bf16 v[0:3], v[234:237], v[210:213], v[0:3]
	v_mfma_f32_16x16x32_bf16 v[44:47], v[230:233], v[190:193], v[44:47]
	s_add_i32 s37, 0, 0x18000
	v_mfma_f32_16x16x32_bf16 v[40:43], v[238:241], v[190:193], v[40:43]
	v_mfma_f32_16x16x32_bf16 v[28:31], v[230:233], v[198:201], v[28:31]
	v_mfma_f32_16x16x32_bf16 v[24:27], v[238:241], v[198:201], v[24:27]
	v_mfma_f32_16x16x32_bf16 v[12:15], v[230:233], v[206:209], v[12:15]
	v_mfma_f32_16x16x32_bf16 v[8:11], v[238:241], v[206:209], v[8:11]
	v_mfma_f32_16x16x32_bf16 v[4:7], v[230:233], v[214:217], v[4:7]
	s_setprio 0
	v_mfma_f32_16x16x32_bf16 v[0:3], v[238:241], v[214:217], v[0:3]
	s_barrier
	ds_read_b128 v[138:141], v135 offset:32768
	ds_read_b128 v[142:145], v135 offset:33792
	ds_read_b128 v[146:149], v135 offset:34816
	ds_read_b128 v[150:153], v135 offset:35840
	s_add_u32 s20, s20, 0x80000
	s_addc_u32 s21, s21, 0
	s_mov_b32 m0, s26
	ds_read_b128 v[186:189], v137 offset:32768
	ds_read_b128 v[190:193], v137 offset:33792
	ds_read_b128 v[194:197], v137 offset:34816
	ds_read_b128 v[198:201], v137 offset:35840
	ds_read_b128 v[202:205], v137 offset:36864
	ds_read_b128 v[206:209], v137 offset:37888
	ds_read_b128 v[210:213], v137 offset:38912
	ds_read_b128 v[214:217], v137 offset:39936
	global_load_lds_dwordx4 v158, s[20:21]
	s_mov_b32 m0, s27
	s_nop 0
	global_load_lds_dwordx4 v128, s[20:21]
	s_waitcnt lgkmcnt(8)
	s_setprio 1
	s_barrier
	s_waitcnt lgkmcnt(0)
	v_mfma_f32_16x16x32_bf16 v[124:127], v[138:141], v[186:189], v[124:127]
	v_mfma_f32_16x16x32_bf16 v[120:123], v[146:149], v[186:189], v[120:123]
	v_mfma_f32_16x16x32_bf16 v[116:119], v[138:141], v[194:197], v[116:119]
	v_mfma_f32_16x16x32_bf16 v[112:115], v[146:149], v[194:197], v[112:115]
	v_mfma_f32_16x16x32_bf16 v[100:103], v[138:141], v[202:205], v[100:103]
	v_mfma_f32_16x16x32_bf16 v[96:99], v[146:149], v[202:205], v[96:99]
	v_mfma_f32_16x16x32_bf16 v[84:87], v[138:141], v[210:213], v[84:87]
	v_mfma_f32_16x16x32_bf16 v[80:83], v[146:149], v[210:213], v[80:83]
	v_mfma_f32_16x16x32_bf16 v[124:127], v[142:145], v[190:193], v[124:127]
	v_mfma_f32_16x16x32_bf16 v[120:123], v[150:153], v[190:193], v[120:123]
	v_mfma_f32_16x16x32_bf16 v[116:119], v[142:145], v[198:201], v[116:119]
	v_mfma_f32_16x16x32_bf16 v[112:115], v[150:153], v[198:201], v[112:115]
	v_mfma_f32_16x16x32_bf16 v[100:103], v[142:145], v[206:209], v[100:103]
	v_mfma_f32_16x16x32_bf16 v[96:99], v[150:153], v[206:209], v[96:99]
	v_mfma_f32_16x16x32_bf16 v[84:87], v[142:145], v[214:217], v[84:87]
	s_setprio 0
	v_mfma_f32_16x16x32_bf16 v[80:83], v[150:153], v[214:217], v[80:83]
	s_barrier
	s_add_i32 s20, 0, 0x1c000
	s_add_i32 s21, s37, s23
	s_add_i32 m0, s21, 0xffffff80
	ds_read_b128 v[226:229], v135 offset:49152
	ds_read_b128 v[230:233], v135 offset:50176
	ds_read_b128 v[234:237], v135 offset:51200
	ds_read_b128 v[238:241], v135 offset:52224
	global_load_lds_dwordx4 v158, s[18:19] offset:128
	s_add_i32 m0, s21, 0x1f80
	s_nop 0
	global_load_lds_dwordx4 v128, s[18:19] offset:128
	s_waitcnt lgkmcnt(0)
	s_setprio 1
	s_barrier
	v_mfma_f32_16x16x32_bf16 v[108:111], v[226:229], v[186:189], v[108:111]
	v_mfma_f32_16x16x32_bf16 v[104:107], v[234:237], v[186:189], v[104:107]
	v_mfma_f32_16x16x32_bf16 v[92:95], v[226:229], v[194:197], v[92:95]
	v_mfma_f32_16x16x32_bf16 v[88:91], v[234:237], v[194:197], v[88:91]
	v_mfma_f32_16x16x32_bf16 v[76:79], v[226:229], v[202:205], v[76:79]
	v_mfma_f32_16x16x32_bf16 v[72:75], v[234:237], v[202:205], v[72:75]
	v_mfma_f32_16x16x32_bf16 v[68:71], v[226:229], v[210:213], v[68:71]
	v_mfma_f32_16x16x32_bf16 v[64:67], v[234:237], v[210:213], v[64:67]
	v_mfma_f32_16x16x32_bf16 v[108:111], v[230:233], v[190:193], v[108:111]
	s_add_i32 m0, s28, 0xffffff80
	v_mfma_f32_16x16x32_bf16 v[104:107], v[238:241], v[190:193], v[104:107]
	v_mfma_f32_16x16x32_bf16 v[92:95], v[230:233], v[198:201], v[92:95]
	v_mfma_f32_16x16x32_bf16 v[88:91], v[238:241], v[198:201], v[88:91]
	v_mfma_f32_16x16x32_bf16 v[76:79], v[230:233], v[206:209], v[76:79]
	v_mfma_f32_16x16x32_bf16 v[72:75], v[238:241], v[206:209], v[72:75]
	v_mfma_f32_16x16x32_bf16 v[68:71], v[230:233], v[214:217], v[68:71]
	s_setprio 0
	v_mfma_f32_16x16x32_bf16 v[64:67], v[238:241], v[214:217], v[64:67]
	s_barrier
	ds_read_b128 v[186:189], v137 offset:49152
	ds_read_b128 v[190:193], v137 offset:50176
	ds_read_b128 v[194:197], v137 offset:51200
	ds_read_b128 v[198:201], v137 offset:52224
	ds_read_b128 v[202:205], v137 offset:53248
	ds_read_b128 v[206:209], v137 offset:54272
	ds_read_b128 v[210:213], v137 offset:55296
	ds_read_b128 v[214:217], v137 offset:56320
	global_load_lds_dwordx4 v158, s[100:101] offset:128
	s_add_i32 m0, s29, 0xffffff80
	s_nop 0
	global_load_lds_dwordx4 v128, s[100:101] offset:128
	s_waitcnt lgkmcnt(0)
	s_setprio 1
	s_barrier
; #define PG8_STAGE(bufoff, gbase) do { _Pragma("unroll") for (int _i = 0; _i < 2; ++_i) \
;         __builtin_amdgcn_global_load_lds((const unsigned*)((const char*)(gbase) + voff[_i]), (LAS unsigned*)(lds + (bufoff) + ldsw + _i * 8192), 16, 0, 0); } while (0)
; #define PG8_MMA(ai, bj, At, Bt) do { __builtin_amdgcn_s_setprio(1); _Pragma("unroll") for (int m = 0; m < 4; ++m) _Pragma("unroll") for (int n = 0; n < 2; ++n) _Pragma("unroll") for (int k = 0; k < 2; ++k) \
;         acc[ai][bj][m][n] = __builtin_amdgcn_mfma_f32_16x16x32_bf16(Bt[n][k], At[m][k], acc[ai][bj][m][n], 0, 0, 0); __builtin_amdgcn_s_setprio(0); } while (0)
; #define PG8_WAIT_V(n) asm volatile("s_waitcnt vmcnt(" #n ")" ::: "memory")
; #define PG8_WAIT_L(n) asm volatile("s_waitcnt lgkmcnt(" #n ")" ::: "memory")
; #define PG8_BAR __builtin_amdgcn_s_barrier()
; #define PG8_SCHED __builtin_amdgcn_sched_barrier(0)
; template <class Epi>
; DI void gemm_phase(LAS unsigned char* lds, const Gemm g, const StaticOrder& S, const Epi& E) {
;     ...
;             PG8_BAR; PG8_WAIT_L(0); PG8_MMA(1, 0, At, B0); PG8_BAR; PG8_SCHED;
;             PG8_STAGE(PG8_SB(1, 1), b3 + hstep);
;             PG8_WAIT_V(6); PG8_BAR; PG8_MMA(1, 1, At, B1); PG8_BAR;
	v_mfma_f32_16x16x32_bf16 v[60:63], v[138:141], v[186:189], v[60:63]
	v_mfma_f32_16x16x32_bf16 v[56:59], v[146:149], v[186:189], v[56:59]
	v_mfma_f32_16x16x32_bf16 v[52:55], v[138:141], v[194:197], v[52:55]
	v_mfma_f32_16x16x32_bf16 v[48:51], v[146:149], v[194:197], v[48:51]
	v_mfma_f32_16x16x32_bf16 v[36:39], v[138:141], v[202:205], v[36:39]
	v_mfma_f32_16x16x32_bf16 v[32:35], v[146:149], v[202:205], v[32:35]
	v_mfma_f32_16x16x32_bf16 v[20:23], v[138:141], v[210:213], v[20:23]
	v_mfma_f32_16x16x32_bf16 v[16:19], v[146:149], v[210:213], v[16:19]
	v_mfma_f32_16x16x32_bf16 v[60:63], v[142:145], v[190:193], v[60:63]
	v_mfma_f32_16x16x32_bf16 v[56:59], v[150:153], v[190:193], v[56:59]
	v_mfma_f32_16x16x32_bf16 v[52:55], v[142:145], v[198:201], v[52:55]
	v_mfma_f32_16x16x32_bf16 v[48:51], v[150:153], v[198:201], v[48:51]
	v_mfma_f32_16x16x32_bf16 v[36:39], v[142:145], v[206:209], v[36:39]
	v_mfma_f32_16x16x32_bf16 v[32:35], v[150:153], v[206:209], v[32:35]
	v_mfma_f32_16x16x32_bf16 v[20:23], v[142:145], v[214:217], v[20:23]
	s_setprio 0
	v_mfma_f32_16x16x32_bf16 v[16:19], v[150:153], v[214:217], v[16:19]
	s_barrier
	s_add_u32 s18, s18, 0x80080
	s_addc_u32 s19, s19, 0
	s_add_i32 s20, s20, s23
	s_mov_b32 m0, s20
	s_nop 0
	global_load_lds_dwordx4 v158, s[18:19]
	s_add_i32 m0, s20, 0x2000
	s_nop 0
	global_load_lds_dwordx4 v128, s[18:19]
	s_waitcnt vmcnt(6)
	s_setprio 1
	s_barrier
	v_mfma_f32_16x16x32_bf16 v[44:47], v[226:229], v[186:189], v[44:47]
	v_mfma_f32_16x16x32_bf16 v[40:43], v[234:237], v[186:189], v[40:43]
	v_mfma_f32_16x16x32_bf16 v[28:31], v[226:229], v[194:197], v[28:31]
	v_mfma_f32_16x16x32_bf16 v[24:27], v[234:237], v[194:197], v[24:27]
	v_mfma_f32_16x16x32_bf16 v[12:15], v[226:229], v[202:205], v[12:15]
	v_mfma_f32_16x16x32_bf16 v[8:11], v[234:237], v[202:205], v[8:11]
	v_mfma_f32_16x16x32_bf16 v[4:7], v[226:229], v[210:213], v[4:7]
	v_mfma_f32_16x16x32_bf16 v[0:3], v[234:237], v[210:213], v[0:3]
	v_mfma_f32_16x16x32_bf16 v[44:47], v[230:233], v[190:193], v[44:47]
	s_add_i32 s36, s36, 2
	v_mfma_f32_16x16x32_bf16 v[40:43], v[238:241], v[190:193], v[40:43]
	s_add_u32 s16, s16, 0x100
	v_mfma_f32_16x16x32_bf16 v[28:31], v[230:233], v[198:201], v[28:31]
	s_addc_u32 s17, s17, 0
	v_mfma_f32_16x16x32_bf16 v[24:27], v[238:241], v[198:201], v[24:27]
	s_add_u32 s34, s34, 0x100
	v_mfma_f32_16x16x32_bf16 v[12:15], v[230:233], v[206:209], v[12:15]
	s_addc_u32 s35, s35, 0
	v_mfma_f32_16x16x32_bf16 v[8:11], v[238:241], v[206:209], v[8:11]
	s_cmp_gt_u32 s36, 29
	v_mfma_f32_16x16x32_bf16 v[4:7], v[230:233], v[214:217], v[4:7]
	s_setprio 0
	v_mfma_f32_16x16x32_bf16 v[0:3], v[238:241], v[214:217], v[0:3]
	s_barrier
	s_cbranch_scc0 .LBB0_231
; #define PG8_WAIT_V(n) asm volatile("s_waitcnt vmcnt(" #n ")" ::: "memory")
; #define PG8_BAR __builtin_amdgcn_s_barrier()
; template <class Epi>
; DI void gemm_phase(LAS unsigned char* lds, const Gemm g, const StaticOrder& S, const Epi& E) {
;     ...
;         cur = nxt; cA = nA; cB = nB; ++ui;
;     }
;     PG8_WAIT_V(0);
;     if (wr == 0) PG8_BAR;
;     DI void operator()(const f32x4 (&acc)[2][2][4][2], const Unit& u, int wr, int wc, int fr, int fq) const {
;         const int row0 = u.pm * BM + wr * 64 + fr, col0 = u.pn * BM + wc * 32 + 8 * fq;
; #pragma unroll
;         for (int ai = 0; ai < 2; ++ai)
; #pragma unroll
;             for (int m = 0; m < 4; ++m) { u16* rowp = O + (size_t)(row0 + ai * HALF + m * 16) * ldc + col0;
; #pragma unroll
;                 for (int bj = 0; bj < 2; ++bj) { const f32x4 v0 = acc[ai][bj][m][0], v1 = acc[ai][bj][m][1];
;                     *(u32x4*)(rowp + bj * HALF) = (u32x4){pk(v0[0], v0[1]), pk(v0[2], v0[3]), pk(v1[0], v1[1]), pk(v1[2], v1[3])}; } }
	v_lshl_add_u32 v144, s33, 8, v134
	v_lshl_or_b32 v138, s31, 8, v136
	v_ashrrev_i32_e32 v139, 31, v138
	v_mov_b64_e32 v[140:141], s[50:51]
	s_movk_i32 s9, 0x3000
	v_cvt_pk_bf16_f32 v68, v68, v69
	v_cvt_pk_bf16_f32 v69, v70, v71
	v_cvt_pk_bf16_f32 v70, v64, v65
	v_add_u32_e32 v64, 0x80, v144
	v_mad_i64_i32 v[142:143], s[4:5], v144, s9, v[140:141]
	v_lshlrev_b64 v[138:139], 1, v[138:139]
	v_cvt_pk_bf16_f32 v108, v108, v109
	v_cvt_pk_bf16_f32 v109, v110, v111
	v_cvt_pk_bf16_f32 v110, v104, v105
	v_or_b32_e32 v104, 16, v144
	v_mad_i64_i32 v[64:65], s[4:5], v64, s9, v[140:141]
	v_cvt_pk_bf16_f32 v44, v44, v45
	v_cvt_pk_bf16_f32 v45, v46, v47
	v_cvt_pk_bf16_f32 v46, v40, v41
	v_add_u32_e32 v40, 0x90, v144
	v_lshl_add_u64 v[142:143], v[142:143], 0, v[138:139]
	v_cvt_pk_bf16_f32 v111, v106, v107
	v_mad_i64_i32 v[104:105], s[4:5], v104, s9, v[140:141]
	v_cvt_pk_bf16_f32 v92, v92, v93
	v_cvt_pk_bf16_f32 v93, v94, v95
	v_cvt_pk_bf16_f32 v94, v88, v89
	v_or_b32_e32 v88, 32, v144
	v_lshl_add_u64 v[64:65], v[64:65], 0, v[138:139]
	v_cvt_pk_bf16_f32 v47, v42, v43
	v_mad_i64_i32 v[40:41], s[4:5], v40, s9, v[140:141]
	v_cvt_pk_bf16_f32 v28, v28, v29
	v_cvt_pk_bf16_f32 v29, v30, v31
	v_cvt_pk_bf16_f32 v30, v24, v25
	v_add_u32_e32 v24, 0xa0, v144
	global_store_dwordx4 v[142:143], v[108:111], off offset:256
	v_cvt_pk_bf16_f32 v95, v90, v91
	v_mad_i64_i32 v[88:89], s[4:5], v88, s9, v[140:141]
	v_lshl_add_u64 v[108:109], v[104:105], 0, v[138:139]
	v_cvt_pk_bf16_f32 v76, v76, v77
	v_cvt_pk_bf16_f32 v77, v78, v79
	v_cvt_pk_bf16_f32 v78, v72, v73
	v_or_b32_e32 v72, 48, v144
	global_store_dwordx4 v[64:65], v[44:47], off offset:256
	v_cvt_pk_bf16_f32 v31, v26, v27
	v_mad_i64_i32 v[24:25], s[4:5], v24, s9, v[140:141]
	v_lshl_add_u64 v[44:45], v[40:41], 0, v[138:139]
	v_cvt_pk_bf16_f32 v12, v12, v13
	v_cvt_pk_bf16_f32 v13, v14, v15
	v_cvt_pk_bf16_f32 v14, v8, v9
	v_add_u32_e32 v8, 0xb0, v144
	global_store_dwordx4 v[108:109], v[92:95], off offset:256
	v_cvt_pk_bf16_f32 v79, v74, v75
	v_mad_i64_i32 v[72:73], s[4:5], v72, s9, v[140:141]
	v_lshl_add_u64 v[92:93], v[88:89], 0, v[138:139]
	global_store_dwordx4 v[44:45], v[28:31], off offset:256
	v_cvt_pk_bf16_f32 v15, v10, v11
	v_mad_i64_i32 v[8:9], s[4:5], v8, s9, v[140:141]
	v_lshl_add_u64 v[28:29], v[24:25], 0, v[138:139]
	v_cvt_pk_bf16_f32 v124, v124, v125
	v_cvt_pk_bf16_f32 v125, v126, v127
	v_cvt_pk_bf16_f32 v126, v120, v121
	v_cvt_pk_bf16_f32 v127, v122, v123
	v_cvt_pk_bf16_f32 v104, v116, v117
	v_cvt_pk_bf16_f32 v105, v118, v119
	v_cvt_pk_bf16_f32 v106, v112, v113
	v_cvt_pk_bf16_f32 v107, v114, v115
	v_cvt_pk_bf16_f32 v88, v100, v101
	v_cvt_pk_bf16_f32 v89, v102, v103
	v_cvt_pk_bf16_f32 v90, v96, v97
	v_cvt_pk_bf16_f32 v91, v98, v99
	global_store_dwordx4 v[92:93], v[76:79], off offset:256
	v_cvt_pk_bf16_f32 v74, v80, v81
	v_cvt_pk_bf16_f32 v75, v82, v83
	v_lshl_add_u64 v[76:77], v[72:73], 0, v[138:139]
	v_cvt_pk_bf16_f32 v72, v84, v85
	v_cvt_pk_bf16_f32 v73, v86, v87
	v_cvt_pk_bf16_f32 v71, v66, v67
	v_cvt_pk_bf16_f32 v60, v60, v61
	v_cvt_pk_bf16_f32 v61, v62, v63
	v_cvt_pk_bf16_f32 v62, v56, v57
	v_cvt_pk_bf16_f32 v63, v58, v59
	v_cvt_pk_bf16_f32 v40, v52, v53
	v_cvt_pk_bf16_f32 v41, v54, v55
	v_cvt_pk_bf16_f32 v42, v48, v49
	v_cvt_pk_bf16_f32 v43, v50, v51
	v_cvt_pk_bf16_f32 v24, v36, v37
	v_cvt_pk_bf16_f32 v25, v38, v39
	v_cvt_pk_bf16_f32 v26, v32, v33
	v_cvt_pk_bf16_f32 v27, v34, v35
	global_store_dwordx4 v[28:29], v[12:15], off offset:256
	v_cvt_pk_bf16_f32 v10, v16, v17
	v_cvt_pk_bf16_f32 v11, v18, v19
	v_lshl_add_u64 v[12:13], v[8:9], 0, v[138:139]
	v_cvt_pk_bf16_f32 v8, v20, v21
	v_cvt_pk_bf16_f32 v9, v22, v23
	v_cvt_pk_bf16_f32 v4, v4, v5
	v_cvt_pk_bf16_f32 v5, v6, v7
	v_cvt_pk_bf16_f32 v6, v0, v1
	v_cvt_pk_bf16_f32 v7, v2, v3
	s_and_b64 vcc, exec, s[6:7]
	s_mov_b32 s31, s8
	s_mov_b32 s33, s10
	s_mov_b64 s[18:19], s[14:15]
	s_mov_b64 s[16:17], s[12:13]
	global_store_dwordx4 v[142:143], v[124:127], off
	global_store_dwordx4 v[108:109], v[104:107], off
	global_store_dwordx4 v[92:93], v[88:91], off
	global_store_dwordx4 v[76:77], v[72:75], off
	global_store_dwordx4 v[76:77], v[68:71], off offset:256
	global_store_dwordx4 v[64:65], v[60:63], off
	global_store_dwordx4 v[44:45], v[40:43], off
	global_store_dwordx4 v[28:29], v[24:27], off
	global_store_dwordx4 v[12:13], v[8:11], off
	global_store_dwordx4 v[12:13], v[4:7], off offset:256
	s_cbranch_vccz .LBB0_228
	s_waitcnt vmcnt(0)
	s_cmpk_gt_u32 s2, 0xff
	s_cbranch_scc1 .LBB0_235
	s_barrier

; #define PG8_STAGE(bufoff, gbase) do { _Pragma("unroll") for (int _i = 0; _i < 2; ++_i) \
;         __builtin_amdgcn_global_load_lds((const unsigned*)((const char*)(gbase) + voff[_i]), (LAS unsigned*)(lds + (bufoff) + ldsw + _i * 8192), 16, 0, 0); } while (0)
; #define PG8_LDA(dst, b, h) do { _Pragma("unroll") for (int m = 0; m < 4; ++m) _Pragma("unroll") for (int k = 0; k < 2; ++k) dst[m][k] = *(const LAS bf16x8*)(lds + PG8_SA(b, h) + aoff + m * 2048 + k * 1024); } while (0)
; #define PG8_LDB(dst, b, h) do { _Pragma("unroll") for (int n = 0; n < 2; ++n) _Pragma("unroll") for (int k = 0; k < 2; ++k) dst[n][k] = *(const LAS bf16x8*)(lds + PG8_SB(b, h) + boff + n * 2048 + k * 1024); } while (0)
; #define PG8_MMA(ai, bj, At, Bt) do { __builtin_amdgcn_s_setprio(1); _Pragma("unroll") for (int m = 0; m < 4; ++m) _Pragma("unroll") for (int n = 0; n < 2; ++n) _Pragma("unroll") for (int k = 0; k < 2; ++k) \
;         acc[ai][bj][m][n] = __builtin_amdgcn_mfma_f32_16x16x32_bf16(Bt[n][k], At[m][k], acc[ai][bj][m][n], 0, 0, 0); __builtin_amdgcn_s_setprio(0); } while (0)
; #define PG8_WAIT_V(n) asm volatile("s_waitcnt vmcnt(" #n ")" ::: "memory")
; #define PG8_WAIT_L(n) asm volatile("s_waitcnt lgkmcnt(" #n ")" ::: "memory")
; #define PG8_BAR __builtin_amdgcn_s_barrier()
; #define PG8_SCHED __builtin_amdgcn_sched_barrier(0)
; template <class Epi>
; DI void gemm_phase(LAS unsigned char* lds, const Gemm g, const StaticOrder& S, const Epi& E) {
;     ...
;         for (int t = 0; t < nt; t += 2) {
;             const bool last = (t == nt - 2);
;             const char* a1 = cA + (size_t)(t + 1) * kstep;
;             const char* a2 = last ? nA : cA + (size_t)(t + 2) * kstep; const char* b2 = last ? nB : cB + (size_t)(t + 2) * kstep;
;             const char* a3 = a2 + kstep; const char* b3 = b2 + kstep;
;             PG8_LDB(B0, 0, 0); PG8_SCHED; PG8_LDA(At, 0, 0); PG8_STAGE(PG8_SA(1, 1), a1 + hstep);
;             PG8_WAIT_L(8); PG8_BAR; PG8_WAIT_L(0); PG8_MMA(0, 0, At, B0); PG8_BAR; PG8_SCHED;
;             PG8_LDB(B1, 0, 1); PG8_STAGE(PG8_SB(0, 0), b2);
;             PG8_BAR; PG8_WAIT_L(0); PG8_MMA(0, 1, At, B1); PG8_BAR;
;             PG8_LDA(At, 0, 1); PG8_STAGE(PG8_SA(0, 0), a2);
;             PG8_BAR; PG8_WAIT_L(0); PG8_MMA(1, 0, At, B0); PG8_BAR; PG8_SCHED;
;             PG8_STAGE(PG8_SB(0, 1), b2 + hstep);
;             PG8_WAIT_V(6); PG8_BAR; PG8_MMA(1, 1, At, B1); PG8_BAR;
.LBB0_320:
	s_add_u32 s26, s24, 0x100
	s_addc_u32 s27, s25, 0
	s_add_i32 s47, 0, 0x10000
	ds_read_b128 v[128:131], v226
	ds_read_b128 v[132:135], v226 offset:1024
	ds_read_b128 v[136:139], v226 offset:2048
	ds_read_b128 v[140:143], v226 offset:3072
	s_cmp_eq_u32 s46, 28
	s_cselect_b32 s31, s4, s27
	s_cselect_b32 s30, s5, s26
	s_cselect_b32 s29, s9, s45
	s_cselect_b32 s28, s11, s33
	v_lshl_add_u64 v[214:215], s[24:25], 0, v[190:191]
	s_add_i32 m0, s38, 0xc000
	ds_read_b128 v[144:147], v228
	ds_read_b128 v[148:151], v228 offset:1024
	ds_read_b128 v[152:155], v228 offset:2048
	ds_read_b128 v[194:197], v228 offset:3072
	ds_read_b128 v[198:201], v228 offset:4096
	ds_read_b128 v[202:205], v228 offset:5120
	ds_read_b128 v[206:209], v228 offset:6144
	ds_read_b128 v[210:213], v228 offset:7168
	global_load_lds_dwordx4 v[214:215], off
	v_lshl_add_u64 v[214:215], s[24:25], 0, v[192:193]
	s_add_i32 m0, s38, 0xe000
	s_nop 0
	global_load_lds_dwordx4 v[214:215], off
	s_waitcnt lgkmcnt(8)
	s_setprio 1
	s_barrier
	s_waitcnt lgkmcnt(0)
	v_mfma_f32_16x16x32_bf16 v[124:127], v[128:131], v[144:147], v[124:127]
	v_mfma_f32_16x16x32_bf16 v[120:123], v[136:139], v[144:147], v[120:123]
	v_mfma_f32_16x16x32_bf16 v[116:119], v[128:131], v[152:155], v[116:119]
	v_mfma_f32_16x16x32_bf16 v[112:115], v[136:139], v[152:155], v[112:115]
	v_mfma_f32_16x16x32_bf16 v[108:111], v[128:131], v[198:201], v[108:111]
	v_mfma_f32_16x16x32_bf16 v[104:107], v[136:139], v[198:201], v[104:107]
	v_mfma_f32_16x16x32_bf16 v[100:103], v[128:131], v[206:209], v[100:103]
	v_mfma_f32_16x16x32_bf16 v[96:99], v[136:139], v[206:209], v[96:99]
	v_mfma_f32_16x16x32_bf16 v[124:127], v[132:135], v[148:151], v[124:127]
	v_mfma_f32_16x16x32_bf16 v[120:123], v[140:143], v[148:151], v[120:123]
	v_mfma_f32_16x16x32_bf16 v[116:119], v[132:135], v[194:197], v[116:119]
	v_mfma_f32_16x16x32_bf16 v[112:115], v[140:143], v[194:197], v[112:115]
	v_mfma_f32_16x16x32_bf16 v[108:111], v[132:135], v[202:205], v[108:111]
	v_mfma_f32_16x16x32_bf16 v[104:107], v[140:143], v[202:205], v[104:107]
	v_mfma_f32_16x16x32_bf16 v[100:103], v[132:135], v[210:213], v[100:103]
	s_setprio 0
	v_mfma_f32_16x16x32_bf16 v[96:99], v[140:143], v[210:213], v[96:99]
	s_barrier
	s_add_i32 s48, 0, 0x14000
	s_add_i32 s24, s47, s37
	s_mov_b32 m0, s24
	ds_read_b128 v[214:217], v226 offset:16384
	ds_read_b128 v[230:233], v226 offset:17408
	ds_read_b128 v[234:237], v226 offset:18432
	ds_read_b128 v[238:241], v226 offset:19456
	global_load_lds_dwordx4 v188, s[28:29]
	s_add_i32 m0, s24, 0x2000
	s_nop 0
	global_load_lds_dwordx4 v186, s[28:29]
	s_waitcnt lgkmcnt(0)
	s_setprio 1
	s_barrier
	v_mfma_f32_16x16x32_bf16 v[60:63], v[214:217], v[144:147], v[60:63]
	v_mfma_f32_16x16x32_bf16 v[56:59], v[234:237], v[144:147], v[56:59]
	v_mfma_f32_16x16x32_bf16 v[52:55], v[214:217], v[152:155], v[52:55]
	v_mfma_f32_16x16x32_bf16 v[48:51], v[234:237], v[152:155], v[48:51]
	v_mfma_f32_16x16x32_bf16 v[44:47], v[214:217], v[198:201], v[44:47]
	v_mfma_f32_16x16x32_bf16 v[40:43], v[234:237], v[198:201], v[40:43]
	v_mfma_f32_16x16x32_bf16 v[36:39], v[214:217], v[206:209], v[36:39]
	v_mfma_f32_16x16x32_bf16 v[32:35], v[234:237], v[206:209], v[32:35]
	v_mfma_f32_16x16x32_bf16 v[60:63], v[230:233], v[148:151], v[60:63]
	s_mov_b32 m0, s38
	v_mfma_f32_16x16x32_bf16 v[56:59], v[238:241], v[148:151], v[56:59]
	s_mov_b64 s[100:101], s[30:31]
	v_mfma_f32_16x16x32_bf16 v[52:55], v[230:233], v[194:197], v[52:55]
	v_mfma_f32_16x16x32_bf16 v[48:51], v[238:241], v[194:197], v[48:51]
	v_mfma_f32_16x16x32_bf16 v[44:47], v[230:233], v[202:205], v[44:47]
	v_mfma_f32_16x16x32_bf16 v[40:43], v[238:241], v[202:205], v[40:43]
	v_mfma_f32_16x16x32_bf16 v[36:39], v[230:233], v[210:213], v[36:39]
	s_setprio 0
	v_mfma_f32_16x16x32_bf16 v[32:35], v[238:241], v[210:213], v[32:35]
	s_barrier
	ds_read_b128 v[144:147], v228 offset:16384
	ds_read_b128 v[148:151], v228 offset:17408
	ds_read_b128 v[152:155], v228 offset:18432
	ds_read_b128 v[194:197], v228 offset:19456
	ds_read_b128 v[198:201], v228 offset:20480
	ds_read_b128 v[202:205], v228 offset:21504
	ds_read_b128 v[206:209], v228 offset:22528
	ds_read_b128 v[210:213], v228 offset:23552
	global_load_lds_dwordx4 v188, s[30:31]
	s_mov_b64 s[100:101], s[30:31]
	s_mov_b32 m0, s39
	s_nop 0
	global_load_lds_dwordx4 v186, s[30:31]
	s_waitcnt lgkmcnt(0)
	s_setprio 1
	s_barrier
	v_mfma_f32_16x16x32_bf16 v[92:95], v[128:131], v[144:147], v[92:95]
	v_mfma_f32_16x16x32_bf16 v[88:91], v[136:139], v[144:147], v[88:91]
	v_mfma_f32_16x16x32_bf16 v[84:87], v[128:131], v[152:155], v[84:87]
	v_mfma_f32_16x16x32_bf16 v[80:83], v[136:139], v[152:155], v[80:83]
	v_mfma_f32_16x16x32_bf16 v[76:79], v[128:131], v[198:201], v[76:79]
	v_mfma_f32_16x16x32_bf16 v[72:75], v[136:139], v[198:201], v[72:75]
	v_mfma_f32_16x16x32_bf16 v[68:71], v[128:131], v[206:209], v[68:71]
	v_mfma_f32_16x16x32_bf16 v[64:67], v[136:139], v[206:209], v[64:67]
	v_mfma_f32_16x16x32_bf16 v[92:95], v[132:135], v[148:151], v[92:95]
	v_mfma_f32_16x16x32_bf16 v[88:91], v[140:143], v[148:151], v[88:91]
	v_mfma_f32_16x16x32_bf16 v[84:87], v[132:135], v[194:197], v[84:87]
	v_mfma_f32_16x16x32_bf16 v[80:83], v[140:143], v[194:197], v[80:83]
	v_mfma_f32_16x16x32_bf16 v[76:79], v[132:135], v[202:205], v[76:79]
	v_mfma_f32_16x16x32_bf16 v[72:75], v[140:143], v[202:205], v[72:75]
	v_mfma_f32_16x16x32_bf16 v[68:71], v[132:135], v[210:213], v[68:71]
	s_setprio 0
	v_mfma_f32_16x16x32_bf16 v[64:67], v[140:143], v[210:213], v[64:67]
	s_barrier
	s_add_u32 s24, s28, 0x80000
	s_addc_u32 s25, s29, 0
	s_add_i32 s47, s48, s37
	s_mov_b32 m0, s47
	s_nop 0
	global_load_lds_dwordx4 v188, s[24:25]
	s_add_i32 m0, s47, 0x2000
	s_nop 0
	global_load_lds_dwordx4 v186, s[24:25]
	s_waitcnt vmcnt(6)
	s_setprio 1
	s_barrier
; #define PG8_STAGE(bufoff, gbase) do { _Pragma("unroll") for (int _i = 0; _i < 2; ++_i) \
;         __builtin_amdgcn_global_load_lds((const unsigned*)((const char*)(gbase) + voff[_i]), (LAS unsigned*)(lds + (bufoff) + ldsw + _i * 8192), 16, 0, 0); } while (0)
; #define PG8_LDA(dst, b, h) do { _Pragma("unroll") for (int m = 0; m < 4; ++m) _Pragma("unroll") for (int k = 0; k < 2; ++k) dst[m][k] = *(const LAS bf16x8*)(lds + PG8_SA(b, h) + aoff + m * 2048 + k * 1024); } while (0)
; #define PG8_LDB(dst, b, h) do { _Pragma("unroll") for (int n = 0; n < 2; ++n) _Pragma("unroll") for (int k = 0; k < 2; ++k) dst[n][k] = *(const LAS bf16x8*)(lds + PG8_SB(b, h) + boff + n * 2048 + k * 1024); } while (0)
; #define PG8_MMA(ai, bj, At, Bt) do { __builtin_amdgcn_s_setprio(1); _Pragma("unroll") for (int m = 0; m < 4; ++m) _Pragma("unroll") for (int n = 0; n < 2; ++n) _Pragma("unroll") for (int k = 0; k < 2; ++k) \
;         acc[ai][bj][m][n] = __builtin_amdgcn_mfma_f32_16x16x32_bf16(Bt[n][k], At[m][k], acc[ai][bj][m][n], 0, 0, 0); __builtin_amdgcn_s_setprio(0); } while (0)
; #define PG8_WAIT_V(n) asm volatile("s_waitcnt vmcnt(" #n ")" ::: "memory")
; #define PG8_WAIT_L(n) asm volatile("s_waitcnt lgkmcnt(" #n ")" ::: "memory")
; #define PG8_BAR __builtin_amdgcn_s_barrier()
; #define PG8_SCHED __builtin_amdgcn_sched_barrier(0)
; template <class Epi>
; DI void gemm_phase(LAS unsigned char* lds, const Gemm g, const StaticOrder& S, const Epi& E) {
;     ...
;             PG8_WAIT_V(6); PG8_BAR; PG8_MMA(1, 1, At, B1); PG8_BAR;
;             PG8_LDB(B0, 1, 0); PG8_SCHED; PG8_LDA(At, 1, 0); PG8_STAGE(PG8_SA(0, 1), a2 + hstep);
;             PG8_WAIT_L(8); PG8_BAR; PG8_WAIT_L(0); PG8_MMA(0, 0, At, B0); PG8_BAR; PG8_SCHED;
;             PG8_LDB(B1, 1, 1); PG8_STAGE(PG8_SB(1, 0), b3);
;             PG8_BAR; PG8_WAIT_L(0); PG8_MMA(0, 1, At, B1); PG8_BAR;
;             PG8_LDA(At, 1, 1); PG8_STAGE(PG8_SA(1, 0), a3);
;             PG8_BAR; PG8_WAIT_L(0); PG8_MMA(1, 0, At, B0); PG8_BAR; PG8_SCHED;
;             PG8_STAGE(PG8_SB(1, 1), b3 + hstep);
	v_mfma_f32_16x16x32_bf16 v[28:31], v[214:217], v[144:147], v[28:31]
	v_mfma_f32_16x16x32_bf16 v[24:27], v[234:237], v[144:147], v[24:27]
	v_mfma_f32_16x16x32_bf16 v[20:23], v[214:217], v[152:155], v[20:23]
	v_mfma_f32_16x16x32_bf16 v[16:19], v[234:237], v[152:155], v[16:19]
	v_mfma_f32_16x16x32_bf16 v[12:15], v[214:217], v[198:201], v[12:15]
	v_mfma_f32_16x16x32_bf16 v[8:11], v[234:237], v[198:201], v[8:11]
	v_mfma_f32_16x16x32_bf16 v[4:7], v[214:217], v[206:209], v[4:7]
	v_mfma_f32_16x16x32_bf16 v[0:3], v[234:237], v[206:209], v[0:3]
	v_mfma_f32_16x16x32_bf16 v[28:31], v[230:233], v[148:151], v[28:31]
	s_add_i32 s47, 0, 0x18000
	v_mfma_f32_16x16x32_bf16 v[24:27], v[238:241], v[148:151], v[24:27]
	v_mfma_f32_16x16x32_bf16 v[20:23], v[230:233], v[194:197], v[20:23]
	v_mfma_f32_16x16x32_bf16 v[16:19], v[238:241], v[194:197], v[16:19]
	v_mfma_f32_16x16x32_bf16 v[12:15], v[230:233], v[202:205], v[12:15]
	v_mfma_f32_16x16x32_bf16 v[8:11], v[238:241], v[202:205], v[8:11]
	v_mfma_f32_16x16x32_bf16 v[4:7], v[230:233], v[210:213], v[4:7]
	s_setprio 0
	v_mfma_f32_16x16x32_bf16 v[0:3], v[238:241], v[210:213], v[0:3]
	s_barrier
	ds_read_b128 v[128:131], v226 offset:32768
	ds_read_b128 v[132:135], v226 offset:33792
	ds_read_b128 v[136:139], v226 offset:34816
	ds_read_b128 v[140:143], v226 offset:35840
	s_add_u32 s24, s30, 0x80000
	s_addc_u32 s25, s31, 0
	s_mov_b32 m0, s40
	ds_read_b128 v[144:147], v228 offset:32768
	ds_read_b128 v[148:151], v228 offset:33792
	ds_read_b128 v[152:155], v228 offset:34816
	ds_read_b128 v[194:197], v228 offset:35840
	ds_read_b128 v[198:201], v228 offset:36864
	ds_read_b128 v[202:205], v228 offset:37888
	ds_read_b128 v[206:209], v228 offset:38912
	ds_read_b128 v[210:213], v228 offset:39936
	global_load_lds_dwordx4 v188, s[24:25]
	s_mov_b32 m0, s41
	s_nop 0
	global_load_lds_dwordx4 v186, s[24:25]
	s_waitcnt lgkmcnt(8)
	s_setprio 1
	s_barrier
	s_waitcnt lgkmcnt(0)
	v_mfma_f32_16x16x32_bf16 v[124:127], v[128:131], v[144:147], v[124:127]
	v_mfma_f32_16x16x32_bf16 v[120:123], v[136:139], v[144:147], v[120:123]
	v_mfma_f32_16x16x32_bf16 v[116:119], v[128:131], v[152:155], v[116:119]
	v_mfma_f32_16x16x32_bf16 v[112:115], v[136:139], v[152:155], v[112:115]
	v_mfma_f32_16x16x32_bf16 v[108:111], v[128:131], v[198:201], v[108:111]
	v_mfma_f32_16x16x32_bf16 v[104:107], v[136:139], v[198:201], v[104:107]
	v_mfma_f32_16x16x32_bf16 v[100:103], v[128:131], v[206:209], v[100:103]
	v_mfma_f32_16x16x32_bf16 v[96:99], v[136:139], v[206:209], v[96:99]
	v_mfma_f32_16x16x32_bf16 v[124:127], v[132:135], v[148:151], v[124:127]
	v_mfma_f32_16x16x32_bf16 v[120:123], v[140:143], v[148:151], v[120:123]
	v_mfma_f32_16x16x32_bf16 v[116:119], v[132:135], v[194:197], v[116:119]
	v_mfma_f32_16x16x32_bf16 v[112:115], v[140:143], v[194:197], v[112:115]
	v_mfma_f32_16x16x32_bf16 v[108:111], v[132:135], v[202:205], v[108:111]
	v_mfma_f32_16x16x32_bf16 v[104:107], v[140:143], v[202:205], v[104:107]
	v_mfma_f32_16x16x32_bf16 v[100:103], v[132:135], v[210:213], v[100:103]
	s_setprio 0
	v_mfma_f32_16x16x32_bf16 v[96:99], v[140:143], v[210:213], v[96:99]
	s_barrier
	s_add_i32 s30, 0, 0x1c000
	s_add_i32 s24, s47, s37
	s_add_i32 m0, s24, 0xffffff80
	ds_read_b128 v[214:217], v226 offset:49152
	ds_read_b128 v[230:233], v226 offset:50176
	ds_read_b128 v[234:237], v226 offset:51200
	ds_read_b128 v[238:241], v226 offset:52224
	global_load_lds_dwordx4 v188, s[28:29] offset:128
	s_add_i32 m0, s24, 0x1f80
	s_nop 0
	global_load_lds_dwordx4 v186, s[28:29] offset:128
	s_waitcnt lgkmcnt(0)
	s_setprio 1
	s_barrier
	v_mfma_f32_16x16x32_bf16 v[60:63], v[214:217], v[144:147], v[60:63]
	v_mfma_f32_16x16x32_bf16 v[56:59], v[234:237], v[144:147], v[56:59]
	v_mfma_f32_16x16x32_bf16 v[52:55], v[214:217], v[152:155], v[52:55]
	v_mfma_f32_16x16x32_bf16 v[48:51], v[234:237], v[152:155], v[48:51]
	v_mfma_f32_16x16x32_bf16 v[44:47], v[214:217], v[198:201], v[44:47]
	v_mfma_f32_16x16x32_bf16 v[40:43], v[234:237], v[198:201], v[40:43]
	v_mfma_f32_16x16x32_bf16 v[36:39], v[214:217], v[206:209], v[36:39]
	v_mfma_f32_16x16x32_bf16 v[32:35], v[234:237], v[206:209], v[32:35]
	v_mfma_f32_16x16x32_bf16 v[60:63], v[230:233], v[148:151], v[60:63]
	s_add_i32 m0, s42, 0xffffff80
	v_mfma_f32_16x16x32_bf16 v[56:59], v[238:241], v[148:151], v[56:59]
	v_mfma_f32_16x16x32_bf16 v[52:55], v[230:233], v[194:197], v[52:55]
	v_mfma_f32_16x16x32_bf16 v[48:51], v[238:241], v[194:197], v[48:51]
	v_mfma_f32_16x16x32_bf16 v[44:47], v[230:233], v[202:205], v[44:47]
	v_mfma_f32_16x16x32_bf16 v[40:43], v[238:241], v[202:205], v[40:43]
	v_mfma_f32_16x16x32_bf16 v[36:39], v[230:233], v[210:213], v[36:39]
	s_setprio 0
	v_mfma_f32_16x16x32_bf16 v[32:35], v[238:241], v[210:213], v[32:35]
	s_barrier
	ds_read_b128 v[144:147], v228 offset:49152
	ds_read_b128 v[148:151], v228 offset:50176
	ds_read_b128 v[152:155], v228 offset:51200
	ds_read_b128 v[194:197], v228 offset:52224
	ds_read_b128 v[198:201], v228 offset:53248
	ds_read_b128 v[202:205], v228 offset:54272
	ds_read_b128 v[206:209], v228 offset:55296
	ds_read_b128 v[210:213], v228 offset:56320
	global_load_lds_dwordx4 v188, s[100:101] offset:128
	s_add_i32 m0, s43, 0xffffff80
	s_nop 0
	global_load_lds_dwordx4 v186, s[100:101] offset:128
	s_waitcnt lgkmcnt(0)
	s_setprio 1
	s_barrier
; #define PG8_WAIT_V(n) asm volatile("s_waitcnt vmcnt(" #n ")" ::: "memory")
; #define PG8_BAR __builtin_amdgcn_s_barrier()
; template <class Epi>
; DI void gemm_phase(LAS unsigned char* lds, const Gemm g, const StaticOrder& S, const Epi& E) {
;     ...
;             PG8_STAGE(PG8_SB(1, 1), b3 + hstep);
;             PG8_WAIT_V(6); PG8_BAR; PG8_MMA(1, 1, At, B1); PG8_BAR;
;         }
;     template <bool LN, int BJ, int LO, int HI> DI void batch(const f32x4 (&acc)[2][2][4][2], unsigned row0, unsigned col0, const f32x4 (&gv)[2], const f32x4 (&bv)[2]) const {
;         f32x4 r[HI - LO]; float mean[(HI - LO) / 2], rstd[(HI - LO) / 2];
; #pragma unroll
;         for (int i = LO; i < HI; ++i) { const int ai = i >> 3, m = (i >> 1) & 3, n = i & 1; const unsigned row = row0 + ai * HALF + m * 16;
;             if (n == 0) { mean[(i - LO) >> 1] = 0.f; rstd[(i - LO) >> 1] = 1.f;
;                 if (LN) { const float2 st = *(const float2*)(stats + row * 2u); mean[(i - LO) >> 1] = st.x; rstd[(i - LO) >> 1] = st.y; } }
;             r[i - LO] = *(const f32x4*)(src + (row * (unsigned)DM + col0 + BJ * HALF + n * 16)); }
; #pragma unroll
;         for (int i = LO; i < HI; ++i) { const int ai = i >> 3, m = (i >> 1) & 3, n = i & 1; const unsigned row = row0 + ai * HALF + m * 16;
;             *(f32x4*)(Y + (row * (unsigned)DM + col0 + BJ * HALF + n * 16)) = acc[ai][BJ][m][n] + ((r[i - LO] - mean[(i - LO) >> 1]) * rstd[(i - LO) >> 1]) * gv[n] + bv[n]; }
;         __builtin_amdgcn_sched_barrier(0);
;     }
;     template <bool LN, int BJ> DI void load_gb(unsigned col0, f32x4 (&gv)[2], f32x4 (&bv)[2]) const {
; #pragma unroll
;         for (int n = 0; n < 2; ++n) {
;             if (LN) { gv[n] = *(const f32x4*)(gam + col0 + BJ * HALF + n * 16) * ALPHA; bv[n] = *(const f32x4*)(bet + col0 + BJ * HALF + n * 16) * ALPHA; }
;             else { gv[n] = (f32x4){ALPHA, ALPHA, ALPHA, ALPHA}; bv[n] = (f32x4){0.f, 0.f, 0.f, 0.f}; }
;         }
;     }
;     template <bool LN> DI void run(const f32x4 (&acc)[2][2][4][2], const Unit& u, int wr, int wc, int fr, int fq) const {
;         const unsigned row0 = u.pm * BM + wr * 64 + fr, col0 = u.pn * BM + wc * 32 + 4 * fq;
;         f32x4 gv[2], bv[2];
;         load_gb<LN, 0>(col0, gv, bv);
;         batch<LN, 0, 0, 4>(acc, row0, col0, gv, bv);
	v_mfma_f32_16x16x32_bf16 v[92:95], v[128:131], v[144:147], v[92:95]
	v_mfma_f32_16x16x32_bf16 v[88:91], v[136:139], v[144:147], v[88:91]
	v_mfma_f32_16x16x32_bf16 v[84:87], v[128:131], v[152:155], v[84:87]
	v_mfma_f32_16x16x32_bf16 v[80:83], v[136:139], v[152:155], v[80:83]
	v_mfma_f32_16x16x32_bf16 v[76:79], v[128:131], v[198:201], v[76:79]
	v_mfma_f32_16x16x32_bf16 v[72:75], v[136:139], v[198:201], v[72:75]
	v_mfma_f32_16x16x32_bf16 v[68:71], v[128:131], v[206:209], v[68:71]
	v_mfma_f32_16x16x32_bf16 v[64:67], v[136:139], v[206:209], v[64:67]
	v_mfma_f32_16x16x32_bf16 v[92:95], v[132:135], v[148:151], v[92:95]
	v_mfma_f32_16x16x32_bf16 v[88:91], v[140:143], v[148:151], v[88:91]
	v_mfma_f32_16x16x32_bf16 v[84:87], v[132:135], v[194:197], v[84:87]
	v_mfma_f32_16x16x32_bf16 v[80:83], v[140:143], v[194:197], v[80:83]
	v_mfma_f32_16x16x32_bf16 v[76:79], v[132:135], v[202:205], v[76:79]
	v_mfma_f32_16x16x32_bf16 v[72:75], v[140:143], v[202:205], v[72:75]
	v_mfma_f32_16x16x32_bf16 v[68:71], v[132:135], v[210:213], v[68:71]
	s_setprio 0
	v_mfma_f32_16x16x32_bf16 v[64:67], v[140:143], v[210:213], v[64:67]
	s_barrier
	s_add_u32 s24, s28, 0x80080
	s_addc_u32 s25, s29, 0
	s_add_i32 s28, s30, s37
	s_mov_b32 m0, s28
	s_nop 0
	global_load_lds_dwordx4 v188, s[24:25]
	s_add_i32 m0, s28, 0x2000
	s_nop 0
	global_load_lds_dwordx4 v186, s[24:25]
	s_waitcnt vmcnt(6)
	s_setprio 1
	s_barrier
	v_mfma_f32_16x16x32_bf16 v[28:31], v[214:217], v[144:147], v[28:31]
	v_mfma_f32_16x16x32_bf16 v[24:27], v[234:237], v[144:147], v[24:27]
	v_mfma_f32_16x16x32_bf16 v[20:23], v[214:217], v[152:155], v[20:23]
	v_mfma_f32_16x16x32_bf16 v[16:19], v[234:237], v[152:155], v[16:19]
	v_mfma_f32_16x16x32_bf16 v[12:15], v[214:217], v[198:201], v[12:15]
	v_mfma_f32_16x16x32_bf16 v[8:11], v[234:237], v[198:201], v[8:11]
	v_mfma_f32_16x16x32_bf16 v[4:7], v[214:217], v[206:209], v[4:7]
	v_mfma_f32_16x16x32_bf16 v[0:3], v[234:237], v[206:209], v[0:3]
	v_mfma_f32_16x16x32_bf16 v[28:31], v[230:233], v[148:151], v[28:31]
	s_add_i32 s46, s46, 2
	v_mfma_f32_16x16x32_bf16 v[24:27], v[238:241], v[148:151], v[24:27]
	s_add_u32 s33, s33, 0x100
	v_mfma_f32_16x16x32_bf16 v[20:23], v[230:233], v[194:197], v[20:23]
	s_addc_u32 s45, s45, 0
	v_mfma_f32_16x16x32_bf16 v[16:19], v[238:241], v[194:197], v[16:19]
	s_cmp_gt_u32 s46, 29
	v_mfma_f32_16x16x32_bf16 v[12:15], v[230:233], v[202:205], v[12:15]
	s_mov_b64 s[24:25], s[26:27]
	v_mfma_f32_16x16x32_bf16 v[8:11], v[238:241], v[202:205], v[8:11]
	v_mfma_f32_16x16x32_bf16 v[4:7], v[230:233], v[210:213], v[4:7]
	s_setprio 0
	v_mfma_f32_16x16x32_bf16 v[0:3], v[238:241], v[210:213], v[0:3]
	s_barrier
	s_cbranch_scc0 .LBB0_320
	v_lshl_add_u32 v206, s3, 8, v225
	v_lshl_or_b32 v158, s2, 8, v227
	v_lshlrev_b32_e32 v232, 11, v206
	s_andn2_b64 vcc, exec, s[14:15]
	v_or_b32_e32 v231, 16, v158
	v_add_u32_e32 v194, v232, v158
	v_or_b32_e32 v230, 0x80, v158
	v_or_b32_e32 v229, 0x90, v158
	s_cbranch_vccnz .LBB0_323
	v_lshlrev_b64 v[132:133], 2, v[158:159]
	v_lshl_add_u64 v[140:141], s[16:17], 0, v[132:133]
	global_load_dwordx4 v[128:131], v[140:141], off
	v_lshl_add_u64 v[142:143], s[18:19], 0, v[132:133]
	v_readlane_b32 s2, v253, 8
	v_mov_b32_e32 v195, v159
	v_lshlrev_b32_e32 v136, 1, v206
	v_mov_b32_e32 v137, v159
	v_readlane_b32 s3, v253, 9
	v_lshlrev_b64 v[212:213], 2, v[194:195]
	v_add_u32_e32 v146, v232, v231
	v_lshl_add_u64 v[144:145], v[136:137], 2, s[2:3]
	v_lshl_add_u64 v[136:137], s[88:89], 0, v[212:213]
	v_mov_b32_e32 v147, v159
	v_lshl_add_u64 v[146:147], v[146:147], 2, s[88:89]
	v_or_b32_e32 v195, 16, v206
	v_mov_b32_e32 v201, v159
	v_mov_b32_e32 v209, v159
	v_lshl_add_u64 v[212:213], s[90:91], 0, v[212:213]
	s_waitcnt vmcnt(0)
	v_pk_mul_f32 v[152:153], v[130:131], s[78:79] op_sel_hi:[1,0]
	v_pk_mul_f32 v[154:155], v[128:129], s[78:79] op_sel_hi:[1,0]
	global_load_dwordx4 v[132:135], v[142:143], off
	global_load_dwordx4 v[128:131], v[140:141], off offset:64
	global_load_dwordx2 v[204:205], v[144:145], off
	global_load_dwordx4 v[196:199], v[146:147], off
	v_lshlrev_b32_e32 v146, 1, v195
	global_load_dwordx4 v[136:139], v[136:137], off
	v_lshlrev_b32_e32 v195, 11, v195
	v_mov_b32_e32 v147, v159
	v_add_u32_e32 v200, v195, v158
	v_lshl_add_u64 v[146:147], v[146:147], 2, s[2:3]
	v_lshl_add_u64 v[200:201], v[200:201], 2, s[88:89]
	global_load_dwordx2 v[214:215], v[146:147], off
	v_add_u32_e32 v208, v195, v231
	global_load_dwordx4 v[200:203], v[200:201], off
	v_lshl_add_u64 v[208:209], v[208:209], 2, s[88:89]
	global_load_dwordx4 v[208:211], v[208:209], off
	s_waitcnt vmcnt(0)
	v_pk_mul_f32 v[148:149], v[130:131], s[78:79] op_sel_hi:[1,0]
	v_pk_mul_f32 v[150:151], v[128:129], s[78:79] op_sel_hi:[1,0]
	global_load_dwordx4 v[128:131], v[142:143], off offset:64
	v_sub_f32_e32 v137, v137, v204
	v_sub_f32_e32 v136, v136, v204
	v_sub_f32_e32 v139, v139, v204
	v_sub_f32_e32 v138, v138, v204
	v_pk_mul_f32 v[138:139], v[204:205], v[138:139] op_sel:[1,0]
	v_pk_mul_f32 v[136:137], v[204:205], v[136:137] op_sel:[1,0]
	v_pk_fma_f32 v[138:139], v[152:153], v[138:139], v[126:127]
	v_pk_fma_f32 v[136:137], v[154:155], v[136:137], v[124:125]
	v_pk_fma_f32 v[138:139], v[134:135], s[78:79], v[138:139] op_sel_hi:[1,0,1]
	v_pk_fma_f32 v[136:137], v[132:133], s[78:79], v[136:137] op_sel_hi:[1,0,1]
	global_store_dwordx4 v[212:213], v[136:139], off
	s_nop 1
	v_sub_f32_e32 v137, v197, v204
	v_sub_f32_e32 v136, v196, v204
	v_sub_f32_e32 v139, v199, v204
	v_sub_f32_e32 v138, v198, v204
	v_pk_mul_f32 v[138:139], v[204:205], v[138:139] op_sel:[1,0]
	v_pk_mul_f32 v[136:137], v[204:205], v[136:137] op_sel:[1,0]
	v_pk_fma_f32 v[138:139], v[148:149], v[138:139], v[122:123]
	v_pk_fma_f32 v[136:137], v[150:151], v[136:137], v[120:121]
	v_or_b32_e32 v196, 16, v194
	v_mov_b32_e32 v197, v159
	v_lshl_add_u64 v[196:197], v[196:197], 2, s[90:91]
	s_waitcnt vmcnt(0)
;     template <bool LN, int BJ, int LO, int HI> DI void batch(const f32x4 (&acc)[2][2][4][2], unsigned row0, unsigned col0, const f32x4 (&gv)[2], const f32x4 (&bv)[2]) const {
;         f32x4 r[HI - LO]; float mean[(HI - LO) / 2], rstd[(HI - LO) / 2];
; #pragma unroll
;         for (int i = LO; i < HI; ++i) { const int ai = i >> 3, m = (i >> 1) & 3, n = i & 1; const unsigned row = row0 + ai * HALF + m * 16;
;             if (n == 0) { mean[(i - LO) >> 1] = 0.f; rstd[(i - LO) >> 1] = 1.f;
;                 if (LN) { const float2 st = *(const float2*)(stats + row * 2u); mean[(i - LO) >> 1] = st.x; rstd[(i - LO) >> 1] = st.y; } }
;             r[i - LO] = *(const f32x4*)(src + (row * (unsigned)DM + col0 + BJ * HALF + n * 16)); }
; #pragma unroll
;         for (int i = LO; i < HI; ++i) { const int ai = i >> 3, m = (i >> 1) & 3, n = i & 1; const unsigned row = row0 + ai * HALF + m * 16;
;             *(f32x4*)(Y + (row * (unsigned)DM + col0 + BJ * HALF + n * 16)) = acc[ai][BJ][m][n] + ((r[i - LO] - mean[(i - LO) >> 1]) * rstd[(i - LO) >> 1]) * gv[n] + bv[n]; }
;         __builtin_amdgcn_sched_barrier(0);
;     }
;     template <bool LN, int BJ> DI void load_gb(unsigned col0, f32x4 (&gv)[2], f32x4 (&bv)[2]) const {
; #pragma unroll
;         for (int n = 0; n < 2; ++n) {
;             if (LN) { gv[n] = *(const f32x4*)(gam + col0 + BJ * HALF + n * 16) * ALPHA; bv[n] = *(const f32x4*)(bet + col0 + BJ * HALF + n * 16) * ALPHA; }
;             else { gv[n] = (f32x4){ALPHA, ALPHA, ALPHA, ALPHA}; bv[n] = (f32x4){0.f, 0.f, 0.f, 0.f}; }
;         }
;     }
;     template <bool LN> DI void run(const f32x4 (&acc)[2][2][4][2], const Unit& u, int wr, int wc, int fr, int fq) const {
;         const unsigned row0 = u.pm * BM + wr * 64 + fr, col0 = u.pn * BM + wc * 32 + 4 * fq;
;         f32x4 gv[2], bv[2];
;         load_gb<LN, 0>(col0, gv, bv);
;         batch<LN, 0, 0, 4>(acc, row0, col0, gv, bv);
;         batch<LN, 0, 4, 8>(acc, row0, col0, gv, bv);
;         batch<LN, 0, 8, 12>(acc, row0, col0, gv, bv);
	v_pk_fma_f32 v[138:139], v[130:131], s[78:79], v[138:139] op_sel_hi:[1,0,1]
	v_pk_fma_f32 v[136:137], v[128:129], s[78:79], v[136:137] op_sel_hi:[1,0,1]
	global_store_dwordx4 v[196:197], v[136:139], off
	v_add_u32_e32 v196, 0x8000, v194
	v_mov_b32_e32 v197, v159
	v_sub_f32_e32 v137, v201, v214
	v_sub_f32_e32 v136, v200, v214
	v_sub_f32_e32 v139, v203, v214
	v_sub_f32_e32 v138, v202, v214
	v_pk_mul_f32 v[138:139], v[214:215], v[138:139] op_sel:[1,0]
	v_pk_mul_f32 v[136:137], v[214:215], v[136:137] op_sel:[1,0]
	v_pk_fma_f32 v[138:139], v[152:153], v[138:139], v[118:119]
	v_pk_fma_f32 v[136:137], v[154:155], v[136:137], v[116:117]
	v_pk_fma_f32 v[138:139], v[134:135], s[78:79], v[138:139] op_sel_hi:[1,0,1]
	v_pk_fma_f32 v[136:137], v[132:133], s[78:79], v[136:137] op_sel_hi:[1,0,1]
	v_lshl_add_u64 v[196:197], v[196:197], 2, s[90:91]
	global_store_dwordx4 v[196:197], v[136:139], off
	v_add_u32_e32 v196, 0x8010, v194
	v_mov_b32_e32 v197, v159
	v_sub_f32_e32 v137, v209, v214
	v_sub_f32_e32 v136, v208, v214
	v_sub_f32_e32 v139, v211, v214
	v_sub_f32_e32 v138, v210, v214
	v_pk_mul_f32 v[138:139], v[214:215], v[138:139] op_sel:[1,0]
	v_pk_mul_f32 v[136:137], v[214:215], v[136:137] op_sel:[1,0]
	v_pk_fma_f32 v[138:139], v[148:149], v[138:139], v[114:115]
	v_pk_fma_f32 v[136:137], v[150:151], v[136:137], v[112:113]
	v_pk_fma_f32 v[138:139], v[130:131], s[78:79], v[138:139] op_sel_hi:[1,0,1]
	v_pk_fma_f32 v[136:137], v[128:129], s[78:79], v[136:137] op_sel_hi:[1,0,1]
	v_lshl_add_u64 v[196:197], v[196:197], 2, s[90:91]
	global_store_dwordx4 v[196:197], v[136:139], off
	s_nop 1
	v_or_b32_e32 v138, 32, v206
	v_lshlrev_b32_e32 v136, 1, v138
	v_mov_b32_e32 v137, v159
	v_lshlrev_b32_e32 v236, 11, v138
	v_lshl_add_u64 v[200:201], v[136:137], 2, s[2:3]
	v_add_u32_e32 v136, v236, v158
	v_lshl_add_u64 v[136:137], v[136:137], 2, s[88:89]
	global_load_dwordx2 v[204:205], v[200:201], off
	v_add_u32_e32 v196, v236, v231
	global_load_dwordx4 v[136:139], v[136:137], off
	v_mov_b32_e32 v197, v159
	v_lshl_add_u64 v[196:197], v[196:197], 2, s[88:89]
	global_load_dwordx4 v[196:199], v[196:197], off
	v_or_b32_e32 v207, 48, v206
	v_lshlrev_b32_e32 v235, 11, v207
	v_lshlrev_b32_e32 v202, 1, v207
	v_mov_b32_e32 v203, v159
	v_add_u32_e32 v208, v235, v158
	v_mov_b32_e32 v209, v159
	v_lshl_add_u64 v[202:203], v[202:203], 2, s[2:3]
	v_lshl_add_u64 v[208:209], v[208:209], 2, s[88:89]
	global_load_dwordx2 v[216:217], v[202:203], off
	v_add_u32_e32 v212, v235, v231
	global_load_dwordx4 v[208:211], v[208:209], off
	v_mov_b32_e32 v213, v159
	v_lshl_add_u64 v[212:213], v[212:213], 2, s[88:89]
	global_load_dwordx4 v[212:215], v[212:213], off
	v_add_u32_e32 v218, 0x10000, v194
	v_mov_b32_e32 v219, v159
	v_lshl_add_u64 v[218:219], v[218:219], 2, s[90:91]
	s_waitcnt vmcnt(0)
	v_sub_f32_e32 v137, v137, v204
	v_sub_f32_e32 v136, v136, v204
	v_sub_f32_e32 v139, v139, v204
	v_sub_f32_e32 v138, v138, v204
	v_pk_mul_f32 v[138:139], v[204:205], v[138:139] op_sel:[1,0]
	v_pk_mul_f32 v[136:137], v[204:205], v[136:137] op_sel:[1,0]
	v_pk_fma_f32 v[138:139], v[152:153], v[138:139], v[110:111]
	v_pk_fma_f32 v[136:137], v[154:155], v[136:137], v[108:109]
	v_pk_fma_f32 v[138:139], v[134:135], s[78:79], v[138:139] op_sel_hi:[1,0,1]
	v_pk_fma_f32 v[136:137], v[132:133], s[78:79], v[136:137] op_sel_hi:[1,0,1]
	global_store_dwordx4 v[218:219], v[136:139], off
	s_nop 1
	v_sub_f32_e32 v137, v197, v204
	v_sub_f32_e32 v136, v196, v204
	v_sub_f32_e32 v139, v199, v204
	v_sub_f32_e32 v138, v198, v204
	v_pk_mul_f32 v[138:139], v[204:205], v[138:139] op_sel:[1,0]
	v_pk_mul_f32 v[136:137], v[204:205], v[136:137] op_sel:[1,0]
	v_pk_fma_f32 v[138:139], v[148:149], v[138:139], v[106:107]
	v_pk_fma_f32 v[136:137], v[150:151], v[136:137], v[104:105]
	v_add_u32_e32 v196, 0x10010, v194
	v_mov_b32_e32 v197, v159
	v_pk_fma_f32 v[138:139], v[130:131], s[78:79], v[138:139] op_sel_hi:[1,0,1]
	v_pk_fma_f32 v[136:137], v[128:129], s[78:79], v[136:137] op_sel_hi:[1,0,1]
	v_lshl_add_u64 v[196:197], v[196:197], 2, s[90:91]
	global_store_dwordx4 v[196:197], v[136:139], off
	v_add_u32_e32 v196, 0x18000, v194
	v_mov_b32_e32 v197, v159
	v_sub_f32_e32 v137, v209, v216
	v_sub_f32_e32 v136, v208, v216
	v_sub_f32_e32 v139, v211, v216
	v_sub_f32_e32 v138, v210, v216
	v_pk_mul_f32 v[138:139], v[216:217], v[138:139] op_sel:[1,0]
	v_pk_mul_f32 v[136:137], v[216:217], v[136:137] op_sel:[1,0]
	v_pk_fma_f32 v[138:139], v[152:153], v[138:139], v[102:103]
	v_pk_fma_f32 v[136:137], v[154:155], v[136:137], v[100:101]
	v_pk_fma_f32 v[138:139], v[134:135], s[78:79], v[138:139] op_sel_hi:[1,0,1]
	v_pk_fma_f32 v[136:137], v[132:133], s[78:79], v[136:137] op_sel_hi:[1,0,1]
	v_lshl_add_u64 v[196:197], v[196:197], 2, s[90:91]
	global_store_dwordx4 v[196:197], v[136:139], off
	v_add_u32_e32 v196, 0x18010, v194
	v_mov_b32_e32 v197, v159
	v_sub_f32_e32 v137, v213, v216
	v_sub_f32_e32 v136, v212, v216
	v_sub_f32_e32 v139, v215, v216
	v_sub_f32_e32 v138, v214, v216
	v_pk_mul_f32 v[138:139], v[216:217], v[138:139] op_sel:[1,0]
	v_pk_mul_f32 v[136:137], v[216:217], v[136:137] op_sel:[1,0]
	v_pk_fma_f32 v[138:139], v[148:149], v[138:139], v[98:99]
	v_pk_fma_f32 v[136:137], v[150:151], v[136:137], v[96:97]
	v_pk_fma_f32 v[138:139], v[130:131], s[78:79], v[138:139] op_sel_hi:[1,0,1]
	v_pk_fma_f32 v[136:137], v[128:129], s[78:79], v[136:137] op_sel_hi:[1,0,1]
	v_lshl_add_u64 v[196:197], v[196:197], 2, s[90:91]
	global_store_dwordx4 v[196:197], v[136:139], off
	s_nop 1
	v_add_u32_e32 v138, 0x80, v206
	v_lshlrev_b32_e32 v136, 1, v138
	v_mov_b32_e32 v137, v159
	v_lshlrev_b32_e32 v233, 11, v138
	v_lshl_add_u64 v[196:197], v[136:137], 2, s[2:3]
	v_add_u32_e32 v136, v233, v158
	v_lshl_add_u64 v[136:137], v[136:137], 2, s[88:89]
	global_load_dwordx2 v[204:205], v[196:197], off
	v_add_u32_e32 v198, v233, v231
	global_load_dwordx4 v[136:139], v[136:137], off
	v_mov_b32_e32 v199, v159
	v_add_u32_e32 v207, 0x90, v206
	v_lshl_add_u64 v[198:199], v[198:199], 2, s[88:89]
	v_lshlrev_b32_e32 v234, 11, v207
	global_load_dwordx4 v[208:211], v[198:199], off
	v_add_u32_e32 v212, v234, v158
	v_mov_b32_e32 v213, v159
	v_lshl_add_u64 v[212:213], v[212:213], 2, s[88:89]
	global_load_dwordx4 v[212:215], v[212:213], off
	v_lshlrev_b32_e32 v198, 1, v207
	v_mov_b32_e32 v199, v159
	v_lshl_add_u64 v[198:199], v[198:199], 2, s[2:3]
	global_load_dwordx2 v[238:239], v[198:199], off
	v_add_u32_e32 v216, v234, v231
	v_mov_b32_e32 v217, v159
	v_lshl_add_u64 v[216:217], v[216:217], 2, s[88:89]
	global_load_dwordx4 v[216:219], v[216:217], off
	v_add_u32_e32 v240, 0x40000, v194
	v_mov_b32_e32 v241, v159
	v_lshl_add_u64 v[240:241], v[240:241], 2, s[90:91]
	s_waitcnt vmcnt(0)
;     template <bool LN, int BJ, int LO, int HI> DI void batch(const f32x4 (&acc)[2][2][4][2], unsigned row0, unsigned col0, const f32x4 (&gv)[2], const f32x4 (&bv)[2]) const {
;         f32x4 r[HI - LO]; float mean[(HI - LO) / 2], rstd[(HI - LO) / 2];
; #pragma unroll
;         for (int i = LO; i < HI; ++i) { const int ai = i >> 3, m = (i >> 1) & 3, n = i & 1; const unsigned row = row0 + ai * HALF + m * 16;
;             if (n == 0) { mean[(i - LO) >> 1] = 0.f; rstd[(i - LO) >> 1] = 1.f;
;                 if (LN) { const float2 st = *(const float2*)(stats + row * 2u); mean[(i - LO) >> 1] = st.x; rstd[(i - LO) >> 1] = st.y; } }
;             r[i - LO] = *(const f32x4*)(src + (row * (unsigned)DM + col0 + BJ * HALF + n * 16)); }
; #pragma unroll
;         for (int i = LO; i < HI; ++i) { const int ai = i >> 3, m = (i >> 1) & 3, n = i & 1; const unsigned row = row0 + ai * HALF + m * 16;
;             *(f32x4*)(Y + (row * (unsigned)DM + col0 + BJ * HALF + n * 16)) = acc[ai][BJ][m][n] + ((r[i - LO] - mean[(i - LO) >> 1]) * rstd[(i - LO) >> 1]) * gv[n] + bv[n]; }
;         __builtin_amdgcn_sched_barrier(0);
;     }
;     template <bool LN, int BJ> DI void load_gb(unsigned col0, f32x4 (&gv)[2], f32x4 (&bv)[2]) const {
; #pragma unroll
;         for (int n = 0; n < 2; ++n) {
;             if (LN) { gv[n] = *(const f32x4*)(gam + col0 + BJ * HALF + n * 16) * ALPHA; bv[n] = *(const f32x4*)(bet + col0 + BJ * HALF + n * 16) * ALPHA; }
;             else { gv[n] = (f32x4){ALPHA, ALPHA, ALPHA, ALPHA}; bv[n] = (f32x4){0.f, 0.f, 0.f, 0.f}; }
;         }
;     }
;     template <bool LN> DI void run(const f32x4 (&acc)[2][2][4][2], const Unit& u, int wr, int wc, int fr, int fq) const {
;         const unsigned row0 = u.pm * BM + wr * 64 + fr, col0 = u.pn * BM + wc * 32 + 4 * fq;
;         f32x4 gv[2], bv[2];
;         load_gb<LN, 0>(col0, gv, bv);
;         batch<LN, 0, 0, 4>(acc, row0, col0, gv, bv);
;         batch<LN, 0, 4, 8>(acc, row0, col0, gv, bv);
;         batch<LN, 0, 8, 12>(acc, row0, col0, gv, bv);
;         batch<LN, 0, 12, 16>(acc, row0, col0, gv, bv);
;         load_gb<LN, 1>(col0, gv, bv);
	v_sub_f32_e32 v137, v137, v204
	v_sub_f32_e32 v136, v136, v204
	v_sub_f32_e32 v139, v139, v204
	v_sub_f32_e32 v138, v138, v204
	v_pk_mul_f32 v[138:139], v[204:205], v[138:139] op_sel:[1,0]
	v_pk_mul_f32 v[136:137], v[204:205], v[136:137] op_sel:[1,0]
	v_pk_fma_f32 v[138:139], v[152:153], v[138:139], v[94:95]
	v_pk_fma_f32 v[136:137], v[154:155], v[136:137], v[92:93]
	v_pk_fma_f32 v[138:139], v[134:135], s[78:79], v[138:139] op_sel_hi:[1,0,1]
	v_pk_fma_f32 v[136:137], v[132:133], s[78:79], v[136:137] op_sel_hi:[1,0,1]
	global_store_dwordx4 v[240:241], v[136:139], off
	s_nop 1
	v_sub_f32_e32 v137, v209, v204
	v_sub_f32_e32 v136, v208, v204
	v_sub_f32_e32 v139, v211, v204
	v_sub_f32_e32 v138, v210, v204
	v_pk_mul_f32 v[138:139], v[204:205], v[138:139] op_sel:[1,0]
	v_pk_mul_f32 v[136:137], v[204:205], v[136:137] op_sel:[1,0]
	v_pk_fma_f32 v[138:139], v[148:149], v[138:139], v[90:91]
	v_pk_fma_f32 v[136:137], v[150:151], v[136:137], v[88:89]
	v_add_u32_e32 v204, 0x40010, v194
	v_mov_b32_e32 v205, v159
	v_pk_fma_f32 v[138:139], v[130:131], s[78:79], v[138:139] op_sel_hi:[1,0,1]
	v_pk_fma_f32 v[136:137], v[128:129], s[78:79], v[136:137] op_sel_hi:[1,0,1]
	v_lshl_add_u64 v[204:205], v[204:205], 2, s[90:91]
	global_store_dwordx4 v[204:205], v[136:139], off
	v_add_u32_e32 v204, 0x48000, v194
	v_mov_b32_e32 v205, v159
	v_sub_f32_e32 v137, v213, v238
	v_sub_f32_e32 v136, v212, v238
	v_sub_f32_e32 v139, v215, v238
	v_sub_f32_e32 v138, v214, v238
	v_pk_mul_f32 v[138:139], v[238:239], v[138:139] op_sel:[1,0]
	v_pk_mul_f32 v[136:137], v[238:239], v[136:137] op_sel:[1,0]
	v_pk_fma_f32 v[138:139], v[152:153], v[138:139], v[86:87]
	v_pk_fma_f32 v[136:137], v[154:155], v[136:137], v[84:85]
	v_pk_fma_f32 v[138:139], v[134:135], s[78:79], v[138:139] op_sel_hi:[1,0,1]
	v_pk_fma_f32 v[136:137], v[132:133], s[78:79], v[136:137] op_sel_hi:[1,0,1]
	v_lshl_add_u64 v[204:205], v[204:205], 2, s[90:91]
	global_store_dwordx4 v[204:205], v[136:139], off
	v_add_u32_e32 v204, 0x48010, v194
	v_mov_b32_e32 v205, v159
	v_sub_f32_e32 v137, v217, v238
	v_sub_f32_e32 v136, v216, v238
	v_sub_f32_e32 v139, v219, v238
	v_sub_f32_e32 v138, v218, v238
	v_pk_mul_f32 v[138:139], v[238:239], v[138:139] op_sel:[1,0]
	v_pk_mul_f32 v[136:137], v[238:239], v[136:137] op_sel:[1,0]
	v_pk_fma_f32 v[138:139], v[148:149], v[138:139], v[82:83]
	v_pk_fma_f32 v[136:137], v[150:151], v[136:137], v[80:81]
	v_pk_fma_f32 v[138:139], v[130:131], s[78:79], v[138:139] op_sel_hi:[1,0,1]
	v_pk_fma_f32 v[136:137], v[128:129], s[78:79], v[136:137] op_sel_hi:[1,0,1]
	v_lshl_add_u64 v[204:205], v[204:205], 2, s[90:91]
	global_store_dwordx4 v[204:205], v[136:139], off
	s_nop 1
	v_add_u32_e32 v138, 0xa0, v206
	v_lshlrev_b32_e32 v136, 1, v138
	v_mov_b32_e32 v137, v159
	v_lshlrev_b32_e32 v237, 11, v138
	v_lshl_add_u64 v[204:205], v[136:137], 2, s[2:3]
	v_add_u32_e32 v136, v237, v158
	v_lshl_add_u64 v[136:137], v[136:137], 2, s[88:89]
	global_load_dwordx2 v[240:241], v[204:205], off
	v_add_u32_e32 v208, v237, v231
	global_load_dwordx4 v[136:139], v[136:137], off
	v_mov_b32_e32 v209, v159
	v_lshl_add_u64 v[208:209], v[208:209], 2, s[88:89]
	global_load_dwordx4 v[212:215], v[208:209], off
	v_add_u32_e32 v208, 0xb0, v206
	v_lshlrev_b32_e32 v206, 1, v208
	v_mov_b32_e32 v207, v159
	v_lshlrev_b32_e32 v238, 11, v208
	v_lshl_add_u64 v[210:211], v[206:207], 2, s[2:3]
	v_add_u32_e32 v206, v238, v158
	v_lshl_add_u64 v[206:207], v[206:207], 2, s[88:89]
	global_load_dwordx2 v[242:243], v[210:211], off
	v_add_u32_e32 v216, v238, v231
	global_load_dwordx4 v[206:209], v[206:207], off
	v_mov_b32_e32 v217, v159
	v_lshl_add_u64 v[216:217], v[216:217], 2, s[88:89]
	global_load_dwordx4 v[216:219], v[216:217], off
	v_add_u32_e32 v244, 0x50000, v194
	v_mov_b32_e32 v245, v159
	v_lshl_add_u64 v[244:245], v[244:245], 2, s[90:91]
	s_waitcnt vmcnt(0)
	v_sub_f32_e32 v137, v137, v240
	v_sub_f32_e32 v136, v136, v240
	v_sub_f32_e32 v139, v139, v240
	v_sub_f32_e32 v138, v138, v240
	v_pk_mul_f32 v[138:139], v[240:241], v[138:139] op_sel:[1,0]
	v_pk_mul_f32 v[136:137], v[240:241], v[136:137] op_sel:[1,0]
	v_pk_fma_f32 v[138:139], v[152:153], v[138:139], v[78:79]
	v_pk_fma_f32 v[136:137], v[154:155], v[136:137], v[76:77]
	v_pk_fma_f32 v[138:139], v[134:135], s[78:79], v[138:139] op_sel_hi:[1,0,1]
	v_pk_fma_f32 v[136:137], v[132:133], s[78:79], v[136:137] op_sel_hi:[1,0,1]
	global_store_dwordx4 v[244:245], v[136:139], off
	s_nop 1
	v_sub_f32_e32 v137, v213, v240
	v_sub_f32_e32 v136, v212, v240
	v_sub_f32_e32 v139, v215, v240
	v_sub_f32_e32 v138, v214, v240
	v_pk_mul_f32 v[138:139], v[240:241], v[138:139] op_sel:[1,0]
	v_pk_mul_f32 v[136:137], v[240:241], v[136:137] op_sel:[1,0]
	v_pk_fma_f32 v[138:139], v[148:149], v[138:139], v[74:75]
	v_pk_fma_f32 v[136:137], v[150:151], v[136:137], v[72:73]
	v_add_u32_e32 v212, 0x50010, v194
	v_mov_b32_e32 v213, v159
	v_pk_fma_f32 v[138:139], v[130:131], s[78:79], v[138:139] op_sel_hi:[1,0,1]
	v_pk_fma_f32 v[136:137], v[128:129], s[78:79], v[136:137] op_sel_hi:[1,0,1]
	v_lshl_add_u64 v[212:213], v[212:213], 2, s[90:91]
	global_store_dwordx4 v[212:213], v[136:139], off
	s_nop 1
	v_sub_f32_e32 v137, v207, v242
	v_sub_f32_e32 v136, v206, v242
	v_sub_f32_e32 v139, v209, v242
	v_sub_f32_e32 v138, v208, v242
	v_pk_mul_f32 v[136:137], v[242:243], v[136:137] op_sel:[1,0]
	v_pk_mul_f32 v[138:139], v[242:243], v[138:139] op_sel:[1,0]
	v_pk_fma_f32 v[136:137], v[154:155], v[136:137], v[68:69]
	v_pk_fma_f32 v[138:139], v[152:153], v[138:139], v[70:71]
	v_pk_fma_f32 v[132:133], v[132:133], s[78:79], v[136:137] op_sel_hi:[1,0,1]
	v_add_u32_e32 v136, 0x58000, v194
	v_mov_b32_e32 v137, v159
	v_pk_fma_f32 v[134:135], v[134:135], s[78:79], v[138:139] op_sel_hi:[1,0,1]
	v_lshl_add_u64 v[136:137], v[136:137], 2, s[90:91]
	global_store_dwordx4 v[136:137], v[132:135], off
	s_nop 1
	v_sub_f32_e32 v133, v217, v242
	v_sub_f32_e32 v132, v216, v242
	v_sub_f32_e32 v135, v219, v242
	v_sub_f32_e32 v134, v218, v242
	v_pk_mul_f32 v[132:133], v[242:243], v[132:133] op_sel:[1,0]
	v_pk_mul_f32 v[134:135], v[242:243], v[134:135] op_sel:[1,0]
	v_pk_fma_f32 v[132:133], v[150:151], v[132:133], v[64:65]
	v_pk_fma_f32 v[134:135], v[148:149], v[134:135], v[66:67]
	v_pk_fma_f32 v[128:129], v[128:129], s[78:79], v[132:133] op_sel_hi:[1,0,1]
	v_add_u32_e32 v132, 0x58010, v194
	v_mov_b32_e32 v133, v159
	v_pk_fma_f32 v[130:131], v[130:131], s[78:79], v[134:135] op_sel_hi:[1,0,1]
	v_lshl_add_u64 v[132:133], v[132:133], 2, s[90:91]
	global_store_dwordx4 v[132:133], v[128:131], off
	global_load_dwordx4 v[128:131], v[140:141], off offset:512
	v_add_u32_e32 v136, v232, v230
	v_mov_b32_e32 v137, v159
	v_lshl_add_u64 v[136:137], v[136:137], 2, s[88:89]
	s_waitcnt vmcnt(0)
;     template <bool LN, int BJ, int LO, int HI> DI void batch(const f32x4 (&acc)[2][2][4][2], unsigned row0, unsigned col0, const f32x4 (&gv)[2], const f32x4 (&bv)[2]) const {
;         f32x4 r[HI - LO]; float mean[(HI - LO) / 2], rstd[(HI - LO) / 2];
; #pragma unroll
;         for (int i = LO; i < HI; ++i) { const int ai = i >> 3, m = (i >> 1) & 3, n = i & 1; const unsigned row = row0 + ai * HALF + m * 16;
;             if (n == 0) { mean[(i - LO) >> 1] = 0.f; rstd[(i - LO) >> 1] = 1.f;
;                 if (LN) { const float2 st = *(const float2*)(stats + row * 2u); mean[(i - LO) >> 1] = st.x; rstd[(i - LO) >> 1] = st.y; } }
;             r[i - LO] = *(const f32x4*)(src + (row * (unsigned)DM + col0 + BJ * HALF + n * 16)); }
; #pragma unroll
;         for (int i = LO; i < HI; ++i) { const int ai = i >> 3, m = (i >> 1) & 3, n = i & 1; const unsigned row = row0 + ai * HALF + m * 16;
;             *(f32x4*)(Y + (row * (unsigned)DM + col0 + BJ * HALF + n * 16)) = acc[ai][BJ][m][n] + ((r[i - LO] - mean[(i - LO) >> 1]) * rstd[(i - LO) >> 1]) * gv[n] + bv[n]; }
;         __builtin_amdgcn_sched_barrier(0);
;     }
;     template <bool LN, int BJ> DI void load_gb(unsigned col0, f32x4 (&gv)[2], f32x4 (&bv)[2]) const {
; #pragma unroll
;         for (int n = 0; n < 2; ++n) {
;             if (LN) { gv[n] = *(const f32x4*)(gam + col0 + BJ * HALF + n * 16) * ALPHA; bv[n] = *(const f32x4*)(bet + col0 + BJ * HALF + n * 16) * ALPHA; }
;             else { gv[n] = (f32x4){ALPHA, ALPHA, ALPHA, ALPHA}; bv[n] = (f32x4){0.f, 0.f, 0.f, 0.f}; }
;         }
;     }
;     template <bool LN> DI void run(const f32x4 (&acc)[2][2][4][2], const Unit& u, int wr, int wc, int fr, int fq) const {
;         const unsigned row0 = u.pm * BM + wr * 64 + fr, col0 = u.pn * BM + wc * 32 + 4 * fq;
;         f32x4 gv[2], bv[2];
;         load_gb<LN, 0>(col0, gv, bv);
;         batch<LN, 0, 0, 4>(acc, row0, col0, gv, bv);
;         batch<LN, 0, 4, 8>(acc, row0, col0, gv, bv);
;         batch<LN, 0, 8, 12>(acc, row0, col0, gv, bv);
;         batch<LN, 0, 12, 16>(acc, row0, col0, gv, bv);
;         load_gb<LN, 1>(col0, gv, bv);
;         batch<LN, 1, 0, 8>(acc, row0, col0, gv, bv);
;         batch<LN, 1, 8, 16>(acc, row0, col0, gv, bv);
	v_pk_mul_f32 v[212:213], v[130:131], s[78:79] op_sel_hi:[1,0]
	v_pk_mul_f32 v[214:215], v[128:129], s[78:79] op_sel_hi:[1,0]
	global_load_dwordx4 v[132:135], v[142:143], off offset:512
	global_load_dwordx4 v[128:131], v[140:141], off offset:576
	s_waitcnt vmcnt(0)
	v_pk_mul_f32 v[206:207], v[130:131], s[78:79] op_sel_hi:[1,0]
	v_pk_mul_f32 v[208:209], v[128:129], s[78:79] op_sel_hi:[1,0]
	global_load_dwordx4 v[128:131], v[142:143], off offset:576
	global_load_dwordx2 v[220:221], v[144:145], off
	global_load_dwordx4 v[240:243], v[136:137], off
	v_add_u32_e32 v136, v232, v229
	v_mov_b32_e32 v137, v159
	v_lshl_add_u64 v[136:137], v[136:137], 2, s[88:89]
	global_load_dwordx4 v[244:247], v[136:137], off
	global_load_dwordx2 v[218:219], v[146:147], off
	v_add_u32_e32 v136, v195, v230
	v_mov_b32_e32 v137, v159
	v_lshl_add_u64 v[136:137], v[136:137], 2, s[88:89]
	global_load_dwordx4 v[248:251], v[136:137], off
	v_add_u32_e32 v136, v195, v229
	v_mov_b32_e32 v137, v159
	v_lshl_add_u64 v[136:137], v[136:137], 2, s[88:89]
	global_load_dwordx4 v[152:155], v[136:137], off
	global_load_dwordx2 v[216:217], v[200:201], off
	v_add_u32_e32 v136, v236, v230
	v_mov_b32_e32 v137, v159
	v_lshl_add_u64 v[136:137], v[136:137], 2, s[88:89]
	global_load_dwordx4 v[148:151], v[136:137], off
	v_add_u32_e32 v136, v236, v229
	v_mov_b32_e32 v137, v159
	v_lshl_add_u64 v[136:137], v[136:137], 2, s[88:89]
	global_load_dwordx4 v[144:147], v[136:137], off
	global_load_dwordx2 v[200:201], v[202:203], off
	v_add_u32_e32 v136, v235, v230
	v_mov_b32_e32 v137, v159
	v_lshl_add_u64 v[136:137], v[136:137], 2, s[88:89]
	global_load_dwordx4 v[140:143], v[136:137], off
	v_add_u32_e32 v136, v235, v229
	v_mov_b32_e32 v137, v159
	v_lshl_add_u64 v[136:137], v[136:137], 2, s[88:89]
	global_load_dwordx4 v[136:139], v[136:137], off
	v_add_u32_e32 v202, 0x80, v194
	v_mov_b32_e32 v203, v159
	v_lshl_add_u64 v[202:203], v[202:203], 2, s[90:91]
	s_waitcnt vmcnt(0)
	v_sub_f32_e32 v241, v241, v220
	v_sub_f32_e32 v240, v240, v220
	v_sub_f32_e32 v243, v243, v220
	v_sub_f32_e32 v242, v242, v220
	v_pk_mul_f32 v[242:243], v[220:221], v[242:243] op_sel:[1,0]
	v_pk_mul_f32 v[240:241], v[220:221], v[240:241] op_sel:[1,0]
	v_pk_fma_f32 v[242:243], v[212:213], v[242:243], v[62:63]
	v_pk_fma_f32 v[240:241], v[214:215], v[240:241], v[60:61]
	v_pk_fma_f32 v[242:243], v[134:135], s[78:79], v[242:243] op_sel_hi:[1,0,1]
	v_pk_fma_f32 v[240:241], v[132:133], s[78:79], v[240:241] op_sel_hi:[1,0,1]
	global_store_dwordx4 v[202:203], v[240:243], off
	v_sub_f32_e32 v203, v245, v220
	v_sub_f32_e32 v202, v244, v220
	v_sub_f32_e32 v241, v247, v220
	v_sub_f32_e32 v240, v246, v220
	v_pk_mul_f32 v[202:203], v[220:221], v[202:203] op_sel:[1,0]
	v_pk_mul_f32 v[240:241], v[220:221], v[240:241] op_sel:[1,0]
	v_pk_fma_f32 v[202:203], v[208:209], v[202:203], v[56:57]
	v_pk_fma_f32 v[220:221], v[206:207], v[240:241], v[58:59]
	v_pk_fma_f32 v[240:241], v[128:129], s[78:79], v[202:203] op_sel_hi:[1,0,1]
	v_add_u32_e32 v202, 0x90, v194
	v_mov_b32_e32 v203, v159
	v_pk_fma_f32 v[242:243], v[130:131], s[78:79], v[220:221] op_sel_hi:[1,0,1]
	v_lshl_add_u64 v[202:203], v[202:203], 2, s[90:91]
	global_store_dwordx4 v[202:203], v[240:243], off
	v_sub_f32_e32 v203, v249, v218
	v_sub_f32_e32 v202, v248, v218
	v_sub_f32_e32 v221, v251, v218
	v_sub_f32_e32 v220, v250, v218
	v_pk_mul_f32 v[202:203], v[218:219], v[202:203] op_sel:[1,0]
	v_pk_mul_f32 v[220:221], v[218:219], v[220:221] op_sel:[1,0]
	v_pk_fma_f32 v[202:203], v[214:215], v[202:203], v[52:53]
	v_pk_fma_f32 v[220:221], v[212:213], v[220:221], v[54:55]
	v_pk_fma_f32 v[240:241], v[132:133], s[78:79], v[202:203] op_sel_hi:[1,0,1]
	v_add_u32_e32 v202, 0x8080, v194
	v_mov_b32_e32 v203, v159
	v_sub_f32_e32 v153, v153, v218
	v_sub_f32_e32 v152, v152, v218
	v_sub_f32_e32 v155, v155, v218
	v_sub_f32_e32 v154, v154, v218
	v_pk_fma_f32 v[242:243], v[134:135], s[78:79], v[220:221] op_sel_hi:[1,0,1]
	v_lshl_add_u64 v[202:203], v[202:203], 2, s[90:91]
	v_pk_mul_f32 v[154:155], v[218:219], v[154:155] op_sel:[1,0]
	v_pk_mul_f32 v[152:153], v[218:219], v[152:153] op_sel:[1,0]
	global_store_dwordx4 v[202:203], v[240:243], off
	v_pk_fma_f32 v[152:153], v[208:209], v[152:153], v[48:49]
	v_pk_fma_f32 v[154:155], v[206:207], v[154:155], v[50:51]
	v_add_u32_e32 v202, 0x8090, v194
	v_mov_b32_e32 v203, v159
	v_sub_f32_e32 v149, v149, v216
	v_sub_f32_e32 v148, v148, v216
	v_sub_f32_e32 v151, v151, v216
	v_sub_f32_e32 v150, v150, v216
	v_pk_fma_f32 v[154:155], v[130:131], s[78:79], v[154:155] op_sel_hi:[1,0,1]
	v_pk_fma_f32 v[152:153], v[128:129], s[78:79], v[152:153] op_sel_hi:[1,0,1]
	v_lshl_add_u64 v[202:203], v[202:203], 2, s[90:91]
	v_pk_mul_f32 v[150:151], v[216:217], v[150:151] op_sel:[1,0]
	v_pk_mul_f32 v[148:149], v[216:217], v[148:149] op_sel:[1,0]
	global_store_dwordx4 v[202:203], v[152:155], off
	v_pk_fma_f32 v[148:149], v[214:215], v[148:149], v[44:45]
	v_pk_fma_f32 v[150:151], v[212:213], v[150:151], v[46:47]
	v_add_u32_e32 v152, 0x10080, v194
	v_mov_b32_e32 v153, v159
	v_sub_f32_e32 v145, v145, v216
	v_sub_f32_e32 v144, v144, v216
	v_sub_f32_e32 v147, v147, v216
	v_sub_f32_e32 v146, v146, v216
	v_pk_fma_f32 v[150:151], v[134:135], s[78:79], v[150:151] op_sel_hi:[1,0,1]
	v_pk_fma_f32 v[148:149], v[132:133], s[78:79], v[148:149] op_sel_hi:[1,0,1]
	v_lshl_add_u64 v[152:153], v[152:153], 2, s[90:91]
	v_pk_mul_f32 v[146:147], v[216:217], v[146:147] op_sel:[1,0]
	v_pk_mul_f32 v[144:145], v[216:217], v[144:145] op_sel:[1,0]
	global_store_dwordx4 v[152:153], v[148:151], off
	v_pk_fma_f32 v[144:145], v[208:209], v[144:145], v[40:41]
	v_pk_fma_f32 v[146:147], v[206:207], v[146:147], v[42:43]
;     template <bool LN, int BJ, int LO, int HI> DI void batch(const f32x4 (&acc)[2][2][4][2], unsigned row0, unsigned col0, const f32x4 (&gv)[2], const f32x4 (&bv)[2]) const {
;         f32x4 r[HI - LO]; float mean[(HI - LO) / 2], rstd[(HI - LO) / 2];
; #pragma unroll
;         for (int i = LO; i < HI; ++i) { const int ai = i >> 3, m = (i >> 1) & 3, n = i & 1; const unsigned row = row0 + ai * HALF + m * 16;
;             if (n == 0) { mean[(i - LO) >> 1] = 0.f; rstd[(i - LO) >> 1] = 1.f;
;                 if (LN) { const float2 st = *(const float2*)(stats + row * 2u); mean[(i - LO) >> 1] = st.x; rstd[(i - LO) >> 1] = st.y; } }
;             r[i - LO] = *(const f32x4*)(src + (row * (unsigned)DM + col0 + BJ * HALF + n * 16)); }
; #pragma unroll
;         for (int i = LO; i < HI; ++i) { const int ai = i >> 3, m = (i >> 1) & 3, n = i & 1; const unsigned row = row0 + ai * HALF + m * 16;
;             *(f32x4*)(Y + (row * (unsigned)DM + col0 + BJ * HALF + n * 16)) = acc[ai][BJ][m][n] + ((r[i - LO] - mean[(i - LO) >> 1]) * rstd[(i - LO) >> 1]) * gv[n] + bv[n]; }
;         __builtin_amdgcn_sched_barrier(0);
;     }
;     template <bool LN, int BJ> DI void load_gb(unsigned col0, f32x4 (&gv)[2], f32x4 (&bv)[2]) const {
; #pragma unroll
;         for (int n = 0; n < 2; ++n) {
;             if (LN) { gv[n] = *(const f32x4*)(gam + col0 + BJ * HALF + n * 16) * ALPHA; bv[n] = *(const f32x4*)(bet + col0 + BJ * HALF + n * 16) * ALPHA; }
;             else { gv[n] = (f32x4){ALPHA, ALPHA, ALPHA, ALPHA}; bv[n] = (f32x4){0.f, 0.f, 0.f, 0.f}; }
;         }
;     }
;     template <bool LN> DI void run(const f32x4 (&acc)[2][2][4][2], const Unit& u, int wr, int wc, int fr, int fq) const {
;         const unsigned row0 = u.pm * BM + wr * 64 + fr, col0 = u.pn * BM + wc * 32 + 4 * fq;
;         f32x4 gv[2], bv[2];
;         load_gb<LN, 0>(col0, gv, bv);
;         batch<LN, 0, 0, 4>(acc, row0, col0, gv, bv);
;         batch<LN, 0, 4, 8>(acc, row0, col0, gv, bv);
;         batch<LN, 0, 8, 12>(acc, row0, col0, gv, bv);
;         batch<LN, 0, 12, 16>(acc, row0, col0, gv, bv);
;         load_gb<LN, 1>(col0, gv, bv);
;         batch<LN, 1, 0, 8>(acc, row0, col0, gv, bv);
;         batch<LN, 1, 8, 16>(acc, row0, col0, gv, bv);
	v_add_u32_e32 v148, 0x10090, v194
	v_mov_b32_e32 v149, v159
	v_sub_f32_e32 v141, v141, v200
	v_sub_f32_e32 v140, v140, v200
	v_sub_f32_e32 v143, v143, v200
	v_sub_f32_e32 v142, v142, v200
	v_pk_fma_f32 v[146:147], v[130:131], s[78:79], v[146:147] op_sel_hi:[1,0,1]
	v_pk_fma_f32 v[144:145], v[128:129], s[78:79], v[144:145] op_sel_hi:[1,0,1]
	v_lshl_add_u64 v[148:149], v[148:149], 2, s[90:91]
	v_pk_mul_f32 v[142:143], v[200:201], v[142:143] op_sel:[1,0]
	v_pk_mul_f32 v[140:141], v[200:201], v[140:141] op_sel:[1,0]
	global_store_dwordx4 v[148:149], v[144:147], off
	v_pk_fma_f32 v[140:141], v[214:215], v[140:141], v[36:37]
	v_pk_fma_f32 v[142:143], v[212:213], v[142:143], v[38:39]
	v_add_u32_e32 v144, 0x18080, v194
	v_mov_b32_e32 v145, v159
	v_sub_f32_e32 v137, v137, v200
	v_sub_f32_e32 v136, v136, v200
	v_sub_f32_e32 v139, v139, v200
	v_sub_f32_e32 v138, v138, v200
	v_pk_fma_f32 v[142:143], v[134:135], s[78:79], v[142:143] op_sel_hi:[1,0,1]
	v_pk_fma_f32 v[140:141], v[132:133], s[78:79], v[140:141] op_sel_hi:[1,0,1]
	v_lshl_add_u64 v[144:145], v[144:145], 2, s[90:91]
	v_pk_mul_f32 v[138:139], v[200:201], v[138:139] op_sel:[1,0]
	v_pk_mul_f32 v[136:137], v[200:201], v[136:137] op_sel:[1,0]
	global_store_dwordx4 v[144:145], v[140:143], off
	v_pk_fma_f32 v[136:137], v[208:209], v[136:137], v[32:33]
	v_pk_fma_f32 v[138:139], v[206:207], v[138:139], v[34:35]
	v_add_u32_e32 v140, 0x18090, v194
	v_mov_b32_e32 v141, v159
	v_pk_fma_f32 v[138:139], v[130:131], s[78:79], v[138:139] op_sel_hi:[1,0,1]
	v_pk_fma_f32 v[136:137], v[128:129], s[78:79], v[136:137] op_sel_hi:[1,0,1]
	v_lshl_add_u64 v[140:141], v[140:141], 2, s[90:91]
	global_store_dwordx4 v[140:141], v[136:139], off
	s_nop 1
	v_add_u32_e32 v136, v233, v230
	v_mov_b32_e32 v137, v159
	v_lshl_add_u64 v[136:137], v[136:137], 2, s[88:89]
	global_load_dwordx2 v[220:221], v[196:197], off
	global_load_dwordx4 v[216:219], v[136:137], off
	v_add_u32_e32 v136, v233, v229
	v_mov_b32_e32 v137, v159
	v_lshl_add_u64 v[136:137], v[136:137], 2, s[88:89]
	global_load_dwordx4 v[240:243], v[136:137], off
	global_load_dwordx2 v[200:201], v[198:199], off
	v_add_u32_e32 v136, v234, v230
	v_mov_b32_e32 v137, v159
	v_lshl_add_u64 v[136:137], v[136:137], 2, s[88:89]
	global_load_dwordx4 v[244:247], v[136:137], off
	v_add_u32_e32 v136, v234, v229
	v_mov_b32_e32 v137, v159
	v_lshl_add_u64 v[136:137], v[136:137], 2, s[88:89]
	global_load_dwordx4 v[152:155], v[136:137], off
	global_load_dwordx2 v[198:199], v[204:205], off
	v_add_u32_e32 v136, v237, v230
	v_mov_b32_e32 v137, v159
	v_lshl_add_u64 v[136:137], v[136:137], 2, s[88:89]
	global_load_dwordx4 v[148:151], v[136:137], off
	v_add_u32_e32 v136, v237, v229
	v_mov_b32_e32 v137, v159
	v_lshl_add_u64 v[136:137], v[136:137], 2, s[88:89]
	global_load_dwordx4 v[144:147], v[136:137], off
	global_load_dwordx2 v[196:197], v[210:211], off
	v_add_u32_e32 v136, v238, v230
	v_mov_b32_e32 v137, v159
	v_lshl_add_u64 v[136:137], v[136:137], 2, s[88:89]
	global_load_dwordx4 v[140:143], v[136:137], off
	v_add_u32_e32 v136, v238, v229
	v_mov_b32_e32 v137, v159
	v_lshl_add_u64 v[136:137], v[136:137], 2, s[88:89]
	global_load_dwordx4 v[136:139], v[136:137], off
	v_add_u32_e32 v210, 0x40080, v194
	v_mov_b32_e32 v211, v159
	v_lshl_add_u64 v[210:211], v[210:211], 2, s[90:91]
	s_waitcnt vmcnt(0)
;     template <bool LN, int BJ, int LO, int HI> DI void batch(const f32x4 (&acc)[2][2][4][2], unsigned row0, unsigned col0, const f32x4 (&gv)[2], const f32x4 (&bv)[2]) const {
;         f32x4 r[HI - LO]; float mean[(HI - LO) / 2], rstd[(HI - LO) / 2];
; #pragma unroll
;         for (int i = LO; i < HI; ++i) { const int ai = i >> 3, m = (i >> 1) & 3, n = i & 1; const unsigned row = row0 + ai * HALF + m * 16;
;             if (n == 0) { mean[(i - LO) >> 1] = 0.f; rstd[(i - LO) >> 1] = 1.f;
;                 if (LN) { const float2 st = *(const float2*)(stats + row * 2u); mean[(i - LO) >> 1] = st.x; rstd[(i - LO) >> 1] = st.y; } }
;             r[i - LO] = *(const f32x4*)(src + (row * (unsigned)DM + col0 + BJ * HALF + n * 16)); }
; #pragma unroll
;         for (int i = LO; i < HI; ++i) { const int ai = i >> 3, m = (i >> 1) & 3, n = i & 1; const unsigned row = row0 + ai * HALF + m * 16;
;             *(f32x4*)(Y + (row * (unsigned)DM + col0 + BJ * HALF + n * 16)) = acc[ai][BJ][m][n] + ((r[i - LO] - mean[(i - LO) >> 1]) * rstd[(i - LO) >> 1]) * gv[n] + bv[n]; }
;         __builtin_amdgcn_sched_barrier(0);
;     }
;     template <bool LN, int BJ> DI void load_gb(unsigned col0, f32x4 (&gv)[2], f32x4 (&bv)[2]) const {
; #pragma unroll
;         for (int n = 0; n < 2; ++n) {
;             if (LN) { gv[n] = *(const f32x4*)(gam + col0 + BJ * HALF + n * 16) * ALPHA; bv[n] = *(const f32x4*)(bet + col0 + BJ * HALF + n * 16) * ALPHA; }
;             else { gv[n] = (f32x4){ALPHA, ALPHA, ALPHA, ALPHA}; bv[n] = (f32x4){0.f, 0.f, 0.f, 0.f}; }
;         }
;     }
;     template <bool LN> DI void run(const f32x4 (&acc)[2][2][4][2], const Unit& u, int wr, int wc, int fr, int fq) const {
;         const unsigned row0 = u.pm * BM + wr * 64 + fr, col0 = u.pn * BM + wc * 32 + 4 * fq;
;         f32x4 gv[2], bv[2];
;         load_gb<LN, 0>(col0, gv, bv);
;         batch<LN, 0, 0, 4>(acc, row0, col0, gv, bv);
;         batch<LN, 0, 4, 8>(acc, row0, col0, gv, bv);
;         batch<LN, 0, 8, 12>(acc, row0, col0, gv, bv);
;         batch<LN, 0, 12, 16>(acc, row0, col0, gv, bv);
;         load_gb<LN, 1>(col0, gv, bv);
;         batch<LN, 1, 0, 8>(acc, row0, col0, gv, bv);
;         batch<LN, 1, 8, 16>(acc, row0, col0, gv, bv);
	v_sub_f32_e32 v203, v217, v220
	v_sub_f32_e32 v202, v216, v220
	v_sub_f32_e32 v205, v219, v220
	v_sub_f32_e32 v204, v218, v220
	v_pk_mul_f32 v[204:205], v[220:221], v[204:205] op_sel:[1,0]
	v_pk_mul_f32 v[202:203], v[220:221], v[202:203] op_sel:[1,0]
	v_pk_fma_f32 v[204:205], v[212:213], v[204:205], v[30:31]
	v_pk_fma_f32 v[202:203], v[214:215], v[202:203], v[28:29]
	v_pk_fma_f32 v[204:205], v[134:135], s[78:79], v[204:205] op_sel_hi:[1,0,1]
	v_pk_fma_f32 v[202:203], v[132:133], s[78:79], v[202:203] op_sel_hi:[1,0,1]
	global_store_dwordx4 v[210:211], v[202:205], off
	v_add_u32_e32 v210, 0x40090, v194
	v_mov_b32_e32 v211, v159
	v_sub_f32_e32 v203, v241, v220
	v_sub_f32_e32 v202, v240, v220
	v_sub_f32_e32 v205, v243, v220
	v_sub_f32_e32 v204, v242, v220
	v_pk_mul_f32 v[204:205], v[220:221], v[204:205] op_sel:[1,0]
	v_pk_mul_f32 v[202:203], v[220:221], v[202:203] op_sel:[1,0]
	v_pk_fma_f32 v[204:205], v[206:207], v[204:205], v[26:27]
	v_pk_fma_f32 v[202:203], v[208:209], v[202:203], v[24:25]
	v_pk_fma_f32 v[204:205], v[130:131], s[78:79], v[204:205] op_sel_hi:[1,0,1]
	v_pk_fma_f32 v[202:203], v[128:129], s[78:79], v[202:203] op_sel_hi:[1,0,1]
	v_lshl_add_u64 v[210:211], v[210:211], 2, s[90:91]
	global_store_dwordx4 v[210:211], v[202:205], off
	v_sub_f32_e32 v149, v149, v198
	v_sub_f32_e32 v148, v148, v198
	v_sub_f32_e32 v203, v245, v200
	v_sub_f32_e32 v202, v244, v200
	v_sub_f32_e32 v141, v141, v196
	v_sub_f32_e32 v140, v140, v196
	v_sub_f32_e32 v205, v247, v200
	v_sub_f32_e32 v204, v246, v200
	v_pk_mul_f32 v[202:203], v[200:201], v[202:203] op_sel:[1,0]
	v_sub_f32_e32 v151, v151, v198
	v_sub_f32_e32 v150, v150, v198
	v_pk_mul_f32 v[148:149], v[198:199], v[148:149] op_sel:[1,0]
	v_sub_f32_e32 v143, v143, v196
	v_sub_f32_e32 v142, v142, v196
	v_pk_mul_f32 v[140:141], v[196:197], v[140:141] op_sel:[1,0]
	v_pk_mul_f32 v[204:205], v[200:201], v[204:205] op_sel:[1,0]
	v_pk_fma_f32 v[202:203], v[214:215], v[202:203], v[20:21]
	v_sub_f32_e32 v153, v153, v200
	v_sub_f32_e32 v152, v152, v200
	v_sub_f32_e32 v155, v155, v200
	v_sub_f32_e32 v154, v154, v200
	v_pk_mul_f32 v[150:151], v[198:199], v[150:151] op_sel:[1,0]
	v_pk_fma_f32 v[148:149], v[214:215], v[148:149], v[12:13]
	v_pk_mul_f32 v[142:143], v[196:197], v[142:143] op_sel:[1,0]
	v_pk_fma_f32 v[140:141], v[214:215], v[140:141], v[4:5]
	v_pk_fma_f32 v[204:205], v[212:213], v[204:205], v[22:23]
	v_pk_fma_f32 v[202:203], v[132:133], s[78:79], v[202:203] op_sel_hi:[1,0,1]
	v_pk_mul_f32 v[154:155], v[200:201], v[154:155] op_sel:[1,0]
	v_pk_mul_f32 v[152:153], v[200:201], v[152:153] op_sel:[1,0]
	v_pk_fma_f32 v[150:151], v[212:213], v[150:151], v[14:15]
	v_pk_fma_f32 v[148:149], v[132:133], s[78:79], v[148:149] op_sel_hi:[1,0,1]
	v_pk_fma_f32 v[142:143], v[212:213], v[142:143], v[6:7]
	v_pk_fma_f32 v[132:133], v[132:133], s[78:79], v[140:141] op_sel_hi:[1,0,1]
	v_add_u32_e32 v140, 0x58080, v194
	v_mov_b32_e32 v141, v159
	v_pk_fma_f32 v[204:205], v[134:135], s[78:79], v[204:205] op_sel_hi:[1,0,1]
	v_pk_fma_f32 v[152:153], v[208:209], v[152:153], v[16:17]
	v_pk_fma_f32 v[154:155], v[206:207], v[154:155], v[18:19]
	v_add_u32_e32 v200, 0x48090, v194
	v_mov_b32_e32 v201, v159
	v_pk_fma_f32 v[150:151], v[134:135], s[78:79], v[150:151] op_sel_hi:[1,0,1]
	v_pk_fma_f32 v[134:135], v[134:135], s[78:79], v[142:143] op_sel_hi:[1,0,1]
	v_lshl_add_u64 v[140:141], v[140:141], 2, s[90:91]
	v_pk_fma_f32 v[154:155], v[130:131], s[78:79], v[154:155] op_sel_hi:[1,0,1]
	v_pk_fma_f32 v[152:153], v[128:129], s[78:79], v[152:153] op_sel_hi:[1,0,1]
	v_lshl_add_u64 v[200:201], v[200:201], 2, s[90:91]
	v_sub_f32_e32 v145, v145, v198
	v_sub_f32_e32 v144, v144, v198
	global_store_dwordx4 v[140:141], v[132:135], off
	global_store_dwordx4 v[200:201], v[152:155], off
	v_sub_f32_e32 v147, v147, v198
	v_sub_f32_e32 v133, v137, v196
	v_sub_f32_e32 v132, v136, v196
	v_add_u32_e32 v152, 0x50080, v194
	v_mov_b32_e32 v153, v159
	v_sub_f32_e32 v146, v146, v198
	v_pk_mul_f32 v[144:145], v[198:199], v[144:145] op_sel:[1,0]
	v_sub_f32_e32 v135, v139, v196
	v_sub_f32_e32 v134, v138, v196
	v_pk_mul_f32 v[132:133], v[196:197], v[132:133] op_sel:[1,0]
	v_lshl_add_u64 v[152:153], v[152:153], 2, s[90:91]
	v_pk_mul_f32 v[146:147], v[198:199], v[146:147] op_sel:[1,0]
	v_pk_fma_f32 v[144:145], v[208:209], v[144:145], v[8:9]
	v_pk_mul_f32 v[134:135], v[196:197], v[134:135] op_sel:[1,0]
	v_pk_fma_f32 v[132:133], v[208:209], v[132:133], v[0:1]
	v_add_u32_e32 v210, 0x48080, v194
	v_mov_b32_e32 v211, v159
	global_store_dwordx4 v[152:153], v[148:151], off
	v_pk_fma_f32 v[146:147], v[206:207], v[146:147], v[10:11]
	v_pk_fma_f32 v[144:145], v[128:129], s[78:79], v[144:145] op_sel_hi:[1,0,1]
	v_add_u32_e32 v148, 0x50090, v194
	v_mov_b32_e32 v149, v159
	v_pk_fma_f32 v[134:135], v[206:207], v[134:135], v[2:3]
	v_pk_fma_f32 v[128:129], v[128:129], s[78:79], v[132:133] op_sel_hi:[1,0,1]
	v_add_u32_e32 v132, 0x58090, v194
	v_mov_b32_e32 v133, v159
	v_lshl_add_u64 v[210:211], v[210:211], 2, s[90:91]
	v_pk_fma_f32 v[146:147], v[130:131], s[78:79], v[146:147] op_sel_hi:[1,0,1]
	v_lshl_add_u64 v[148:149], v[148:149], 2, s[90:91]
	v_pk_fma_f32 v[130:131], v[130:131], s[78:79], v[134:135] op_sel_hi:[1,0,1]
	v_lshl_add_u64 v[132:133], v[132:133], 2, s[90:91]
	global_store_dwordx4 v[210:211], v[202:205], off
	global_store_dwordx4 v[148:149], v[144:147], off
	global_store_dwordx4 v[132:133], v[128:131], off
	s_mov_b64 s[24:25], 0
	s_branch .LBB0_324
